# v21 + the 72 mid-phase s_setprio 0 / s_setprio 1 flip pairs between the two MFMA groups of each GEMM M phase removed
# baseline (speedup 1.0000x reference)
; #define PG8_STAGE(bufoff, gbase, voff) do { _Pragma("unroll") for (int _i = 0; _i < 2; ++_i) \
;         dma16((const char*)(gbase), (voff)[_i], ldsb + (bufoff) + ldsw + _i * 8192); } while (0)
; #define PG8_LDA(dst, b, h) do { const int a1_ = opqv(aoff0) ^ 64; _Pragma("unroll") for (int m = 0; m < 4; ++m) { dst[m][0] = *(const LAS bf16x8*)(lds + PG8_SA(b, h) + aoff0 + m * 2048); dst[m][1] = *(const LAS bf16x8*)(lds + PG8_SA(b, h) + a1_ + m * 2048); } } while (0)
; #define PG8_WAIT_V(n) asm volatile("s_waitcnt vmcnt(" #n ")" ::: "memory")
; #define PG8_BAR __builtin_amdgcn_s_barrier()
; template <class Epi>
; __device__ __forceinline__ void gemm_phase(LAS unsigned char* lds, const Gemm g, const StaticOrder& S, const Epi& E, int wave_) {
;     ...
;         const bool has_next = S.next(ui + 1, nxt);
;         const char* nA = has_next ? (const char*)g.A + (size_t)nxt.pm * tstepA : cA; const char* nB = has_next ? (const char*)g.Bt + (size_t)nxt.pn * tstepB : cB;
; #pragma unroll 1
;         for (int t = 0; t < nt; t += 2) {
;             const bool last = (t == nt - 2);
;             const char* a1 = cA + (size_t)(t + 1) * kstep;
;             const char* a2 = last ? nA : cA + (size_t)(t + 2) * kstep; const char* b2 = last ? nB : cB + (size_t)(t + 2) * kstep;
;             const char* a3 = a2 + kstep; const char* b3 = b2 + kstep;
;             PG8_STAGE(PG8_SA(1, 1), a1 + hstepA, voffA); PG8_LDB(B0, 0, 0); PG8_LDB(B1, 0, 1); PG8_SCHED; PG8_LDA(At, 0, 0);
;             PG8_WAIT_V(8); PG8_WAIT_L(0); PG8_BAR; PG8_MMA(0, 0, At, B0); PG8_MMA(0, 1, At, B1); PG8_BAR; PG8_SCHED;
;             PG8_STAGE(PG8_SB(0, 0), b2, voffB); PG8_STAGE(PG8_SB(0, 1), b2 + hstepB, voffB); PG8_STAGE(PG8_SA(0, 0), a2, voffA); PG8_LDA(At, 0, 1);
;             PG8_WAIT_V(8); PG8_WAIT_L(0); PG8_BAR; PG8_MMA(1, 0, At, B0); PG8_MMA(1, 1, At, B1); PG8_BAR; PG8_SCHED;
;             PG8_STAGE(PG8_SA(0, 1), a2 + hstepA, voffA); PG8_LDB(B0, 1, 0); PG8_LDB(B1, 1, 1); PG8_SCHED; PG8_LDA(At, 1, 0);
;             PG8_WAIT_V(8); PG8_WAIT_L(0); PG8_BAR; PG8_MMA(0, 0, At, B0); PG8_MMA(0, 1, At, B1); PG8_BAR; PG8_SCHED;
;             PG8_STAGE(PG8_SB(1, 0), b3, voffB); PG8_STAGE(PG8_SB(1, 1), b3 + hstepB, voffB); PG8_STAGE(PG8_SA(1, 0), a3, voffA); PG8_LDA(At, 1, 1);
;             PG8_WAIT_V(8); PG8_WAIT_L(0); PG8_BAR; PG8_MMA(1, 0, At, B0); PG8_MMA(1, 1, At, B1); PG8_BAR; PG8_SCHED;
.LBB0_190:
	s_ashr_i32 s7, s6, 31
	s_lshl_b64 s[8:9], s[6:7], 20
	s_add_u32 s8, s16, s8
	s_addc_u32 s9, s17, s9
	s_and_b64 s[10:11], s[40:41], exec
	s_cselect_b32 s7, s9, s19
	s_cselect_b32 s45, s8, s18
	s_ashr_i32 s5, s4, 31
	s_lshl_b64 s[10:11], s[4:5], 20
	s_add_u32 s10, s21, s10
	s_addc_u32 s11, s30, s11
	s_and_b64 s[24:25], s[40:41], exec
	s_cselect_b32 s5, s11, s13
	s_cselect_b32 s46, s10, s12
	s_add_u32 s47, s12, 0x100
	s_addc_u32 s48, s13, 0
	s_add_u32 s12, s18, 0x80080
	s_addc_u32 s13, s19, 0
	s_mov_b32 s49, -2
	s_add_u32 s18, s12, 0xfff80080
	s_addc_u32 s19, s13, -1
	s_cmp_eq_u32 s49, 28
	s_cselect_b32 s26, s45, s18
	v_mov_b32_e32 v128, v139
	s_cselect_b32 s27, s7, s19
	s_cselect_b32 s24, s46, s47
	s_cselect_b32 s25, s5, s48
	s_add_u32 s18, s26, 0x80
	v_xad_u32 v128, v128, 64, s23
	v_add_u32_e32 v141, s23, v139
	s_addc_u32 s19, s27, 0
	ds_read_b128 v[130:133], v141
	ds_read_b128 v[142:145], v141 offset:2048
	ds_read_b128 v[146:149], v128
	ds_read_b128 v[150:153], v128 offset:2048
	v_mov_b32_e32 v128, v139
	s_add_i32 s52, 0, 0x14000
	v_add_u32_e32 v141, s52, v139
	v_xad_u32 v128, v128, 64, s52
	ds_read_b128 v[154:157], v141
	ds_read_b128 v[158:161], v141 offset:2048
	ds_read_b128 v[162:165], v128
	ds_read_b128 v[166:169], v128 offset:2048
	v_mov_b32_e32 v128, v138
	v_add_u32_e32 v141, 0, v138
	v_xad_u32 v128, v128, 64, 0
	ds_read_b128 v[170:173], v141
	ds_read_b128 v[174:177], v141 offset:2048
	ds_read_b128 v[178:181], v128
	ds_read_b128 v[192:195], v128 offset:2048
	ds_read_b128 v[196:199], v141 offset:4096
	ds_read_b128 v[200:203], v141 offset:6144
	ds_read_b128 v[204:207], v128 offset:4096
	ds_read_b128 v[208:211], v128 offset:6144
	s_mov_b32 m0, s14
	s_nop 0
	global_load_lds_dwordx4 v129, s[12:13]
	s_mov_b32 m0, s15
	s_nop 0
	global_load_lds_dwordx4 v135, s[12:13]
	s_waitcnt vmcnt(8)
	s_waitcnt lgkmcnt(0)
	s_setprio 1
	s_barrier
	v_mfma_f32_16x16x32_bf16 v[124:127], v[130:133], v[170:173], 0
	v_mfma_f32_16x16x32_bf16 v[120:123], v[142:145], v[170:173], 0
	v_mfma_f32_16x16x32_bf16 v[112:115], v[130:133], v[174:177], 0
	v_mfma_f32_16x16x32_bf16 v[104:107], v[142:145], v[174:177], 0
	v_mfma_f32_16x16x32_bf16 v[96:99], v[130:133], v[196:199], 0
	v_mfma_f32_16x16x32_bf16 v[88:91], v[142:145], v[196:199], 0
	v_mfma_f32_16x16x32_bf16 v[80:83], v[130:133], v[200:203], 0
	v_mfma_f32_16x16x32_bf16 v[72:75], v[142:145], v[200:203], 0
	v_mfma_f32_16x16x32_bf16 v[124:127], v[146:149], v[178:181], v[124:127]
	v_mfma_f32_16x16x32_bf16 v[120:123], v[150:153], v[178:181], v[120:123]
	v_mfma_f32_16x16x32_bf16 v[112:115], v[146:149], v[192:195], v[112:115]
	v_mfma_f32_16x16x32_bf16 v[104:107], v[150:153], v[192:195], v[104:107]
	v_mfma_f32_16x16x32_bf16 v[96:99], v[146:149], v[204:207], v[96:99]
	v_mfma_f32_16x16x32_bf16 v[88:91], v[150:153], v[204:207], v[88:91]
	v_mfma_f32_16x16x32_bf16 v[80:83], v[146:149], v[208:211], v[80:83]
	v_mfma_f32_16x16x32_bf16 v[72:75], v[150:153], v[208:211], v[72:75]
	v_mfma_f32_16x16x32_bf16 v[116:119], v[154:157], v[170:173], 0
	v_mfma_f32_16x16x32_bf16 v[108:111], v[158:161], v[170:173], 0
	v_mfma_f32_16x16x32_bf16 v[100:103], v[154:157], v[174:177], 0
	v_mfma_f32_16x16x32_bf16 v[92:95], v[158:161], v[174:177], 0
	v_mfma_f32_16x16x32_bf16 v[84:87], v[154:157], v[196:199], 0
	v_mfma_f32_16x16x32_bf16 v[76:79], v[158:161], v[196:199], 0
	v_mfma_f32_16x16x32_bf16 v[68:71], v[154:157], v[200:203], 0
	v_mfma_f32_16x16x32_bf16 v[64:67], v[158:161], v[200:203], 0
	v_mfma_f32_16x16x32_bf16 v[116:119], v[162:165], v[178:181], v[116:119]
	v_mfma_f32_16x16x32_bf16 v[108:111], v[166:169], v[178:181], v[108:111]
	v_mfma_f32_16x16x32_bf16 v[100:103], v[162:165], v[192:195], v[100:103]
	v_mfma_f32_16x16x32_bf16 v[92:95], v[166:169], v[192:195], v[92:95]
	v_mfma_f32_16x16x32_bf16 v[84:87], v[162:165], v[204:207], v[84:87]
	v_mfma_f32_16x16x32_bf16 v[76:79], v[166:169], v[204:207], v[76:79]
	v_mfma_f32_16x16x32_bf16 v[68:71], v[162:165], v[208:211], v[68:71]
	v_mfma_f32_16x16x32_bf16 v[64:67], v[166:169], v[208:211], v[64:67]
	s_barrier
	s_setprio 0
	s_add_u32 s54, s24, 0x80000
	s_addc_u32 s55, s25, 0
	v_mov_b32_e32 v128, v138
	s_nop 0
	s_nop 0
	s_nop 0
	v_xad_u32 v128, v128, 64, 0
	ds_read_b128 v[170:173], v141 offset:16384
	ds_read_b128 v[174:177], v141 offset:18432
	ds_read_b128 v[178:181], v128 offset:16384
	ds_read_b128 v[192:195], v128 offset:18432
	ds_read_b128 v[196:199], v141 offset:20480
	ds_read_b128 v[200:203], v141 offset:22528
	ds_read_b128 v[204:207], v128 offset:20480
	ds_read_b128 v[208:211], v128 offset:22528
	s_mov_b32 m0, s80
	s_nop 0
	global_load_lds_dwordx4 v134, s[24:25]
	s_mov_b32 m0, s81
	s_nop 0
	global_load_lds_dwordx4 v136, s[24:25]
	s_mov_b32 m0, s29
	s_nop 0
	global_load_lds_dwordx4 v134, s[54:55]
	s_mov_b32 m0, s88
	s_nop 0
	global_load_lds_dwordx4 v136, s[54:55]
	s_mov_b32 m0, s76
	s_nop 0
	global_load_lds_dwordx4 v129, s[26:27]
	s_mov_b32 m0, s89
	s_nop 0
	global_load_lds_dwordx4 v135, s[26:27]
	s_waitcnt vmcnt(8)
	s_waitcnt lgkmcnt(0)
	s_setprio 1
	s_barrier
; #define PG8_STAGE(bufoff, gbase, voff) do { _Pragma("unroll") for (int _i = 0; _i < 2; ++_i) \
;         dma16((const char*)(gbase), (voff)[_i], ldsb + (bufoff) + ldsw + _i * 8192); } while (0)
; #define PG8_LDA(dst, b, h) do { const int a1_ = opqv(aoff0) ^ 64; _Pragma("unroll") for (int m = 0; m < 4; ++m) { dst[m][0] = *(const LAS bf16x8*)(lds + PG8_SA(b, h) + aoff0 + m * 2048); dst[m][1] = *(const LAS bf16x8*)(lds + PG8_SA(b, h) + a1_ + m * 2048); } } while (0)
; #define PG8_LDB(dst, b, h) do { const int b1_ = opqv(boff0) ^ 64; _Pragma("unroll") for (int n = 0; n < 2; ++n) { dst[n][0] = *(const LAS bf16x8*)(lds + PG8_SB(b, h) + boff0 + n * 2048); dst[n][1] = *(const LAS bf16x8*)(lds + PG8_SB(b, h) + b1_ + n * 2048); } } while (0)
; #define PG8_MMA(ai, bj, At, Bt) do { __builtin_amdgcn_s_setprio(1); _Pragma("unroll") for (int m = 0; m < 4; ++m) _Pragma("unroll") for (int n = 0; n < 2; ++n) _Pragma("unroll") for (int k = 0; k < 2; ++k) \
;         acc[ai][bj][m][n] = __builtin_amdgcn_mfma_f32_16x16x32_bf16(Bt[n][k], At[m][k], acc[ai][bj][m][n], 0, 0, 0); __builtin_amdgcn_s_setprio(0); } while (0)
; #define PG8_WAIT_V(n) asm volatile("s_waitcnt vmcnt(" #n ")" ::: "memory")
; #define PG8_WAIT_L(n) asm volatile("s_waitcnt lgkmcnt(" #n ")" ::: "memory")
; #define PG8_BAR __builtin_amdgcn_s_barrier()
; #define PG8_SCHED __builtin_amdgcn_sched_barrier(0)
; template <class Epi>
; __device__ __forceinline__ void gemm_phase(LAS unsigned char* lds, const Gemm g, const StaticOrder& S, const Epi& E, int wave_) {
;     ...
;             PG8_WAIT_V(8); PG8_WAIT_L(0); PG8_BAR; PG8_MMA(1, 0, At, B0); PG8_MMA(1, 1, At, B1); PG8_BAR; PG8_SCHED;
;             PG8_STAGE(PG8_SA(0, 1), a2 + hstepA, voffA); PG8_LDB(B0, 1, 0); PG8_LDB(B1, 1, 1); PG8_SCHED; PG8_LDA(At, 1, 0);
;             PG8_WAIT_V(8); PG8_WAIT_L(0); PG8_BAR; PG8_MMA(0, 0, At, B0); PG8_MMA(0, 1, At, B1); PG8_BAR; PG8_SCHED;
;             PG8_STAGE(PG8_SB(1, 0), b3, voffB); PG8_STAGE(PG8_SB(1, 1), b3 + hstepB, voffB); PG8_STAGE(PG8_SA(1, 0), a3, voffA); PG8_LDA(At, 1, 1);
	v_mfma_f32_16x16x32_bf16 v[60:63], v[130:133], v[170:173], 0
	v_mfma_f32_16x16x32_bf16 v[56:59], v[142:145], v[170:173], 0
	v_mfma_f32_16x16x32_bf16 v[48:51], v[130:133], v[174:177], 0
	v_mfma_f32_16x16x32_bf16 v[40:43], v[142:145], v[174:177], 0
	v_mfma_f32_16x16x32_bf16 v[32:35], v[130:133], v[196:199], 0
	v_mfma_f32_16x16x32_bf16 v[24:27], v[142:145], v[196:199], 0
	v_mfma_f32_16x16x32_bf16 v[16:19], v[130:133], v[200:203], 0
	v_mfma_f32_16x16x32_bf16 v[8:11], v[142:145], v[200:203], 0
	v_mfma_f32_16x16x32_bf16 v[60:63], v[146:149], v[178:181], v[60:63]
	v_mfma_f32_16x16x32_bf16 v[56:59], v[150:153], v[178:181], v[56:59]
	v_mfma_f32_16x16x32_bf16 v[48:51], v[146:149], v[192:195], v[48:51]
	v_mfma_f32_16x16x32_bf16 v[40:43], v[150:153], v[192:195], v[40:43]
	v_mfma_f32_16x16x32_bf16 v[32:35], v[146:149], v[204:207], v[32:35]
	v_mfma_f32_16x16x32_bf16 v[24:27], v[150:153], v[204:207], v[24:27]
	v_mfma_f32_16x16x32_bf16 v[16:19], v[146:149], v[208:211], v[16:19]
	v_mfma_f32_16x16x32_bf16 v[8:11], v[150:153], v[208:211], v[8:11]
	v_mfma_f32_16x16x32_bf16 v[52:55], v[154:157], v[170:173], 0
	v_mfma_f32_16x16x32_bf16 v[44:47], v[158:161], v[170:173], 0
	v_mfma_f32_16x16x32_bf16 v[36:39], v[154:157], v[174:177], 0
	v_mfma_f32_16x16x32_bf16 v[28:31], v[158:161], v[174:177], 0
	v_mfma_f32_16x16x32_bf16 v[20:23], v[154:157], v[196:199], 0
	v_mfma_f32_16x16x32_bf16 v[12:15], v[158:161], v[196:199], 0
	v_mfma_f32_16x16x32_bf16 v[4:7], v[154:157], v[200:203], 0
	v_mfma_f32_16x16x32_bf16 v[0:3], v[158:161], v[200:203], 0
	v_mfma_f32_16x16x32_bf16 v[52:55], v[162:165], v[178:181], v[52:55]
	v_mfma_f32_16x16x32_bf16 v[44:47], v[166:169], v[178:181], v[44:47]
	v_mfma_f32_16x16x32_bf16 v[36:39], v[162:165], v[192:195], v[36:39]
	v_mfma_f32_16x16x32_bf16 v[28:31], v[166:169], v[192:195], v[28:31]
	v_mfma_f32_16x16x32_bf16 v[20:23], v[162:165], v[204:207], v[20:23]
	v_mfma_f32_16x16x32_bf16 v[12:15], v[166:169], v[204:207], v[12:15]
	v_mfma_f32_16x16x32_bf16 v[4:7], v[162:165], v[208:211], v[4:7]
	v_mfma_f32_16x16x32_bf16 v[0:3], v[166:169], v[208:211], v[0:3]
	s_barrier
	s_setprio 0
	s_add_u32 s26, s26, 0x80000
	s_addc_u32 s27, s27, 0
	s_mov_b32 m0, s1
	s_nop 0
	global_load_lds_dwordx4 v129, s[26:27]
	v_mov_b32_e32 v128, v139
	s_mov_b32 m0, s69
	s_nop 0
	global_load_lds_dwordx4 v135, s[26:27]
	v_add_u32_e32 v142, s34, v139
	v_xad_u32 v128, v128, 64, s34
	ds_read_b128 v[130:133], v142
	ds_read_b128 v[142:145], v142 offset:2048
	ds_read_b128 v[146:149], v128
	ds_read_b128 v[150:153], v128 offset:2048
	v_mov_b32_e32 v128, v139
	s_add_i32 s26, 0, 0x1c000
	v_add_u32_e32 v158, s26, v139
	v_xad_u32 v128, v128, 64, s26
	ds_read_b128 v[154:157], v158
	ds_read_b128 v[158:161], v158 offset:2048
	ds_read_b128 v[162:165], v128
	ds_read_b128 v[166:169], v128 offset:2048
	v_mov_b32_e32 v128, v138
	s_nop 0
	v_xad_u32 v128, v128, 64, 0
	ds_read_b128 v[170:173], v141 offset:32768
	ds_read_b128 v[174:177], v141 offset:34816
	ds_read_b128 v[178:181], v128 offset:32768
	ds_read_b128 v[192:195], v128 offset:34816
	ds_read_b128 v[196:199], v141 offset:36864
	ds_read_b128 v[200:203], v141 offset:38912
	ds_read_b128 v[204:207], v128 offset:36864
	ds_read_b128 v[208:211], v128 offset:38912
	s_waitcnt vmcnt(8)
	s_waitcnt lgkmcnt(0)
	s_setprio 1
	s_barrier
	v_mfma_f32_16x16x32_bf16 v[124:127], v[130:133], v[170:173], v[124:127]
	v_mfma_f32_16x16x32_bf16 v[120:123], v[142:145], v[170:173], v[120:123]
	v_mfma_f32_16x16x32_bf16 v[112:115], v[130:133], v[174:177], v[112:115]
	v_mfma_f32_16x16x32_bf16 v[104:107], v[142:145], v[174:177], v[104:107]
	v_mfma_f32_16x16x32_bf16 v[96:99], v[130:133], v[196:199], v[96:99]
	v_mfma_f32_16x16x32_bf16 v[88:91], v[142:145], v[196:199], v[88:91]
	v_mfma_f32_16x16x32_bf16 v[80:83], v[130:133], v[200:203], v[80:83]
	v_mfma_f32_16x16x32_bf16 v[72:75], v[142:145], v[200:203], v[72:75]
	v_mfma_f32_16x16x32_bf16 v[124:127], v[146:149], v[178:181], v[124:127]
	v_mfma_f32_16x16x32_bf16 v[120:123], v[150:153], v[178:181], v[120:123]
	v_mfma_f32_16x16x32_bf16 v[112:115], v[146:149], v[192:195], v[112:115]
	v_mfma_f32_16x16x32_bf16 v[104:107], v[150:153], v[192:195], v[104:107]
	v_mfma_f32_16x16x32_bf16 v[96:99], v[146:149], v[204:207], v[96:99]
	v_mfma_f32_16x16x32_bf16 v[88:91], v[150:153], v[204:207], v[88:91]
	v_mfma_f32_16x16x32_bf16 v[80:83], v[146:149], v[208:211], v[80:83]
	v_mfma_f32_16x16x32_bf16 v[72:75], v[150:153], v[208:211], v[72:75]
	v_mfma_f32_16x16x32_bf16 v[116:119], v[154:157], v[170:173], v[116:119]
	s_add_u32 s26, s24, 0x80
	s_addc_u32 s27, s25, 0
	v_mfma_f32_16x16x32_bf16 v[108:111], v[158:161], v[170:173], v[108:111]
	v_mfma_f32_16x16x32_bf16 v[100:103], v[154:157], v[174:177], v[100:103]
	v_mfma_f32_16x16x32_bf16 v[92:95], v[158:161], v[174:177], v[92:95]
	v_mfma_f32_16x16x32_bf16 v[84:87], v[154:157], v[196:199], v[84:87]
	v_mfma_f32_16x16x32_bf16 v[76:79], v[158:161], v[196:199], v[76:79]
	v_mfma_f32_16x16x32_bf16 v[68:71], v[154:157], v[200:203], v[68:71]
	v_mfma_f32_16x16x32_bf16 v[64:67], v[158:161], v[200:203], v[64:67]
	v_mfma_f32_16x16x32_bf16 v[116:119], v[162:165], v[178:181], v[116:119]
	v_mfma_f32_16x16x32_bf16 v[108:111], v[166:169], v[178:181], v[108:111]
	v_mfma_f32_16x16x32_bf16 v[100:103], v[162:165], v[192:195], v[100:103]
	v_mfma_f32_16x16x32_bf16 v[92:95], v[166:169], v[192:195], v[92:95]
	v_mfma_f32_16x16x32_bf16 v[84:87], v[162:165], v[204:207], v[84:87]
	v_mfma_f32_16x16x32_bf16 v[76:79], v[166:169], v[204:207], v[76:79]
	v_mfma_f32_16x16x32_bf16 v[68:71], v[162:165], v[208:211], v[68:71]
	v_mfma_f32_16x16x32_bf16 v[64:67], v[166:169], v[208:211], v[64:67]
	s_barrier
; #define PG8_STAGE(bufoff, gbase, voff) do { _Pragma("unroll") for (int _i = 0; _i < 2; ++_i) \
;         dma16((const char*)(gbase), (voff)[_i], ldsb + (bufoff) + ldsw + _i * 8192); } while (0)
; #define PG8_LDA(dst, b, h) do { const int a1_ = opqv(aoff0) ^ 64; _Pragma("unroll") for (int m = 0; m < 4; ++m) { dst[m][0] = *(const LAS bf16x8*)(lds + PG8_SA(b, h) + aoff0 + m * 2048); dst[m][1] = *(const LAS bf16x8*)(lds + PG8_SA(b, h) + a1_ + m * 2048); } } while (0)
; #define PG8_LDB(dst, b, h) do { const int b1_ = opqv(boff0) ^ 64; _Pragma("unroll") for (int n = 0; n < 2; ++n) { dst[n][0] = *(const LAS bf16x8*)(lds + PG8_SB(b, h) + boff0 + n * 2048); dst[n][1] = *(const LAS bf16x8*)(lds + PG8_SB(b, h) + b1_ + n * 2048); } } while (0)
; #define PG8_MMA(ai, bj, At, Bt) do { __builtin_amdgcn_s_setprio(1); _Pragma("unroll") for (int m = 0; m < 4; ++m) _Pragma("unroll") for (int n = 0; n < 2; ++n) _Pragma("unroll") for (int k = 0; k < 2; ++k) \
;         acc[ai][bj][m][n] = __builtin_amdgcn_mfma_f32_16x16x32_bf16(Bt[n][k], At[m][k], acc[ai][bj][m][n], 0, 0, 0); __builtin_amdgcn_s_setprio(0); } while (0)
; #define PG8_WAIT_V(n) asm volatile("s_waitcnt vmcnt(" #n ")" ::: "memory")
; #define PG8_WAIT_L(n) asm volatile("s_waitcnt lgkmcnt(" #n ")" ::: "memory")
; #define PG8_BAR __builtin_amdgcn_s_barrier()
; template <class Epi>
; __device__ __forceinline__ void gemm_phase(LAS unsigned char* lds, const Gemm g, const StaticOrder& S, const Epi& E, int wave_) {
;     ...
;             const char* a2 = last ? nA : cA + (size_t)(t + 2) * kstep; const char* b2 = last ? nB : cB + (size_t)(t + 2) * kstep;
;             const char* a3 = a2 + kstep; const char* b3 = b2 + kstep;
;             PG8_STAGE(PG8_SA(1, 1), a1 + hstepA, voffA); PG8_LDB(B0, 0, 0); PG8_LDB(B1, 0, 1); PG8_SCHED; PG8_LDA(At, 0, 0);
;             PG8_WAIT_V(8); PG8_WAIT_L(0); PG8_BAR; PG8_MMA(0, 0, At, B0); PG8_MMA(0, 1, At, B1); PG8_BAR; PG8_SCHED;
;             PG8_STAGE(PG8_SB(0, 0), b2, voffB); PG8_STAGE(PG8_SB(0, 1), b2 + hstepB, voffB); PG8_STAGE(PG8_SA(0, 0), a2, voffA); PG8_LDA(At, 0, 1);
;     ...
;             PG8_STAGE(PG8_SB(1, 0), b3, voffB); PG8_STAGE(PG8_SB(1, 1), b3 + hstepB, voffB); PG8_STAGE(PG8_SA(1, 0), a3, voffA); PG8_LDA(At, 1, 1);
;             PG8_WAIT_V(8); PG8_WAIT_L(0); PG8_BAR; PG8_MMA(1, 0, At, B0); PG8_MMA(1, 1, At, B1); PG8_BAR; PG8_SCHED;
;         }
	s_setprio 0
	s_add_u32 s24, s24, 0x80080
	s_addc_u32 s25, s25, 0
	v_mov_b32_e32 v128, v138
	s_nop 0
	s_nop 0
	v_xad_u32 v128, v128, 64, 0
	ds_read_b128 v[170:173], v141 offset:49152
	ds_read_b128 v[174:177], v141 offset:51200
	ds_read_b128 v[178:181], v128 offset:49152
	ds_read_b128 v[192:195], v128 offset:51200
	ds_read_b128 v[196:199], v141 offset:53248
	ds_read_b128 v[200:203], v141 offset:55296
	ds_read_b128 v[204:207], v128 offset:53248
	ds_read_b128 v[208:211], v128 offset:55296
	s_mov_b32 m0, s35
	s_nop 0
	global_load_lds_dwordx4 v134, s[26:27]
	s_mov_b32 m0, s33
	s_nop 0
	global_load_lds_dwordx4 v136, s[26:27]
	s_mov_b32 m0, s77
	s_nop 0
	global_load_lds_dwordx4 v134, s[24:25]
	s_mov_b32 m0, s3
	s_nop 0
	global_load_lds_dwordx4 v136, s[24:25]
	s_mov_b32 m0, s22
	s_nop 0
	global_load_lds_dwordx4 v129, s[18:19]
	s_mov_b32 m0, s2
	s_nop 0
	global_load_lds_dwordx4 v135, s[18:19]
	s_waitcnt vmcnt(8)
	s_waitcnt lgkmcnt(0)
	s_setprio 1
	s_barrier
	v_mfma_f32_16x16x32_bf16 v[60:63], v[130:133], v[170:173], v[60:63]
	v_mfma_f32_16x16x32_bf16 v[56:59], v[142:145], v[170:173], v[56:59]
	v_mfma_f32_16x16x32_bf16 v[48:51], v[130:133], v[174:177], v[48:51]
	v_mfma_f32_16x16x32_bf16 v[40:43], v[142:145], v[174:177], v[40:43]
	v_mfma_f32_16x16x32_bf16 v[32:35], v[130:133], v[196:199], v[32:35]
	v_mfma_f32_16x16x32_bf16 v[24:27], v[142:145], v[196:199], v[24:27]
	v_mfma_f32_16x16x32_bf16 v[16:19], v[130:133], v[200:203], v[16:19]
	v_mfma_f32_16x16x32_bf16 v[8:11], v[142:145], v[200:203], v[8:11]
	v_mfma_f32_16x16x32_bf16 v[60:63], v[146:149], v[178:181], v[60:63]
	v_mfma_f32_16x16x32_bf16 v[56:59], v[150:153], v[178:181], v[56:59]
	v_mfma_f32_16x16x32_bf16 v[48:51], v[146:149], v[192:195], v[48:51]
	v_mfma_f32_16x16x32_bf16 v[40:43], v[150:153], v[192:195], v[40:43]
	v_mfma_f32_16x16x32_bf16 v[32:35], v[146:149], v[204:207], v[32:35]
	v_mfma_f32_16x16x32_bf16 v[24:27], v[150:153], v[204:207], v[24:27]
	v_mfma_f32_16x16x32_bf16 v[16:19], v[146:149], v[208:211], v[16:19]
	v_mfma_f32_16x16x32_bf16 v[8:11], v[150:153], v[208:211], v[8:11]
	v_mfma_f32_16x16x32_bf16 v[52:55], v[154:157], v[170:173], v[52:55]
	v_mfma_f32_16x16x32_bf16 v[44:47], v[158:161], v[170:173], v[44:47]
	v_mfma_f32_16x16x32_bf16 v[36:39], v[154:157], v[174:177], v[36:39]
	v_mfma_f32_16x16x32_bf16 v[28:31], v[158:161], v[174:177], v[28:31]
	v_mfma_f32_16x16x32_bf16 v[20:23], v[154:157], v[196:199], v[20:23]
	v_mfma_f32_16x16x32_bf16 v[12:15], v[158:161], v[196:199], v[12:15]
	v_mfma_f32_16x16x32_bf16 v[4:7], v[154:157], v[200:203], v[4:7]
	v_mfma_f32_16x16x32_bf16 v[0:3], v[158:161], v[200:203], v[0:3]
	v_mfma_f32_16x16x32_bf16 v[52:55], v[162:165], v[178:181], v[52:55]
	v_mfma_f32_16x16x32_bf16 v[44:47], v[166:169], v[178:181], v[44:47]
	v_mfma_f32_16x16x32_bf16 v[36:39], v[162:165], v[192:195], v[36:39]
	v_mfma_f32_16x16x32_bf16 v[28:31], v[166:169], v[192:195], v[28:31]
	v_mfma_f32_16x16x32_bf16 v[20:23], v[162:165], v[204:207], v[20:23]
	v_mfma_f32_16x16x32_bf16 v[12:15], v[166:169], v[204:207], v[12:15]
	v_mfma_f32_16x16x32_bf16 v[4:7], v[162:165], v[208:211], v[4:7]
	v_mfma_f32_16x16x32_bf16 v[0:3], v[166:169], v[208:211], v[0:3]
	s_barrier
	s_setprio 0
	s_add_i32 s49, s49, 2
	s_add_u32 s47, s47, 0x100
	s_addc_u32 s48, s48, 0
	s_add_u32 s12, s12, 0x100
	s_addc_u32 s13, s13, 0
	s_cmp_gt_u32 s49, 29
	s_cbranch_scc0 .LBB0_191
	s_branch .Lpeel_exit_8
.LBB0_191:
	s_add_u32 s18, s12, 0xfff80080
	s_addc_u32 s19, s13, -1
	s_cmp_eq_u32 s49, 28
	s_cselect_b32 s26, s45, s18
	v_mov_b32_e32 v128, v139
	s_cselect_b32 s27, s7, s19
	s_cselect_b32 s24, s46, s47
	s_cselect_b32 s25, s5, s48
	s_add_u32 s18, s26, 0x80
	v_xad_u32 v128, v128, 64, s23
	v_add_u32_e32 v141, s23, v139
	s_addc_u32 s19, s27, 0
	ds_read_b128 v[130:133], v141
	ds_read_b128 v[142:145], v141 offset:2048
	ds_read_b128 v[146:149], v128
	ds_read_b128 v[150:153], v128 offset:2048
	v_mov_b32_e32 v128, v139
	s_add_i32 s52, 0, 0x14000
	v_add_u32_e32 v141, s52, v139
	v_xad_u32 v128, v128, 64, s52
	ds_read_b128 v[154:157], v141
	ds_read_b128 v[158:161], v141 offset:2048
	ds_read_b128 v[162:165], v128
	ds_read_b128 v[166:169], v128 offset:2048
	v_mov_b32_e32 v128, v138
	v_add_u32_e32 v141, 0, v138
	v_xad_u32 v128, v128, 64, 0
	ds_read_b128 v[170:173], v141
	ds_read_b128 v[174:177], v141 offset:2048
	ds_read_b128 v[178:181], v128
	ds_read_b128 v[192:195], v128 offset:2048
	ds_read_b128 v[196:199], v141 offset:4096
	ds_read_b128 v[200:203], v141 offset:6144
	ds_read_b128 v[204:207], v128 offset:4096
	ds_read_b128 v[208:211], v128 offset:6144
	s_mov_b32 m0, s14
	s_nop 0
	global_load_lds_dwordx4 v129, s[12:13]
	s_mov_b32 m0, s15
	s_nop 0
	global_load_lds_dwordx4 v135, s[12:13]
	s_waitcnt vmcnt(8)
	s_waitcnt lgkmcnt(0)
	s_setprio 1
	s_barrier
; #define PG8_STAGE(bufoff, gbase, voff) do { _Pragma("unroll") for (int _i = 0; _i < 2; ++_i) \
;         dma16((const char*)(gbase), (voff)[_i], ldsb + (bufoff) + ldsw + _i * 8192); } while (0)
; #define PG8_LDA(dst, b, h) do { const int a1_ = opqv(aoff0) ^ 64; _Pragma("unroll") for (int m = 0; m < 4; ++m) { dst[m][0] = *(const LAS bf16x8*)(lds + PG8_SA(b, h) + aoff0 + m * 2048); dst[m][1] = *(const LAS bf16x8*)(lds + PG8_SA(b, h) + a1_ + m * 2048); } } while (0)
; #define PG8_LDB(dst, b, h) do { const int b1_ = opqv(boff0) ^ 64; _Pragma("unroll") for (int n = 0; n < 2; ++n) { dst[n][0] = *(const LAS bf16x8*)(lds + PG8_SB(b, h) + boff0 + n * 2048); dst[n][1] = *(const LAS bf16x8*)(lds + PG8_SB(b, h) + b1_ + n * 2048); } } while (0)
; #define PG8_MMA(ai, bj, At, Bt) do { __builtin_amdgcn_s_setprio(1); _Pragma("unroll") for (int m = 0; m < 4; ++m) _Pragma("unroll") for (int n = 0; n < 2; ++n) _Pragma("unroll") for (int k = 0; k < 2; ++k) \
;         acc[ai][bj][m][n] = __builtin_amdgcn_mfma_f32_16x16x32_bf16(Bt[n][k], At[m][k], acc[ai][bj][m][n], 0, 0, 0); __builtin_amdgcn_s_setprio(0); } while (0)
; #define PG8_WAIT_V(n) asm volatile("s_waitcnt vmcnt(" #n ")" ::: "memory")
; #define PG8_WAIT_L(n) asm volatile("s_waitcnt lgkmcnt(" #n ")" ::: "memory")
; #define PG8_BAR __builtin_amdgcn_s_barrier()
; #define PG8_SCHED __builtin_amdgcn_sched_barrier(0)
; template <class Epi>
; __device__ __forceinline__ void gemm_phase(LAS unsigned char* lds, const Gemm g, const StaticOrder& S, const Epi& E, int wave_) {
;     ...
;             PG8_WAIT_V(8); PG8_WAIT_L(0); PG8_BAR; PG8_MMA(0, 0, At, B0); PG8_MMA(0, 1, At, B1); PG8_BAR; PG8_SCHED;
;             PG8_STAGE(PG8_SB(0, 0), b2, voffB); PG8_STAGE(PG8_SB(0, 1), b2 + hstepB, voffB); PG8_STAGE(PG8_SA(0, 0), a2, voffA); PG8_LDA(At, 0, 1);
;             PG8_WAIT_V(8); PG8_WAIT_L(0); PG8_BAR; PG8_MMA(1, 0, At, B0); PG8_MMA(1, 1, At, B1); PG8_BAR; PG8_SCHED;
;             PG8_STAGE(PG8_SA(0, 1), a2 + hstepA, voffA); PG8_LDB(B0, 1, 0); PG8_LDB(B1, 1, 1); PG8_SCHED; PG8_LDA(At, 1, 0);
	v_mfma_f32_16x16x32_bf16 v[124:127], v[130:133], v[170:173], v[124:127]
	v_mfma_f32_16x16x32_bf16 v[120:123], v[142:145], v[170:173], v[120:123]
	v_mfma_f32_16x16x32_bf16 v[112:115], v[130:133], v[174:177], v[112:115]
	v_mfma_f32_16x16x32_bf16 v[104:107], v[142:145], v[174:177], v[104:107]
	v_mfma_f32_16x16x32_bf16 v[96:99], v[130:133], v[196:199], v[96:99]
	v_mfma_f32_16x16x32_bf16 v[88:91], v[142:145], v[196:199], v[88:91]
	v_mfma_f32_16x16x32_bf16 v[80:83], v[130:133], v[200:203], v[80:83]
	v_mfma_f32_16x16x32_bf16 v[72:75], v[142:145], v[200:203], v[72:75]
	v_mfma_f32_16x16x32_bf16 v[124:127], v[146:149], v[178:181], v[124:127]
	v_mfma_f32_16x16x32_bf16 v[120:123], v[150:153], v[178:181], v[120:123]
	v_mfma_f32_16x16x32_bf16 v[112:115], v[146:149], v[192:195], v[112:115]
	v_mfma_f32_16x16x32_bf16 v[104:107], v[150:153], v[192:195], v[104:107]
	v_mfma_f32_16x16x32_bf16 v[96:99], v[146:149], v[204:207], v[96:99]
	v_mfma_f32_16x16x32_bf16 v[88:91], v[150:153], v[204:207], v[88:91]
	v_mfma_f32_16x16x32_bf16 v[80:83], v[146:149], v[208:211], v[80:83]
	v_mfma_f32_16x16x32_bf16 v[72:75], v[150:153], v[208:211], v[72:75]
	v_mfma_f32_16x16x32_bf16 v[116:119], v[154:157], v[170:173], v[116:119]
	v_mfma_f32_16x16x32_bf16 v[108:111], v[158:161], v[170:173], v[108:111]
	v_mfma_f32_16x16x32_bf16 v[100:103], v[154:157], v[174:177], v[100:103]
	v_mfma_f32_16x16x32_bf16 v[92:95], v[158:161], v[174:177], v[92:95]
	v_mfma_f32_16x16x32_bf16 v[84:87], v[154:157], v[196:199], v[84:87]
	v_mfma_f32_16x16x32_bf16 v[76:79], v[158:161], v[196:199], v[76:79]
	v_mfma_f32_16x16x32_bf16 v[68:71], v[154:157], v[200:203], v[68:71]
	v_mfma_f32_16x16x32_bf16 v[64:67], v[158:161], v[200:203], v[64:67]
	v_mfma_f32_16x16x32_bf16 v[116:119], v[162:165], v[178:181], v[116:119]
	v_mfma_f32_16x16x32_bf16 v[108:111], v[166:169], v[178:181], v[108:111]
	v_mfma_f32_16x16x32_bf16 v[100:103], v[162:165], v[192:195], v[100:103]
	v_mfma_f32_16x16x32_bf16 v[92:95], v[166:169], v[192:195], v[92:95]
	v_mfma_f32_16x16x32_bf16 v[84:87], v[162:165], v[204:207], v[84:87]
	v_mfma_f32_16x16x32_bf16 v[76:79], v[166:169], v[204:207], v[76:79]
	v_mfma_f32_16x16x32_bf16 v[68:71], v[162:165], v[208:211], v[68:71]
	v_mfma_f32_16x16x32_bf16 v[64:67], v[166:169], v[208:211], v[64:67]
	s_barrier
	s_setprio 0
	s_add_u32 s54, s24, 0x80000
	s_addc_u32 s55, s25, 0
	v_mov_b32_e32 v128, v138
	s_nop 0
	s_nop 0
	s_nop 0
	v_xad_u32 v128, v128, 64, 0
	ds_read_b128 v[170:173], v141 offset:16384
	ds_read_b128 v[174:177], v141 offset:18432
	ds_read_b128 v[178:181], v128 offset:16384
	ds_read_b128 v[192:195], v128 offset:18432
	ds_read_b128 v[196:199], v141 offset:20480
	ds_read_b128 v[200:203], v141 offset:22528
	ds_read_b128 v[204:207], v128 offset:20480
	ds_read_b128 v[208:211], v128 offset:22528
	s_mov_b32 m0, s80
	s_nop 0
	global_load_lds_dwordx4 v134, s[24:25]
	s_mov_b32 m0, s81
	s_nop 0
	global_load_lds_dwordx4 v136, s[24:25]
	s_mov_b32 m0, s29
	s_nop 0
	global_load_lds_dwordx4 v134, s[54:55]
	s_mov_b32 m0, s88
	s_nop 0
	global_load_lds_dwordx4 v136, s[54:55]
	s_mov_b32 m0, s76
	s_nop 0
	global_load_lds_dwordx4 v129, s[26:27]
	s_mov_b32 m0, s89
	s_nop 0
	global_load_lds_dwordx4 v135, s[26:27]
	s_waitcnt vmcnt(8)
	s_waitcnt lgkmcnt(0)
	s_setprio 1
	s_barrier
	v_mfma_f32_16x16x32_bf16 v[60:63], v[130:133], v[170:173], v[60:63]
	v_mfma_f32_16x16x32_bf16 v[56:59], v[142:145], v[170:173], v[56:59]
	v_mfma_f32_16x16x32_bf16 v[48:51], v[130:133], v[174:177], v[48:51]
	v_mfma_f32_16x16x32_bf16 v[40:43], v[142:145], v[174:177], v[40:43]
	v_mfma_f32_16x16x32_bf16 v[32:35], v[130:133], v[196:199], v[32:35]
	v_mfma_f32_16x16x32_bf16 v[24:27], v[142:145], v[196:199], v[24:27]
	v_mfma_f32_16x16x32_bf16 v[16:19], v[130:133], v[200:203], v[16:19]
	v_mfma_f32_16x16x32_bf16 v[8:11], v[142:145], v[200:203], v[8:11]
	v_mfma_f32_16x16x32_bf16 v[60:63], v[146:149], v[178:181], v[60:63]
	v_mfma_f32_16x16x32_bf16 v[56:59], v[150:153], v[178:181], v[56:59]
	v_mfma_f32_16x16x32_bf16 v[48:51], v[146:149], v[192:195], v[48:51]
	v_mfma_f32_16x16x32_bf16 v[40:43], v[150:153], v[192:195], v[40:43]
	v_mfma_f32_16x16x32_bf16 v[32:35], v[146:149], v[204:207], v[32:35]
	v_mfma_f32_16x16x32_bf16 v[24:27], v[150:153], v[204:207], v[24:27]
	v_mfma_f32_16x16x32_bf16 v[16:19], v[146:149], v[208:211], v[16:19]
	v_mfma_f32_16x16x32_bf16 v[8:11], v[150:153], v[208:211], v[8:11]
	v_mfma_f32_16x16x32_bf16 v[52:55], v[154:157], v[170:173], v[52:55]
	v_mfma_f32_16x16x32_bf16 v[44:47], v[158:161], v[170:173], v[44:47]
	v_mfma_f32_16x16x32_bf16 v[36:39], v[154:157], v[174:177], v[36:39]
	v_mfma_f32_16x16x32_bf16 v[28:31], v[158:161], v[174:177], v[28:31]
	v_mfma_f32_16x16x32_bf16 v[20:23], v[154:157], v[196:199], v[20:23]
	v_mfma_f32_16x16x32_bf16 v[12:15], v[158:161], v[196:199], v[12:15]
	v_mfma_f32_16x16x32_bf16 v[4:7], v[154:157], v[200:203], v[4:7]
	v_mfma_f32_16x16x32_bf16 v[0:3], v[158:161], v[200:203], v[0:3]
	v_mfma_f32_16x16x32_bf16 v[52:55], v[162:165], v[178:181], v[52:55]
	v_mfma_f32_16x16x32_bf16 v[44:47], v[166:169], v[178:181], v[44:47]
	v_mfma_f32_16x16x32_bf16 v[36:39], v[162:165], v[192:195], v[36:39]
	v_mfma_f32_16x16x32_bf16 v[28:31], v[166:169], v[192:195], v[28:31]
	v_mfma_f32_16x16x32_bf16 v[20:23], v[162:165], v[204:207], v[20:23]
	v_mfma_f32_16x16x32_bf16 v[12:15], v[166:169], v[204:207], v[12:15]
	v_mfma_f32_16x16x32_bf16 v[4:7], v[162:165], v[208:211], v[4:7]
	v_mfma_f32_16x16x32_bf16 v[0:3], v[166:169], v[208:211], v[0:3]
	s_barrier
; #define PG8_STAGE(bufoff, gbase, voff) do { _Pragma("unroll") for (int _i = 0; _i < 2; ++_i) \
;         dma16((const char*)(gbase), (voff)[_i], ldsb + (bufoff) + ldsw + _i * 8192); } while (0)
; #define PG8_LDA(dst, b, h) do { const int a1_ = opqv(aoff0) ^ 64; _Pragma("unroll") for (int m = 0; m < 4; ++m) { dst[m][0] = *(const LAS bf16x8*)(lds + PG8_SA(b, h) + aoff0 + m * 2048); dst[m][1] = *(const LAS bf16x8*)(lds + PG8_SA(b, h) + a1_ + m * 2048); } } while (0)
; #define PG8_LDB(dst, b, h) do { const int b1_ = opqv(boff0) ^ 64; _Pragma("unroll") for (int n = 0; n < 2; ++n) { dst[n][0] = *(const LAS bf16x8*)(lds + PG8_SB(b, h) + boff0 + n * 2048); dst[n][1] = *(const LAS bf16x8*)(lds + PG8_SB(b, h) + b1_ + n * 2048); } } while (0)
; #define PG8_MMA(ai, bj, At, Bt) do { __builtin_amdgcn_s_setprio(1); _Pragma("unroll") for (int m = 0; m < 4; ++m) _Pragma("unroll") for (int n = 0; n < 2; ++n) _Pragma("unroll") for (int k = 0; k < 2; ++k) \
;         acc[ai][bj][m][n] = __builtin_amdgcn_mfma_f32_16x16x32_bf16(Bt[n][k], At[m][k], acc[ai][bj][m][n], 0, 0, 0); __builtin_amdgcn_s_setprio(0); } while (0)
; #define PG8_WAIT_V(n) asm volatile("s_waitcnt vmcnt(" #n ")" ::: "memory")
; #define PG8_WAIT_L(n) asm volatile("s_waitcnt lgkmcnt(" #n ")" ::: "memory")
; #define PG8_BAR __builtin_amdgcn_s_barrier()
; #define PG8_SCHED __builtin_amdgcn_sched_barrier(0)
; template <class Epi>
; __device__ __forceinline__ void gemm_phase(LAS unsigned char* lds, const Gemm g, const StaticOrder& S, const Epi& E, int wave_) {
;     ...
;             PG8_STAGE(PG8_SA(0, 1), a2 + hstepA, voffA); PG8_LDB(B0, 1, 0); PG8_LDB(B1, 1, 1); PG8_SCHED; PG8_LDA(At, 1, 0);
;             PG8_WAIT_V(8); PG8_WAIT_L(0); PG8_BAR; PG8_MMA(0, 0, At, B0); PG8_MMA(0, 1, At, B1); PG8_BAR; PG8_SCHED;
;             PG8_STAGE(PG8_SB(1, 0), b3, voffB); PG8_STAGE(PG8_SB(1, 1), b3 + hstepB, voffB); PG8_STAGE(PG8_SA(1, 0), a3, voffA); PG8_LDA(At, 1, 1);
;             PG8_WAIT_V(8); PG8_WAIT_L(0); PG8_BAR; PG8_MMA(1, 0, At, B0); PG8_MMA(1, 1, At, B1); PG8_BAR; PG8_SCHED;
;         }
	s_setprio 0
	s_add_u32 s26, s26, 0x80000
	s_addc_u32 s27, s27, 0
	s_mov_b32 m0, s1
	s_nop 0
	global_load_lds_dwordx4 v129, s[26:27]
	v_mov_b32_e32 v128, v139
	s_mov_b32 m0, s69
	s_nop 0
	global_load_lds_dwordx4 v135, s[26:27]
	v_add_u32_e32 v142, s34, v139
	v_xad_u32 v128, v128, 64, s34
	ds_read_b128 v[130:133], v142
	ds_read_b128 v[142:145], v142 offset:2048
	ds_read_b128 v[146:149], v128
	ds_read_b128 v[150:153], v128 offset:2048
	v_mov_b32_e32 v128, v139
	s_add_i32 s26, 0, 0x1c000
	v_add_u32_e32 v158, s26, v139
	v_xad_u32 v128, v128, 64, s26
	ds_read_b128 v[154:157], v158
	ds_read_b128 v[158:161], v158 offset:2048
	ds_read_b128 v[162:165], v128
	ds_read_b128 v[166:169], v128 offset:2048
	v_mov_b32_e32 v128, v138
	s_nop 0
	v_xad_u32 v128, v128, 64, 0
	ds_read_b128 v[170:173], v141 offset:32768
	ds_read_b128 v[174:177], v141 offset:34816
	ds_read_b128 v[178:181], v128 offset:32768
	ds_read_b128 v[192:195], v128 offset:34816
	ds_read_b128 v[196:199], v141 offset:36864
	ds_read_b128 v[200:203], v141 offset:38912
	ds_read_b128 v[204:207], v128 offset:36864
	ds_read_b128 v[208:211], v128 offset:38912
	s_waitcnt vmcnt(8)
	s_waitcnt lgkmcnt(0)
	s_setprio 1
	s_barrier
	v_mfma_f32_16x16x32_bf16 v[124:127], v[130:133], v[170:173], v[124:127]
	v_mfma_f32_16x16x32_bf16 v[120:123], v[142:145], v[170:173], v[120:123]
	v_mfma_f32_16x16x32_bf16 v[112:115], v[130:133], v[174:177], v[112:115]
	v_mfma_f32_16x16x32_bf16 v[104:107], v[142:145], v[174:177], v[104:107]
	v_mfma_f32_16x16x32_bf16 v[96:99], v[130:133], v[196:199], v[96:99]
	v_mfma_f32_16x16x32_bf16 v[88:91], v[142:145], v[196:199], v[88:91]
	v_mfma_f32_16x16x32_bf16 v[80:83], v[130:133], v[200:203], v[80:83]
	v_mfma_f32_16x16x32_bf16 v[72:75], v[142:145], v[200:203], v[72:75]
	v_mfma_f32_16x16x32_bf16 v[124:127], v[146:149], v[178:181], v[124:127]
	v_mfma_f32_16x16x32_bf16 v[120:123], v[150:153], v[178:181], v[120:123]
	v_mfma_f32_16x16x32_bf16 v[112:115], v[146:149], v[192:195], v[112:115]
	v_mfma_f32_16x16x32_bf16 v[104:107], v[150:153], v[192:195], v[104:107]
	v_mfma_f32_16x16x32_bf16 v[96:99], v[146:149], v[204:207], v[96:99]
	v_mfma_f32_16x16x32_bf16 v[88:91], v[150:153], v[204:207], v[88:91]
	v_mfma_f32_16x16x32_bf16 v[80:83], v[146:149], v[208:211], v[80:83]
	v_mfma_f32_16x16x32_bf16 v[72:75], v[150:153], v[208:211], v[72:75]
	v_mfma_f32_16x16x32_bf16 v[116:119], v[154:157], v[170:173], v[116:119]
	s_add_u32 s26, s24, 0x80
	s_addc_u32 s27, s25, 0
	v_mfma_f32_16x16x32_bf16 v[108:111], v[158:161], v[170:173], v[108:111]
	v_mfma_f32_16x16x32_bf16 v[100:103], v[154:157], v[174:177], v[100:103]
	v_mfma_f32_16x16x32_bf16 v[92:95], v[158:161], v[174:177], v[92:95]
	v_mfma_f32_16x16x32_bf16 v[84:87], v[154:157], v[196:199], v[84:87]
	v_mfma_f32_16x16x32_bf16 v[76:79], v[158:161], v[196:199], v[76:79]
	v_mfma_f32_16x16x32_bf16 v[68:71], v[154:157], v[200:203], v[68:71]
	v_mfma_f32_16x16x32_bf16 v[64:67], v[158:161], v[200:203], v[64:67]
	v_mfma_f32_16x16x32_bf16 v[116:119], v[162:165], v[178:181], v[116:119]
	v_mfma_f32_16x16x32_bf16 v[108:111], v[166:169], v[178:181], v[108:111]
	v_mfma_f32_16x16x32_bf16 v[100:103], v[162:165], v[192:195], v[100:103]
	v_mfma_f32_16x16x32_bf16 v[92:95], v[166:169], v[192:195], v[92:95]
	v_mfma_f32_16x16x32_bf16 v[84:87], v[162:165], v[204:207], v[84:87]
	v_mfma_f32_16x16x32_bf16 v[76:79], v[166:169], v[204:207], v[76:79]
	v_mfma_f32_16x16x32_bf16 v[68:71], v[162:165], v[208:211], v[68:71]
	v_mfma_f32_16x16x32_bf16 v[64:67], v[166:169], v[208:211], v[64:67]
	s_barrier
	s_setprio 0
	s_add_u32 s24, s24, 0x80080
	s_addc_u32 s25, s25, 0
	v_mov_b32_e32 v128, v138
	s_nop 0
	s_nop 0
	v_xad_u32 v128, v128, 64, 0
	ds_read_b128 v[170:173], v141 offset:49152
	ds_read_b128 v[174:177], v141 offset:51200
	ds_read_b128 v[178:181], v128 offset:49152
	ds_read_b128 v[192:195], v128 offset:51200
	ds_read_b128 v[196:199], v141 offset:53248
	ds_read_b128 v[200:203], v141 offset:55296
	ds_read_b128 v[204:207], v128 offset:53248
	ds_read_b128 v[208:211], v128 offset:55296
	s_mov_b32 m0, s35
	s_nop 0
	global_load_lds_dwordx4 v134, s[26:27]
	s_mov_b32 m0, s33
	s_nop 0
	global_load_lds_dwordx4 v136, s[26:27]
	s_mov_b32 m0, s77
	s_nop 0
	global_load_lds_dwordx4 v134, s[24:25]
	s_mov_b32 m0, s3
	s_nop 0
	global_load_lds_dwordx4 v136, s[24:25]
	s_mov_b32 m0, s22
	s_nop 0
	global_load_lds_dwordx4 v129, s[18:19]
	s_mov_b32 m0, s2
	s_nop 0
	global_load_lds_dwordx4 v135, s[18:19]
	s_waitcnt vmcnt(8)
	s_waitcnt lgkmcnt(0)
	s_setprio 1
	s_barrier
	v_mfma_f32_16x16x32_bf16 v[60:63], v[130:133], v[170:173], v[60:63]
	v_mfma_f32_16x16x32_bf16 v[56:59], v[142:145], v[170:173], v[56:59]
	v_mfma_f32_16x16x32_bf16 v[48:51], v[130:133], v[174:177], v[48:51]
	v_mfma_f32_16x16x32_bf16 v[40:43], v[142:145], v[174:177], v[40:43]
	v_mfma_f32_16x16x32_bf16 v[32:35], v[130:133], v[196:199], v[32:35]
	v_mfma_f32_16x16x32_bf16 v[24:27], v[142:145], v[196:199], v[24:27]
	v_mfma_f32_16x16x32_bf16 v[16:19], v[130:133], v[200:203], v[16:19]
	v_mfma_f32_16x16x32_bf16 v[8:11], v[142:145], v[200:203], v[8:11]
	v_mfma_f32_16x16x32_bf16 v[60:63], v[146:149], v[178:181], v[60:63]
	v_mfma_f32_16x16x32_bf16 v[56:59], v[150:153], v[178:181], v[56:59]
	v_mfma_f32_16x16x32_bf16 v[48:51], v[146:149], v[192:195], v[48:51]
	v_mfma_f32_16x16x32_bf16 v[40:43], v[150:153], v[192:195], v[40:43]
	v_mfma_f32_16x16x32_bf16 v[32:35], v[146:149], v[204:207], v[32:35]
	v_mfma_f32_16x16x32_bf16 v[24:27], v[150:153], v[204:207], v[24:27]
	v_mfma_f32_16x16x32_bf16 v[16:19], v[146:149], v[208:211], v[16:19]
	v_mfma_f32_16x16x32_bf16 v[8:11], v[150:153], v[208:211], v[8:11]
	v_mfma_f32_16x16x32_bf16 v[52:55], v[154:157], v[170:173], v[52:55]
	v_mfma_f32_16x16x32_bf16 v[44:47], v[158:161], v[170:173], v[44:47]
	v_mfma_f32_16x16x32_bf16 v[36:39], v[154:157], v[174:177], v[36:39]
	v_mfma_f32_16x16x32_bf16 v[28:31], v[158:161], v[174:177], v[28:31]
	v_mfma_f32_16x16x32_bf16 v[20:23], v[154:157], v[196:199], v[20:23]
	v_mfma_f32_16x16x32_bf16 v[12:15], v[158:161], v[196:199], v[12:15]
	v_mfma_f32_16x16x32_bf16 v[4:7], v[154:157], v[200:203], v[4:7]
	v_mfma_f32_16x16x32_bf16 v[0:3], v[158:161], v[200:203], v[0:3]
	v_mfma_f32_16x16x32_bf16 v[52:55], v[162:165], v[178:181], v[52:55]
	v_mfma_f32_16x16x32_bf16 v[44:47], v[166:169], v[178:181], v[44:47]
	v_mfma_f32_16x16x32_bf16 v[36:39], v[162:165], v[192:195], v[36:39]
	v_mfma_f32_16x16x32_bf16 v[28:31], v[166:169], v[192:195], v[28:31]
	v_mfma_f32_16x16x32_bf16 v[20:23], v[162:165], v[204:207], v[20:23]
	v_mfma_f32_16x16x32_bf16 v[12:15], v[166:169], v[204:207], v[12:15]
	v_mfma_f32_16x16x32_bf16 v[4:7], v[162:165], v[208:211], v[4:7]
	v_mfma_f32_16x16x32_bf16 v[0:3], v[166:169], v[208:211], v[0:3]
	s_barrier
	s_setprio 0
	s_add_i32 s49, s49, 2
	s_add_u32 s47, s47, 0x100
	s_addc_u32 s48, s48, 0
	s_add_u32 s12, s12, 0x100
	s_addc_u32 s13, s13, 0
	s_cmp_gt_u32 s49, 29
	s_cbranch_scc0 .LBB0_191

; #define PG8_STAGE(bufoff, gbase, voff) do { _Pragma("unroll") for (int _i = 0; _i < 2; ++_i) \
;         dma16((const char*)(gbase), (voff)[_i], ldsb + (bufoff) + ldsw + _i * 8192); } while (0)
; #define PG8_LDA(dst, b, h) do { const int a1_ = opqv(aoff0) ^ 64; _Pragma("unroll") for (int m = 0; m < 4; ++m) { dst[m][0] = *(const LAS bf16x8*)(lds + PG8_SA(b, h) + aoff0 + m * 2048); dst[m][1] = *(const LAS bf16x8*)(lds + PG8_SA(b, h) + a1_ + m * 2048); } } while (0)
; #define PG8_LDB(dst, b, h) do { const int b1_ = opqv(boff0) ^ 64; _Pragma("unroll") for (int n = 0; n < 2; ++n) { dst[n][0] = *(const LAS bf16x8*)(lds + PG8_SB(b, h) + boff0 + n * 2048); dst[n][1] = *(const LAS bf16x8*)(lds + PG8_SB(b, h) + b1_ + n * 2048); } } while (0)
; #define PG8_MMA(ai, bj, At, Bt) do { __builtin_amdgcn_s_setprio(1); _Pragma("unroll") for (int m = 0; m < 4; ++m) _Pragma("unroll") for (int n = 0; n < 2; ++n) _Pragma("unroll") for (int k = 0; k < 2; ++k) \
;         acc[ai][bj][m][n] = __builtin_amdgcn_mfma_f32_16x16x32_bf16(Bt[n][k], At[m][k], acc[ai][bj][m][n], 0, 0, 0); __builtin_amdgcn_s_setprio(0); } while (0)
; template <class Epi>
; __device__ __forceinline__ void gemm_phase(LAS unsigned char* lds, const Gemm g, const StaticOrder& S, const Epi& E, int wave_) {
;     ...
;         const bool has_next = S.next(ui + 1, nxt);
;         const char* nA = has_next ? (const char*)g.A + (size_t)nxt.pm * tstepA : cA; const char* nB = has_next ? (const char*)g.Bt + (size_t)nxt.pn * tstepB : cB;
; #pragma unroll 1
;         for (int t = 0; t < nt; t += 2) {
;             const bool last = (t == nt - 2);
;             const char* a1 = cA + (size_t)(t + 1) * kstep;
;             const char* a2 = last ? nA : cA + (size_t)(t + 2) * kstep; const char* b2 = last ? nB : cB + (size_t)(t + 2) * kstep;
;             const char* a3 = a2 + kstep; const char* b3 = b2 + kstep;
;             PG8_STAGE(PG8_SA(1, 1), a1 + hstepA, voffA); PG8_LDB(B0, 0, 0); PG8_LDB(B1, 0, 1); PG8_SCHED; PG8_LDA(At, 0, 0);
;             PG8_WAIT_V(8); PG8_WAIT_L(0); PG8_BAR; PG8_MMA(0, 0, At, B0); PG8_MMA(0, 1, At, B1); PG8_BAR; PG8_SCHED;
;             PG8_STAGE(PG8_SB(0, 0), b2, voffB); PG8_STAGE(PG8_SB(0, 1), b2 + hstepB, voffB); PG8_STAGE(PG8_SA(0, 0), a2, voffA); PG8_LDA(At, 0, 1);
;             PG8_WAIT_V(8); PG8_WAIT_L(0); PG8_BAR; PG8_MMA(1, 0, At, B0); PG8_MMA(1, 1, At, B1); PG8_BAR; PG8_SCHED;
.LBB0_573:
	s_ashr_i32 s11, s10, 31
	s_lshl_b64 s[16:17], s[10:11], 20
	s_add_u32 s18, s21, s16
	s_addc_u32 s19, s44, s17
	s_and_b64 s[16:17], s[42:43], exec
	s_cselect_b32 s11, s19, s27
	s_cselect_b32 s16, s18, s26
	s_ashr_i32 s9, s8, 31
	s_lshl_b64 s[24:25], s[8:9], 20
	s_add_u32 s24, s45, s24
	s_addc_u32 s25, s46, s25
	s_and_b64 s[30:31], s[42:43], exec
	s_cselect_b32 s9, s25, s13
	s_cselect_b32 s17, s24, s12
	s_add_u32 s52, s12, 0x100
	s_addc_u32 s56, s13, 0
	s_add_u32 s12, s26, 0x80080
	s_addc_u32 s13, s27, 0
	s_mov_b32 s57, -2
	s_add_u32 s26, s12, 0xfff80080
	s_addc_u32 s27, s13, -1
	s_cmp_eq_u32 s57, 28
	s_cselect_b32 s36, s16, s26
	v_mov_b32_e32 v128, v144
	s_cselect_b32 s37, s11, s27
	s_cselect_b32 s30, s17, s52
	s_cselect_b32 s31, s9, s56
	s_add_u32 s26, s36, 0x80
	v_add_u32_e32 v137, s23, v144
	v_xad_u32 v136, v128, 64, s23
	s_addc_u32 s27, s37, 0
	ds_read_b128 v[128:131], v137
	ds_read_b128 v[146:149], v137 offset:2048
	ds_read_b128 v[150:153], v136
	ds_read_b128 v[154:157], v136 offset:2048
	v_mov_b32_e32 v136, v144
	s_add_i32 s58, 0, 0x14000
	v_add_u32_e32 v137, s58, v144
	v_xad_u32 v136, v136, 64, s58
	ds_read_b128 v[158:161], v137
	ds_read_b128 v[162:165], v137 offset:2048
	ds_read_b128 v[166:169], v136
	ds_read_b128 v[170:173], v136 offset:2048
	v_mov_b32_e32 v136, v143
	v_add_u32_e32 v137, 0, v143
	v_xad_u32 v136, v136, 64, 0
	ds_read_b128 v[174:177], v137
	ds_read_b128 v[178:181], v137 offset:2048
	ds_read_b128 v[192:195], v136
	ds_read_b128 v[196:199], v136 offset:2048
	ds_read_b128 v[200:203], v137 offset:4096
	ds_read_b128 v[204:207], v137 offset:6144
	ds_read_b128 v[208:211], v136 offset:4096
	ds_read_b128 v[212:215], v136 offset:6144
	s_mov_b32 m0, s14
	s_nop 0
	global_load_lds_dwordx4 v138, s[12:13]
	s_mov_b32 m0, s15
	s_nop 0
	global_load_lds_dwordx4 v140, s[12:13]
	s_waitcnt vmcnt(8)
	s_waitcnt lgkmcnt(0)
	s_setprio 1
	s_barrier
	v_mfma_f32_16x16x32_bf16 v[124:127], v[128:131], v[174:177], 0
	v_mfma_f32_16x16x32_bf16 v[120:123], v[146:149], v[174:177], 0
	v_mfma_f32_16x16x32_bf16 v[108:111], v[128:131], v[178:181], 0
	v_mfma_f32_16x16x32_bf16 v[104:107], v[146:149], v[178:181], 0
	v_mfma_f32_16x16x32_bf16 v[92:95], v[128:131], v[200:203], 0
	v_mfma_f32_16x16x32_bf16 v[88:91], v[146:149], v[200:203], 0
	v_mfma_f32_16x16x32_bf16 v[76:79], v[128:131], v[204:207], 0
	v_mfma_f32_16x16x32_bf16 v[72:75], v[146:149], v[204:207], 0
	v_mfma_f32_16x16x32_bf16 v[124:127], v[150:153], v[192:195], v[124:127]
	v_mfma_f32_16x16x32_bf16 v[120:123], v[154:157], v[192:195], v[120:123]
	v_mfma_f32_16x16x32_bf16 v[108:111], v[150:153], v[196:199], v[108:111]
	v_mfma_f32_16x16x32_bf16 v[104:107], v[154:157], v[196:199], v[104:107]
	v_mfma_f32_16x16x32_bf16 v[92:95], v[150:153], v[208:211], v[92:95]
	v_mfma_f32_16x16x32_bf16 v[88:91], v[154:157], v[208:211], v[88:91]
	v_mfma_f32_16x16x32_bf16 v[76:79], v[150:153], v[212:215], v[76:79]
	v_mfma_f32_16x16x32_bf16 v[72:75], v[154:157], v[212:215], v[72:75]
	v_mfma_f32_16x16x32_bf16 v[116:119], v[158:161], v[174:177], 0
	v_mfma_f32_16x16x32_bf16 v[112:115], v[162:165], v[174:177], 0
	v_mfma_f32_16x16x32_bf16 v[100:103], v[158:161], v[178:181], 0
	v_mfma_f32_16x16x32_bf16 v[96:99], v[162:165], v[178:181], 0
	v_mfma_f32_16x16x32_bf16 v[84:87], v[158:161], v[200:203], 0
	v_mfma_f32_16x16x32_bf16 v[80:83], v[162:165], v[200:203], 0
	v_mfma_f32_16x16x32_bf16 v[68:71], v[158:161], v[204:207], 0
	v_mfma_f32_16x16x32_bf16 v[64:67], v[162:165], v[204:207], 0
	v_mfma_f32_16x16x32_bf16 v[116:119], v[166:169], v[192:195], v[116:119]
	v_mfma_f32_16x16x32_bf16 v[112:115], v[170:173], v[192:195], v[112:115]
	v_mfma_f32_16x16x32_bf16 v[100:103], v[166:169], v[196:199], v[100:103]
	v_mfma_f32_16x16x32_bf16 v[96:99], v[170:173], v[196:199], v[96:99]
	v_mfma_f32_16x16x32_bf16 v[84:87], v[166:169], v[208:211], v[84:87]
	v_mfma_f32_16x16x32_bf16 v[80:83], v[170:173], v[208:211], v[80:83]
	v_mfma_f32_16x16x32_bf16 v[68:71], v[166:169], v[212:215], v[68:71]
	v_mfma_f32_16x16x32_bf16 v[64:67], v[170:173], v[212:215], v[64:67]
	s_barrier
	s_setprio 0
	v_mov_b32_e32 v136, v143
	s_add_u32 s58, s30, 0x80000
	s_addc_u32 s59, s31, 0
	s_nop 0
	s_nop 0
	s_nop 0
	v_xad_u32 v136, v136, 64, 0
	ds_read_b128 v[174:177], v137 offset:16384
	ds_read_b128 v[178:181], v137 offset:18432
	ds_read_b128 v[192:195], v136 offset:16384
	ds_read_b128 v[196:199], v136 offset:18432
	ds_read_b128 v[200:203], v137 offset:20480
	ds_read_b128 v[204:207], v137 offset:22528
	ds_read_b128 v[208:211], v136 offset:20480
	ds_read_b128 v[212:215], v136 offset:22528
	s_mov_b32 m0, s80
	s_nop 0
	global_load_lds_dwordx4 v139, s[30:31]
	s_mov_b32 m0, s81
	s_nop 0
	global_load_lds_dwordx4 v141, s[30:31]
	s_mov_b32 m0, s29
	s_nop 0
	global_load_lds_dwordx4 v139, s[58:59]
	s_mov_b32 m0, s88
	s_nop 0
	global_load_lds_dwordx4 v141, s[58:59]
	s_mov_b32 m0, s76
	s_nop 0
	global_load_lds_dwordx4 v138, s[36:37]
	s_mov_b32 m0, s89
	s_nop 0
	global_load_lds_dwordx4 v140, s[36:37]
	s_waitcnt vmcnt(8)
	s_waitcnt lgkmcnt(0)
	s_setprio 1
	s_barrier
; #define PG8_STAGE(bufoff, gbase, voff) do { _Pragma("unroll") for (int _i = 0; _i < 2; ++_i) \
;         dma16((const char*)(gbase), (voff)[_i], ldsb + (bufoff) + ldsw + _i * 8192); } while (0)
; #define PG8_LDA(dst, b, h) do { const int a1_ = opqv(aoff0) ^ 64; _Pragma("unroll") for (int m = 0; m < 4; ++m) { dst[m][0] = *(const LAS bf16x8*)(lds + PG8_SA(b, h) + aoff0 + m * 2048); dst[m][1] = *(const LAS bf16x8*)(lds + PG8_SA(b, h) + a1_ + m * 2048); } } while (0)
; #define PG8_LDB(dst, b, h) do { const int b1_ = opqv(boff0) ^ 64; _Pragma("unroll") for (int n = 0; n < 2; ++n) { dst[n][0] = *(const LAS bf16x8*)(lds + PG8_SB(b, h) + boff0 + n * 2048); dst[n][1] = *(const LAS bf16x8*)(lds + PG8_SB(b, h) + b1_ + n * 2048); } } while (0)
; #define PG8_MMA(ai, bj, At, Bt) do { __builtin_amdgcn_s_setprio(1); _Pragma("unroll") for (int m = 0; m < 4; ++m) _Pragma("unroll") for (int n = 0; n < 2; ++n) _Pragma("unroll") for (int k = 0; k < 2; ++k) \
;         acc[ai][bj][m][n] = __builtin_amdgcn_mfma_f32_16x16x32_bf16(Bt[n][k], At[m][k], acc[ai][bj][m][n], 0, 0, 0); __builtin_amdgcn_s_setprio(0); } while (0)
; #define PG8_WAIT_V(n) asm volatile("s_waitcnt vmcnt(" #n ")" ::: "memory")
; #define PG8_WAIT_L(n) asm volatile("s_waitcnt lgkmcnt(" #n ")" ::: "memory")
; #define PG8_BAR __builtin_amdgcn_s_barrier()
; #define PG8_SCHED __builtin_amdgcn_sched_barrier(0)
; template <class Epi>
; __device__ __forceinline__ void gemm_phase(LAS unsigned char* lds, const Gemm g, const StaticOrder& S, const Epi& E, int wave_) {
;     ...
;             PG8_WAIT_V(8); PG8_WAIT_L(0); PG8_BAR; PG8_MMA(1, 0, At, B0); PG8_MMA(1, 1, At, B1); PG8_BAR; PG8_SCHED;
;             PG8_STAGE(PG8_SA(0, 1), a2 + hstepA, voffA); PG8_LDB(B0, 1, 0); PG8_LDB(B1, 1, 1); PG8_SCHED; PG8_LDA(At, 1, 0);
;             PG8_WAIT_V(8); PG8_WAIT_L(0); PG8_BAR; PG8_MMA(0, 0, At, B0); PG8_MMA(0, 1, At, B1); PG8_BAR; PG8_SCHED;
	v_mfma_f32_16x16x32_bf16 v[60:63], v[128:131], v[174:177], 0
	v_mfma_f32_16x16x32_bf16 v[56:59], v[146:149], v[174:177], 0
	v_mfma_f32_16x16x32_bf16 v[44:47], v[128:131], v[178:181], 0
	v_mfma_f32_16x16x32_bf16 v[40:43], v[146:149], v[178:181], 0
	v_mfma_f32_16x16x32_bf16 v[28:31], v[128:131], v[200:203], 0
	v_mfma_f32_16x16x32_bf16 v[24:27], v[146:149], v[200:203], 0
	v_mfma_f32_16x16x32_bf16 v[12:15], v[128:131], v[204:207], 0
	v_mfma_f32_16x16x32_bf16 v[8:11], v[146:149], v[204:207], 0
	v_mfma_f32_16x16x32_bf16 v[60:63], v[150:153], v[192:195], v[60:63]
	v_mfma_f32_16x16x32_bf16 v[56:59], v[154:157], v[192:195], v[56:59]
	v_mfma_f32_16x16x32_bf16 v[44:47], v[150:153], v[196:199], v[44:47]
	v_mfma_f32_16x16x32_bf16 v[40:43], v[154:157], v[196:199], v[40:43]
	v_mfma_f32_16x16x32_bf16 v[28:31], v[150:153], v[208:211], v[28:31]
	v_mfma_f32_16x16x32_bf16 v[24:27], v[154:157], v[208:211], v[24:27]
	v_mfma_f32_16x16x32_bf16 v[12:15], v[150:153], v[212:215], v[12:15]
	v_mfma_f32_16x16x32_bf16 v[8:11], v[154:157], v[212:215], v[8:11]
	v_mfma_f32_16x16x32_bf16 v[52:55], v[158:161], v[174:177], 0
	v_mfma_f32_16x16x32_bf16 v[48:51], v[162:165], v[174:177], 0
	v_mfma_f32_16x16x32_bf16 v[36:39], v[158:161], v[178:181], 0
	v_mfma_f32_16x16x32_bf16 v[32:35], v[162:165], v[178:181], 0
	v_mfma_f32_16x16x32_bf16 v[20:23], v[158:161], v[200:203], 0
	v_mfma_f32_16x16x32_bf16 v[16:19], v[162:165], v[200:203], 0
	v_mfma_f32_16x16x32_bf16 v[4:7], v[158:161], v[204:207], 0
	v_mfma_f32_16x16x32_bf16 v[0:3], v[162:165], v[204:207], 0
	v_mfma_f32_16x16x32_bf16 v[52:55], v[166:169], v[192:195], v[52:55]
	v_mfma_f32_16x16x32_bf16 v[48:51], v[170:173], v[192:195], v[48:51]
	v_mfma_f32_16x16x32_bf16 v[36:39], v[166:169], v[196:199], v[36:39]
	v_mfma_f32_16x16x32_bf16 v[32:35], v[170:173], v[196:199], v[32:35]
	v_mfma_f32_16x16x32_bf16 v[20:23], v[166:169], v[208:211], v[20:23]
	v_mfma_f32_16x16x32_bf16 v[16:19], v[170:173], v[208:211], v[16:19]
	v_mfma_f32_16x16x32_bf16 v[4:7], v[166:169], v[212:215], v[4:7]
	v_mfma_f32_16x16x32_bf16 v[0:3], v[170:173], v[212:215], v[0:3]
	s_barrier
	s_setprio 0
	s_add_u32 s36, s36, 0x80000
	s_addc_u32 s37, s37, 0
	s_mov_b32 m0, s1
	s_nop 0
	global_load_lds_dwordx4 v138, s[36:37]
	v_mov_b32_e32 v128, v144
	s_mov_b32 m0, s69
	s_nop 0
	global_load_lds_dwordx4 v140, s[36:37]
	v_add_u32_e32 v146, s34, v144
	v_xad_u32 v136, v128, 64, s34
	ds_read_b128 v[128:131], v146
	ds_read_b128 v[146:149], v146 offset:2048
	ds_read_b128 v[150:153], v136
	ds_read_b128 v[154:157], v136 offset:2048
	v_mov_b32_e32 v136, v144
	s_add_i32 s36, 0, 0x1c000
	v_add_u32_e32 v162, s36, v144
	v_xad_u32 v136, v136, 64, s36
	ds_read_b128 v[158:161], v162
	ds_read_b128 v[162:165], v162 offset:2048
	ds_read_b128 v[166:169], v136
	ds_read_b128 v[170:173], v136 offset:2048
	v_mov_b32_e32 v136, v143
	s_nop 0
	v_xad_u32 v136, v136, 64, 0
	ds_read_b128 v[174:177], v137 offset:32768
	ds_read_b128 v[178:181], v137 offset:34816
	ds_read_b128 v[192:195], v136 offset:32768
	ds_read_b128 v[196:199], v136 offset:34816
	ds_read_b128 v[200:203], v137 offset:36864
	ds_read_b128 v[204:207], v137 offset:38912
	ds_read_b128 v[208:211], v136 offset:36864
	ds_read_b128 v[212:215], v136 offset:38912
	s_waitcnt vmcnt(8)
	s_waitcnt lgkmcnt(0)
	s_setprio 1
	s_barrier
	v_mfma_f32_16x16x32_bf16 v[124:127], v[128:131], v[174:177], v[124:127]
	v_mfma_f32_16x16x32_bf16 v[120:123], v[146:149], v[174:177], v[120:123]
	v_mfma_f32_16x16x32_bf16 v[108:111], v[128:131], v[178:181], v[108:111]
	v_mfma_f32_16x16x32_bf16 v[104:107], v[146:149], v[178:181], v[104:107]
	v_mfma_f32_16x16x32_bf16 v[92:95], v[128:131], v[200:203], v[92:95]
	v_mfma_f32_16x16x32_bf16 v[88:91], v[146:149], v[200:203], v[88:91]
	v_mfma_f32_16x16x32_bf16 v[76:79], v[128:131], v[204:207], v[76:79]
	v_mfma_f32_16x16x32_bf16 v[72:75], v[146:149], v[204:207], v[72:75]
	v_mfma_f32_16x16x32_bf16 v[124:127], v[150:153], v[192:195], v[124:127]
	v_mfma_f32_16x16x32_bf16 v[120:123], v[154:157], v[192:195], v[120:123]
	v_mfma_f32_16x16x32_bf16 v[108:111], v[150:153], v[196:199], v[108:111]
	v_mfma_f32_16x16x32_bf16 v[104:107], v[154:157], v[196:199], v[104:107]
	v_mfma_f32_16x16x32_bf16 v[92:95], v[150:153], v[208:211], v[92:95]
	v_mfma_f32_16x16x32_bf16 v[88:91], v[154:157], v[208:211], v[88:91]
	v_mfma_f32_16x16x32_bf16 v[76:79], v[150:153], v[212:215], v[76:79]
	v_mfma_f32_16x16x32_bf16 v[72:75], v[154:157], v[212:215], v[72:75]
	v_mfma_f32_16x16x32_bf16 v[116:119], v[158:161], v[174:177], v[116:119]
	s_add_u32 s36, s30, 0x80
	s_addc_u32 s37, s31, 0
	v_mfma_f32_16x16x32_bf16 v[112:115], v[162:165], v[174:177], v[112:115]
	v_mfma_f32_16x16x32_bf16 v[100:103], v[158:161], v[178:181], v[100:103]
	v_mfma_f32_16x16x32_bf16 v[96:99], v[162:165], v[178:181], v[96:99]
	v_mfma_f32_16x16x32_bf16 v[84:87], v[158:161], v[200:203], v[84:87]
	v_mfma_f32_16x16x32_bf16 v[80:83], v[162:165], v[200:203], v[80:83]
	v_mfma_f32_16x16x32_bf16 v[68:71], v[158:161], v[204:207], v[68:71]
	v_mfma_f32_16x16x32_bf16 v[64:67], v[162:165], v[204:207], v[64:67]
	v_mfma_f32_16x16x32_bf16 v[116:119], v[166:169], v[192:195], v[116:119]
	v_mfma_f32_16x16x32_bf16 v[112:115], v[170:173], v[192:195], v[112:115]
	v_mfma_f32_16x16x32_bf16 v[100:103], v[166:169], v[196:199], v[100:103]
	v_mfma_f32_16x16x32_bf16 v[96:99], v[170:173], v[196:199], v[96:99]
	v_mfma_f32_16x16x32_bf16 v[84:87], v[166:169], v[208:211], v[84:87]
	v_mfma_f32_16x16x32_bf16 v[80:83], v[170:173], v[208:211], v[80:83]
	v_mfma_f32_16x16x32_bf16 v[68:71], v[166:169], v[212:215], v[68:71]
	v_mfma_f32_16x16x32_bf16 v[64:67], v[170:173], v[212:215], v[64:67]
	s_barrier
; #define PG8_STAGE(bufoff, gbase, voff) do { _Pragma("unroll") for (int _i = 0; _i < 2; ++_i) \
;         dma16((const char*)(gbase), (voff)[_i], ldsb + (bufoff) + ldsw + _i * 8192); } while (0)
; #define PG8_LDA(dst, b, h) do { const int a1_ = opqv(aoff0) ^ 64; _Pragma("unroll") for (int m = 0; m < 4; ++m) { dst[m][0] = *(const LAS bf16x8*)(lds + PG8_SA(b, h) + aoff0 + m * 2048); dst[m][1] = *(const LAS bf16x8*)(lds + PG8_SA(b, h) + a1_ + m * 2048); } } while (0)
; #define PG8_LDB(dst, b, h) do { const int b1_ = opqv(boff0) ^ 64; _Pragma("unroll") for (int n = 0; n < 2; ++n) { dst[n][0] = *(const LAS bf16x8*)(lds + PG8_SB(b, h) + boff0 + n * 2048); dst[n][1] = *(const LAS bf16x8*)(lds + PG8_SB(b, h) + b1_ + n * 2048); } } while (0)
; #define PG8_MMA(ai, bj, At, Bt) do { __builtin_amdgcn_s_setprio(1); _Pragma("unroll") for (int m = 0; m < 4; ++m) _Pragma("unroll") for (int n = 0; n < 2; ++n) _Pragma("unroll") for (int k = 0; k < 2; ++k) \
;         acc[ai][bj][m][n] = __builtin_amdgcn_mfma_f32_16x16x32_bf16(Bt[n][k], At[m][k], acc[ai][bj][m][n], 0, 0, 0); __builtin_amdgcn_s_setprio(0); } while (0)
; #define PG8_WAIT_V(n) asm volatile("s_waitcnt vmcnt(" #n ")" ::: "memory")
; template <class Epi>
; __device__ __forceinline__ void gemm_phase(LAS unsigned char* lds, const Gemm g, const StaticOrder& S, const Epi& E, int wave_) {
;     ...
;             PG8_STAGE(PG8_SA(1, 1), a1 + hstepA, voffA); PG8_LDB(B0, 0, 0); PG8_LDB(B1, 0, 1); PG8_SCHED; PG8_LDA(At, 0, 0);
;             PG8_WAIT_V(8); PG8_WAIT_L(0); PG8_BAR; PG8_MMA(0, 0, At, B0); PG8_MMA(0, 1, At, B1); PG8_BAR; PG8_SCHED;
;             PG8_STAGE(PG8_SB(0, 0), b2, voffB); PG8_STAGE(PG8_SB(0, 1), b2 + hstepB, voffB); PG8_STAGE(PG8_SA(0, 0), a2, voffA); PG8_LDA(At, 0, 1);
;             PG8_WAIT_V(8); PG8_WAIT_L(0); PG8_BAR; PG8_MMA(1, 0, At, B0); PG8_MMA(1, 1, At, B1); PG8_BAR; PG8_SCHED;
;             PG8_STAGE(PG8_SA(0, 1), a2 + hstepA, voffA); PG8_LDB(B0, 1, 0); PG8_LDB(B1, 1, 1); PG8_SCHED; PG8_LDA(At, 1, 0);
;             PG8_WAIT_V(8); PG8_WAIT_L(0); PG8_BAR; PG8_MMA(0, 0, At, B0); PG8_MMA(0, 1, At, B1); PG8_BAR; PG8_SCHED;
;             PG8_STAGE(PG8_SB(1, 0), b3, voffB); PG8_STAGE(PG8_SB(1, 1), b3 + hstepB, voffB); PG8_STAGE(PG8_SA(1, 0), a3, voffA); PG8_LDA(At, 1, 1);
;             PG8_WAIT_V(8); PG8_WAIT_L(0); PG8_BAR; PG8_MMA(1, 0, At, B0); PG8_MMA(1, 1, At, B1); PG8_BAR; PG8_SCHED;
	s_setprio 0
	s_add_u32 s30, s30, 0x80080
	s_addc_u32 s31, s31, 0
	v_mov_b32_e32 v136, v143
	s_nop 0
	s_nop 0
	v_xad_u32 v136, v136, 64, 0
	ds_read_b128 v[174:177], v137 offset:49152
	ds_read_b128 v[178:181], v137 offset:51200
	ds_read_b128 v[192:195], v136 offset:49152
	ds_read_b128 v[196:199], v136 offset:51200
	ds_read_b128 v[200:203], v137 offset:53248
	ds_read_b128 v[204:207], v137 offset:55296
	ds_read_b128 v[208:211], v136 offset:53248
	ds_read_b128 v[212:215], v136 offset:55296
	s_mov_b32 m0, s35
	s_nop 0
	global_load_lds_dwordx4 v139, s[36:37]
	s_mov_b32 m0, s33
	s_nop 0
	global_load_lds_dwordx4 v141, s[36:37]
	s_mov_b32 m0, s77
	s_nop 0
	global_load_lds_dwordx4 v139, s[30:31]
	s_mov_b32 m0, s3
	s_nop 0
	global_load_lds_dwordx4 v141, s[30:31]
	s_mov_b32 m0, s22
	s_nop 0
	global_load_lds_dwordx4 v138, s[26:27]
	s_mov_b32 m0, s2
	s_nop 0
	global_load_lds_dwordx4 v140, s[26:27]
	s_waitcnt vmcnt(8)
	s_waitcnt lgkmcnt(0)
	s_setprio 1
	s_barrier
	v_mfma_f32_16x16x32_bf16 v[60:63], v[128:131], v[174:177], v[60:63]
	v_mfma_f32_16x16x32_bf16 v[56:59], v[146:149], v[174:177], v[56:59]
	v_mfma_f32_16x16x32_bf16 v[44:47], v[128:131], v[178:181], v[44:47]
	v_mfma_f32_16x16x32_bf16 v[40:43], v[146:149], v[178:181], v[40:43]
	v_mfma_f32_16x16x32_bf16 v[28:31], v[128:131], v[200:203], v[28:31]
	v_mfma_f32_16x16x32_bf16 v[24:27], v[146:149], v[200:203], v[24:27]
	v_mfma_f32_16x16x32_bf16 v[12:15], v[128:131], v[204:207], v[12:15]
	v_mfma_f32_16x16x32_bf16 v[8:11], v[146:149], v[204:207], v[8:11]
	v_mfma_f32_16x16x32_bf16 v[60:63], v[150:153], v[192:195], v[60:63]
	v_mfma_f32_16x16x32_bf16 v[56:59], v[154:157], v[192:195], v[56:59]
	v_mfma_f32_16x16x32_bf16 v[44:47], v[150:153], v[196:199], v[44:47]
	v_mfma_f32_16x16x32_bf16 v[40:43], v[154:157], v[196:199], v[40:43]
	v_mfma_f32_16x16x32_bf16 v[28:31], v[150:153], v[208:211], v[28:31]
	v_mfma_f32_16x16x32_bf16 v[24:27], v[154:157], v[208:211], v[24:27]
	v_mfma_f32_16x16x32_bf16 v[12:15], v[150:153], v[212:215], v[12:15]
	v_mfma_f32_16x16x32_bf16 v[8:11], v[154:157], v[212:215], v[8:11]
	v_mfma_f32_16x16x32_bf16 v[52:55], v[158:161], v[174:177], v[52:55]
	v_mfma_f32_16x16x32_bf16 v[48:51], v[162:165], v[174:177], v[48:51]
	v_mfma_f32_16x16x32_bf16 v[36:39], v[158:161], v[178:181], v[36:39]
	v_mfma_f32_16x16x32_bf16 v[32:35], v[162:165], v[178:181], v[32:35]
	v_mfma_f32_16x16x32_bf16 v[20:23], v[158:161], v[200:203], v[20:23]
	v_mfma_f32_16x16x32_bf16 v[16:19], v[162:165], v[200:203], v[16:19]
	v_mfma_f32_16x16x32_bf16 v[4:7], v[158:161], v[204:207], v[4:7]
	v_mfma_f32_16x16x32_bf16 v[0:3], v[162:165], v[204:207], v[0:3]
	v_mfma_f32_16x16x32_bf16 v[52:55], v[166:169], v[192:195], v[52:55]
	v_mfma_f32_16x16x32_bf16 v[48:51], v[170:173], v[192:195], v[48:51]
	v_mfma_f32_16x16x32_bf16 v[36:39], v[166:169], v[196:199], v[36:39]
	v_mfma_f32_16x16x32_bf16 v[32:35], v[170:173], v[196:199], v[32:35]
	v_mfma_f32_16x16x32_bf16 v[20:23], v[166:169], v[208:211], v[20:23]
	v_mfma_f32_16x16x32_bf16 v[16:19], v[170:173], v[208:211], v[16:19]
	v_mfma_f32_16x16x32_bf16 v[4:7], v[166:169], v[212:215], v[4:7]
	v_mfma_f32_16x16x32_bf16 v[0:3], v[170:173], v[212:215], v[0:3]
	s_barrier
	s_setprio 0
	s_add_i32 s57, s57, 2
	s_add_u32 s52, s52, 0x100
	s_addc_u32 s56, s56, 0
	s_add_u32 s12, s12, 0x100
	s_addc_u32 s13, s13, 0
	s_cmp_gt_u32 s57, 29
	s_cbranch_scc0 .LBB0_574
	s_branch .Lpeel_exit_7
.LBB0_574:
	s_add_u32 s26, s12, 0xfff80080
	s_addc_u32 s27, s13, -1
	s_cmp_eq_u32 s57, 28
	s_cselect_b32 s36, s16, s26
	v_mov_b32_e32 v128, v144
	s_cselect_b32 s37, s11, s27
	s_cselect_b32 s30, s17, s52
	s_cselect_b32 s31, s9, s56
	s_add_u32 s26, s36, 0x80
	v_add_u32_e32 v137, s23, v144
	v_xad_u32 v136, v128, 64, s23
	s_addc_u32 s27, s37, 0
	ds_read_b128 v[128:131], v137
	ds_read_b128 v[146:149], v137 offset:2048
	ds_read_b128 v[150:153], v136
	ds_read_b128 v[154:157], v136 offset:2048
	v_mov_b32_e32 v136, v144
	s_add_i32 s58, 0, 0x14000
	v_add_u32_e32 v137, s58, v144
	v_xad_u32 v136, v136, 64, s58
	ds_read_b128 v[158:161], v137
	ds_read_b128 v[162:165], v137 offset:2048
	ds_read_b128 v[166:169], v136
	ds_read_b128 v[170:173], v136 offset:2048
	v_mov_b32_e32 v136, v143
	v_add_u32_e32 v137, 0, v143
	v_xad_u32 v136, v136, 64, 0
	ds_read_b128 v[174:177], v137
	ds_read_b128 v[178:181], v137 offset:2048
	ds_read_b128 v[192:195], v136
	ds_read_b128 v[196:199], v136 offset:2048
	ds_read_b128 v[200:203], v137 offset:4096
	ds_read_b128 v[204:207], v137 offset:6144
	ds_read_b128 v[208:211], v136 offset:4096
	ds_read_b128 v[212:215], v136 offset:6144
	s_mov_b32 m0, s14
	s_nop 0
	global_load_lds_dwordx4 v138, s[12:13]
	s_mov_b32 m0, s15
	s_nop 0
	global_load_lds_dwordx4 v140, s[12:13]
	s_waitcnt vmcnt(8)
	s_waitcnt lgkmcnt(0)
	s_setprio 1
	s_barrier
; #define PG8_STAGE(bufoff, gbase, voff) do { _Pragma("unroll") for (int _i = 0; _i < 2; ++_i) \
;         dma16((const char*)(gbase), (voff)[_i], ldsb + (bufoff) + ldsw + _i * 8192); } while (0)
; #define PG8_LDA(dst, b, h) do { const int a1_ = opqv(aoff0) ^ 64; _Pragma("unroll") for (int m = 0; m < 4; ++m) { dst[m][0] = *(const LAS bf16x8*)(lds + PG8_SA(b, h) + aoff0 + m * 2048); dst[m][1] = *(const LAS bf16x8*)(lds + PG8_SA(b, h) + a1_ + m * 2048); } } while (0)
; #define PG8_MMA(ai, bj, At, Bt) do { __builtin_amdgcn_s_setprio(1); _Pragma("unroll") for (int m = 0; m < 4; ++m) _Pragma("unroll") for (int n = 0; n < 2; ++n) _Pragma("unroll") for (int k = 0; k < 2; ++k) \
;         acc[ai][bj][m][n] = __builtin_amdgcn_mfma_f32_16x16x32_bf16(Bt[n][k], At[m][k], acc[ai][bj][m][n], 0, 0, 0); __builtin_amdgcn_s_setprio(0); } while (0)
; #define PG8_WAIT_V(n) asm volatile("s_waitcnt vmcnt(" #n ")" ::: "memory")
; #define PG8_WAIT_L(n) asm volatile("s_waitcnt lgkmcnt(" #n ")" ::: "memory")
; #define PG8_BAR __builtin_amdgcn_s_barrier()
; #define PG8_SCHED __builtin_amdgcn_sched_barrier(0)
; template <class Epi>
; __device__ __forceinline__ void gemm_phase(LAS unsigned char* lds, const Gemm g, const StaticOrder& S, const Epi& E, int wave_) {
;     ...
;             PG8_WAIT_V(8); PG8_WAIT_L(0); PG8_BAR; PG8_MMA(0, 0, At, B0); PG8_MMA(0, 1, At, B1); PG8_BAR; PG8_SCHED;
;             PG8_STAGE(PG8_SB(0, 0), b2, voffB); PG8_STAGE(PG8_SB(0, 1), b2 + hstepB, voffB); PG8_STAGE(PG8_SA(0, 0), a2, voffA); PG8_LDA(At, 0, 1);
;             PG8_WAIT_V(8); PG8_WAIT_L(0); PG8_BAR; PG8_MMA(1, 0, At, B0); PG8_MMA(1, 1, At, B1); PG8_BAR; PG8_SCHED;
	v_mfma_f32_16x16x32_bf16 v[124:127], v[128:131], v[174:177], v[124:127]
	v_mfma_f32_16x16x32_bf16 v[120:123], v[146:149], v[174:177], v[120:123]
	v_mfma_f32_16x16x32_bf16 v[108:111], v[128:131], v[178:181], v[108:111]
	v_mfma_f32_16x16x32_bf16 v[104:107], v[146:149], v[178:181], v[104:107]
	v_mfma_f32_16x16x32_bf16 v[92:95], v[128:131], v[200:203], v[92:95]
	v_mfma_f32_16x16x32_bf16 v[88:91], v[146:149], v[200:203], v[88:91]
	v_mfma_f32_16x16x32_bf16 v[76:79], v[128:131], v[204:207], v[76:79]
	v_mfma_f32_16x16x32_bf16 v[72:75], v[146:149], v[204:207], v[72:75]
	v_mfma_f32_16x16x32_bf16 v[124:127], v[150:153], v[192:195], v[124:127]
	v_mfma_f32_16x16x32_bf16 v[120:123], v[154:157], v[192:195], v[120:123]
	v_mfma_f32_16x16x32_bf16 v[108:111], v[150:153], v[196:199], v[108:111]
	v_mfma_f32_16x16x32_bf16 v[104:107], v[154:157], v[196:199], v[104:107]
	v_mfma_f32_16x16x32_bf16 v[92:95], v[150:153], v[208:211], v[92:95]
	v_mfma_f32_16x16x32_bf16 v[88:91], v[154:157], v[208:211], v[88:91]
	v_mfma_f32_16x16x32_bf16 v[76:79], v[150:153], v[212:215], v[76:79]
	v_mfma_f32_16x16x32_bf16 v[72:75], v[154:157], v[212:215], v[72:75]
	v_mfma_f32_16x16x32_bf16 v[116:119], v[158:161], v[174:177], v[116:119]
	v_mfma_f32_16x16x32_bf16 v[112:115], v[162:165], v[174:177], v[112:115]
	v_mfma_f32_16x16x32_bf16 v[100:103], v[158:161], v[178:181], v[100:103]
	v_mfma_f32_16x16x32_bf16 v[96:99], v[162:165], v[178:181], v[96:99]
	v_mfma_f32_16x16x32_bf16 v[84:87], v[158:161], v[200:203], v[84:87]
	v_mfma_f32_16x16x32_bf16 v[80:83], v[162:165], v[200:203], v[80:83]
	v_mfma_f32_16x16x32_bf16 v[68:71], v[158:161], v[204:207], v[68:71]
	v_mfma_f32_16x16x32_bf16 v[64:67], v[162:165], v[204:207], v[64:67]
	v_mfma_f32_16x16x32_bf16 v[116:119], v[166:169], v[192:195], v[116:119]
	v_mfma_f32_16x16x32_bf16 v[112:115], v[170:173], v[192:195], v[112:115]
	v_mfma_f32_16x16x32_bf16 v[100:103], v[166:169], v[196:199], v[100:103]
	v_mfma_f32_16x16x32_bf16 v[96:99], v[170:173], v[196:199], v[96:99]
	v_mfma_f32_16x16x32_bf16 v[84:87], v[166:169], v[208:211], v[84:87]
	v_mfma_f32_16x16x32_bf16 v[80:83], v[170:173], v[208:211], v[80:83]
	v_mfma_f32_16x16x32_bf16 v[68:71], v[166:169], v[212:215], v[68:71]
	v_mfma_f32_16x16x32_bf16 v[64:67], v[170:173], v[212:215], v[64:67]
	s_barrier
	s_setprio 0
	v_mov_b32_e32 v136, v143
	s_add_u32 s58, s30, 0x80000
	s_addc_u32 s59, s31, 0
	s_nop 0
	s_nop 0
	s_nop 0
	v_xad_u32 v136, v136, 64, 0
	ds_read_b128 v[174:177], v137 offset:16384
	ds_read_b128 v[178:181], v137 offset:18432
	ds_read_b128 v[192:195], v136 offset:16384
	ds_read_b128 v[196:199], v136 offset:18432
	ds_read_b128 v[200:203], v137 offset:20480
	ds_read_b128 v[204:207], v137 offset:22528
	ds_read_b128 v[208:211], v136 offset:20480
	ds_read_b128 v[212:215], v136 offset:22528
	s_mov_b32 m0, s80
	s_nop 0
	global_load_lds_dwordx4 v139, s[30:31]
	s_mov_b32 m0, s81
	s_nop 0
	global_load_lds_dwordx4 v141, s[30:31]
	s_mov_b32 m0, s29
	s_nop 0
	global_load_lds_dwordx4 v139, s[58:59]
	s_mov_b32 m0, s88
	s_nop 0
	global_load_lds_dwordx4 v141, s[58:59]
	s_mov_b32 m0, s76
	s_nop 0
	global_load_lds_dwordx4 v138, s[36:37]
	s_mov_b32 m0, s89
	s_nop 0
	global_load_lds_dwordx4 v140, s[36:37]
	s_waitcnt vmcnt(8)
	s_waitcnt lgkmcnt(0)
	s_setprio 1
	s_barrier
	v_mfma_f32_16x16x32_bf16 v[60:63], v[128:131], v[174:177], v[60:63]
	v_mfma_f32_16x16x32_bf16 v[56:59], v[146:149], v[174:177], v[56:59]
	v_mfma_f32_16x16x32_bf16 v[44:47], v[128:131], v[178:181], v[44:47]
	v_mfma_f32_16x16x32_bf16 v[40:43], v[146:149], v[178:181], v[40:43]
	v_mfma_f32_16x16x32_bf16 v[28:31], v[128:131], v[200:203], v[28:31]
	v_mfma_f32_16x16x32_bf16 v[24:27], v[146:149], v[200:203], v[24:27]
	v_mfma_f32_16x16x32_bf16 v[12:15], v[128:131], v[204:207], v[12:15]
	v_mfma_f32_16x16x32_bf16 v[8:11], v[146:149], v[204:207], v[8:11]
	v_mfma_f32_16x16x32_bf16 v[60:63], v[150:153], v[192:195], v[60:63]
	v_mfma_f32_16x16x32_bf16 v[56:59], v[154:157], v[192:195], v[56:59]
	v_mfma_f32_16x16x32_bf16 v[44:47], v[150:153], v[196:199], v[44:47]
	v_mfma_f32_16x16x32_bf16 v[40:43], v[154:157], v[196:199], v[40:43]
	v_mfma_f32_16x16x32_bf16 v[28:31], v[150:153], v[208:211], v[28:31]
	v_mfma_f32_16x16x32_bf16 v[24:27], v[154:157], v[208:211], v[24:27]
	v_mfma_f32_16x16x32_bf16 v[12:15], v[150:153], v[212:215], v[12:15]
	v_mfma_f32_16x16x32_bf16 v[8:11], v[154:157], v[212:215], v[8:11]
	v_mfma_f32_16x16x32_bf16 v[52:55], v[158:161], v[174:177], v[52:55]
	v_mfma_f32_16x16x32_bf16 v[48:51], v[162:165], v[174:177], v[48:51]
	v_mfma_f32_16x16x32_bf16 v[36:39], v[158:161], v[178:181], v[36:39]
	v_mfma_f32_16x16x32_bf16 v[32:35], v[162:165], v[178:181], v[32:35]
	v_mfma_f32_16x16x32_bf16 v[20:23], v[158:161], v[200:203], v[20:23]
	v_mfma_f32_16x16x32_bf16 v[16:19], v[162:165], v[200:203], v[16:19]
	v_mfma_f32_16x16x32_bf16 v[4:7], v[158:161], v[204:207], v[4:7]
	v_mfma_f32_16x16x32_bf16 v[0:3], v[162:165], v[204:207], v[0:3]
	v_mfma_f32_16x16x32_bf16 v[52:55], v[166:169], v[192:195], v[52:55]
	v_mfma_f32_16x16x32_bf16 v[48:51], v[170:173], v[192:195], v[48:51]
	v_mfma_f32_16x16x32_bf16 v[36:39], v[166:169], v[196:199], v[36:39]
	v_mfma_f32_16x16x32_bf16 v[32:35], v[170:173], v[196:199], v[32:35]
	v_mfma_f32_16x16x32_bf16 v[20:23], v[166:169], v[208:211], v[20:23]
	v_mfma_f32_16x16x32_bf16 v[16:19], v[170:173], v[208:211], v[16:19]
	v_mfma_f32_16x16x32_bf16 v[4:7], v[166:169], v[212:215], v[4:7]
	v_mfma_f32_16x16x32_bf16 v[0:3], v[170:173], v[212:215], v[0:3]
	s_barrier
; #define PG8_STAGE(bufoff, gbase, voff) do { _Pragma("unroll") for (int _i = 0; _i < 2; ++_i) \
;         dma16((const char*)(gbase), (voff)[_i], ldsb + (bufoff) + ldsw + _i * 8192); } while (0)
; #define PG8_LDA(dst, b, h) do { const int a1_ = opqv(aoff0) ^ 64; _Pragma("unroll") for (int m = 0; m < 4; ++m) { dst[m][0] = *(const LAS bf16x8*)(lds + PG8_SA(b, h) + aoff0 + m * 2048); dst[m][1] = *(const LAS bf16x8*)(lds + PG8_SA(b, h) + a1_ + m * 2048); } } while (0)
; #define PG8_LDB(dst, b, h) do { const int b1_ = opqv(boff0) ^ 64; _Pragma("unroll") for (int n = 0; n < 2; ++n) { dst[n][0] = *(const LAS bf16x8*)(lds + PG8_SB(b, h) + boff0 + n * 2048); dst[n][1] = *(const LAS bf16x8*)(lds + PG8_SB(b, h) + b1_ + n * 2048); } } while (0)
; #define PG8_MMA(ai, bj, At, Bt) do { __builtin_amdgcn_s_setprio(1); _Pragma("unroll") for (int m = 0; m < 4; ++m) _Pragma("unroll") for (int n = 0; n < 2; ++n) _Pragma("unroll") for (int k = 0; k < 2; ++k) \
;         acc[ai][bj][m][n] = __builtin_amdgcn_mfma_f32_16x16x32_bf16(Bt[n][k], At[m][k], acc[ai][bj][m][n], 0, 0, 0); __builtin_amdgcn_s_setprio(0); } while (0)
; #define PG8_WAIT_V(n) asm volatile("s_waitcnt vmcnt(" #n ")" ::: "memory")
; #define PG8_WAIT_L(n) asm volatile("s_waitcnt lgkmcnt(" #n ")" ::: "memory")
; #define PG8_BAR __builtin_amdgcn_s_barrier()
; #define PG8_SCHED __builtin_amdgcn_sched_barrier(0)
; template <class Epi>
; __device__ __forceinline__ void gemm_phase(LAS unsigned char* lds, const Gemm g, const StaticOrder& S, const Epi& E, int wave_) {
;     ...
;             PG8_STAGE(PG8_SA(0, 1), a2 + hstepA, voffA); PG8_LDB(B0, 1, 0); PG8_LDB(B1, 1, 1); PG8_SCHED; PG8_LDA(At, 1, 0);
;             PG8_WAIT_V(8); PG8_WAIT_L(0); PG8_BAR; PG8_MMA(0, 0, At, B0); PG8_MMA(0, 1, At, B1); PG8_BAR; PG8_SCHED;
;             PG8_STAGE(PG8_SB(1, 0), b3, voffB); PG8_STAGE(PG8_SB(1, 1), b3 + hstepB, voffB); PG8_STAGE(PG8_SA(1, 0), a3, voffA); PG8_LDA(At, 1, 1);
;             PG8_WAIT_V(8); PG8_WAIT_L(0); PG8_BAR; PG8_MMA(1, 0, At, B0); PG8_MMA(1, 1, At, B1); PG8_BAR; PG8_SCHED;
	s_setprio 0
	s_add_u32 s36, s36, 0x80000
	s_addc_u32 s37, s37, 0
	s_mov_b32 m0, s1
	s_nop 0
	global_load_lds_dwordx4 v138, s[36:37]
	v_mov_b32_e32 v128, v144
	s_mov_b32 m0, s69
	s_nop 0
	global_load_lds_dwordx4 v140, s[36:37]
	v_add_u32_e32 v146, s34, v144
	v_xad_u32 v136, v128, 64, s34
	ds_read_b128 v[128:131], v146
	ds_read_b128 v[146:149], v146 offset:2048
	ds_read_b128 v[150:153], v136
	ds_read_b128 v[154:157], v136 offset:2048
	v_mov_b32_e32 v136, v144
	s_add_i32 s36, 0, 0x1c000
	v_add_u32_e32 v162, s36, v144
	v_xad_u32 v136, v136, 64, s36
	ds_read_b128 v[158:161], v162
	ds_read_b128 v[162:165], v162 offset:2048
	ds_read_b128 v[166:169], v136
	ds_read_b128 v[170:173], v136 offset:2048
	v_mov_b32_e32 v136, v143
	s_nop 0
	v_xad_u32 v136, v136, 64, 0
	ds_read_b128 v[174:177], v137 offset:32768
	ds_read_b128 v[178:181], v137 offset:34816
	ds_read_b128 v[192:195], v136 offset:32768
	ds_read_b128 v[196:199], v136 offset:34816
	ds_read_b128 v[200:203], v137 offset:36864
	ds_read_b128 v[204:207], v137 offset:38912
	ds_read_b128 v[208:211], v136 offset:36864
	ds_read_b128 v[212:215], v136 offset:38912
	s_waitcnt vmcnt(8)
	s_waitcnt lgkmcnt(0)
	s_setprio 1
	s_barrier
	v_mfma_f32_16x16x32_bf16 v[124:127], v[128:131], v[174:177], v[124:127]
	v_mfma_f32_16x16x32_bf16 v[120:123], v[146:149], v[174:177], v[120:123]
	v_mfma_f32_16x16x32_bf16 v[108:111], v[128:131], v[178:181], v[108:111]
	v_mfma_f32_16x16x32_bf16 v[104:107], v[146:149], v[178:181], v[104:107]
	v_mfma_f32_16x16x32_bf16 v[92:95], v[128:131], v[200:203], v[92:95]
	v_mfma_f32_16x16x32_bf16 v[88:91], v[146:149], v[200:203], v[88:91]
	v_mfma_f32_16x16x32_bf16 v[76:79], v[128:131], v[204:207], v[76:79]
	v_mfma_f32_16x16x32_bf16 v[72:75], v[146:149], v[204:207], v[72:75]
	v_mfma_f32_16x16x32_bf16 v[124:127], v[150:153], v[192:195], v[124:127]
	v_mfma_f32_16x16x32_bf16 v[120:123], v[154:157], v[192:195], v[120:123]
	v_mfma_f32_16x16x32_bf16 v[108:111], v[150:153], v[196:199], v[108:111]
	v_mfma_f32_16x16x32_bf16 v[104:107], v[154:157], v[196:199], v[104:107]
	v_mfma_f32_16x16x32_bf16 v[92:95], v[150:153], v[208:211], v[92:95]
	v_mfma_f32_16x16x32_bf16 v[88:91], v[154:157], v[208:211], v[88:91]
	v_mfma_f32_16x16x32_bf16 v[76:79], v[150:153], v[212:215], v[76:79]
	v_mfma_f32_16x16x32_bf16 v[72:75], v[154:157], v[212:215], v[72:75]
	v_mfma_f32_16x16x32_bf16 v[116:119], v[158:161], v[174:177], v[116:119]
	s_add_u32 s36, s30, 0x80
	s_addc_u32 s37, s31, 0
	v_mfma_f32_16x16x32_bf16 v[112:115], v[162:165], v[174:177], v[112:115]
	v_mfma_f32_16x16x32_bf16 v[100:103], v[158:161], v[178:181], v[100:103]
	v_mfma_f32_16x16x32_bf16 v[96:99], v[162:165], v[178:181], v[96:99]
	v_mfma_f32_16x16x32_bf16 v[84:87], v[158:161], v[200:203], v[84:87]
	v_mfma_f32_16x16x32_bf16 v[80:83], v[162:165], v[200:203], v[80:83]
	v_mfma_f32_16x16x32_bf16 v[68:71], v[158:161], v[204:207], v[68:71]
	v_mfma_f32_16x16x32_bf16 v[64:67], v[162:165], v[204:207], v[64:67]
	v_mfma_f32_16x16x32_bf16 v[116:119], v[166:169], v[192:195], v[116:119]
	v_mfma_f32_16x16x32_bf16 v[112:115], v[170:173], v[192:195], v[112:115]
	v_mfma_f32_16x16x32_bf16 v[100:103], v[166:169], v[196:199], v[100:103]
	v_mfma_f32_16x16x32_bf16 v[96:99], v[170:173], v[196:199], v[96:99]
	v_mfma_f32_16x16x32_bf16 v[84:87], v[166:169], v[208:211], v[84:87]
	v_mfma_f32_16x16x32_bf16 v[80:83], v[170:173], v[208:211], v[80:83]
	v_mfma_f32_16x16x32_bf16 v[68:71], v[166:169], v[212:215], v[68:71]
	v_mfma_f32_16x16x32_bf16 v[64:67], v[170:173], v[212:215], v[64:67]
	s_barrier
	s_setprio 0
	s_add_u32 s30, s30, 0x80080
	s_addc_u32 s31, s31, 0
	v_mov_b32_e32 v136, v143
	s_nop 0
	s_nop 0
	v_xad_u32 v136, v136, 64, 0
	ds_read_b128 v[174:177], v137 offset:49152
	ds_read_b128 v[178:181], v137 offset:51200
	ds_read_b128 v[192:195], v136 offset:49152
	ds_read_b128 v[196:199], v136 offset:51200
	ds_read_b128 v[200:203], v137 offset:53248
	ds_read_b128 v[204:207], v137 offset:55296
	ds_read_b128 v[208:211], v136 offset:53248
	ds_read_b128 v[212:215], v136 offset:55296
	s_mov_b32 m0, s35
	s_nop 0
	global_load_lds_dwordx4 v139, s[36:37]
	s_mov_b32 m0, s33
	s_nop 0
	global_load_lds_dwordx4 v141, s[36:37]
	s_mov_b32 m0, s77
	s_nop 0
	global_load_lds_dwordx4 v139, s[30:31]
	s_mov_b32 m0, s3
	s_nop 0
	global_load_lds_dwordx4 v141, s[30:31]
	s_mov_b32 m0, s22
	s_nop 0
	global_load_lds_dwordx4 v138, s[26:27]
	s_mov_b32 m0, s2
	s_nop 0
	global_load_lds_dwordx4 v140, s[26:27]
	s_waitcnt vmcnt(8)
	s_waitcnt lgkmcnt(0)
	s_setprio 1
	s_barrier
	v_mfma_f32_16x16x32_bf16 v[60:63], v[128:131], v[174:177], v[60:63]
	v_mfma_f32_16x16x32_bf16 v[56:59], v[146:149], v[174:177], v[56:59]
	v_mfma_f32_16x16x32_bf16 v[44:47], v[128:131], v[178:181], v[44:47]
	v_mfma_f32_16x16x32_bf16 v[40:43], v[146:149], v[178:181], v[40:43]
	v_mfma_f32_16x16x32_bf16 v[28:31], v[128:131], v[200:203], v[28:31]
	v_mfma_f32_16x16x32_bf16 v[24:27], v[146:149], v[200:203], v[24:27]
	v_mfma_f32_16x16x32_bf16 v[12:15], v[128:131], v[204:207], v[12:15]
	v_mfma_f32_16x16x32_bf16 v[8:11], v[146:149], v[204:207], v[8:11]
	v_mfma_f32_16x16x32_bf16 v[60:63], v[150:153], v[192:195], v[60:63]
	v_mfma_f32_16x16x32_bf16 v[56:59], v[154:157], v[192:195], v[56:59]
	v_mfma_f32_16x16x32_bf16 v[44:47], v[150:153], v[196:199], v[44:47]
	v_mfma_f32_16x16x32_bf16 v[40:43], v[154:157], v[196:199], v[40:43]
	v_mfma_f32_16x16x32_bf16 v[28:31], v[150:153], v[208:211], v[28:31]
	v_mfma_f32_16x16x32_bf16 v[24:27], v[154:157], v[208:211], v[24:27]
	v_mfma_f32_16x16x32_bf16 v[12:15], v[150:153], v[212:215], v[12:15]
	v_mfma_f32_16x16x32_bf16 v[8:11], v[154:157], v[212:215], v[8:11]
	v_mfma_f32_16x16x32_bf16 v[52:55], v[158:161], v[174:177], v[52:55]
	v_mfma_f32_16x16x32_bf16 v[48:51], v[162:165], v[174:177], v[48:51]
	v_mfma_f32_16x16x32_bf16 v[36:39], v[158:161], v[178:181], v[36:39]
	v_mfma_f32_16x16x32_bf16 v[32:35], v[162:165], v[178:181], v[32:35]
	v_mfma_f32_16x16x32_bf16 v[20:23], v[158:161], v[200:203], v[20:23]
	v_mfma_f32_16x16x32_bf16 v[16:19], v[162:165], v[200:203], v[16:19]
	v_mfma_f32_16x16x32_bf16 v[4:7], v[158:161], v[204:207], v[4:7]
	v_mfma_f32_16x16x32_bf16 v[0:3], v[162:165], v[204:207], v[0:3]
	v_mfma_f32_16x16x32_bf16 v[52:55], v[166:169], v[192:195], v[52:55]
	v_mfma_f32_16x16x32_bf16 v[48:51], v[170:173], v[192:195], v[48:51]
	v_mfma_f32_16x16x32_bf16 v[36:39], v[166:169], v[196:199], v[36:39]
	v_mfma_f32_16x16x32_bf16 v[32:35], v[170:173], v[196:199], v[32:35]
	v_mfma_f32_16x16x32_bf16 v[20:23], v[166:169], v[208:211], v[20:23]
	v_mfma_f32_16x16x32_bf16 v[16:19], v[170:173], v[208:211], v[16:19]
	v_mfma_f32_16x16x32_bf16 v[4:7], v[166:169], v[212:215], v[4:7]
	v_mfma_f32_16x16x32_bf16 v[0:3], v[170:173], v[212:215], v[0:3]
	s_barrier
	s_setprio 0
	s_add_i32 s57, s57, 2
	s_add_u32 s52, s52, 0x100
	s_addc_u32 s56, s56, 0
	s_add_u32 s12, s12, 0x100
	s_addc_u32 s13, s13, 0
	s_cmp_gt_u32 s57, 29
	s_cbranch_scc0 .LBB0_574

; #define PG8_STAGE(bufoff, gbase, voff) do { _Pragma("unroll") for (int _i = 0; _i < 2; ++_i) \
;         dma16((const char*)(gbase), (voff)[_i], ldsb + (bufoff) + ldsw + _i * 8192); } while (0)
; #define PG8_LDA(dst, b, h) do { const int a1_ = opqv(aoff0) ^ 64; _Pragma("unroll") for (int m = 0; m < 4; ++m) { dst[m][0] = *(const LAS bf16x8*)(lds + PG8_SA(b, h) + aoff0 + m * 2048); dst[m][1] = *(const LAS bf16x8*)(lds + PG8_SA(b, h) + a1_ + m * 2048); } } while (0)
; #define PG8_LDB(dst, b, h) do { const int b1_ = opqv(boff0) ^ 64; _Pragma("unroll") for (int n = 0; n < 2; ++n) { dst[n][0] = *(const LAS bf16x8*)(lds + PG8_SB(b, h) + boff0 + n * 2048); dst[n][1] = *(const LAS bf16x8*)(lds + PG8_SB(b, h) + b1_ + n * 2048); } } while (0)
; #define PG8_MMA(ai, bj, At, Bt) do { __builtin_amdgcn_s_setprio(1); _Pragma("unroll") for (int m = 0; m < 4; ++m) _Pragma("unroll") for (int n = 0; n < 2; ++n) _Pragma("unroll") for (int k = 0; k < 2; ++k) \
;         acc[ai][bj][m][n] = __builtin_amdgcn_mfma_f32_16x16x32_bf16(Bt[n][k], At[m][k], acc[ai][bj][m][n], 0, 0, 0); __builtin_amdgcn_s_setprio(0); } while (0)
; template <class Epi>
; __device__ __forceinline__ void gemm_phase(LAS unsigned char* lds, const Gemm g, const StaticOrder& S, const Epi& E, int wave_) {
;     ...
;         const bool has_next = S.next(ui + 1, nxt);
;         const char* nA = has_next ? (const char*)g.A + (size_t)nxt.pm * tstepA : cA; const char* nB = has_next ? (const char*)g.Bt + (size_t)nxt.pn * tstepB : cB;
; #pragma unroll 1
;         for (int t = 0; t < nt; t += 2) {
;             const bool last = (t == nt - 2);
;             const char* a1 = cA + (size_t)(t + 1) * kstep;
;             const char* a2 = last ? nA : cA + (size_t)(t + 2) * kstep; const char* b2 = last ? nB : cB + (size_t)(t + 2) * kstep;
;             const char* a3 = a2 + kstep; const char* b3 = b2 + kstep;
;             PG8_STAGE(PG8_SA(1, 1), a1 + hstepA, voffA); PG8_LDB(B0, 0, 0); PG8_LDB(B1, 0, 1); PG8_SCHED; PG8_LDA(At, 0, 0);
;             PG8_WAIT_V(8); PG8_WAIT_L(0); PG8_BAR; PG8_MMA(0, 0, At, B0); PG8_MMA(0, 1, At, B1); PG8_BAR; PG8_SCHED;
;             PG8_STAGE(PG8_SB(0, 0), b2, voffB); PG8_STAGE(PG8_SB(0, 1), b2 + hstepB, voffB); PG8_STAGE(PG8_SA(0, 0), a2, voffA); PG8_LDA(At, 0, 1);
;             PG8_WAIT_V(8); PG8_WAIT_L(0); PG8_BAR; PG8_MMA(1, 0, At, B0); PG8_MMA(1, 1, At, B1); PG8_BAR; PG8_SCHED;
.LBB0_743:
	s_ashr_i32 s19, s18, 31
	s_lshl_b64 s[16:17], s[18:19], 19
	s_add_u32 s24, s21, s16
	s_addc_u32 s25, s46, s17
	s_and_b64 s[16:17], s[40:41], exec
	s_cselect_b32 s16, s25, s31
	s_cselect_b32 s17, s24, s30
	s_ashr_i32 s11, s10, 31
	s_lshl_b64 s[26:27], s[10:11], 18
	s_add_u32 s26, s47, s26
	s_addc_u32 s27, s48, s27
	s_and_b64 s[36:37], s[40:41], exec
	s_cselect_b32 s11, s27, s13
	s_cselect_b32 s19, s26, s12
	s_add_u32 s52, s12, 0x100
	s_addc_u32 s56, s13, 0
	s_add_u32 s12, s30, 0x40080
	s_addc_u32 s13, s31, 0
	s_mov_b32 s57, -2
	s_add_u32 s30, s12, 0xfffc0080
	s_addc_u32 s31, s13, -1
	s_cmp_eq_u32 s57, 4
	s_cselect_b32 s42, s17, s30
	s_cselect_b32 s43, s16, s31
	s_cselect_b32 s36, s19, s52
	s_cselect_b32 s37, s11, s56
	s_add_u32 s30, s42, 0x80
	v_mov_b32_e32 v128, v180
	s_addc_u32 s31, s43, 0
	v_add_u32_e32 v132, s23, v180
	v_xad_u32 v144, v128, 64, s23
	v_mov_b32_e32 v148, v180
	s_add_i32 s58, 0, 0x14000
	ds_read_b128 v[128:131], v132
	ds_read_b128 v[132:135], v132 offset:2048
	ds_read_b128 v[140:143], v144
	ds_read_b128 v[144:147], v144 offset:2048
	v_add_u32_e32 v152, s58, v180
	v_xad_u32 v160, v148, 64, s58
	ds_read_b128 v[148:151], v152
	ds_read_b128 v[152:155], v152 offset:2048
	ds_read_b128 v[156:159], v160
	ds_read_b128 v[160:163], v160 offset:2048
	v_mov_b32_e32 v164, v179
	v_add_u32_e32 v182, 0, v179
	v_xad_u32 v172, v164, 64, 0
	ds_read_b128 v[164:167], v182
	ds_read_b128 v[168:171], v182 offset:2048
	ds_read_b128 v[192:195], v172
	ds_read_b128 v[196:199], v172 offset:2048
	ds_read_b128 v[200:203], v182 offset:4096
	ds_read_b128 v[204:207], v182 offset:6144
	ds_read_b128 v[208:211], v172 offset:4096
	ds_read_b128 v[212:215], v172 offset:6144
	s_mov_b32 m0, s14
	s_nop 0
	global_load_lds_dwordx4 v137, s[12:13]
	s_mov_b32 m0, s15
	s_nop 0
	global_load_lds_dwordx4 v176, s[12:13]
	s_waitcnt vmcnt(8)
	s_waitcnt lgkmcnt(0)
	s_setprio 1
	s_barrier
	v_mfma_f32_16x16x32_bf16 v[124:127], v[128:131], v[164:167], 0
	v_mfma_f32_16x16x32_bf16 v[120:123], v[132:135], v[164:167], 0
	v_mfma_f32_16x16x32_bf16 v[108:111], v[128:131], v[168:171], 0
	v_mfma_f32_16x16x32_bf16 v[104:107], v[132:135], v[168:171], 0
	v_mfma_f32_16x16x32_bf16 v[92:95], v[128:131], v[200:203], 0
	v_mfma_f32_16x16x32_bf16 v[88:91], v[132:135], v[200:203], 0
	v_mfma_f32_16x16x32_bf16 v[76:79], v[128:131], v[204:207], 0
	v_mfma_f32_16x16x32_bf16 v[72:75], v[132:135], v[204:207], 0
	v_mfma_f32_16x16x32_bf16 v[124:127], v[140:143], v[192:195], v[124:127]
	v_mfma_f32_16x16x32_bf16 v[120:123], v[144:147], v[192:195], v[120:123]
	v_mfma_f32_16x16x32_bf16 v[108:111], v[140:143], v[196:199], v[108:111]
	v_mfma_f32_16x16x32_bf16 v[104:107], v[144:147], v[196:199], v[104:107]
	v_mfma_f32_16x16x32_bf16 v[92:95], v[140:143], v[208:211], v[92:95]
	v_mfma_f32_16x16x32_bf16 v[88:91], v[144:147], v[208:211], v[88:91]
	v_mfma_f32_16x16x32_bf16 v[76:79], v[140:143], v[212:215], v[76:79]
	v_mfma_f32_16x16x32_bf16 v[72:75], v[144:147], v[212:215], v[72:75]
	v_mfma_f32_16x16x32_bf16 v[116:119], v[148:151], v[164:167], 0
	v_mfma_f32_16x16x32_bf16 v[112:115], v[152:155], v[164:167], 0
	v_mfma_f32_16x16x32_bf16 v[100:103], v[148:151], v[168:171], 0
	v_mfma_f32_16x16x32_bf16 v[96:99], v[152:155], v[168:171], 0
	v_mfma_f32_16x16x32_bf16 v[84:87], v[148:151], v[200:203], 0
	v_mfma_f32_16x16x32_bf16 v[80:83], v[152:155], v[200:203], 0
	v_mfma_f32_16x16x32_bf16 v[68:71], v[148:151], v[204:207], 0
	v_mfma_f32_16x16x32_bf16 v[64:67], v[152:155], v[204:207], 0
	v_mfma_f32_16x16x32_bf16 v[116:119], v[156:159], v[192:195], v[116:119]
	v_mfma_f32_16x16x32_bf16 v[112:115], v[160:163], v[192:195], v[112:115]
	v_mfma_f32_16x16x32_bf16 v[100:103], v[156:159], v[196:199], v[100:103]
	v_mfma_f32_16x16x32_bf16 v[96:99], v[160:163], v[196:199], v[96:99]
	v_mfma_f32_16x16x32_bf16 v[84:87], v[156:159], v[208:211], v[84:87]
	v_mfma_f32_16x16x32_bf16 v[80:83], v[160:163], v[208:211], v[80:83]
	v_mfma_f32_16x16x32_bf16 v[68:71], v[156:159], v[212:215], v[68:71]
	v_mfma_f32_16x16x32_bf16 v[64:67], v[160:163], v[212:215], v[64:67]
	s_barrier
	s_setprio 0
	v_mov_b32_e32 v164, v179
	s_add_u32 s58, s36, 0x20000
	s_addc_u32 s59, s37, 0
	s_nop 0
	s_nop 0
	s_nop 0
	v_xad_u32 v172, v164, 64, 0
	ds_read_b128 v[164:167], v182 offset:16384
	ds_read_b128 v[168:171], v182 offset:18432
	ds_read_b128 v[192:195], v172 offset:16384
	ds_read_b128 v[196:199], v172 offset:18432
	ds_read_b128 v[200:203], v182 offset:20480
	ds_read_b128 v[204:207], v182 offset:22528
	ds_read_b128 v[208:211], v172 offset:20480
	ds_read_b128 v[212:215], v172 offset:22528
	s_mov_b32 m0, s80
	s_nop 0
	global_load_lds_dwordx4 v175, s[36:37]
	s_mov_b32 m0, s81
	s_nop 0
	global_load_lds_dwordx4 v177, s[36:37]
	s_mov_b32 m0, s29
	s_nop 0
	global_load_lds_dwordx4 v175, s[58:59]
	s_mov_b32 m0, s88
	s_nop 0
	global_load_lds_dwordx4 v177, s[58:59]
	s_mov_b32 m0, s76
	s_nop 0
	global_load_lds_dwordx4 v137, s[42:43]
	s_mov_b32 m0, s89
	s_nop 0
	global_load_lds_dwordx4 v176, s[42:43]
	s_waitcnt vmcnt(8)
	s_waitcnt lgkmcnt(0)
	s_setprio 1
	s_barrier
; #define PG8_STAGE(bufoff, gbase, voff) do { _Pragma("unroll") for (int _i = 0; _i < 2; ++_i) \
;         dma16((const char*)(gbase), (voff)[_i], ldsb + (bufoff) + ldsw + _i * 8192); } while (0)
; #define PG8_LDA(dst, b, h) do { const int a1_ = opqv(aoff0) ^ 64; _Pragma("unroll") for (int m = 0; m < 4; ++m) { dst[m][0] = *(const LAS bf16x8*)(lds + PG8_SA(b, h) + aoff0 + m * 2048); dst[m][1] = *(const LAS bf16x8*)(lds + PG8_SA(b, h) + a1_ + m * 2048); } } while (0)
; #define PG8_LDB(dst, b, h) do { const int b1_ = opqv(boff0) ^ 64; _Pragma("unroll") for (int n = 0; n < 2; ++n) { dst[n][0] = *(const LAS bf16x8*)(lds + PG8_SB(b, h) + boff0 + n * 2048); dst[n][1] = *(const LAS bf16x8*)(lds + PG8_SB(b, h) + b1_ + n * 2048); } } while (0)
; #define PG8_MMA(ai, bj, At, Bt) do { __builtin_amdgcn_s_setprio(1); _Pragma("unroll") for (int m = 0; m < 4; ++m) _Pragma("unroll") for (int n = 0; n < 2; ++n) _Pragma("unroll") for (int k = 0; k < 2; ++k) \
;         acc[ai][bj][m][n] = __builtin_amdgcn_mfma_f32_16x16x32_bf16(Bt[n][k], At[m][k], acc[ai][bj][m][n], 0, 0, 0); __builtin_amdgcn_s_setprio(0); } while (0)
; #define PG8_WAIT_V(n) asm volatile("s_waitcnt vmcnt(" #n ")" ::: "memory")
; #define PG8_WAIT_L(n) asm volatile("s_waitcnt lgkmcnt(" #n ")" ::: "memory")
; #define PG8_BAR __builtin_amdgcn_s_barrier()
; #define PG8_SCHED __builtin_amdgcn_sched_barrier(0)
; template <class Epi>
; __device__ __forceinline__ void gemm_phase(LAS unsigned char* lds, const Gemm g, const StaticOrder& S, const Epi& E, int wave_) {
;     ...
;             PG8_WAIT_V(8); PG8_WAIT_L(0); PG8_BAR; PG8_MMA(1, 0, At, B0); PG8_MMA(1, 1, At, B1); PG8_BAR; PG8_SCHED;
;             PG8_STAGE(PG8_SA(0, 1), a2 + hstepA, voffA); PG8_LDB(B0, 1, 0); PG8_LDB(B1, 1, 1); PG8_SCHED; PG8_LDA(At, 1, 0);
;             PG8_WAIT_V(8); PG8_WAIT_L(0); PG8_BAR; PG8_MMA(0, 0, At, B0); PG8_MMA(0, 1, At, B1); PG8_BAR; PG8_SCHED;
	v_mfma_f32_16x16x32_bf16 v[60:63], v[128:131], v[164:167], 0
	v_mfma_f32_16x16x32_bf16 v[56:59], v[132:135], v[164:167], 0
	v_mfma_f32_16x16x32_bf16 v[44:47], v[128:131], v[168:171], 0
	v_mfma_f32_16x16x32_bf16 v[40:43], v[132:135], v[168:171], 0
	v_mfma_f32_16x16x32_bf16 v[28:31], v[128:131], v[200:203], 0
	v_mfma_f32_16x16x32_bf16 v[24:27], v[132:135], v[200:203], 0
	v_mfma_f32_16x16x32_bf16 v[12:15], v[128:131], v[204:207], 0
	v_mfma_f32_16x16x32_bf16 v[8:11], v[132:135], v[204:207], 0
	v_mfma_f32_16x16x32_bf16 v[60:63], v[140:143], v[192:195], v[60:63]
	v_mfma_f32_16x16x32_bf16 v[56:59], v[144:147], v[192:195], v[56:59]
	v_mfma_f32_16x16x32_bf16 v[44:47], v[140:143], v[196:199], v[44:47]
	v_mfma_f32_16x16x32_bf16 v[40:43], v[144:147], v[196:199], v[40:43]
	v_mfma_f32_16x16x32_bf16 v[28:31], v[140:143], v[208:211], v[28:31]
	v_mfma_f32_16x16x32_bf16 v[24:27], v[144:147], v[208:211], v[24:27]
	v_mfma_f32_16x16x32_bf16 v[12:15], v[140:143], v[212:215], v[12:15]
	v_mfma_f32_16x16x32_bf16 v[8:11], v[144:147], v[212:215], v[8:11]
	v_mfma_f32_16x16x32_bf16 v[52:55], v[148:151], v[164:167], 0
	v_mfma_f32_16x16x32_bf16 v[48:51], v[152:155], v[164:167], 0
	v_mfma_f32_16x16x32_bf16 v[36:39], v[148:151], v[168:171], 0
	v_mfma_f32_16x16x32_bf16 v[32:35], v[152:155], v[168:171], 0
	v_mfma_f32_16x16x32_bf16 v[20:23], v[148:151], v[200:203], 0
	v_mfma_f32_16x16x32_bf16 v[16:19], v[152:155], v[200:203], 0
	v_mfma_f32_16x16x32_bf16 v[4:7], v[148:151], v[204:207], 0
	v_mfma_f32_16x16x32_bf16 v[0:3], v[152:155], v[204:207], 0
	v_mfma_f32_16x16x32_bf16 v[52:55], v[156:159], v[192:195], v[52:55]
	v_mfma_f32_16x16x32_bf16 v[48:51], v[160:163], v[192:195], v[48:51]
	v_mfma_f32_16x16x32_bf16 v[36:39], v[156:159], v[196:199], v[36:39]
	v_mfma_f32_16x16x32_bf16 v[32:35], v[160:163], v[196:199], v[32:35]
	v_mfma_f32_16x16x32_bf16 v[20:23], v[156:159], v[208:211], v[20:23]
	v_mfma_f32_16x16x32_bf16 v[16:19], v[160:163], v[208:211], v[16:19]
	v_mfma_f32_16x16x32_bf16 v[4:7], v[156:159], v[212:215], v[4:7]
	v_mfma_f32_16x16x32_bf16 v[0:3], v[160:163], v[212:215], v[0:3]
	s_barrier
	s_setprio 0
	s_add_u32 s42, s42, 0x40000
	s_addc_u32 s43, s43, 0
	s_mov_b32 m0, s1
	s_nop 0
	global_load_lds_dwordx4 v137, s[42:43]
	v_mov_b32_e32 v128, v180
	s_mov_b32 m0, s69
	s_nop 0
	global_load_lds_dwordx4 v176, s[42:43]
	v_add_u32_e32 v132, s34, v180
	v_xad_u32 v144, v128, 64, s34
	v_mov_b32_e32 v148, v180
	s_add_i32 s42, 0, 0x1c000
	ds_read_b128 v[128:131], v132
	ds_read_b128 v[132:135], v132 offset:2048
	ds_read_b128 v[140:143], v144
	ds_read_b128 v[144:147], v144 offset:2048
	v_add_u32_e32 v152, s42, v180
	v_xad_u32 v160, v148, 64, s42
	ds_read_b128 v[148:151], v152
	ds_read_b128 v[152:155], v152 offset:2048
	ds_read_b128 v[156:159], v160
	ds_read_b128 v[160:163], v160 offset:2048
	v_mov_b32_e32 v164, v179
	s_nop 0
	v_xad_u32 v172, v164, 64, 0
	ds_read_b128 v[164:167], v182 offset:32768
	ds_read_b128 v[168:171], v182 offset:34816
	ds_read_b128 v[192:195], v172 offset:32768
	ds_read_b128 v[196:199], v172 offset:34816
	ds_read_b128 v[200:203], v182 offset:36864
	ds_read_b128 v[204:207], v182 offset:38912
	ds_read_b128 v[208:211], v172 offset:36864
	ds_read_b128 v[212:215], v172 offset:38912
	s_waitcnt vmcnt(8)
	s_waitcnt lgkmcnt(0)
	s_setprio 1
	s_barrier
	v_mfma_f32_16x16x32_bf16 v[124:127], v[128:131], v[164:167], v[124:127]
	v_mfma_f32_16x16x32_bf16 v[120:123], v[132:135], v[164:167], v[120:123]
	v_mfma_f32_16x16x32_bf16 v[108:111], v[128:131], v[168:171], v[108:111]
	v_mfma_f32_16x16x32_bf16 v[104:107], v[132:135], v[168:171], v[104:107]
	v_mfma_f32_16x16x32_bf16 v[92:95], v[128:131], v[200:203], v[92:95]
	v_mfma_f32_16x16x32_bf16 v[88:91], v[132:135], v[200:203], v[88:91]
	v_mfma_f32_16x16x32_bf16 v[76:79], v[128:131], v[204:207], v[76:79]
	v_mfma_f32_16x16x32_bf16 v[72:75], v[132:135], v[204:207], v[72:75]
	v_mfma_f32_16x16x32_bf16 v[124:127], v[140:143], v[192:195], v[124:127]
	v_mfma_f32_16x16x32_bf16 v[120:123], v[144:147], v[192:195], v[120:123]
	v_mfma_f32_16x16x32_bf16 v[108:111], v[140:143], v[196:199], v[108:111]
	v_mfma_f32_16x16x32_bf16 v[104:107], v[144:147], v[196:199], v[104:107]
	v_mfma_f32_16x16x32_bf16 v[92:95], v[140:143], v[208:211], v[92:95]
	v_mfma_f32_16x16x32_bf16 v[88:91], v[144:147], v[208:211], v[88:91]
	v_mfma_f32_16x16x32_bf16 v[76:79], v[140:143], v[212:215], v[76:79]
	v_mfma_f32_16x16x32_bf16 v[72:75], v[144:147], v[212:215], v[72:75]
	v_mfma_f32_16x16x32_bf16 v[116:119], v[148:151], v[164:167], v[116:119]
	s_add_u32 s42, s36, 0x80
	s_addc_u32 s43, s37, 0
	v_mfma_f32_16x16x32_bf16 v[112:115], v[152:155], v[164:167], v[112:115]
	v_mfma_f32_16x16x32_bf16 v[100:103], v[148:151], v[168:171], v[100:103]
	v_mfma_f32_16x16x32_bf16 v[96:99], v[152:155], v[168:171], v[96:99]
	v_mfma_f32_16x16x32_bf16 v[84:87], v[148:151], v[200:203], v[84:87]
	v_mfma_f32_16x16x32_bf16 v[80:83], v[152:155], v[200:203], v[80:83]
	v_mfma_f32_16x16x32_bf16 v[68:71], v[148:151], v[204:207], v[68:71]
	v_mfma_f32_16x16x32_bf16 v[64:67], v[152:155], v[204:207], v[64:67]
	v_mfma_f32_16x16x32_bf16 v[116:119], v[156:159], v[192:195], v[116:119]
	v_mfma_f32_16x16x32_bf16 v[112:115], v[160:163], v[192:195], v[112:115]
	v_mfma_f32_16x16x32_bf16 v[100:103], v[156:159], v[196:199], v[100:103]
	v_mfma_f32_16x16x32_bf16 v[96:99], v[160:163], v[196:199], v[96:99]
	v_mfma_f32_16x16x32_bf16 v[84:87], v[156:159], v[208:211], v[84:87]
	v_mfma_f32_16x16x32_bf16 v[80:83], v[160:163], v[208:211], v[80:83]
	v_mfma_f32_16x16x32_bf16 v[68:71], v[156:159], v[212:215], v[68:71]
	v_mfma_f32_16x16x32_bf16 v[64:67], v[160:163], v[212:215], v[64:67]
	s_barrier
; #define PG8_STAGE(bufoff, gbase, voff) do { _Pragma("unroll") for (int _i = 0; _i < 2; ++_i) \
;         dma16((const char*)(gbase), (voff)[_i], ldsb + (bufoff) + ldsw + _i * 8192); } while (0)
; #define PG8_LDA(dst, b, h) do { const int a1_ = opqv(aoff0) ^ 64; _Pragma("unroll") for (int m = 0; m < 4; ++m) { dst[m][0] = *(const LAS bf16x8*)(lds + PG8_SA(b, h) + aoff0 + m * 2048); dst[m][1] = *(const LAS bf16x8*)(lds + PG8_SA(b, h) + a1_ + m * 2048); } } while (0)
; #define PG8_LDB(dst, b, h) do { const int b1_ = opqv(boff0) ^ 64; _Pragma("unroll") for (int n = 0; n < 2; ++n) { dst[n][0] = *(const LAS bf16x8*)(lds + PG8_SB(b, h) + boff0 + n * 2048); dst[n][1] = *(const LAS bf16x8*)(lds + PG8_SB(b, h) + b1_ + n * 2048); } } while (0)
; #define PG8_MMA(ai, bj, At, Bt) do { __builtin_amdgcn_s_setprio(1); _Pragma("unroll") for (int m = 0; m < 4; ++m) _Pragma("unroll") for (int n = 0; n < 2; ++n) _Pragma("unroll") for (int k = 0; k < 2; ++k) \
;         acc[ai][bj][m][n] = __builtin_amdgcn_mfma_f32_16x16x32_bf16(Bt[n][k], At[m][k], acc[ai][bj][m][n], 0, 0, 0); __builtin_amdgcn_s_setprio(0); } while (0)
; #define PG8_WAIT_V(n) asm volatile("s_waitcnt vmcnt(" #n ")" ::: "memory")
; template <class Epi>
; __device__ __forceinline__ void gemm_phase(LAS unsigned char* lds, const Gemm g, const StaticOrder& S, const Epi& E, int wave_) {
;     ...
;             PG8_STAGE(PG8_SA(1, 1), a1 + hstepA, voffA); PG8_LDB(B0, 0, 0); PG8_LDB(B1, 0, 1); PG8_SCHED; PG8_LDA(At, 0, 0);
;             PG8_WAIT_V(8); PG8_WAIT_L(0); PG8_BAR; PG8_MMA(0, 0, At, B0); PG8_MMA(0, 1, At, B1); PG8_BAR; PG8_SCHED;
;             PG8_STAGE(PG8_SB(0, 0), b2, voffB); PG8_STAGE(PG8_SB(0, 1), b2 + hstepB, voffB); PG8_STAGE(PG8_SA(0, 0), a2, voffA); PG8_LDA(At, 0, 1);
;             PG8_WAIT_V(8); PG8_WAIT_L(0); PG8_BAR; PG8_MMA(1, 0, At, B0); PG8_MMA(1, 1, At, B1); PG8_BAR; PG8_SCHED;
;             PG8_STAGE(PG8_SA(0, 1), a2 + hstepA, voffA); PG8_LDB(B0, 1, 0); PG8_LDB(B1, 1, 1); PG8_SCHED; PG8_LDA(At, 1, 0);
;             PG8_WAIT_V(8); PG8_WAIT_L(0); PG8_BAR; PG8_MMA(0, 0, At, B0); PG8_MMA(0, 1, At, B1); PG8_BAR; PG8_SCHED;
;             PG8_STAGE(PG8_SB(1, 0), b3, voffB); PG8_STAGE(PG8_SB(1, 1), b3 + hstepB, voffB); PG8_STAGE(PG8_SA(1, 0), a3, voffA); PG8_LDA(At, 1, 1);
;             PG8_WAIT_V(8); PG8_WAIT_L(0); PG8_BAR; PG8_MMA(1, 0, At, B0); PG8_MMA(1, 1, At, B1); PG8_BAR; PG8_SCHED;
	s_setprio 0
	s_add_u32 s36, s36, 0x20080
	s_addc_u32 s37, s37, 0
	v_mov_b32_e32 v164, v179
	s_nop 0
	s_nop 0
	v_xad_u32 v172, v164, 64, 0
	ds_read_b128 v[164:167], v182 offset:49152
	ds_read_b128 v[168:171], v182 offset:51200
	ds_read_b128 v[192:195], v172 offset:49152
	ds_read_b128 v[196:199], v172 offset:51200
	ds_read_b128 v[200:203], v182 offset:53248
	ds_read_b128 v[204:207], v182 offset:55296
	ds_read_b128 v[208:211], v172 offset:53248
	ds_read_b128 v[212:215], v172 offset:55296
	s_mov_b32 m0, s35
	s_nop 0
	global_load_lds_dwordx4 v175, s[42:43]
	s_mov_b32 m0, s33
	s_nop 0
	global_load_lds_dwordx4 v177, s[42:43]
	s_mov_b32 m0, s77
	s_nop 0
	global_load_lds_dwordx4 v175, s[36:37]
	s_mov_b32 m0, s3
	s_nop 0
	global_load_lds_dwordx4 v177, s[36:37]
	s_mov_b32 m0, s22
	s_nop 0
	global_load_lds_dwordx4 v137, s[30:31]
	s_mov_b32 m0, s2
	s_nop 0
	global_load_lds_dwordx4 v176, s[30:31]
	s_waitcnt vmcnt(8)
	s_waitcnt lgkmcnt(0)
	s_setprio 1
	s_barrier
	v_mfma_f32_16x16x32_bf16 v[60:63], v[128:131], v[164:167], v[60:63]
	v_mfma_f32_16x16x32_bf16 v[56:59], v[132:135], v[164:167], v[56:59]
	v_mfma_f32_16x16x32_bf16 v[44:47], v[128:131], v[168:171], v[44:47]
	v_mfma_f32_16x16x32_bf16 v[40:43], v[132:135], v[168:171], v[40:43]
	v_mfma_f32_16x16x32_bf16 v[28:31], v[128:131], v[200:203], v[28:31]
	v_mfma_f32_16x16x32_bf16 v[24:27], v[132:135], v[200:203], v[24:27]
	v_mfma_f32_16x16x32_bf16 v[12:15], v[128:131], v[204:207], v[12:15]
	v_mfma_f32_16x16x32_bf16 v[8:11], v[132:135], v[204:207], v[8:11]
	v_mfma_f32_16x16x32_bf16 v[60:63], v[140:143], v[192:195], v[60:63]
	v_mfma_f32_16x16x32_bf16 v[56:59], v[144:147], v[192:195], v[56:59]
	v_mfma_f32_16x16x32_bf16 v[44:47], v[140:143], v[196:199], v[44:47]
	v_mfma_f32_16x16x32_bf16 v[40:43], v[144:147], v[196:199], v[40:43]
	v_mfma_f32_16x16x32_bf16 v[28:31], v[140:143], v[208:211], v[28:31]
	v_mfma_f32_16x16x32_bf16 v[24:27], v[144:147], v[208:211], v[24:27]
	v_mfma_f32_16x16x32_bf16 v[12:15], v[140:143], v[212:215], v[12:15]
	v_mfma_f32_16x16x32_bf16 v[8:11], v[144:147], v[212:215], v[8:11]
	v_mfma_f32_16x16x32_bf16 v[52:55], v[148:151], v[164:167], v[52:55]
	v_mfma_f32_16x16x32_bf16 v[48:51], v[152:155], v[164:167], v[48:51]
	v_mfma_f32_16x16x32_bf16 v[36:39], v[148:151], v[168:171], v[36:39]
	v_mfma_f32_16x16x32_bf16 v[32:35], v[152:155], v[168:171], v[32:35]
	v_mfma_f32_16x16x32_bf16 v[20:23], v[148:151], v[200:203], v[20:23]
	v_mfma_f32_16x16x32_bf16 v[16:19], v[152:155], v[200:203], v[16:19]
	v_mfma_f32_16x16x32_bf16 v[4:7], v[148:151], v[204:207], v[4:7]
	v_mfma_f32_16x16x32_bf16 v[0:3], v[152:155], v[204:207], v[0:3]
	v_mfma_f32_16x16x32_bf16 v[52:55], v[156:159], v[192:195], v[52:55]
	v_mfma_f32_16x16x32_bf16 v[48:51], v[160:163], v[192:195], v[48:51]
	v_mfma_f32_16x16x32_bf16 v[36:39], v[156:159], v[196:199], v[36:39]
	v_mfma_f32_16x16x32_bf16 v[32:35], v[160:163], v[196:199], v[32:35]
	v_mfma_f32_16x16x32_bf16 v[20:23], v[156:159], v[208:211], v[20:23]
	v_mfma_f32_16x16x32_bf16 v[16:19], v[160:163], v[208:211], v[16:19]
	v_mfma_f32_16x16x32_bf16 v[4:7], v[156:159], v[212:215], v[4:7]
	v_mfma_f32_16x16x32_bf16 v[0:3], v[160:163], v[212:215], v[0:3]
	s_barrier
	s_setprio 0
	s_add_i32 s57, s57, 2
	s_add_u32 s52, s52, 0x100
	s_addc_u32 s56, s56, 0
	s_add_u32 s12, s12, 0x100
	s_addc_u32 s13, s13, 0
	s_cmp_gt_u32 s57, 5
	s_cbranch_scc0 .LBB0_744
	s_branch .Lpeel_exit_6
.LBB0_744:
	s_add_u32 s30, s12, 0xfffc0080
	s_addc_u32 s31, s13, -1
	s_cmp_eq_u32 s57, 4
	s_cselect_b32 s42, s17, s30
	s_cselect_b32 s43, s16, s31
	s_cselect_b32 s36, s19, s52
	s_cselect_b32 s37, s11, s56
	s_add_u32 s30, s42, 0x80
	v_mov_b32_e32 v128, v180
	s_addc_u32 s31, s43, 0
	v_add_u32_e32 v132, s23, v180
	v_xad_u32 v144, v128, 64, s23
	v_mov_b32_e32 v148, v180
	s_add_i32 s58, 0, 0x14000
	ds_read_b128 v[128:131], v132
	ds_read_b128 v[132:135], v132 offset:2048
	ds_read_b128 v[140:143], v144
	ds_read_b128 v[144:147], v144 offset:2048
	v_add_u32_e32 v152, s58, v180
	v_xad_u32 v160, v148, 64, s58
	ds_read_b128 v[148:151], v152
	ds_read_b128 v[152:155], v152 offset:2048
	ds_read_b128 v[156:159], v160
	ds_read_b128 v[160:163], v160 offset:2048
	v_mov_b32_e32 v164, v179
	v_add_u32_e32 v182, 0, v179
	v_xad_u32 v172, v164, 64, 0
	ds_read_b128 v[164:167], v182
	ds_read_b128 v[168:171], v182 offset:2048
	ds_read_b128 v[192:195], v172
	ds_read_b128 v[196:199], v172 offset:2048
	ds_read_b128 v[200:203], v182 offset:4096
	ds_read_b128 v[204:207], v182 offset:6144
	ds_read_b128 v[208:211], v172 offset:4096
	ds_read_b128 v[212:215], v172 offset:6144
	s_mov_b32 m0, s14
	s_nop 0
	global_load_lds_dwordx4 v137, s[12:13]
	s_mov_b32 m0, s15
	s_nop 0
	global_load_lds_dwordx4 v176, s[12:13]
	s_waitcnt vmcnt(8)
	s_waitcnt lgkmcnt(0)
	s_setprio 1
	s_barrier
; #define PG8_STAGE(bufoff, gbase, voff) do { _Pragma("unroll") for (int _i = 0; _i < 2; ++_i) \
;         dma16((const char*)(gbase), (voff)[_i], ldsb + (bufoff) + ldsw + _i * 8192); } while (0)
; #define PG8_LDA(dst, b, h) do { const int a1_ = opqv(aoff0) ^ 64; _Pragma("unroll") for (int m = 0; m < 4; ++m) { dst[m][0] = *(const LAS bf16x8*)(lds + PG8_SA(b, h) + aoff0 + m * 2048); dst[m][1] = *(const LAS bf16x8*)(lds + PG8_SA(b, h) + a1_ + m * 2048); } } while (0)
; #define PG8_MMA(ai, bj, At, Bt) do { __builtin_amdgcn_s_setprio(1); _Pragma("unroll") for (int m = 0; m < 4; ++m) _Pragma("unroll") for (int n = 0; n < 2; ++n) _Pragma("unroll") for (int k = 0; k < 2; ++k) \
;         acc[ai][bj][m][n] = __builtin_amdgcn_mfma_f32_16x16x32_bf16(Bt[n][k], At[m][k], acc[ai][bj][m][n], 0, 0, 0); __builtin_amdgcn_s_setprio(0); } while (0)
; #define PG8_WAIT_V(n) asm volatile("s_waitcnt vmcnt(" #n ")" ::: "memory")
; #define PG8_WAIT_L(n) asm volatile("s_waitcnt lgkmcnt(" #n ")" ::: "memory")
; #define PG8_BAR __builtin_amdgcn_s_barrier()
; #define PG8_SCHED __builtin_amdgcn_sched_barrier(0)
; template <class Epi>
; __device__ __forceinline__ void gemm_phase(LAS unsigned char* lds, const Gemm g, const StaticOrder& S, const Epi& E, int wave_) {
;     ...
;             PG8_WAIT_V(8); PG8_WAIT_L(0); PG8_BAR; PG8_MMA(0, 0, At, B0); PG8_MMA(0, 1, At, B1); PG8_BAR; PG8_SCHED;
;             PG8_STAGE(PG8_SB(0, 0), b2, voffB); PG8_STAGE(PG8_SB(0, 1), b2 + hstepB, voffB); PG8_STAGE(PG8_SA(0, 0), a2, voffA); PG8_LDA(At, 0, 1);
;             PG8_WAIT_V(8); PG8_WAIT_L(0); PG8_BAR; PG8_MMA(1, 0, At, B0); PG8_MMA(1, 1, At, B1); PG8_BAR; PG8_SCHED;
	v_mfma_f32_16x16x32_bf16 v[124:127], v[128:131], v[164:167], v[124:127]
	v_mfma_f32_16x16x32_bf16 v[120:123], v[132:135], v[164:167], v[120:123]
	v_mfma_f32_16x16x32_bf16 v[108:111], v[128:131], v[168:171], v[108:111]
	v_mfma_f32_16x16x32_bf16 v[104:107], v[132:135], v[168:171], v[104:107]
	v_mfma_f32_16x16x32_bf16 v[92:95], v[128:131], v[200:203], v[92:95]
	v_mfma_f32_16x16x32_bf16 v[88:91], v[132:135], v[200:203], v[88:91]
	v_mfma_f32_16x16x32_bf16 v[76:79], v[128:131], v[204:207], v[76:79]
	v_mfma_f32_16x16x32_bf16 v[72:75], v[132:135], v[204:207], v[72:75]
	v_mfma_f32_16x16x32_bf16 v[124:127], v[140:143], v[192:195], v[124:127]
	v_mfma_f32_16x16x32_bf16 v[120:123], v[144:147], v[192:195], v[120:123]
	v_mfma_f32_16x16x32_bf16 v[108:111], v[140:143], v[196:199], v[108:111]
	v_mfma_f32_16x16x32_bf16 v[104:107], v[144:147], v[196:199], v[104:107]
	v_mfma_f32_16x16x32_bf16 v[92:95], v[140:143], v[208:211], v[92:95]
	v_mfma_f32_16x16x32_bf16 v[88:91], v[144:147], v[208:211], v[88:91]
	v_mfma_f32_16x16x32_bf16 v[76:79], v[140:143], v[212:215], v[76:79]
	v_mfma_f32_16x16x32_bf16 v[72:75], v[144:147], v[212:215], v[72:75]
	v_mfma_f32_16x16x32_bf16 v[116:119], v[148:151], v[164:167], v[116:119]
	v_mfma_f32_16x16x32_bf16 v[112:115], v[152:155], v[164:167], v[112:115]
	v_mfma_f32_16x16x32_bf16 v[100:103], v[148:151], v[168:171], v[100:103]
	v_mfma_f32_16x16x32_bf16 v[96:99], v[152:155], v[168:171], v[96:99]
	v_mfma_f32_16x16x32_bf16 v[84:87], v[148:151], v[200:203], v[84:87]
	v_mfma_f32_16x16x32_bf16 v[80:83], v[152:155], v[200:203], v[80:83]
	v_mfma_f32_16x16x32_bf16 v[68:71], v[148:151], v[204:207], v[68:71]
	v_mfma_f32_16x16x32_bf16 v[64:67], v[152:155], v[204:207], v[64:67]
	v_mfma_f32_16x16x32_bf16 v[116:119], v[156:159], v[192:195], v[116:119]
	v_mfma_f32_16x16x32_bf16 v[112:115], v[160:163], v[192:195], v[112:115]
	v_mfma_f32_16x16x32_bf16 v[100:103], v[156:159], v[196:199], v[100:103]
	v_mfma_f32_16x16x32_bf16 v[96:99], v[160:163], v[196:199], v[96:99]
	v_mfma_f32_16x16x32_bf16 v[84:87], v[156:159], v[208:211], v[84:87]
	v_mfma_f32_16x16x32_bf16 v[80:83], v[160:163], v[208:211], v[80:83]
	v_mfma_f32_16x16x32_bf16 v[68:71], v[156:159], v[212:215], v[68:71]
	v_mfma_f32_16x16x32_bf16 v[64:67], v[160:163], v[212:215], v[64:67]
	s_barrier
	s_setprio 0
	v_mov_b32_e32 v164, v179
	s_add_u32 s58, s36, 0x20000
	s_addc_u32 s59, s37, 0
	s_nop 0
	s_nop 0
	s_nop 0
	v_xad_u32 v172, v164, 64, 0
	ds_read_b128 v[164:167], v182 offset:16384
	ds_read_b128 v[168:171], v182 offset:18432
	ds_read_b128 v[192:195], v172 offset:16384
	ds_read_b128 v[196:199], v172 offset:18432
	ds_read_b128 v[200:203], v182 offset:20480
	ds_read_b128 v[204:207], v182 offset:22528
	ds_read_b128 v[208:211], v172 offset:20480
	ds_read_b128 v[212:215], v172 offset:22528
	s_mov_b32 m0, s80
	s_nop 0
	global_load_lds_dwordx4 v175, s[36:37]
	s_mov_b32 m0, s81
	s_nop 0
	global_load_lds_dwordx4 v177, s[36:37]
	s_mov_b32 m0, s29
	s_nop 0
	global_load_lds_dwordx4 v175, s[58:59]
	s_mov_b32 m0, s88
	s_nop 0
	global_load_lds_dwordx4 v177, s[58:59]
	s_mov_b32 m0, s76
	s_nop 0
	global_load_lds_dwordx4 v137, s[42:43]
	s_mov_b32 m0, s89
	s_nop 0
	global_load_lds_dwordx4 v176, s[42:43]
	s_waitcnt vmcnt(8)
	s_waitcnt lgkmcnt(0)
	s_setprio 1
	s_barrier
	v_mfma_f32_16x16x32_bf16 v[60:63], v[128:131], v[164:167], v[60:63]
	v_mfma_f32_16x16x32_bf16 v[56:59], v[132:135], v[164:167], v[56:59]
	v_mfma_f32_16x16x32_bf16 v[44:47], v[128:131], v[168:171], v[44:47]
	v_mfma_f32_16x16x32_bf16 v[40:43], v[132:135], v[168:171], v[40:43]
	v_mfma_f32_16x16x32_bf16 v[28:31], v[128:131], v[200:203], v[28:31]
	v_mfma_f32_16x16x32_bf16 v[24:27], v[132:135], v[200:203], v[24:27]
	v_mfma_f32_16x16x32_bf16 v[12:15], v[128:131], v[204:207], v[12:15]
	v_mfma_f32_16x16x32_bf16 v[8:11], v[132:135], v[204:207], v[8:11]
	v_mfma_f32_16x16x32_bf16 v[60:63], v[140:143], v[192:195], v[60:63]
	v_mfma_f32_16x16x32_bf16 v[56:59], v[144:147], v[192:195], v[56:59]
	v_mfma_f32_16x16x32_bf16 v[44:47], v[140:143], v[196:199], v[44:47]
	v_mfma_f32_16x16x32_bf16 v[40:43], v[144:147], v[196:199], v[40:43]
	v_mfma_f32_16x16x32_bf16 v[28:31], v[140:143], v[208:211], v[28:31]
	v_mfma_f32_16x16x32_bf16 v[24:27], v[144:147], v[208:211], v[24:27]
	v_mfma_f32_16x16x32_bf16 v[12:15], v[140:143], v[212:215], v[12:15]
	v_mfma_f32_16x16x32_bf16 v[8:11], v[144:147], v[212:215], v[8:11]
	v_mfma_f32_16x16x32_bf16 v[52:55], v[148:151], v[164:167], v[52:55]
	v_mfma_f32_16x16x32_bf16 v[48:51], v[152:155], v[164:167], v[48:51]
	v_mfma_f32_16x16x32_bf16 v[36:39], v[148:151], v[168:171], v[36:39]
	v_mfma_f32_16x16x32_bf16 v[32:35], v[152:155], v[168:171], v[32:35]
	v_mfma_f32_16x16x32_bf16 v[20:23], v[148:151], v[200:203], v[20:23]
	v_mfma_f32_16x16x32_bf16 v[16:19], v[152:155], v[200:203], v[16:19]
	v_mfma_f32_16x16x32_bf16 v[4:7], v[148:151], v[204:207], v[4:7]
	v_mfma_f32_16x16x32_bf16 v[0:3], v[152:155], v[204:207], v[0:3]
	v_mfma_f32_16x16x32_bf16 v[52:55], v[156:159], v[192:195], v[52:55]
	v_mfma_f32_16x16x32_bf16 v[48:51], v[160:163], v[192:195], v[48:51]
	v_mfma_f32_16x16x32_bf16 v[36:39], v[156:159], v[196:199], v[36:39]
	v_mfma_f32_16x16x32_bf16 v[32:35], v[160:163], v[196:199], v[32:35]
	v_mfma_f32_16x16x32_bf16 v[20:23], v[156:159], v[208:211], v[20:23]
	v_mfma_f32_16x16x32_bf16 v[16:19], v[160:163], v[208:211], v[16:19]
	v_mfma_f32_16x16x32_bf16 v[4:7], v[156:159], v[212:215], v[4:7]
	v_mfma_f32_16x16x32_bf16 v[0:3], v[160:163], v[212:215], v[0:3]
	s_barrier
; #define PG8_STAGE(bufoff, gbase, voff) do { _Pragma("unroll") for (int _i = 0; _i < 2; ++_i) \
;         dma16((const char*)(gbase), (voff)[_i], ldsb + (bufoff) + ldsw + _i * 8192); } while (0)
; #define PG8_LDA(dst, b, h) do { const int a1_ = opqv(aoff0) ^ 64; _Pragma("unroll") for (int m = 0; m < 4; ++m) { dst[m][0] = *(const LAS bf16x8*)(lds + PG8_SA(b, h) + aoff0 + m * 2048); dst[m][1] = *(const LAS bf16x8*)(lds + PG8_SA(b, h) + a1_ + m * 2048); } } while (0)
; #define PG8_LDB(dst, b, h) do { const int b1_ = opqv(boff0) ^ 64; _Pragma("unroll") for (int n = 0; n < 2; ++n) { dst[n][0] = *(const LAS bf16x8*)(lds + PG8_SB(b, h) + boff0 + n * 2048); dst[n][1] = *(const LAS bf16x8*)(lds + PG8_SB(b, h) + b1_ + n * 2048); } } while (0)
; #define PG8_MMA(ai, bj, At, Bt) do { __builtin_amdgcn_s_setprio(1); _Pragma("unroll") for (int m = 0; m < 4; ++m) _Pragma("unroll") for (int n = 0; n < 2; ++n) _Pragma("unroll") for (int k = 0; k < 2; ++k) \
;         acc[ai][bj][m][n] = __builtin_amdgcn_mfma_f32_16x16x32_bf16(Bt[n][k], At[m][k], acc[ai][bj][m][n], 0, 0, 0); __builtin_amdgcn_s_setprio(0); } while (0)
; #define PG8_WAIT_V(n) asm volatile("s_waitcnt vmcnt(" #n ")" ::: "memory")
; #define PG8_WAIT_L(n) asm volatile("s_waitcnt lgkmcnt(" #n ")" ::: "memory")
; #define PG8_BAR __builtin_amdgcn_s_barrier()
; #define PG8_SCHED __builtin_amdgcn_sched_barrier(0)
; template <class Epi>
; __device__ __forceinline__ void gemm_phase(LAS unsigned char* lds, const Gemm g, const StaticOrder& S, const Epi& E, int wave_) {
;     ...
;             PG8_STAGE(PG8_SA(0, 1), a2 + hstepA, voffA); PG8_LDB(B0, 1, 0); PG8_LDB(B1, 1, 1); PG8_SCHED; PG8_LDA(At, 1, 0);
;             PG8_WAIT_V(8); PG8_WAIT_L(0); PG8_BAR; PG8_MMA(0, 0, At, B0); PG8_MMA(0, 1, At, B1); PG8_BAR; PG8_SCHED;
;             PG8_STAGE(PG8_SB(1, 0), b3, voffB); PG8_STAGE(PG8_SB(1, 1), b3 + hstepB, voffB); PG8_STAGE(PG8_SA(1, 0), a3, voffA); PG8_LDA(At, 1, 1);
;             PG8_WAIT_V(8); PG8_WAIT_L(0); PG8_BAR; PG8_MMA(1, 0, At, B0); PG8_MMA(1, 1, At, B1); PG8_BAR; PG8_SCHED;
	s_setprio 0
	s_add_u32 s42, s42, 0x40000
	s_addc_u32 s43, s43, 0
	s_mov_b32 m0, s1
	s_nop 0
	global_load_lds_dwordx4 v137, s[42:43]
	v_mov_b32_e32 v128, v180
	s_mov_b32 m0, s69
	s_nop 0
	global_load_lds_dwordx4 v176, s[42:43]
	v_add_u32_e32 v132, s34, v180
	v_xad_u32 v144, v128, 64, s34
	v_mov_b32_e32 v148, v180
	s_add_i32 s42, 0, 0x1c000
	ds_read_b128 v[128:131], v132
	ds_read_b128 v[132:135], v132 offset:2048
	ds_read_b128 v[140:143], v144
	ds_read_b128 v[144:147], v144 offset:2048
	v_add_u32_e32 v152, s42, v180
	v_xad_u32 v160, v148, 64, s42
	ds_read_b128 v[148:151], v152
	ds_read_b128 v[152:155], v152 offset:2048
	ds_read_b128 v[156:159], v160
	ds_read_b128 v[160:163], v160 offset:2048
	v_mov_b32_e32 v164, v179
	s_nop 0
	v_xad_u32 v172, v164, 64, 0
	ds_read_b128 v[164:167], v182 offset:32768
	ds_read_b128 v[168:171], v182 offset:34816
	ds_read_b128 v[192:195], v172 offset:32768
	ds_read_b128 v[196:199], v172 offset:34816
	ds_read_b128 v[200:203], v182 offset:36864
	ds_read_b128 v[204:207], v182 offset:38912
	ds_read_b128 v[208:211], v172 offset:36864
	ds_read_b128 v[212:215], v172 offset:38912
	s_waitcnt vmcnt(8)
	s_waitcnt lgkmcnt(0)
	s_setprio 1
	s_barrier
	v_mfma_f32_16x16x32_bf16 v[124:127], v[128:131], v[164:167], v[124:127]
	v_mfma_f32_16x16x32_bf16 v[120:123], v[132:135], v[164:167], v[120:123]
	v_mfma_f32_16x16x32_bf16 v[108:111], v[128:131], v[168:171], v[108:111]
	v_mfma_f32_16x16x32_bf16 v[104:107], v[132:135], v[168:171], v[104:107]
	v_mfma_f32_16x16x32_bf16 v[92:95], v[128:131], v[200:203], v[92:95]
	v_mfma_f32_16x16x32_bf16 v[88:91], v[132:135], v[200:203], v[88:91]
	v_mfma_f32_16x16x32_bf16 v[76:79], v[128:131], v[204:207], v[76:79]
	v_mfma_f32_16x16x32_bf16 v[72:75], v[132:135], v[204:207], v[72:75]
	v_mfma_f32_16x16x32_bf16 v[124:127], v[140:143], v[192:195], v[124:127]
	v_mfma_f32_16x16x32_bf16 v[120:123], v[144:147], v[192:195], v[120:123]
	v_mfma_f32_16x16x32_bf16 v[108:111], v[140:143], v[196:199], v[108:111]
	v_mfma_f32_16x16x32_bf16 v[104:107], v[144:147], v[196:199], v[104:107]
	v_mfma_f32_16x16x32_bf16 v[92:95], v[140:143], v[208:211], v[92:95]
	v_mfma_f32_16x16x32_bf16 v[88:91], v[144:147], v[208:211], v[88:91]
	v_mfma_f32_16x16x32_bf16 v[76:79], v[140:143], v[212:215], v[76:79]
	v_mfma_f32_16x16x32_bf16 v[72:75], v[144:147], v[212:215], v[72:75]
	v_mfma_f32_16x16x32_bf16 v[116:119], v[148:151], v[164:167], v[116:119]
	s_add_u32 s42, s36, 0x80
	s_addc_u32 s43, s37, 0
	v_mfma_f32_16x16x32_bf16 v[112:115], v[152:155], v[164:167], v[112:115]
	v_mfma_f32_16x16x32_bf16 v[100:103], v[148:151], v[168:171], v[100:103]
	v_mfma_f32_16x16x32_bf16 v[96:99], v[152:155], v[168:171], v[96:99]
	v_mfma_f32_16x16x32_bf16 v[84:87], v[148:151], v[200:203], v[84:87]
	v_mfma_f32_16x16x32_bf16 v[80:83], v[152:155], v[200:203], v[80:83]
	v_mfma_f32_16x16x32_bf16 v[68:71], v[148:151], v[204:207], v[68:71]
	v_mfma_f32_16x16x32_bf16 v[64:67], v[152:155], v[204:207], v[64:67]
	v_mfma_f32_16x16x32_bf16 v[116:119], v[156:159], v[192:195], v[116:119]
	v_mfma_f32_16x16x32_bf16 v[112:115], v[160:163], v[192:195], v[112:115]
	v_mfma_f32_16x16x32_bf16 v[100:103], v[156:159], v[196:199], v[100:103]
	v_mfma_f32_16x16x32_bf16 v[96:99], v[160:163], v[196:199], v[96:99]
	v_mfma_f32_16x16x32_bf16 v[84:87], v[156:159], v[208:211], v[84:87]
	v_mfma_f32_16x16x32_bf16 v[80:83], v[160:163], v[208:211], v[80:83]
	v_mfma_f32_16x16x32_bf16 v[68:71], v[156:159], v[212:215], v[68:71]
	v_mfma_f32_16x16x32_bf16 v[64:67], v[160:163], v[212:215], v[64:67]
	s_barrier
	s_setprio 0
	s_add_u32 s36, s36, 0x20080
	s_addc_u32 s37, s37, 0
	v_mov_b32_e32 v164, v179
	s_nop 0
	s_nop 0
	v_xad_u32 v172, v164, 64, 0
	ds_read_b128 v[164:167], v182 offset:49152
	ds_read_b128 v[168:171], v182 offset:51200
	ds_read_b128 v[192:195], v172 offset:49152
	ds_read_b128 v[196:199], v172 offset:51200
	ds_read_b128 v[200:203], v182 offset:53248
	ds_read_b128 v[204:207], v182 offset:55296
	ds_read_b128 v[208:211], v172 offset:53248
	ds_read_b128 v[212:215], v172 offset:55296
	s_mov_b32 m0, s35
	s_nop 0
	global_load_lds_dwordx4 v175, s[42:43]
	s_mov_b32 m0, s33
	s_nop 0
	global_load_lds_dwordx4 v177, s[42:43]
	s_mov_b32 m0, s77
	s_nop 0
	global_load_lds_dwordx4 v175, s[36:37]
	s_mov_b32 m0, s3
	s_nop 0
	global_load_lds_dwordx4 v177, s[36:37]
	s_mov_b32 m0, s22
	s_nop 0
	global_load_lds_dwordx4 v137, s[30:31]
	s_mov_b32 m0, s2
	s_nop 0
	global_load_lds_dwordx4 v176, s[30:31]
	s_waitcnt vmcnt(8)
	s_waitcnt lgkmcnt(0)
	s_setprio 1
	s_barrier
	v_mfma_f32_16x16x32_bf16 v[60:63], v[128:131], v[164:167], v[60:63]
	v_mfma_f32_16x16x32_bf16 v[56:59], v[132:135], v[164:167], v[56:59]
	v_mfma_f32_16x16x32_bf16 v[44:47], v[128:131], v[168:171], v[44:47]
	v_mfma_f32_16x16x32_bf16 v[40:43], v[132:135], v[168:171], v[40:43]
	v_mfma_f32_16x16x32_bf16 v[28:31], v[128:131], v[200:203], v[28:31]
	v_mfma_f32_16x16x32_bf16 v[24:27], v[132:135], v[200:203], v[24:27]
	v_mfma_f32_16x16x32_bf16 v[12:15], v[128:131], v[204:207], v[12:15]
	v_mfma_f32_16x16x32_bf16 v[8:11], v[132:135], v[204:207], v[8:11]
	v_mfma_f32_16x16x32_bf16 v[60:63], v[140:143], v[192:195], v[60:63]
	v_mfma_f32_16x16x32_bf16 v[56:59], v[144:147], v[192:195], v[56:59]
	v_mfma_f32_16x16x32_bf16 v[44:47], v[140:143], v[196:199], v[44:47]
	v_mfma_f32_16x16x32_bf16 v[40:43], v[144:147], v[196:199], v[40:43]
	v_mfma_f32_16x16x32_bf16 v[28:31], v[140:143], v[208:211], v[28:31]
	v_mfma_f32_16x16x32_bf16 v[24:27], v[144:147], v[208:211], v[24:27]
	v_mfma_f32_16x16x32_bf16 v[12:15], v[140:143], v[212:215], v[12:15]
	v_mfma_f32_16x16x32_bf16 v[8:11], v[144:147], v[212:215], v[8:11]
	v_mfma_f32_16x16x32_bf16 v[52:55], v[148:151], v[164:167], v[52:55]
	v_mfma_f32_16x16x32_bf16 v[48:51], v[152:155], v[164:167], v[48:51]
	v_mfma_f32_16x16x32_bf16 v[36:39], v[148:151], v[168:171], v[36:39]
	v_mfma_f32_16x16x32_bf16 v[32:35], v[152:155], v[168:171], v[32:35]
	v_mfma_f32_16x16x32_bf16 v[20:23], v[148:151], v[200:203], v[20:23]
	v_mfma_f32_16x16x32_bf16 v[16:19], v[152:155], v[200:203], v[16:19]
	v_mfma_f32_16x16x32_bf16 v[4:7], v[148:151], v[204:207], v[4:7]
	v_mfma_f32_16x16x32_bf16 v[0:3], v[152:155], v[204:207], v[0:3]
	v_mfma_f32_16x16x32_bf16 v[52:55], v[156:159], v[192:195], v[52:55]
	v_mfma_f32_16x16x32_bf16 v[48:51], v[160:163], v[192:195], v[48:51]
	v_mfma_f32_16x16x32_bf16 v[36:39], v[156:159], v[196:199], v[36:39]
	v_mfma_f32_16x16x32_bf16 v[32:35], v[160:163], v[196:199], v[32:35]
	v_mfma_f32_16x16x32_bf16 v[20:23], v[156:159], v[208:211], v[20:23]
	v_mfma_f32_16x16x32_bf16 v[16:19], v[160:163], v[208:211], v[16:19]
	v_mfma_f32_16x16x32_bf16 v[4:7], v[156:159], v[212:215], v[4:7]
	v_mfma_f32_16x16x32_bf16 v[0:3], v[160:163], v[212:215], v[0:3]
	s_barrier
	s_setprio 0
	s_add_i32 s57, s57, 2
	s_add_u32 s52, s52, 0x100
	s_addc_u32 s56, s56, 0
	s_add_u32 s12, s12, 0x100
	s_addc_u32 s13, s13, 0
	s_cmp_gt_u32 s57, 5
	s_cbranch_scc0 .LBB0_744

; #define PG8_STAGE(bufoff, gbase, voff) do { _Pragma("unroll") for (int _i = 0; _i < 2; ++_i) \
;         dma16((const char*)(gbase), (voff)[_i], ldsb + (bufoff) + ldsw + _i * 8192); } while (0)
; #define PG8_LDA(dst, b, h) do { const int a1_ = opqv(aoff0) ^ 64; _Pragma("unroll") for (int m = 0; m < 4; ++m) { dst[m][0] = *(const LAS bf16x8*)(lds + PG8_SA(b, h) + aoff0 + m * 2048); dst[m][1] = *(const LAS bf16x8*)(lds + PG8_SA(b, h) + a1_ + m * 2048); } } while (0)
; #define PG8_LDB(dst, b, h) do { const int b1_ = opqv(boff0) ^ 64; _Pragma("unroll") for (int n = 0; n < 2; ++n) { dst[n][0] = *(const LAS bf16x8*)(lds + PG8_SB(b, h) + boff0 + n * 2048); dst[n][1] = *(const LAS bf16x8*)(lds + PG8_SB(b, h) + b1_ + n * 2048); } } while (0)
; #define PG8_MMA(ai, bj, At, Bt) do { __builtin_amdgcn_s_setprio(1); _Pragma("unroll") for (int m = 0; m < 4; ++m) _Pragma("unroll") for (int n = 0; n < 2; ++n) _Pragma("unroll") for (int k = 0; k < 2; ++k) \
;         acc[ai][bj][m][n] = __builtin_amdgcn_mfma_f32_16x16x32_bf16(Bt[n][k], At[m][k], acc[ai][bj][m][n], 0, 0, 0); __builtin_amdgcn_s_setprio(0); } while (0)
; template <class Epi>
; __device__ __forceinline__ void gemm_phase(LAS unsigned char* lds, const Gemm g, const StaticOrder& S, const Epi& E, int wave_) {
;     ...
;         const bool has_next = S.next(ui + 1, nxt);
;         const char* nA = has_next ? (const char*)g.A + (size_t)nxt.pm * tstepA : cA; const char* nB = has_next ? (const char*)g.Bt + (size_t)nxt.pn * tstepB : cB;
; #pragma unroll 1
;         for (int t = 0; t < nt; t += 2) {
;             const bool last = (t == nt - 2);
;             const char* a1 = cA + (size_t)(t + 1) * kstep;
;             const char* a2 = last ? nA : cA + (size_t)(t + 2) * kstep; const char* b2 = last ? nB : cB + (size_t)(t + 2) * kstep;
;             const char* a3 = a2 + kstep; const char* b3 = b2 + kstep;
;             PG8_STAGE(PG8_SA(1, 1), a1 + hstepA, voffA); PG8_LDB(B0, 0, 0); PG8_LDB(B1, 0, 1); PG8_SCHED; PG8_LDA(At, 0, 0);
;             PG8_WAIT_V(8); PG8_WAIT_L(0); PG8_BAR; PG8_MMA(0, 0, At, B0); PG8_MMA(0, 1, At, B1); PG8_BAR; PG8_SCHED;
;             PG8_STAGE(PG8_SB(0, 0), b2, voffB); PG8_STAGE(PG8_SB(0, 1), b2 + hstepB, voffB); PG8_STAGE(PG8_SA(0, 0), a2, voffA); PG8_LDA(At, 0, 1);
;             PG8_WAIT_V(8); PG8_WAIT_L(0); PG8_BAR; PG8_MMA(1, 0, At, B0); PG8_MMA(1, 1, At, B1); PG8_BAR; PG8_SCHED;
.LBB0_795:
	s_ashr_i32 s19, s18, 31
	s_lshl_b64 s[16:17], s[18:19], 19
	s_add_u32 s24, s21, s16
	s_addc_u32 s25, s44, s17
	s_and_b64 s[16:17], s[40:41], exec
	s_cselect_b32 s16, s25, s31
	s_cselect_b32 s17, s24, s30
	s_ashr_i32 s11, s10, 31
	s_lshl_b64 s[26:27], s[10:11], 18
	s_add_u32 s26, s45, s26
	s_addc_u32 s27, s46, s27
	s_and_b64 s[36:37], s[40:41], exec
	s_cselect_b32 s11, s27, s13
	s_cselect_b32 s19, s26, s12
	s_add_u32 s52, s12, 0x100
	s_addc_u32 s54, s13, 0
	s_add_u32 s12, s30, 0x40080
	s_addc_u32 s13, s31, 0
	s_mov_b32 s55, -2
	s_add_u32 s30, s12, 0xfffc0080
	s_addc_u32 s31, s13, -1
	s_cmp_eq_u32 s55, 4
	s_cselect_b32 s42, s17, s30
	s_cselect_b32 s43, s16, s31
	s_cselect_b32 s36, s19, s52
	s_cselect_b32 s37, s11, s54
	s_add_u32 s30, s42, 0x80
	v_mov_b32_e32 v130, v161
	s_addc_u32 s31, s43, 0
	v_add_u32_e32 v134, s23, v161
	v_xad_u32 v142, v130, 64, s23
	v_mov_b32_e32 v146, v161
	s_add_i32 s56, 0, 0x14000
	ds_read_b128 v[130:133], v134
	ds_read_b128 v[134:137], v134 offset:2048
	ds_read_b128 v[138:141], v142
	ds_read_b128 v[142:145], v142 offset:2048
	v_add_u32_e32 v150, s56, v161
	v_xad_u32 v154, v146, 64, s56
	ds_read_b128 v[146:149], v150
	ds_read_b128 v[150:153], v150 offset:2048
	ds_read_b128 v[162:165], v154
	ds_read_b128 v[166:169], v154 offset:2048
	v_mov_b32_e32 v154, v160
	v_add_u32_e32 v155, 0, v160
	v_xad_u32 v154, v154, 64, 0
	ds_read_b128 v[176:179], v155
	ds_read_b128 v[180:183], v155 offset:2048
	ds_read_b128 v[192:195], v154
	ds_read_b128 v[196:199], v154 offset:2048
	ds_read_b128 v[200:203], v155 offset:4096
	ds_read_b128 v[204:207], v155 offset:6144
	ds_read_b128 v[208:211], v154 offset:4096
	ds_read_b128 v[212:215], v154 offset:6144
	s_mov_b32 m0, s14
	s_nop 0
	global_load_lds_dwordx4 v129, s[12:13]
	s_mov_b32 m0, s15
	s_nop 0
	global_load_lds_dwordx4 v157, s[12:13]
	s_waitcnt vmcnt(8)
	s_waitcnt lgkmcnt(0)
	s_setprio 1
	s_barrier
	v_mfma_f32_16x16x32_bf16 v[124:127], v[130:133], v[176:179], 0
	v_mfma_f32_16x16x32_bf16 v[120:123], v[134:137], v[176:179], 0
	v_mfma_f32_16x16x32_bf16 v[108:111], v[130:133], v[180:183], 0
	v_mfma_f32_16x16x32_bf16 v[104:107], v[134:137], v[180:183], 0
	v_mfma_f32_16x16x32_bf16 v[92:95], v[130:133], v[200:203], 0
	v_mfma_f32_16x16x32_bf16 v[88:91], v[134:137], v[200:203], 0
	v_mfma_f32_16x16x32_bf16 v[76:79], v[130:133], v[204:207], 0
	v_mfma_f32_16x16x32_bf16 v[72:75], v[134:137], v[204:207], 0
	v_mfma_f32_16x16x32_bf16 v[124:127], v[138:141], v[192:195], v[124:127]
	v_mfma_f32_16x16x32_bf16 v[120:123], v[142:145], v[192:195], v[120:123]
	v_mfma_f32_16x16x32_bf16 v[108:111], v[138:141], v[196:199], v[108:111]
	v_mfma_f32_16x16x32_bf16 v[104:107], v[142:145], v[196:199], v[104:107]
	v_mfma_f32_16x16x32_bf16 v[92:95], v[138:141], v[208:211], v[92:95]
	v_mfma_f32_16x16x32_bf16 v[88:91], v[142:145], v[208:211], v[88:91]
	v_mfma_f32_16x16x32_bf16 v[76:79], v[138:141], v[212:215], v[76:79]
	v_mfma_f32_16x16x32_bf16 v[72:75], v[142:145], v[212:215], v[72:75]
	v_mfma_f32_16x16x32_bf16 v[116:119], v[146:149], v[176:179], 0
	v_mfma_f32_16x16x32_bf16 v[112:115], v[150:153], v[176:179], 0
	v_mfma_f32_16x16x32_bf16 v[100:103], v[146:149], v[180:183], 0
	v_mfma_f32_16x16x32_bf16 v[96:99], v[150:153], v[180:183], 0
	v_mfma_f32_16x16x32_bf16 v[84:87], v[146:149], v[200:203], 0
	v_mfma_f32_16x16x32_bf16 v[80:83], v[150:153], v[200:203], 0
	v_mfma_f32_16x16x32_bf16 v[68:71], v[146:149], v[204:207], 0
	v_mfma_f32_16x16x32_bf16 v[64:67], v[150:153], v[204:207], 0
	v_mfma_f32_16x16x32_bf16 v[116:119], v[162:165], v[192:195], v[116:119]
	v_mfma_f32_16x16x32_bf16 v[112:115], v[166:169], v[192:195], v[112:115]
	v_mfma_f32_16x16x32_bf16 v[100:103], v[162:165], v[196:199], v[100:103]
	v_mfma_f32_16x16x32_bf16 v[96:99], v[166:169], v[196:199], v[96:99]
	v_mfma_f32_16x16x32_bf16 v[84:87], v[162:165], v[208:211], v[84:87]
	v_mfma_f32_16x16x32_bf16 v[80:83], v[166:169], v[208:211], v[80:83]
	v_mfma_f32_16x16x32_bf16 v[68:71], v[162:165], v[212:215], v[68:71]
	v_mfma_f32_16x16x32_bf16 v[64:67], v[166:169], v[212:215], v[64:67]
	s_barrier
	s_setprio 0
	v_mov_b32_e32 v154, v160
	s_add_u32 s56, s36, 0x20000
	s_addc_u32 s57, s37, 0
	s_nop 0
	s_nop 0
	s_nop 0
	v_xad_u32 v154, v154, 64, 0
	ds_read_b128 v[176:179], v155 offset:16384
	ds_read_b128 v[180:183], v155 offset:18432
	ds_read_b128 v[192:195], v154 offset:16384
	ds_read_b128 v[196:199], v154 offset:18432
	ds_read_b128 v[200:203], v155 offset:20480
	ds_read_b128 v[204:207], v155 offset:22528
	ds_read_b128 v[208:211], v154 offset:20480
	ds_read_b128 v[212:215], v154 offset:22528
	s_mov_b32 m0, s80
	s_nop 0
	global_load_lds_dwordx4 v156, s[36:37]
	s_mov_b32 m0, s81
	s_nop 0
	global_load_lds_dwordx4 v158, s[36:37]
	s_mov_b32 m0, s29
	s_nop 0
	global_load_lds_dwordx4 v156, s[56:57]
	s_mov_b32 m0, s88
	s_nop 0
	global_load_lds_dwordx4 v158, s[56:57]
	s_mov_b32 m0, s76
	s_nop 0
	global_load_lds_dwordx4 v129, s[42:43]
	s_mov_b32 m0, s89
	s_nop 0
	global_load_lds_dwordx4 v157, s[42:43]
	s_waitcnt vmcnt(8)
	s_waitcnt lgkmcnt(0)
	s_setprio 1
	s_barrier
; #define PG8_STAGE(bufoff, gbase, voff) do { _Pragma("unroll") for (int _i = 0; _i < 2; ++_i) \
;         dma16((const char*)(gbase), (voff)[_i], ldsb + (bufoff) + ldsw + _i * 8192); } while (0)
; #define PG8_LDA(dst, b, h) do { const int a1_ = opqv(aoff0) ^ 64; _Pragma("unroll") for (int m = 0; m < 4; ++m) { dst[m][0] = *(const LAS bf16x8*)(lds + PG8_SA(b, h) + aoff0 + m * 2048); dst[m][1] = *(const LAS bf16x8*)(lds + PG8_SA(b, h) + a1_ + m * 2048); } } while (0)
; #define PG8_LDB(dst, b, h) do { const int b1_ = opqv(boff0) ^ 64; _Pragma("unroll") for (int n = 0; n < 2; ++n) { dst[n][0] = *(const LAS bf16x8*)(lds + PG8_SB(b, h) + boff0 + n * 2048); dst[n][1] = *(const LAS bf16x8*)(lds + PG8_SB(b, h) + b1_ + n * 2048); } } while (0)
; #define PG8_MMA(ai, bj, At, Bt) do { __builtin_amdgcn_s_setprio(1); _Pragma("unroll") for (int m = 0; m < 4; ++m) _Pragma("unroll") for (int n = 0; n < 2; ++n) _Pragma("unroll") for (int k = 0; k < 2; ++k) \
;         acc[ai][bj][m][n] = __builtin_amdgcn_mfma_f32_16x16x32_bf16(Bt[n][k], At[m][k], acc[ai][bj][m][n], 0, 0, 0); __builtin_amdgcn_s_setprio(0); } while (0)
; #define PG8_WAIT_V(n) asm volatile("s_waitcnt vmcnt(" #n ")" ::: "memory")
; #define PG8_WAIT_L(n) asm volatile("s_waitcnt lgkmcnt(" #n ")" ::: "memory")
; #define PG8_BAR __builtin_amdgcn_s_barrier()
; #define PG8_SCHED __builtin_amdgcn_sched_barrier(0)
; template <class Epi>
; __device__ __forceinline__ void gemm_phase(LAS unsigned char* lds, const Gemm g, const StaticOrder& S, const Epi& E, int wave_) {
;     ...
;             PG8_WAIT_V(8); PG8_WAIT_L(0); PG8_BAR; PG8_MMA(1, 0, At, B0); PG8_MMA(1, 1, At, B1); PG8_BAR; PG8_SCHED;
;             PG8_STAGE(PG8_SA(0, 1), a2 + hstepA, voffA); PG8_LDB(B0, 1, 0); PG8_LDB(B1, 1, 1); PG8_SCHED; PG8_LDA(At, 1, 0);
;             PG8_WAIT_V(8); PG8_WAIT_L(0); PG8_BAR; PG8_MMA(0, 0, At, B0); PG8_MMA(0, 1, At, B1); PG8_BAR; PG8_SCHED;
	v_mfma_f32_16x16x32_bf16 v[60:63], v[130:133], v[176:179], 0
	v_mfma_f32_16x16x32_bf16 v[56:59], v[134:137], v[176:179], 0
	v_mfma_f32_16x16x32_bf16 v[44:47], v[130:133], v[180:183], 0
	v_mfma_f32_16x16x32_bf16 v[40:43], v[134:137], v[180:183], 0
	v_mfma_f32_16x16x32_bf16 v[28:31], v[130:133], v[200:203], 0
	v_mfma_f32_16x16x32_bf16 v[24:27], v[134:137], v[200:203], 0
	v_mfma_f32_16x16x32_bf16 v[12:15], v[130:133], v[204:207], 0
	v_mfma_f32_16x16x32_bf16 v[8:11], v[134:137], v[204:207], 0
	v_mfma_f32_16x16x32_bf16 v[60:63], v[138:141], v[192:195], v[60:63]
	v_mfma_f32_16x16x32_bf16 v[56:59], v[142:145], v[192:195], v[56:59]
	v_mfma_f32_16x16x32_bf16 v[44:47], v[138:141], v[196:199], v[44:47]
	v_mfma_f32_16x16x32_bf16 v[40:43], v[142:145], v[196:199], v[40:43]
	v_mfma_f32_16x16x32_bf16 v[28:31], v[138:141], v[208:211], v[28:31]
	v_mfma_f32_16x16x32_bf16 v[24:27], v[142:145], v[208:211], v[24:27]
	v_mfma_f32_16x16x32_bf16 v[12:15], v[138:141], v[212:215], v[12:15]
	v_mfma_f32_16x16x32_bf16 v[8:11], v[142:145], v[212:215], v[8:11]
	v_mfma_f32_16x16x32_bf16 v[52:55], v[146:149], v[176:179], 0
	v_mfma_f32_16x16x32_bf16 v[48:51], v[150:153], v[176:179], 0
	v_mfma_f32_16x16x32_bf16 v[36:39], v[146:149], v[180:183], 0
	v_mfma_f32_16x16x32_bf16 v[32:35], v[150:153], v[180:183], 0
	v_mfma_f32_16x16x32_bf16 v[20:23], v[146:149], v[200:203], 0
	v_mfma_f32_16x16x32_bf16 v[16:19], v[150:153], v[200:203], 0
	v_mfma_f32_16x16x32_bf16 v[4:7], v[146:149], v[204:207], 0
	v_mfma_f32_16x16x32_bf16 v[0:3], v[150:153], v[204:207], 0
	v_mfma_f32_16x16x32_bf16 v[52:55], v[162:165], v[192:195], v[52:55]
	v_mfma_f32_16x16x32_bf16 v[48:51], v[166:169], v[192:195], v[48:51]
	v_mfma_f32_16x16x32_bf16 v[36:39], v[162:165], v[196:199], v[36:39]
	v_mfma_f32_16x16x32_bf16 v[32:35], v[166:169], v[196:199], v[32:35]
	v_mfma_f32_16x16x32_bf16 v[20:23], v[162:165], v[208:211], v[20:23]
	v_mfma_f32_16x16x32_bf16 v[16:19], v[166:169], v[208:211], v[16:19]
	v_mfma_f32_16x16x32_bf16 v[4:7], v[162:165], v[212:215], v[4:7]
	v_mfma_f32_16x16x32_bf16 v[0:3], v[166:169], v[212:215], v[0:3]
	s_barrier
	s_setprio 0
	s_add_u32 s42, s42, 0x40000
	s_addc_u32 s43, s43, 0
	s_mov_b32 m0, s1
	s_nop 0
	global_load_lds_dwordx4 v129, s[42:43]
	v_mov_b32_e32 v130, v161
	s_mov_b32 m0, s69
	s_nop 0
	global_load_lds_dwordx4 v157, s[42:43]
	v_add_u32_e32 v134, s34, v161
	v_xad_u32 v142, v130, 64, s34
	v_mov_b32_e32 v146, v161
	s_add_i32 s42, 0, 0x1c000
	ds_read_b128 v[130:133], v134
	ds_read_b128 v[134:137], v134 offset:2048
	ds_read_b128 v[138:141], v142
	ds_read_b128 v[142:145], v142 offset:2048
	v_add_u32_e32 v150, s42, v161
	v_xad_u32 v154, v146, 64, s42
	ds_read_b128 v[146:149], v150
	ds_read_b128 v[150:153], v150 offset:2048
	ds_read_b128 v[162:165], v154
	ds_read_b128 v[166:169], v154 offset:2048
	v_mov_b32_e32 v154, v160
	s_nop 0
	v_xad_u32 v154, v154, 64, 0
	ds_read_b128 v[176:179], v155 offset:32768
	ds_read_b128 v[180:183], v155 offset:34816
	ds_read_b128 v[192:195], v154 offset:32768
	ds_read_b128 v[196:199], v154 offset:34816
	ds_read_b128 v[200:203], v155 offset:36864
	ds_read_b128 v[204:207], v155 offset:38912
	ds_read_b128 v[208:211], v154 offset:36864
	ds_read_b128 v[212:215], v154 offset:38912
	s_waitcnt vmcnt(8)
	s_waitcnt lgkmcnt(0)
	s_setprio 1
	s_barrier
	v_mfma_f32_16x16x32_bf16 v[124:127], v[130:133], v[176:179], v[124:127]
	v_mfma_f32_16x16x32_bf16 v[120:123], v[134:137], v[176:179], v[120:123]
	v_mfma_f32_16x16x32_bf16 v[108:111], v[130:133], v[180:183], v[108:111]
	v_mfma_f32_16x16x32_bf16 v[104:107], v[134:137], v[180:183], v[104:107]
	v_mfma_f32_16x16x32_bf16 v[92:95], v[130:133], v[200:203], v[92:95]
	v_mfma_f32_16x16x32_bf16 v[88:91], v[134:137], v[200:203], v[88:91]
	v_mfma_f32_16x16x32_bf16 v[76:79], v[130:133], v[204:207], v[76:79]
	v_mfma_f32_16x16x32_bf16 v[72:75], v[134:137], v[204:207], v[72:75]
	v_mfma_f32_16x16x32_bf16 v[124:127], v[138:141], v[192:195], v[124:127]
	v_mfma_f32_16x16x32_bf16 v[120:123], v[142:145], v[192:195], v[120:123]
	v_mfma_f32_16x16x32_bf16 v[108:111], v[138:141], v[196:199], v[108:111]
	v_mfma_f32_16x16x32_bf16 v[104:107], v[142:145], v[196:199], v[104:107]
	v_mfma_f32_16x16x32_bf16 v[92:95], v[138:141], v[208:211], v[92:95]
	v_mfma_f32_16x16x32_bf16 v[88:91], v[142:145], v[208:211], v[88:91]
	v_mfma_f32_16x16x32_bf16 v[76:79], v[138:141], v[212:215], v[76:79]
	v_mfma_f32_16x16x32_bf16 v[72:75], v[142:145], v[212:215], v[72:75]
	v_mfma_f32_16x16x32_bf16 v[116:119], v[146:149], v[176:179], v[116:119]
	s_add_u32 s42, s36, 0x80
	s_addc_u32 s43, s37, 0
	v_mfma_f32_16x16x32_bf16 v[112:115], v[150:153], v[176:179], v[112:115]
	v_mfma_f32_16x16x32_bf16 v[100:103], v[146:149], v[180:183], v[100:103]
	v_mfma_f32_16x16x32_bf16 v[96:99], v[150:153], v[180:183], v[96:99]
	v_mfma_f32_16x16x32_bf16 v[84:87], v[146:149], v[200:203], v[84:87]
	v_mfma_f32_16x16x32_bf16 v[80:83], v[150:153], v[200:203], v[80:83]
	v_mfma_f32_16x16x32_bf16 v[68:71], v[146:149], v[204:207], v[68:71]
	v_mfma_f32_16x16x32_bf16 v[64:67], v[150:153], v[204:207], v[64:67]
	v_mfma_f32_16x16x32_bf16 v[116:119], v[162:165], v[192:195], v[116:119]
	v_mfma_f32_16x16x32_bf16 v[112:115], v[166:169], v[192:195], v[112:115]
	v_mfma_f32_16x16x32_bf16 v[100:103], v[162:165], v[196:199], v[100:103]
	v_mfma_f32_16x16x32_bf16 v[96:99], v[166:169], v[196:199], v[96:99]
	v_mfma_f32_16x16x32_bf16 v[84:87], v[162:165], v[208:211], v[84:87]
	v_mfma_f32_16x16x32_bf16 v[80:83], v[166:169], v[208:211], v[80:83]
	v_mfma_f32_16x16x32_bf16 v[68:71], v[162:165], v[212:215], v[68:71]
	v_mfma_f32_16x16x32_bf16 v[64:67], v[166:169], v[212:215], v[64:67]
	s_barrier
; #define PG8_STAGE(bufoff, gbase, voff) do { _Pragma("unroll") for (int _i = 0; _i < 2; ++_i) \
;         dma16((const char*)(gbase), (voff)[_i], ldsb + (bufoff) + ldsw + _i * 8192); } while (0)
; #define PG8_LDA(dst, b, h) do { const int a1_ = opqv(aoff0) ^ 64; _Pragma("unroll") for (int m = 0; m < 4; ++m) { dst[m][0] = *(const LAS bf16x8*)(lds + PG8_SA(b, h) + aoff0 + m * 2048); dst[m][1] = *(const LAS bf16x8*)(lds + PG8_SA(b, h) + a1_ + m * 2048); } } while (0)
; #define PG8_LDB(dst, b, h) do { const int b1_ = opqv(boff0) ^ 64; _Pragma("unroll") for (int n = 0; n < 2; ++n) { dst[n][0] = *(const LAS bf16x8*)(lds + PG8_SB(b, h) + boff0 + n * 2048); dst[n][1] = *(const LAS bf16x8*)(lds + PG8_SB(b, h) + b1_ + n * 2048); } } while (0)
; #define PG8_MMA(ai, bj, At, Bt) do { __builtin_amdgcn_s_setprio(1); _Pragma("unroll") for (int m = 0; m < 4; ++m) _Pragma("unroll") for (int n = 0; n < 2; ++n) _Pragma("unroll") for (int k = 0; k < 2; ++k) \
;         acc[ai][bj][m][n] = __builtin_amdgcn_mfma_f32_16x16x32_bf16(Bt[n][k], At[m][k], acc[ai][bj][m][n], 0, 0, 0); __builtin_amdgcn_s_setprio(0); } while (0)
; #define PG8_WAIT_V(n) asm volatile("s_waitcnt vmcnt(" #n ")" ::: "memory")
; template <class Epi>
; __device__ __forceinline__ void gemm_phase(LAS unsigned char* lds, const Gemm g, const StaticOrder& S, const Epi& E, int wave_) {
;     ...
;             PG8_STAGE(PG8_SA(1, 1), a1 + hstepA, voffA); PG8_LDB(B0, 0, 0); PG8_LDB(B1, 0, 1); PG8_SCHED; PG8_LDA(At, 0, 0);
;             PG8_WAIT_V(8); PG8_WAIT_L(0); PG8_BAR; PG8_MMA(0, 0, At, B0); PG8_MMA(0, 1, At, B1); PG8_BAR; PG8_SCHED;
;             PG8_STAGE(PG8_SB(0, 0), b2, voffB); PG8_STAGE(PG8_SB(0, 1), b2 + hstepB, voffB); PG8_STAGE(PG8_SA(0, 0), a2, voffA); PG8_LDA(At, 0, 1);
;             PG8_WAIT_V(8); PG8_WAIT_L(0); PG8_BAR; PG8_MMA(1, 0, At, B0); PG8_MMA(1, 1, At, B1); PG8_BAR; PG8_SCHED;
;             PG8_STAGE(PG8_SA(0, 1), a2 + hstepA, voffA); PG8_LDB(B0, 1, 0); PG8_LDB(B1, 1, 1); PG8_SCHED; PG8_LDA(At, 1, 0);
;             PG8_WAIT_V(8); PG8_WAIT_L(0); PG8_BAR; PG8_MMA(0, 0, At, B0); PG8_MMA(0, 1, At, B1); PG8_BAR; PG8_SCHED;
;             PG8_STAGE(PG8_SB(1, 0), b3, voffB); PG8_STAGE(PG8_SB(1, 1), b3 + hstepB, voffB); PG8_STAGE(PG8_SA(1, 0), a3, voffA); PG8_LDA(At, 1, 1);
;             PG8_WAIT_V(8); PG8_WAIT_L(0); PG8_BAR; PG8_MMA(1, 0, At, B0); PG8_MMA(1, 1, At, B1); PG8_BAR; PG8_SCHED;
	s_setprio 0
	s_add_u32 s36, s36, 0x20080
	s_addc_u32 s37, s37, 0
	v_mov_b32_e32 v154, v160
	s_nop 0
	s_nop 0
	v_xad_u32 v154, v154, 64, 0
	ds_read_b128 v[176:179], v155 offset:49152
	ds_read_b128 v[180:183], v155 offset:51200
	ds_read_b128 v[192:195], v154 offset:49152
	ds_read_b128 v[196:199], v154 offset:51200
	ds_read_b128 v[200:203], v155 offset:53248
	ds_read_b128 v[204:207], v155 offset:55296
	ds_read_b128 v[208:211], v154 offset:53248
	ds_read_b128 v[212:215], v154 offset:55296
	s_mov_b32 m0, s35
	s_nop 0
	global_load_lds_dwordx4 v156, s[42:43]
	s_mov_b32 m0, s33
	s_nop 0
	global_load_lds_dwordx4 v158, s[42:43]
	s_mov_b32 m0, s77
	s_nop 0
	global_load_lds_dwordx4 v156, s[36:37]
	s_mov_b32 m0, s3
	s_nop 0
	global_load_lds_dwordx4 v158, s[36:37]
	s_mov_b32 m0, s22
	s_nop 0
	global_load_lds_dwordx4 v129, s[30:31]
	s_mov_b32 m0, s2
	s_nop 0
	global_load_lds_dwordx4 v157, s[30:31]
	s_waitcnt vmcnt(8)
	s_waitcnt lgkmcnt(0)
	s_setprio 1
	s_barrier
	v_mfma_f32_16x16x32_bf16 v[60:63], v[130:133], v[176:179], v[60:63]
	v_mfma_f32_16x16x32_bf16 v[56:59], v[134:137], v[176:179], v[56:59]
	v_mfma_f32_16x16x32_bf16 v[44:47], v[130:133], v[180:183], v[44:47]
	v_mfma_f32_16x16x32_bf16 v[40:43], v[134:137], v[180:183], v[40:43]
	v_mfma_f32_16x16x32_bf16 v[28:31], v[130:133], v[200:203], v[28:31]
	v_mfma_f32_16x16x32_bf16 v[24:27], v[134:137], v[200:203], v[24:27]
	v_mfma_f32_16x16x32_bf16 v[12:15], v[130:133], v[204:207], v[12:15]
	v_mfma_f32_16x16x32_bf16 v[8:11], v[134:137], v[204:207], v[8:11]
	v_mfma_f32_16x16x32_bf16 v[60:63], v[138:141], v[192:195], v[60:63]
	v_mfma_f32_16x16x32_bf16 v[56:59], v[142:145], v[192:195], v[56:59]
	v_mfma_f32_16x16x32_bf16 v[44:47], v[138:141], v[196:199], v[44:47]
	v_mfma_f32_16x16x32_bf16 v[40:43], v[142:145], v[196:199], v[40:43]
	v_mfma_f32_16x16x32_bf16 v[28:31], v[138:141], v[208:211], v[28:31]
	v_mfma_f32_16x16x32_bf16 v[24:27], v[142:145], v[208:211], v[24:27]
	v_mfma_f32_16x16x32_bf16 v[12:15], v[138:141], v[212:215], v[12:15]
	v_mfma_f32_16x16x32_bf16 v[8:11], v[142:145], v[212:215], v[8:11]
	v_mfma_f32_16x16x32_bf16 v[52:55], v[146:149], v[176:179], v[52:55]
	v_mfma_f32_16x16x32_bf16 v[48:51], v[150:153], v[176:179], v[48:51]
	v_mfma_f32_16x16x32_bf16 v[36:39], v[146:149], v[180:183], v[36:39]
	v_mfma_f32_16x16x32_bf16 v[32:35], v[150:153], v[180:183], v[32:35]
	v_mfma_f32_16x16x32_bf16 v[20:23], v[146:149], v[200:203], v[20:23]
	v_mfma_f32_16x16x32_bf16 v[16:19], v[150:153], v[200:203], v[16:19]
	v_mfma_f32_16x16x32_bf16 v[4:7], v[146:149], v[204:207], v[4:7]
	v_mfma_f32_16x16x32_bf16 v[0:3], v[150:153], v[204:207], v[0:3]
	v_mfma_f32_16x16x32_bf16 v[52:55], v[162:165], v[192:195], v[52:55]
	v_mfma_f32_16x16x32_bf16 v[48:51], v[166:169], v[192:195], v[48:51]
	v_mfma_f32_16x16x32_bf16 v[36:39], v[162:165], v[196:199], v[36:39]
	v_mfma_f32_16x16x32_bf16 v[32:35], v[166:169], v[196:199], v[32:35]
	v_mfma_f32_16x16x32_bf16 v[20:23], v[162:165], v[208:211], v[20:23]
	v_mfma_f32_16x16x32_bf16 v[16:19], v[166:169], v[208:211], v[16:19]
	v_mfma_f32_16x16x32_bf16 v[4:7], v[162:165], v[212:215], v[4:7]
	v_mfma_f32_16x16x32_bf16 v[0:3], v[166:169], v[212:215], v[0:3]
	s_barrier
	s_setprio 0
	s_add_i32 s55, s55, 2
	s_add_u32 s52, s52, 0x100
	s_addc_u32 s54, s54, 0
	s_add_u32 s12, s12, 0x100
	s_addc_u32 s13, s13, 0
	s_cmp_gt_u32 s55, 5
	s_cbranch_scc0 .LBB0_796
	s_branch .Lpeel_exit_5
.LBB0_796:
	s_add_u32 s30, s12, 0xfffc0080
	s_addc_u32 s31, s13, -1
	s_cmp_eq_u32 s55, 4
	s_cselect_b32 s42, s17, s30
	s_cselect_b32 s43, s16, s31
	s_cselect_b32 s36, s19, s52
	s_cselect_b32 s37, s11, s54
	s_add_u32 s30, s42, 0x80
	v_mov_b32_e32 v130, v161
	s_addc_u32 s31, s43, 0
	v_add_u32_e32 v134, s23, v161
	v_xad_u32 v142, v130, 64, s23
	v_mov_b32_e32 v146, v161
	s_add_i32 s56, 0, 0x14000
	ds_read_b128 v[130:133], v134
	ds_read_b128 v[134:137], v134 offset:2048
	ds_read_b128 v[138:141], v142
	ds_read_b128 v[142:145], v142 offset:2048
	v_add_u32_e32 v150, s56, v161
	v_xad_u32 v154, v146, 64, s56
	ds_read_b128 v[146:149], v150
	ds_read_b128 v[150:153], v150 offset:2048
	ds_read_b128 v[162:165], v154
	ds_read_b128 v[166:169], v154 offset:2048
	v_mov_b32_e32 v154, v160
	v_add_u32_e32 v155, 0, v160
	v_xad_u32 v154, v154, 64, 0
	ds_read_b128 v[176:179], v155
	ds_read_b128 v[180:183], v155 offset:2048
	ds_read_b128 v[192:195], v154
	ds_read_b128 v[196:199], v154 offset:2048
	ds_read_b128 v[200:203], v155 offset:4096
	ds_read_b128 v[204:207], v155 offset:6144
	ds_read_b128 v[208:211], v154 offset:4096
	ds_read_b128 v[212:215], v154 offset:6144
	s_mov_b32 m0, s14
	s_nop 0
	global_load_lds_dwordx4 v129, s[12:13]
	s_mov_b32 m0, s15
	s_nop 0
	global_load_lds_dwordx4 v157, s[12:13]
	s_waitcnt vmcnt(8)
	s_waitcnt lgkmcnt(0)
	s_setprio 1
	s_barrier
; #define PG8_STAGE(bufoff, gbase, voff) do { _Pragma("unroll") for (int _i = 0; _i < 2; ++_i) \
;         dma16((const char*)(gbase), (voff)[_i], ldsb + (bufoff) + ldsw + _i * 8192); } while (0)
; #define PG8_LDA(dst, b, h) do { const int a1_ = opqv(aoff0) ^ 64; _Pragma("unroll") for (int m = 0; m < 4; ++m) { dst[m][0] = *(const LAS bf16x8*)(lds + PG8_SA(b, h) + aoff0 + m * 2048); dst[m][1] = *(const LAS bf16x8*)(lds + PG8_SA(b, h) + a1_ + m * 2048); } } while (0)
; #define PG8_MMA(ai, bj, At, Bt) do { __builtin_amdgcn_s_setprio(1); _Pragma("unroll") for (int m = 0; m < 4; ++m) _Pragma("unroll") for (int n = 0; n < 2; ++n) _Pragma("unroll") for (int k = 0; k < 2; ++k) \
;         acc[ai][bj][m][n] = __builtin_amdgcn_mfma_f32_16x16x32_bf16(Bt[n][k], At[m][k], acc[ai][bj][m][n], 0, 0, 0); __builtin_amdgcn_s_setprio(0); } while (0)
; #define PG8_WAIT_V(n) asm volatile("s_waitcnt vmcnt(" #n ")" ::: "memory")
; #define PG8_WAIT_L(n) asm volatile("s_waitcnt lgkmcnt(" #n ")" ::: "memory")
; #define PG8_BAR __builtin_amdgcn_s_barrier()
; #define PG8_SCHED __builtin_amdgcn_sched_barrier(0)
; template <class Epi>
; __device__ __forceinline__ void gemm_phase(LAS unsigned char* lds, const Gemm g, const StaticOrder& S, const Epi& E, int wave_) {
;     ...
;             PG8_WAIT_V(8); PG8_WAIT_L(0); PG8_BAR; PG8_MMA(0, 0, At, B0); PG8_MMA(0, 1, At, B1); PG8_BAR; PG8_SCHED;
;             PG8_STAGE(PG8_SB(0, 0), b2, voffB); PG8_STAGE(PG8_SB(0, 1), b2 + hstepB, voffB); PG8_STAGE(PG8_SA(0, 0), a2, voffA); PG8_LDA(At, 0, 1);
;             PG8_WAIT_V(8); PG8_WAIT_L(0); PG8_BAR; PG8_MMA(1, 0, At, B0); PG8_MMA(1, 1, At, B1); PG8_BAR; PG8_SCHED;
	v_mfma_f32_16x16x32_bf16 v[124:127], v[130:133], v[176:179], v[124:127]
	v_mfma_f32_16x16x32_bf16 v[120:123], v[134:137], v[176:179], v[120:123]
	v_mfma_f32_16x16x32_bf16 v[108:111], v[130:133], v[180:183], v[108:111]
	v_mfma_f32_16x16x32_bf16 v[104:107], v[134:137], v[180:183], v[104:107]
	v_mfma_f32_16x16x32_bf16 v[92:95], v[130:133], v[200:203], v[92:95]
	v_mfma_f32_16x16x32_bf16 v[88:91], v[134:137], v[200:203], v[88:91]
	v_mfma_f32_16x16x32_bf16 v[76:79], v[130:133], v[204:207], v[76:79]
	v_mfma_f32_16x16x32_bf16 v[72:75], v[134:137], v[204:207], v[72:75]
	v_mfma_f32_16x16x32_bf16 v[124:127], v[138:141], v[192:195], v[124:127]
	v_mfma_f32_16x16x32_bf16 v[120:123], v[142:145], v[192:195], v[120:123]
	v_mfma_f32_16x16x32_bf16 v[108:111], v[138:141], v[196:199], v[108:111]
	v_mfma_f32_16x16x32_bf16 v[104:107], v[142:145], v[196:199], v[104:107]
	v_mfma_f32_16x16x32_bf16 v[92:95], v[138:141], v[208:211], v[92:95]
	v_mfma_f32_16x16x32_bf16 v[88:91], v[142:145], v[208:211], v[88:91]
	v_mfma_f32_16x16x32_bf16 v[76:79], v[138:141], v[212:215], v[76:79]
	v_mfma_f32_16x16x32_bf16 v[72:75], v[142:145], v[212:215], v[72:75]
	v_mfma_f32_16x16x32_bf16 v[116:119], v[146:149], v[176:179], v[116:119]
	v_mfma_f32_16x16x32_bf16 v[112:115], v[150:153], v[176:179], v[112:115]
	v_mfma_f32_16x16x32_bf16 v[100:103], v[146:149], v[180:183], v[100:103]
	v_mfma_f32_16x16x32_bf16 v[96:99], v[150:153], v[180:183], v[96:99]
	v_mfma_f32_16x16x32_bf16 v[84:87], v[146:149], v[200:203], v[84:87]
	v_mfma_f32_16x16x32_bf16 v[80:83], v[150:153], v[200:203], v[80:83]
	v_mfma_f32_16x16x32_bf16 v[68:71], v[146:149], v[204:207], v[68:71]
	v_mfma_f32_16x16x32_bf16 v[64:67], v[150:153], v[204:207], v[64:67]
	v_mfma_f32_16x16x32_bf16 v[116:119], v[162:165], v[192:195], v[116:119]
	v_mfma_f32_16x16x32_bf16 v[112:115], v[166:169], v[192:195], v[112:115]
	v_mfma_f32_16x16x32_bf16 v[100:103], v[162:165], v[196:199], v[100:103]
	v_mfma_f32_16x16x32_bf16 v[96:99], v[166:169], v[196:199], v[96:99]
	v_mfma_f32_16x16x32_bf16 v[84:87], v[162:165], v[208:211], v[84:87]
	v_mfma_f32_16x16x32_bf16 v[80:83], v[166:169], v[208:211], v[80:83]
	v_mfma_f32_16x16x32_bf16 v[68:71], v[162:165], v[212:215], v[68:71]
	v_mfma_f32_16x16x32_bf16 v[64:67], v[166:169], v[212:215], v[64:67]
	s_barrier
	s_setprio 0
	v_mov_b32_e32 v154, v160
	s_add_u32 s56, s36, 0x20000
	s_addc_u32 s57, s37, 0
	s_nop 0
	s_nop 0
	s_nop 0
	v_xad_u32 v154, v154, 64, 0
	ds_read_b128 v[176:179], v155 offset:16384
	ds_read_b128 v[180:183], v155 offset:18432
	ds_read_b128 v[192:195], v154 offset:16384
	ds_read_b128 v[196:199], v154 offset:18432
	ds_read_b128 v[200:203], v155 offset:20480
	ds_read_b128 v[204:207], v155 offset:22528
	ds_read_b128 v[208:211], v154 offset:20480
	ds_read_b128 v[212:215], v154 offset:22528
	s_mov_b32 m0, s80
	s_nop 0
	global_load_lds_dwordx4 v156, s[36:37]
	s_mov_b32 m0, s81
	s_nop 0
	global_load_lds_dwordx4 v158, s[36:37]
	s_mov_b32 m0, s29
	s_nop 0
	global_load_lds_dwordx4 v156, s[56:57]
	s_mov_b32 m0, s88
	s_nop 0
	global_load_lds_dwordx4 v158, s[56:57]
	s_mov_b32 m0, s76
	s_nop 0
	global_load_lds_dwordx4 v129, s[42:43]
	s_mov_b32 m0, s89
	s_nop 0
	global_load_lds_dwordx4 v157, s[42:43]
	s_waitcnt vmcnt(8)
	s_waitcnt lgkmcnt(0)
	s_setprio 1
	s_barrier
	v_mfma_f32_16x16x32_bf16 v[60:63], v[130:133], v[176:179], v[60:63]
	v_mfma_f32_16x16x32_bf16 v[56:59], v[134:137], v[176:179], v[56:59]
	v_mfma_f32_16x16x32_bf16 v[44:47], v[130:133], v[180:183], v[44:47]
	v_mfma_f32_16x16x32_bf16 v[40:43], v[134:137], v[180:183], v[40:43]
	v_mfma_f32_16x16x32_bf16 v[28:31], v[130:133], v[200:203], v[28:31]
	v_mfma_f32_16x16x32_bf16 v[24:27], v[134:137], v[200:203], v[24:27]
	v_mfma_f32_16x16x32_bf16 v[12:15], v[130:133], v[204:207], v[12:15]
	v_mfma_f32_16x16x32_bf16 v[8:11], v[134:137], v[204:207], v[8:11]
	v_mfma_f32_16x16x32_bf16 v[60:63], v[138:141], v[192:195], v[60:63]
	v_mfma_f32_16x16x32_bf16 v[56:59], v[142:145], v[192:195], v[56:59]
	v_mfma_f32_16x16x32_bf16 v[44:47], v[138:141], v[196:199], v[44:47]
	v_mfma_f32_16x16x32_bf16 v[40:43], v[142:145], v[196:199], v[40:43]
	v_mfma_f32_16x16x32_bf16 v[28:31], v[138:141], v[208:211], v[28:31]
	v_mfma_f32_16x16x32_bf16 v[24:27], v[142:145], v[208:211], v[24:27]
	v_mfma_f32_16x16x32_bf16 v[12:15], v[138:141], v[212:215], v[12:15]
	v_mfma_f32_16x16x32_bf16 v[8:11], v[142:145], v[212:215], v[8:11]
	v_mfma_f32_16x16x32_bf16 v[52:55], v[146:149], v[176:179], v[52:55]
	v_mfma_f32_16x16x32_bf16 v[48:51], v[150:153], v[176:179], v[48:51]
	v_mfma_f32_16x16x32_bf16 v[36:39], v[146:149], v[180:183], v[36:39]
	v_mfma_f32_16x16x32_bf16 v[32:35], v[150:153], v[180:183], v[32:35]
	v_mfma_f32_16x16x32_bf16 v[20:23], v[146:149], v[200:203], v[20:23]
	v_mfma_f32_16x16x32_bf16 v[16:19], v[150:153], v[200:203], v[16:19]
	v_mfma_f32_16x16x32_bf16 v[4:7], v[146:149], v[204:207], v[4:7]
	v_mfma_f32_16x16x32_bf16 v[0:3], v[150:153], v[204:207], v[0:3]
	v_mfma_f32_16x16x32_bf16 v[52:55], v[162:165], v[192:195], v[52:55]
	v_mfma_f32_16x16x32_bf16 v[48:51], v[166:169], v[192:195], v[48:51]
	v_mfma_f32_16x16x32_bf16 v[36:39], v[162:165], v[196:199], v[36:39]
	v_mfma_f32_16x16x32_bf16 v[32:35], v[166:169], v[196:199], v[32:35]
	v_mfma_f32_16x16x32_bf16 v[20:23], v[162:165], v[208:211], v[20:23]
	v_mfma_f32_16x16x32_bf16 v[16:19], v[166:169], v[208:211], v[16:19]
	v_mfma_f32_16x16x32_bf16 v[4:7], v[162:165], v[212:215], v[4:7]
	v_mfma_f32_16x16x32_bf16 v[0:3], v[166:169], v[212:215], v[0:3]
	s_barrier
; #define PG8_STAGE(bufoff, gbase, voff) do { _Pragma("unroll") for (int _i = 0; _i < 2; ++_i) \
;         dma16((const char*)(gbase), (voff)[_i], ldsb + (bufoff) + ldsw + _i * 8192); } while (0)
; #define PG8_LDA(dst, b, h) do { const int a1_ = opqv(aoff0) ^ 64; _Pragma("unroll") for (int m = 0; m < 4; ++m) { dst[m][0] = *(const LAS bf16x8*)(lds + PG8_SA(b, h) + aoff0 + m * 2048); dst[m][1] = *(const LAS bf16x8*)(lds + PG8_SA(b, h) + a1_ + m * 2048); } } while (0)
; #define PG8_LDB(dst, b, h) do { const int b1_ = opqv(boff0) ^ 64; _Pragma("unroll") for (int n = 0; n < 2; ++n) { dst[n][0] = *(const LAS bf16x8*)(lds + PG8_SB(b, h) + boff0 + n * 2048); dst[n][1] = *(const LAS bf16x8*)(lds + PG8_SB(b, h) + b1_ + n * 2048); } } while (0)
; #define PG8_MMA(ai, bj, At, Bt) do { __builtin_amdgcn_s_setprio(1); _Pragma("unroll") for (int m = 0; m < 4; ++m) _Pragma("unroll") for (int n = 0; n < 2; ++n) _Pragma("unroll") for (int k = 0; k < 2; ++k) \
;         acc[ai][bj][m][n] = __builtin_amdgcn_mfma_f32_16x16x32_bf16(Bt[n][k], At[m][k], acc[ai][bj][m][n], 0, 0, 0); __builtin_amdgcn_s_setprio(0); } while (0)
; #define PG8_WAIT_V(n) asm volatile("s_waitcnt vmcnt(" #n ")" ::: "memory")
; #define PG8_WAIT_L(n) asm volatile("s_waitcnt lgkmcnt(" #n ")" ::: "memory")
; #define PG8_BAR __builtin_amdgcn_s_barrier()
; #define PG8_SCHED __builtin_amdgcn_sched_barrier(0)
; template <class Epi>
; __device__ __forceinline__ void gemm_phase(LAS unsigned char* lds, const Gemm g, const StaticOrder& S, const Epi& E, int wave_) {
;     ...
;             PG8_STAGE(PG8_SA(0, 1), a2 + hstepA, voffA); PG8_LDB(B0, 1, 0); PG8_LDB(B1, 1, 1); PG8_SCHED; PG8_LDA(At, 1, 0);
;             PG8_WAIT_V(8); PG8_WAIT_L(0); PG8_BAR; PG8_MMA(0, 0, At, B0); PG8_MMA(0, 1, At, B1); PG8_BAR; PG8_SCHED;
;             PG8_STAGE(PG8_SB(1, 0), b3, voffB); PG8_STAGE(PG8_SB(1, 1), b3 + hstepB, voffB); PG8_STAGE(PG8_SA(1, 0), a3, voffA); PG8_LDA(At, 1, 1);
;             PG8_WAIT_V(8); PG8_WAIT_L(0); PG8_BAR; PG8_MMA(1, 0, At, B0); PG8_MMA(1, 1, At, B1); PG8_BAR; PG8_SCHED;
	s_setprio 0
	s_add_u32 s42, s42, 0x40000
	s_addc_u32 s43, s43, 0
	s_mov_b32 m0, s1
	s_nop 0
	global_load_lds_dwordx4 v129, s[42:43]
	v_mov_b32_e32 v130, v161
	s_mov_b32 m0, s69
	s_nop 0
	global_load_lds_dwordx4 v157, s[42:43]
	v_add_u32_e32 v134, s34, v161
	v_xad_u32 v142, v130, 64, s34
	v_mov_b32_e32 v146, v161
	s_add_i32 s42, 0, 0x1c000
	ds_read_b128 v[130:133], v134
	ds_read_b128 v[134:137], v134 offset:2048
	ds_read_b128 v[138:141], v142
	ds_read_b128 v[142:145], v142 offset:2048
	v_add_u32_e32 v150, s42, v161
	v_xad_u32 v154, v146, 64, s42
	ds_read_b128 v[146:149], v150
	ds_read_b128 v[150:153], v150 offset:2048
	ds_read_b128 v[162:165], v154
	ds_read_b128 v[166:169], v154 offset:2048
	v_mov_b32_e32 v154, v160
	s_nop 0
	v_xad_u32 v154, v154, 64, 0
	ds_read_b128 v[176:179], v155 offset:32768
	ds_read_b128 v[180:183], v155 offset:34816
	ds_read_b128 v[192:195], v154 offset:32768
	ds_read_b128 v[196:199], v154 offset:34816
	ds_read_b128 v[200:203], v155 offset:36864
	ds_read_b128 v[204:207], v155 offset:38912
	ds_read_b128 v[208:211], v154 offset:36864
	ds_read_b128 v[212:215], v154 offset:38912
	s_waitcnt vmcnt(8)
	s_waitcnt lgkmcnt(0)
	s_setprio 1
	s_barrier
	v_mfma_f32_16x16x32_bf16 v[124:127], v[130:133], v[176:179], v[124:127]
	v_mfma_f32_16x16x32_bf16 v[120:123], v[134:137], v[176:179], v[120:123]
	v_mfma_f32_16x16x32_bf16 v[108:111], v[130:133], v[180:183], v[108:111]
	v_mfma_f32_16x16x32_bf16 v[104:107], v[134:137], v[180:183], v[104:107]
	v_mfma_f32_16x16x32_bf16 v[92:95], v[130:133], v[200:203], v[92:95]
	v_mfma_f32_16x16x32_bf16 v[88:91], v[134:137], v[200:203], v[88:91]
	v_mfma_f32_16x16x32_bf16 v[76:79], v[130:133], v[204:207], v[76:79]
	v_mfma_f32_16x16x32_bf16 v[72:75], v[134:137], v[204:207], v[72:75]
	v_mfma_f32_16x16x32_bf16 v[124:127], v[138:141], v[192:195], v[124:127]
	v_mfma_f32_16x16x32_bf16 v[120:123], v[142:145], v[192:195], v[120:123]
	v_mfma_f32_16x16x32_bf16 v[108:111], v[138:141], v[196:199], v[108:111]
	v_mfma_f32_16x16x32_bf16 v[104:107], v[142:145], v[196:199], v[104:107]
	v_mfma_f32_16x16x32_bf16 v[92:95], v[138:141], v[208:211], v[92:95]
	v_mfma_f32_16x16x32_bf16 v[88:91], v[142:145], v[208:211], v[88:91]
	v_mfma_f32_16x16x32_bf16 v[76:79], v[138:141], v[212:215], v[76:79]
	v_mfma_f32_16x16x32_bf16 v[72:75], v[142:145], v[212:215], v[72:75]
	v_mfma_f32_16x16x32_bf16 v[116:119], v[146:149], v[176:179], v[116:119]
	s_add_u32 s42, s36, 0x80
	s_addc_u32 s43, s37, 0
	v_mfma_f32_16x16x32_bf16 v[112:115], v[150:153], v[176:179], v[112:115]
	v_mfma_f32_16x16x32_bf16 v[100:103], v[146:149], v[180:183], v[100:103]
	v_mfma_f32_16x16x32_bf16 v[96:99], v[150:153], v[180:183], v[96:99]
	v_mfma_f32_16x16x32_bf16 v[84:87], v[146:149], v[200:203], v[84:87]
	v_mfma_f32_16x16x32_bf16 v[80:83], v[150:153], v[200:203], v[80:83]
	v_mfma_f32_16x16x32_bf16 v[68:71], v[146:149], v[204:207], v[68:71]
	v_mfma_f32_16x16x32_bf16 v[64:67], v[150:153], v[204:207], v[64:67]
	v_mfma_f32_16x16x32_bf16 v[116:119], v[162:165], v[192:195], v[116:119]
	v_mfma_f32_16x16x32_bf16 v[112:115], v[166:169], v[192:195], v[112:115]
	v_mfma_f32_16x16x32_bf16 v[100:103], v[162:165], v[196:199], v[100:103]
	v_mfma_f32_16x16x32_bf16 v[96:99], v[166:169], v[196:199], v[96:99]
	v_mfma_f32_16x16x32_bf16 v[84:87], v[162:165], v[208:211], v[84:87]
	v_mfma_f32_16x16x32_bf16 v[80:83], v[166:169], v[208:211], v[80:83]
	v_mfma_f32_16x16x32_bf16 v[68:71], v[162:165], v[212:215], v[68:71]
	v_mfma_f32_16x16x32_bf16 v[64:67], v[166:169], v[212:215], v[64:67]
	s_barrier
	s_setprio 0
	s_add_u32 s36, s36, 0x20080
	s_addc_u32 s37, s37, 0
	v_mov_b32_e32 v154, v160
	s_nop 0
	s_nop 0
	v_xad_u32 v154, v154, 64, 0
	ds_read_b128 v[176:179], v155 offset:49152
	ds_read_b128 v[180:183], v155 offset:51200
	ds_read_b128 v[192:195], v154 offset:49152
	ds_read_b128 v[196:199], v154 offset:51200
	ds_read_b128 v[200:203], v155 offset:53248
	ds_read_b128 v[204:207], v155 offset:55296
	ds_read_b128 v[208:211], v154 offset:53248
	ds_read_b128 v[212:215], v154 offset:55296
	s_mov_b32 m0, s35
	s_nop 0
	global_load_lds_dwordx4 v156, s[42:43]
	s_mov_b32 m0, s33
	s_nop 0
	global_load_lds_dwordx4 v158, s[42:43]
	s_mov_b32 m0, s77
	s_nop 0
	global_load_lds_dwordx4 v156, s[36:37]
	s_mov_b32 m0, s3
	s_nop 0
	global_load_lds_dwordx4 v158, s[36:37]
	s_mov_b32 m0, s22
	s_nop 0
	global_load_lds_dwordx4 v129, s[30:31]
	s_mov_b32 m0, s2
	s_nop 0
	global_load_lds_dwordx4 v157, s[30:31]
	s_waitcnt vmcnt(8)
	s_waitcnt lgkmcnt(0)
	s_setprio 1
	s_barrier
	v_mfma_f32_16x16x32_bf16 v[60:63], v[130:133], v[176:179], v[60:63]
	v_mfma_f32_16x16x32_bf16 v[56:59], v[134:137], v[176:179], v[56:59]
	v_mfma_f32_16x16x32_bf16 v[44:47], v[130:133], v[180:183], v[44:47]
	v_mfma_f32_16x16x32_bf16 v[40:43], v[134:137], v[180:183], v[40:43]
	v_mfma_f32_16x16x32_bf16 v[28:31], v[130:133], v[200:203], v[28:31]
	v_mfma_f32_16x16x32_bf16 v[24:27], v[134:137], v[200:203], v[24:27]
	v_mfma_f32_16x16x32_bf16 v[12:15], v[130:133], v[204:207], v[12:15]
	v_mfma_f32_16x16x32_bf16 v[8:11], v[134:137], v[204:207], v[8:11]
	v_mfma_f32_16x16x32_bf16 v[60:63], v[138:141], v[192:195], v[60:63]
	v_mfma_f32_16x16x32_bf16 v[56:59], v[142:145], v[192:195], v[56:59]
	v_mfma_f32_16x16x32_bf16 v[44:47], v[138:141], v[196:199], v[44:47]
	v_mfma_f32_16x16x32_bf16 v[40:43], v[142:145], v[196:199], v[40:43]
	v_mfma_f32_16x16x32_bf16 v[28:31], v[138:141], v[208:211], v[28:31]
	v_mfma_f32_16x16x32_bf16 v[24:27], v[142:145], v[208:211], v[24:27]
	v_mfma_f32_16x16x32_bf16 v[12:15], v[138:141], v[212:215], v[12:15]
	v_mfma_f32_16x16x32_bf16 v[8:11], v[142:145], v[212:215], v[8:11]
	v_mfma_f32_16x16x32_bf16 v[52:55], v[146:149], v[176:179], v[52:55]
	v_mfma_f32_16x16x32_bf16 v[48:51], v[150:153], v[176:179], v[48:51]
	v_mfma_f32_16x16x32_bf16 v[36:39], v[146:149], v[180:183], v[36:39]
	v_mfma_f32_16x16x32_bf16 v[32:35], v[150:153], v[180:183], v[32:35]
	v_mfma_f32_16x16x32_bf16 v[20:23], v[146:149], v[200:203], v[20:23]
	v_mfma_f32_16x16x32_bf16 v[16:19], v[150:153], v[200:203], v[16:19]
	v_mfma_f32_16x16x32_bf16 v[4:7], v[146:149], v[204:207], v[4:7]
	v_mfma_f32_16x16x32_bf16 v[0:3], v[150:153], v[204:207], v[0:3]
	v_mfma_f32_16x16x32_bf16 v[52:55], v[162:165], v[192:195], v[52:55]
	v_mfma_f32_16x16x32_bf16 v[48:51], v[166:169], v[192:195], v[48:51]
	v_mfma_f32_16x16x32_bf16 v[36:39], v[162:165], v[196:199], v[36:39]
	v_mfma_f32_16x16x32_bf16 v[32:35], v[166:169], v[196:199], v[32:35]
	v_mfma_f32_16x16x32_bf16 v[20:23], v[162:165], v[208:211], v[20:23]
	v_mfma_f32_16x16x32_bf16 v[16:19], v[166:169], v[208:211], v[16:19]
	v_mfma_f32_16x16x32_bf16 v[4:7], v[162:165], v[212:215], v[4:7]
	v_mfma_f32_16x16x32_bf16 v[0:3], v[166:169], v[212:215], v[0:3]
	s_barrier
	s_setprio 0
	s_add_i32 s55, s55, 2
	s_add_u32 s52, s52, 0x100
	s_addc_u32 s54, s54, 0
	s_add_u32 s12, s12, 0x100
	s_addc_u32 s13, s13, 0
	s_cmp_gt_u32 s55, 5
	s_cbranch_scc0 .LBB0_796

; #define PG8_STAGE(bufoff, gbase, voff) do { _Pragma("unroll") for (int _i = 0; _i < 2; ++_i) \
;         dma16((const char*)(gbase), (voff)[_i], ldsb + (bufoff) + ldsw + _i * 8192); } while (0)
; #define PG8_LDA(dst, b, h) do { const int a1_ = opqv(aoff0) ^ 64; _Pragma("unroll") for (int m = 0; m < 4; ++m) { dst[m][0] = *(const LAS bf16x8*)(lds + PG8_SA(b, h) + aoff0 + m * 2048); dst[m][1] = *(const LAS bf16x8*)(lds + PG8_SA(b, h) + a1_ + m * 2048); } } while (0)
; #define PG8_LDB(dst, b, h) do { const int b1_ = opqv(boff0) ^ 64; _Pragma("unroll") for (int n = 0; n < 2; ++n) { dst[n][0] = *(const LAS bf16x8*)(lds + PG8_SB(b, h) + boff0 + n * 2048); dst[n][1] = *(const LAS bf16x8*)(lds + PG8_SB(b, h) + b1_ + n * 2048); } } while (0)
; #define PG8_MMA(ai, bj, At, Bt) do { __builtin_amdgcn_s_setprio(1); _Pragma("unroll") for (int m = 0; m < 4; ++m) _Pragma("unroll") for (int n = 0; n < 2; ++n) _Pragma("unroll") for (int k = 0; k < 2; ++k) \
;         acc[ai][bj][m][n] = __builtin_amdgcn_mfma_f32_16x16x32_bf16(Bt[n][k], At[m][k], acc[ai][bj][m][n], 0, 0, 0); __builtin_amdgcn_s_setprio(0); } while (0)
; template <class Epi>
; __device__ __forceinline__ void gemm_phase(LAS unsigned char* lds, const Gemm g, const StaticOrder& S, const Epi& E, int wave_) {
;     ...
;         const bool has_next = S.next(ui + 1, nxt);
;         const char* nA = has_next ? (const char*)g.A + (size_t)nxt.pm * tstepA : cA; const char* nB = has_next ? (const char*)g.Bt + (size_t)nxt.pn * tstepB : cB;
; #pragma unroll 1
;         for (int t = 0; t < nt; t += 2) {
;             const bool last = (t == nt - 2);
;             const char* a1 = cA + (size_t)(t + 1) * kstep;
;             const char* a2 = last ? nA : cA + (size_t)(t + 2) * kstep; const char* b2 = last ? nB : cB + (size_t)(t + 2) * kstep;
;             const char* a3 = a2 + kstep; const char* b3 = b2 + kstep;
;             PG8_STAGE(PG8_SA(1, 1), a1 + hstepA, voffA); PG8_LDB(B0, 0, 0); PG8_LDB(B1, 0, 1); PG8_SCHED; PG8_LDA(At, 0, 0);
;             PG8_WAIT_V(8); PG8_WAIT_L(0); PG8_BAR; PG8_MMA(0, 0, At, B0); PG8_MMA(0, 1, At, B1); PG8_BAR; PG8_SCHED;
;             PG8_STAGE(PG8_SB(0, 0), b2, voffB); PG8_STAGE(PG8_SB(0, 1), b2 + hstepB, voffB); PG8_STAGE(PG8_SA(0, 0), a2, voffA); PG8_LDA(At, 0, 1);
;             PG8_WAIT_V(8); PG8_WAIT_L(0); PG8_BAR; PG8_MMA(1, 0, At, B0); PG8_MMA(1, 1, At, B1); PG8_BAR; PG8_SCHED;
.LBB0_1103:
	s_ashr_i32 s19, s18, 31
	s_lshl_b64 s[16:17], s[18:19], 20
	s_add_u32 s24, s21, s16
	s_addc_u32 s25, s46, s17
	s_and_b64 s[16:17], s[44:45], exec
	s_cselect_b32 s16, s25, s31
	s_cselect_b32 s17, s24, s30
	s_ashr_i32 s11, s10, 31
	s_lshl_b64 s[26:27], s[10:11], 20
	s_add_u32 s26, s47, s26
	s_addc_u32 s27, s48, s27
	s_and_b64 s[36:37], s[44:45], exec
	s_cselect_b32 s11, s27, s13
	s_cselect_b32 s19, s26, s12
	s_add_u32 s55, s12, 0x100
	s_addc_u32 s56, s13, 0
	s_add_u32 s12, s30, 0x80080
	s_addc_u32 s13, s31, 0
	s_mov_b32 s57, -2
	s_add_u32 s30, s12, 0xfff80080
	s_addc_u32 s31, s13, -1
	s_cmp_eq_u32 s57, 28
	s_cselect_b32 s40, s17, s30
	s_cselect_b32 s41, s16, s31
	s_cselect_b32 s36, s19, s55
	s_cselect_b32 s37, s11, s56
	s_add_u32 s30, s40, 0x80
	v_mov_b32_e32 v128, v172
	s_addc_u32 s31, s41, 0
	v_add_u32_e32 v132, s23, v172
	v_xad_u32 v140, v128, 64, s23
	v_mov_b32_e32 v144, v172
	s_add_i32 s60, 0, 0x14000
	ds_read_b128 v[128:131], v132
	ds_read_b128 v[132:135], v132 offset:2048
	ds_read_b128 v[136:139], v140
	ds_read_b128 v[140:143], v140 offset:2048
	v_add_u32_e32 v148, s60, v172
	v_xad_u32 v156, v144, 64, s60
	ds_read_b128 v[144:147], v148
	ds_read_b128 v[148:151], v148 offset:2048
	ds_read_b128 v[152:155], v156
	ds_read_b128 v[156:159], v156 offset:2048
	v_mov_b32_e32 v160, v171
	v_add_u32_e32 v183, 0, v171
	v_xad_u32 v182, v160, 64, 0
	ds_read_b128 v[160:163], v183
	ds_read_b128 v[174:177], v183 offset:2048
	ds_read_b128 v[178:181], v182
	ds_read_b128 v[192:195], v182 offset:2048
	ds_read_b128 v[196:199], v183 offset:4096
	ds_read_b128 v[200:203], v183 offset:6144
	ds_read_b128 v[204:207], v182 offset:4096
	ds_read_b128 v[208:211], v182 offset:6144
	s_mov_b32 m0, s14
	s_nop 0
	global_load_lds_dwordx4 v166, s[12:13]
	s_mov_b32 m0, s15
	s_nop 0
	global_load_lds_dwordx4 v168, s[12:13]
	s_waitcnt vmcnt(8)
	s_waitcnt lgkmcnt(0)
	s_setprio 1
	s_barrier
	v_mfma_f32_16x16x32_bf16 v[124:127], v[128:131], v[160:163], 0
	v_mfma_f32_16x16x32_bf16 v[120:123], v[132:135], v[160:163], 0
	v_mfma_f32_16x16x32_bf16 v[108:111], v[128:131], v[174:177], 0
	v_mfma_f32_16x16x32_bf16 v[104:107], v[132:135], v[174:177], 0
	v_mfma_f32_16x16x32_bf16 v[92:95], v[128:131], v[196:199], 0
	v_mfma_f32_16x16x32_bf16 v[88:91], v[132:135], v[196:199], 0
	v_mfma_f32_16x16x32_bf16 v[76:79], v[128:131], v[200:203], 0
	v_mfma_f32_16x16x32_bf16 v[72:75], v[132:135], v[200:203], 0
	v_mfma_f32_16x16x32_bf16 v[124:127], v[136:139], v[178:181], v[124:127]
	v_mfma_f32_16x16x32_bf16 v[120:123], v[140:143], v[178:181], v[120:123]
	v_mfma_f32_16x16x32_bf16 v[108:111], v[136:139], v[192:195], v[108:111]
	v_mfma_f32_16x16x32_bf16 v[104:107], v[140:143], v[192:195], v[104:107]
	v_mfma_f32_16x16x32_bf16 v[92:95], v[136:139], v[204:207], v[92:95]
	v_mfma_f32_16x16x32_bf16 v[88:91], v[140:143], v[204:207], v[88:91]
	v_mfma_f32_16x16x32_bf16 v[76:79], v[136:139], v[208:211], v[76:79]
	v_mfma_f32_16x16x32_bf16 v[72:75], v[140:143], v[208:211], v[72:75]
	v_mfma_f32_16x16x32_bf16 v[116:119], v[144:147], v[160:163], 0
	v_mfma_f32_16x16x32_bf16 v[112:115], v[148:151], v[160:163], 0
	v_mfma_f32_16x16x32_bf16 v[100:103], v[144:147], v[174:177], 0
	v_mfma_f32_16x16x32_bf16 v[96:99], v[148:151], v[174:177], 0
	v_mfma_f32_16x16x32_bf16 v[84:87], v[144:147], v[196:199], 0
	v_mfma_f32_16x16x32_bf16 v[80:83], v[148:151], v[196:199], 0
	v_mfma_f32_16x16x32_bf16 v[68:71], v[144:147], v[200:203], 0
	v_mfma_f32_16x16x32_bf16 v[64:67], v[148:151], v[200:203], 0
	v_mfma_f32_16x16x32_bf16 v[116:119], v[152:155], v[178:181], v[116:119]
	v_mfma_f32_16x16x32_bf16 v[112:115], v[156:159], v[178:181], v[112:115]
	v_mfma_f32_16x16x32_bf16 v[100:103], v[152:155], v[192:195], v[100:103]
	v_mfma_f32_16x16x32_bf16 v[96:99], v[156:159], v[192:195], v[96:99]
	v_mfma_f32_16x16x32_bf16 v[84:87], v[152:155], v[204:207], v[84:87]
	v_mfma_f32_16x16x32_bf16 v[80:83], v[156:159], v[204:207], v[80:83]
	v_mfma_f32_16x16x32_bf16 v[68:71], v[152:155], v[208:211], v[68:71]
	v_mfma_f32_16x16x32_bf16 v[64:67], v[156:159], v[208:211], v[64:67]
	s_barrier
	s_setprio 0
	v_mov_b32_e32 v160, v171
	s_add_u32 s60, s36, 0x80000
	s_addc_u32 s61, s37, 0
	s_nop 0
	s_nop 0
	s_nop 0
	v_xad_u32 v182, v160, 64, 0
	ds_read_b128 v[160:163], v183 offset:16384
	ds_read_b128 v[174:177], v183 offset:18432
	ds_read_b128 v[178:181], v182 offset:16384
	ds_read_b128 v[192:195], v182 offset:18432
	ds_read_b128 v[196:199], v183 offset:20480
	ds_read_b128 v[200:203], v183 offset:22528
	ds_read_b128 v[204:207], v182 offset:20480
	ds_read_b128 v[208:211], v182 offset:22528
	s_mov_b32 m0, s80
	s_nop 0
	global_load_lds_dwordx4 v167, s[36:37]
	s_mov_b32 m0, s81
	s_nop 0
	global_load_lds_dwordx4 v169, s[36:37]
	s_mov_b32 m0, s29
	s_nop 0
	global_load_lds_dwordx4 v167, s[60:61]
	s_mov_b32 m0, s88
	s_nop 0
	global_load_lds_dwordx4 v169, s[60:61]
	s_mov_b32 m0, s76
	s_nop 0
	global_load_lds_dwordx4 v166, s[40:41]
	s_mov_b32 m0, s89
	s_nop 0
	global_load_lds_dwordx4 v168, s[40:41]
	s_waitcnt vmcnt(8)
	s_waitcnt lgkmcnt(0)
	s_setprio 1
	s_barrier
; #define PG8_STAGE(bufoff, gbase, voff) do { _Pragma("unroll") for (int _i = 0; _i < 2; ++_i) \
;         dma16((const char*)(gbase), (voff)[_i], ldsb + (bufoff) + ldsw + _i * 8192); } while (0)
; #define PG8_LDA(dst, b, h) do { const int a1_ = opqv(aoff0) ^ 64; _Pragma("unroll") for (int m = 0; m < 4; ++m) { dst[m][0] = *(const LAS bf16x8*)(lds + PG8_SA(b, h) + aoff0 + m * 2048); dst[m][1] = *(const LAS bf16x8*)(lds + PG8_SA(b, h) + a1_ + m * 2048); } } while (0)
; #define PG8_LDB(dst, b, h) do { const int b1_ = opqv(boff0) ^ 64; _Pragma("unroll") for (int n = 0; n < 2; ++n) { dst[n][0] = *(const LAS bf16x8*)(lds + PG8_SB(b, h) + boff0 + n * 2048); dst[n][1] = *(const LAS bf16x8*)(lds + PG8_SB(b, h) + b1_ + n * 2048); } } while (0)
; #define PG8_MMA(ai, bj, At, Bt) do { __builtin_amdgcn_s_setprio(1); _Pragma("unroll") for (int m = 0; m < 4; ++m) _Pragma("unroll") for (int n = 0; n < 2; ++n) _Pragma("unroll") for (int k = 0; k < 2; ++k) \
;         acc[ai][bj][m][n] = __builtin_amdgcn_mfma_f32_16x16x32_bf16(Bt[n][k], At[m][k], acc[ai][bj][m][n], 0, 0, 0); __builtin_amdgcn_s_setprio(0); } while (0)
; #define PG8_WAIT_V(n) asm volatile("s_waitcnt vmcnt(" #n ")" ::: "memory")
; #define PG8_WAIT_L(n) asm volatile("s_waitcnt lgkmcnt(" #n ")" ::: "memory")
; #define PG8_BAR __builtin_amdgcn_s_barrier()
; #define PG8_SCHED __builtin_amdgcn_sched_barrier(0)
; template <class Epi>
; __device__ __forceinline__ void gemm_phase(LAS unsigned char* lds, const Gemm g, const StaticOrder& S, const Epi& E, int wave_) {
;     ...
;             PG8_WAIT_V(8); PG8_WAIT_L(0); PG8_BAR; PG8_MMA(1, 0, At, B0); PG8_MMA(1, 1, At, B1); PG8_BAR; PG8_SCHED;
;             PG8_STAGE(PG8_SA(0, 1), a2 + hstepA, voffA); PG8_LDB(B0, 1, 0); PG8_LDB(B1, 1, 1); PG8_SCHED; PG8_LDA(At, 1, 0);
;             PG8_WAIT_V(8); PG8_WAIT_L(0); PG8_BAR; PG8_MMA(0, 0, At, B0); PG8_MMA(0, 1, At, B1); PG8_BAR; PG8_SCHED;
	v_mfma_f32_16x16x32_bf16 v[60:63], v[128:131], v[160:163], 0
	v_mfma_f32_16x16x32_bf16 v[56:59], v[132:135], v[160:163], 0
	v_mfma_f32_16x16x32_bf16 v[44:47], v[128:131], v[174:177], 0
	v_mfma_f32_16x16x32_bf16 v[40:43], v[132:135], v[174:177], 0
	v_mfma_f32_16x16x32_bf16 v[28:31], v[128:131], v[196:199], 0
	v_mfma_f32_16x16x32_bf16 v[24:27], v[132:135], v[196:199], 0
	v_mfma_f32_16x16x32_bf16 v[12:15], v[128:131], v[200:203], 0
	v_mfma_f32_16x16x32_bf16 v[8:11], v[132:135], v[200:203], 0
	v_mfma_f32_16x16x32_bf16 v[60:63], v[136:139], v[178:181], v[60:63]
	v_mfma_f32_16x16x32_bf16 v[56:59], v[140:143], v[178:181], v[56:59]
	v_mfma_f32_16x16x32_bf16 v[44:47], v[136:139], v[192:195], v[44:47]
	v_mfma_f32_16x16x32_bf16 v[40:43], v[140:143], v[192:195], v[40:43]
	v_mfma_f32_16x16x32_bf16 v[28:31], v[136:139], v[204:207], v[28:31]
	v_mfma_f32_16x16x32_bf16 v[24:27], v[140:143], v[204:207], v[24:27]
	v_mfma_f32_16x16x32_bf16 v[12:15], v[136:139], v[208:211], v[12:15]
	v_mfma_f32_16x16x32_bf16 v[8:11], v[140:143], v[208:211], v[8:11]
	v_mfma_f32_16x16x32_bf16 v[52:55], v[144:147], v[160:163], 0
	v_mfma_f32_16x16x32_bf16 v[48:51], v[148:151], v[160:163], 0
	v_mfma_f32_16x16x32_bf16 v[36:39], v[144:147], v[174:177], 0
	v_mfma_f32_16x16x32_bf16 v[32:35], v[148:151], v[174:177], 0
	v_mfma_f32_16x16x32_bf16 v[20:23], v[144:147], v[196:199], 0
	v_mfma_f32_16x16x32_bf16 v[16:19], v[148:151], v[196:199], 0
	v_mfma_f32_16x16x32_bf16 v[4:7], v[144:147], v[200:203], 0
	v_mfma_f32_16x16x32_bf16 v[0:3], v[148:151], v[200:203], 0
	v_mfma_f32_16x16x32_bf16 v[52:55], v[152:155], v[178:181], v[52:55]
	v_mfma_f32_16x16x32_bf16 v[48:51], v[156:159], v[178:181], v[48:51]
	v_mfma_f32_16x16x32_bf16 v[36:39], v[152:155], v[192:195], v[36:39]
	v_mfma_f32_16x16x32_bf16 v[32:35], v[156:159], v[192:195], v[32:35]
	v_mfma_f32_16x16x32_bf16 v[20:23], v[152:155], v[204:207], v[20:23]
	v_mfma_f32_16x16x32_bf16 v[16:19], v[156:159], v[204:207], v[16:19]
	v_mfma_f32_16x16x32_bf16 v[4:7], v[152:155], v[208:211], v[4:7]
	v_mfma_f32_16x16x32_bf16 v[0:3], v[156:159], v[208:211], v[0:3]
	s_barrier
	s_setprio 0
	s_add_u32 s40, s40, 0x80000
	s_addc_u32 s41, s41, 0
	s_mov_b32 m0, s1
	s_nop 0
	global_load_lds_dwordx4 v166, s[40:41]
	v_mov_b32_e32 v128, v172
	s_mov_b32 m0, s69
	s_nop 0
	global_load_lds_dwordx4 v168, s[40:41]
	v_add_u32_e32 v132, s34, v172
	v_xad_u32 v140, v128, 64, s34
	v_mov_b32_e32 v144, v172
	s_add_i32 s40, 0, 0x1c000
	ds_read_b128 v[128:131], v132
	ds_read_b128 v[132:135], v132 offset:2048
	ds_read_b128 v[136:139], v140
	ds_read_b128 v[140:143], v140 offset:2048
	v_add_u32_e32 v148, s40, v172
	v_xad_u32 v156, v144, 64, s40
	ds_read_b128 v[144:147], v148
	ds_read_b128 v[148:151], v148 offset:2048
	ds_read_b128 v[152:155], v156
	ds_read_b128 v[156:159], v156 offset:2048
	v_mov_b32_e32 v160, v171
	s_nop 0
	v_xad_u32 v182, v160, 64, 0
	ds_read_b128 v[160:163], v183 offset:32768
	ds_read_b128 v[174:177], v183 offset:34816
	ds_read_b128 v[178:181], v182 offset:32768
	ds_read_b128 v[192:195], v182 offset:34816
	ds_read_b128 v[196:199], v183 offset:36864
	ds_read_b128 v[200:203], v183 offset:38912
	ds_read_b128 v[204:207], v182 offset:36864
	ds_read_b128 v[208:211], v182 offset:38912
	s_waitcnt vmcnt(8)
	s_waitcnt lgkmcnt(0)
	s_setprio 1
	s_barrier
	v_mfma_f32_16x16x32_bf16 v[124:127], v[128:131], v[160:163], v[124:127]
	v_mfma_f32_16x16x32_bf16 v[120:123], v[132:135], v[160:163], v[120:123]
	v_mfma_f32_16x16x32_bf16 v[108:111], v[128:131], v[174:177], v[108:111]
	v_mfma_f32_16x16x32_bf16 v[104:107], v[132:135], v[174:177], v[104:107]
	v_mfma_f32_16x16x32_bf16 v[92:95], v[128:131], v[196:199], v[92:95]
	v_mfma_f32_16x16x32_bf16 v[88:91], v[132:135], v[196:199], v[88:91]
	v_mfma_f32_16x16x32_bf16 v[76:79], v[128:131], v[200:203], v[76:79]
	v_mfma_f32_16x16x32_bf16 v[72:75], v[132:135], v[200:203], v[72:75]
	v_mfma_f32_16x16x32_bf16 v[124:127], v[136:139], v[178:181], v[124:127]
	v_mfma_f32_16x16x32_bf16 v[120:123], v[140:143], v[178:181], v[120:123]
	v_mfma_f32_16x16x32_bf16 v[108:111], v[136:139], v[192:195], v[108:111]
	v_mfma_f32_16x16x32_bf16 v[104:107], v[140:143], v[192:195], v[104:107]
	v_mfma_f32_16x16x32_bf16 v[92:95], v[136:139], v[204:207], v[92:95]
	v_mfma_f32_16x16x32_bf16 v[88:91], v[140:143], v[204:207], v[88:91]
	v_mfma_f32_16x16x32_bf16 v[76:79], v[136:139], v[208:211], v[76:79]
	v_mfma_f32_16x16x32_bf16 v[72:75], v[140:143], v[208:211], v[72:75]
	v_mfma_f32_16x16x32_bf16 v[116:119], v[144:147], v[160:163], v[116:119]
	s_add_u32 s40, s36, 0x80
	s_addc_u32 s41, s37, 0
	v_mfma_f32_16x16x32_bf16 v[112:115], v[148:151], v[160:163], v[112:115]
	v_mfma_f32_16x16x32_bf16 v[100:103], v[144:147], v[174:177], v[100:103]
	v_mfma_f32_16x16x32_bf16 v[96:99], v[148:151], v[174:177], v[96:99]
	v_mfma_f32_16x16x32_bf16 v[84:87], v[144:147], v[196:199], v[84:87]
	v_mfma_f32_16x16x32_bf16 v[80:83], v[148:151], v[196:199], v[80:83]
	v_mfma_f32_16x16x32_bf16 v[68:71], v[144:147], v[200:203], v[68:71]
	v_mfma_f32_16x16x32_bf16 v[64:67], v[148:151], v[200:203], v[64:67]
	v_mfma_f32_16x16x32_bf16 v[116:119], v[152:155], v[178:181], v[116:119]
	v_mfma_f32_16x16x32_bf16 v[112:115], v[156:159], v[178:181], v[112:115]
	v_mfma_f32_16x16x32_bf16 v[100:103], v[152:155], v[192:195], v[100:103]
	v_mfma_f32_16x16x32_bf16 v[96:99], v[156:159], v[192:195], v[96:99]
	v_mfma_f32_16x16x32_bf16 v[84:87], v[152:155], v[204:207], v[84:87]
	v_mfma_f32_16x16x32_bf16 v[80:83], v[156:159], v[204:207], v[80:83]
	v_mfma_f32_16x16x32_bf16 v[68:71], v[152:155], v[208:211], v[68:71]
	v_mfma_f32_16x16x32_bf16 v[64:67], v[156:159], v[208:211], v[64:67]
	s_barrier
; #define PG8_STAGE(bufoff, gbase, voff) do { _Pragma("unroll") for (int _i = 0; _i < 2; ++_i) \
;         dma16((const char*)(gbase), (voff)[_i], ldsb + (bufoff) + ldsw + _i * 8192); } while (0)
; #define PG8_LDA(dst, b, h) do { const int a1_ = opqv(aoff0) ^ 64; _Pragma("unroll") for (int m = 0; m < 4; ++m) { dst[m][0] = *(const LAS bf16x8*)(lds + PG8_SA(b, h) + aoff0 + m * 2048); dst[m][1] = *(const LAS bf16x8*)(lds + PG8_SA(b, h) + a1_ + m * 2048); } } while (0)
; #define PG8_LDB(dst, b, h) do { const int b1_ = opqv(boff0) ^ 64; _Pragma("unroll") for (int n = 0; n < 2; ++n) { dst[n][0] = *(const LAS bf16x8*)(lds + PG8_SB(b, h) + boff0 + n * 2048); dst[n][1] = *(const LAS bf16x8*)(lds + PG8_SB(b, h) + b1_ + n * 2048); } } while (0)
; #define PG8_MMA(ai, bj, At, Bt) do { __builtin_amdgcn_s_setprio(1); _Pragma("unroll") for (int m = 0; m < 4; ++m) _Pragma("unroll") for (int n = 0; n < 2; ++n) _Pragma("unroll") for (int k = 0; k < 2; ++k) \
;         acc[ai][bj][m][n] = __builtin_amdgcn_mfma_f32_16x16x32_bf16(Bt[n][k], At[m][k], acc[ai][bj][m][n], 0, 0, 0); __builtin_amdgcn_s_setprio(0); } while (0)
; #define PG8_WAIT_V(n) asm volatile("s_waitcnt vmcnt(" #n ")" ::: "memory")
; template <class Epi>
; __device__ __forceinline__ void gemm_phase(LAS unsigned char* lds, const Gemm g, const StaticOrder& S, const Epi& E, int wave_) {
;     ...
;             PG8_STAGE(PG8_SA(1, 1), a1 + hstepA, voffA); PG8_LDB(B0, 0, 0); PG8_LDB(B1, 0, 1); PG8_SCHED; PG8_LDA(At, 0, 0);
;             PG8_WAIT_V(8); PG8_WAIT_L(0); PG8_BAR; PG8_MMA(0, 0, At, B0); PG8_MMA(0, 1, At, B1); PG8_BAR; PG8_SCHED;
;             PG8_STAGE(PG8_SB(0, 0), b2, voffB); PG8_STAGE(PG8_SB(0, 1), b2 + hstepB, voffB); PG8_STAGE(PG8_SA(0, 0), a2, voffA); PG8_LDA(At, 0, 1);
;             PG8_WAIT_V(8); PG8_WAIT_L(0); PG8_BAR; PG8_MMA(1, 0, At, B0); PG8_MMA(1, 1, At, B1); PG8_BAR; PG8_SCHED;
;             PG8_STAGE(PG8_SA(0, 1), a2 + hstepA, voffA); PG8_LDB(B0, 1, 0); PG8_LDB(B1, 1, 1); PG8_SCHED; PG8_LDA(At, 1, 0);
;             PG8_WAIT_V(8); PG8_WAIT_L(0); PG8_BAR; PG8_MMA(0, 0, At, B0); PG8_MMA(0, 1, At, B1); PG8_BAR; PG8_SCHED;
;             PG8_STAGE(PG8_SB(1, 0), b3, voffB); PG8_STAGE(PG8_SB(1, 1), b3 + hstepB, voffB); PG8_STAGE(PG8_SA(1, 0), a3, voffA); PG8_LDA(At, 1, 1);
;             PG8_WAIT_V(8); PG8_WAIT_L(0); PG8_BAR; PG8_MMA(1, 0, At, B0); PG8_MMA(1, 1, At, B1); PG8_BAR; PG8_SCHED;
	s_setprio 0
	s_add_u32 s36, s36, 0x80080
	s_addc_u32 s37, s37, 0
	v_mov_b32_e32 v160, v171
	s_nop 0
	s_nop 0
	v_xad_u32 v182, v160, 64, 0
	ds_read_b128 v[160:163], v183 offset:49152
	ds_read_b128 v[174:177], v183 offset:51200
	ds_read_b128 v[178:181], v182 offset:49152
	ds_read_b128 v[192:195], v182 offset:51200
	ds_read_b128 v[196:199], v183 offset:53248
	ds_read_b128 v[200:203], v183 offset:55296
	ds_read_b128 v[204:207], v182 offset:53248
	ds_read_b128 v[208:211], v182 offset:55296
	s_mov_b32 m0, s35
	s_nop 0
	global_load_lds_dwordx4 v167, s[40:41]
	s_mov_b32 m0, s33
	s_nop 0
	global_load_lds_dwordx4 v169, s[40:41]
	s_mov_b32 m0, s77
	s_nop 0
	global_load_lds_dwordx4 v167, s[36:37]
	s_mov_b32 m0, s3
	s_nop 0
	global_load_lds_dwordx4 v169, s[36:37]
	s_mov_b32 m0, s22
	s_nop 0
	global_load_lds_dwordx4 v166, s[30:31]
	s_mov_b32 m0, s2
	s_nop 0
	global_load_lds_dwordx4 v168, s[30:31]
	s_waitcnt vmcnt(8)
	s_waitcnt lgkmcnt(0)
	s_setprio 1
	s_barrier
	v_mfma_f32_16x16x32_bf16 v[60:63], v[128:131], v[160:163], v[60:63]
	v_mfma_f32_16x16x32_bf16 v[56:59], v[132:135], v[160:163], v[56:59]
	v_mfma_f32_16x16x32_bf16 v[44:47], v[128:131], v[174:177], v[44:47]
	v_mfma_f32_16x16x32_bf16 v[40:43], v[132:135], v[174:177], v[40:43]
	v_mfma_f32_16x16x32_bf16 v[28:31], v[128:131], v[196:199], v[28:31]
	v_mfma_f32_16x16x32_bf16 v[24:27], v[132:135], v[196:199], v[24:27]
	v_mfma_f32_16x16x32_bf16 v[12:15], v[128:131], v[200:203], v[12:15]
	v_mfma_f32_16x16x32_bf16 v[8:11], v[132:135], v[200:203], v[8:11]
	v_mfma_f32_16x16x32_bf16 v[60:63], v[136:139], v[178:181], v[60:63]
	v_mfma_f32_16x16x32_bf16 v[56:59], v[140:143], v[178:181], v[56:59]
	v_mfma_f32_16x16x32_bf16 v[44:47], v[136:139], v[192:195], v[44:47]
	v_mfma_f32_16x16x32_bf16 v[40:43], v[140:143], v[192:195], v[40:43]
	v_mfma_f32_16x16x32_bf16 v[28:31], v[136:139], v[204:207], v[28:31]
	v_mfma_f32_16x16x32_bf16 v[24:27], v[140:143], v[204:207], v[24:27]
	v_mfma_f32_16x16x32_bf16 v[12:15], v[136:139], v[208:211], v[12:15]
	v_mfma_f32_16x16x32_bf16 v[8:11], v[140:143], v[208:211], v[8:11]
	v_mfma_f32_16x16x32_bf16 v[52:55], v[144:147], v[160:163], v[52:55]
	v_mfma_f32_16x16x32_bf16 v[48:51], v[148:151], v[160:163], v[48:51]
	v_mfma_f32_16x16x32_bf16 v[36:39], v[144:147], v[174:177], v[36:39]
	v_mfma_f32_16x16x32_bf16 v[32:35], v[148:151], v[174:177], v[32:35]
	v_mfma_f32_16x16x32_bf16 v[20:23], v[144:147], v[196:199], v[20:23]
	v_mfma_f32_16x16x32_bf16 v[16:19], v[148:151], v[196:199], v[16:19]
	v_mfma_f32_16x16x32_bf16 v[4:7], v[144:147], v[200:203], v[4:7]
	v_mfma_f32_16x16x32_bf16 v[0:3], v[148:151], v[200:203], v[0:3]
	v_mfma_f32_16x16x32_bf16 v[52:55], v[152:155], v[178:181], v[52:55]
	v_mfma_f32_16x16x32_bf16 v[48:51], v[156:159], v[178:181], v[48:51]
	v_mfma_f32_16x16x32_bf16 v[36:39], v[152:155], v[192:195], v[36:39]
	v_mfma_f32_16x16x32_bf16 v[32:35], v[156:159], v[192:195], v[32:35]
	v_mfma_f32_16x16x32_bf16 v[20:23], v[152:155], v[204:207], v[20:23]
	v_mfma_f32_16x16x32_bf16 v[16:19], v[156:159], v[204:207], v[16:19]
	v_mfma_f32_16x16x32_bf16 v[4:7], v[152:155], v[208:211], v[4:7]
	v_mfma_f32_16x16x32_bf16 v[0:3], v[156:159], v[208:211], v[0:3]
	s_barrier
	s_setprio 0
	s_add_i32 s57, s57, 2
	s_add_u32 s55, s55, 0x100
	s_addc_u32 s56, s56, 0
	s_add_u32 s12, s12, 0x100
	s_addc_u32 s13, s13, 0
	s_cmp_gt_u32 s57, 29
	s_cbranch_scc0 .LBB0_1104
	s_branch .Lpeel_exit_4
.LBB0_1104:
	s_add_u32 s30, s12, 0xfff80080
	s_addc_u32 s31, s13, -1
	s_cmp_eq_u32 s57, 28
	s_cselect_b32 s40, s17, s30
	s_cselect_b32 s41, s16, s31
	s_cselect_b32 s36, s19, s55
	s_cselect_b32 s37, s11, s56
	s_add_u32 s30, s40, 0x80
	v_mov_b32_e32 v128, v172
	s_addc_u32 s31, s41, 0
	v_add_u32_e32 v132, s23, v172
	v_xad_u32 v140, v128, 64, s23
	v_mov_b32_e32 v144, v172
	s_add_i32 s60, 0, 0x14000
	ds_read_b128 v[128:131], v132
	ds_read_b128 v[132:135], v132 offset:2048
	ds_read_b128 v[136:139], v140
	ds_read_b128 v[140:143], v140 offset:2048
	v_add_u32_e32 v148, s60, v172
	v_xad_u32 v156, v144, 64, s60
	ds_read_b128 v[144:147], v148
	ds_read_b128 v[148:151], v148 offset:2048
	ds_read_b128 v[152:155], v156
	ds_read_b128 v[156:159], v156 offset:2048
	v_mov_b32_e32 v160, v171
	v_add_u32_e32 v183, 0, v171
	v_xad_u32 v182, v160, 64, 0
	ds_read_b128 v[160:163], v183
	ds_read_b128 v[174:177], v183 offset:2048
	ds_read_b128 v[178:181], v182
	ds_read_b128 v[192:195], v182 offset:2048
	ds_read_b128 v[196:199], v183 offset:4096
	ds_read_b128 v[200:203], v183 offset:6144
	ds_read_b128 v[204:207], v182 offset:4096
	ds_read_b128 v[208:211], v182 offset:6144
	s_mov_b32 m0, s14
	s_nop 0
	global_load_lds_dwordx4 v166, s[12:13]
	s_mov_b32 m0, s15
	s_nop 0
	global_load_lds_dwordx4 v168, s[12:13]
	s_waitcnt vmcnt(8)
	s_waitcnt lgkmcnt(0)
	s_setprio 1
	s_barrier
; #define PG8_STAGE(bufoff, gbase, voff) do { _Pragma("unroll") for (int _i = 0; _i < 2; ++_i) \
;         dma16((const char*)(gbase), (voff)[_i], ldsb + (bufoff) + ldsw + _i * 8192); } while (0)
; #define PG8_LDA(dst, b, h) do { const int a1_ = opqv(aoff0) ^ 64; _Pragma("unroll") for (int m = 0; m < 4; ++m) { dst[m][0] = *(const LAS bf16x8*)(lds + PG8_SA(b, h) + aoff0 + m * 2048); dst[m][1] = *(const LAS bf16x8*)(lds + PG8_SA(b, h) + a1_ + m * 2048); } } while (0)
; #define PG8_MMA(ai, bj, At, Bt) do { __builtin_amdgcn_s_setprio(1); _Pragma("unroll") for (int m = 0; m < 4; ++m) _Pragma("unroll") for (int n = 0; n < 2; ++n) _Pragma("unroll") for (int k = 0; k < 2; ++k) \
;         acc[ai][bj][m][n] = __builtin_amdgcn_mfma_f32_16x16x32_bf16(Bt[n][k], At[m][k], acc[ai][bj][m][n], 0, 0, 0); __builtin_amdgcn_s_setprio(0); } while (0)
; #define PG8_WAIT_V(n) asm volatile("s_waitcnt vmcnt(" #n ")" ::: "memory")
; #define PG8_WAIT_L(n) asm volatile("s_waitcnt lgkmcnt(" #n ")" ::: "memory")
; #define PG8_BAR __builtin_amdgcn_s_barrier()
; #define PG8_SCHED __builtin_amdgcn_sched_barrier(0)
; template <class Epi>
; __device__ __forceinline__ void gemm_phase(LAS unsigned char* lds, const Gemm g, const StaticOrder& S, const Epi& E, int wave_) {
;     ...
;             PG8_WAIT_V(8); PG8_WAIT_L(0); PG8_BAR; PG8_MMA(0, 0, At, B0); PG8_MMA(0, 1, At, B1); PG8_BAR; PG8_SCHED;
;             PG8_STAGE(PG8_SB(0, 0), b2, voffB); PG8_STAGE(PG8_SB(0, 1), b2 + hstepB, voffB); PG8_STAGE(PG8_SA(0, 0), a2, voffA); PG8_LDA(At, 0, 1);
;             PG8_WAIT_V(8); PG8_WAIT_L(0); PG8_BAR; PG8_MMA(1, 0, At, B0); PG8_MMA(1, 1, At, B1); PG8_BAR; PG8_SCHED;
	v_mfma_f32_16x16x32_bf16 v[124:127], v[128:131], v[160:163], v[124:127]
	v_mfma_f32_16x16x32_bf16 v[120:123], v[132:135], v[160:163], v[120:123]
	v_mfma_f32_16x16x32_bf16 v[108:111], v[128:131], v[174:177], v[108:111]
	v_mfma_f32_16x16x32_bf16 v[104:107], v[132:135], v[174:177], v[104:107]
	v_mfma_f32_16x16x32_bf16 v[92:95], v[128:131], v[196:199], v[92:95]
	v_mfma_f32_16x16x32_bf16 v[88:91], v[132:135], v[196:199], v[88:91]
	v_mfma_f32_16x16x32_bf16 v[76:79], v[128:131], v[200:203], v[76:79]
	v_mfma_f32_16x16x32_bf16 v[72:75], v[132:135], v[200:203], v[72:75]
	v_mfma_f32_16x16x32_bf16 v[124:127], v[136:139], v[178:181], v[124:127]
	v_mfma_f32_16x16x32_bf16 v[120:123], v[140:143], v[178:181], v[120:123]
	v_mfma_f32_16x16x32_bf16 v[108:111], v[136:139], v[192:195], v[108:111]
	v_mfma_f32_16x16x32_bf16 v[104:107], v[140:143], v[192:195], v[104:107]
	v_mfma_f32_16x16x32_bf16 v[92:95], v[136:139], v[204:207], v[92:95]
	v_mfma_f32_16x16x32_bf16 v[88:91], v[140:143], v[204:207], v[88:91]
	v_mfma_f32_16x16x32_bf16 v[76:79], v[136:139], v[208:211], v[76:79]
	v_mfma_f32_16x16x32_bf16 v[72:75], v[140:143], v[208:211], v[72:75]
	v_mfma_f32_16x16x32_bf16 v[116:119], v[144:147], v[160:163], v[116:119]
	v_mfma_f32_16x16x32_bf16 v[112:115], v[148:151], v[160:163], v[112:115]
	v_mfma_f32_16x16x32_bf16 v[100:103], v[144:147], v[174:177], v[100:103]
	v_mfma_f32_16x16x32_bf16 v[96:99], v[148:151], v[174:177], v[96:99]
	v_mfma_f32_16x16x32_bf16 v[84:87], v[144:147], v[196:199], v[84:87]
	v_mfma_f32_16x16x32_bf16 v[80:83], v[148:151], v[196:199], v[80:83]
	v_mfma_f32_16x16x32_bf16 v[68:71], v[144:147], v[200:203], v[68:71]
	v_mfma_f32_16x16x32_bf16 v[64:67], v[148:151], v[200:203], v[64:67]
	v_mfma_f32_16x16x32_bf16 v[116:119], v[152:155], v[178:181], v[116:119]
	v_mfma_f32_16x16x32_bf16 v[112:115], v[156:159], v[178:181], v[112:115]
	v_mfma_f32_16x16x32_bf16 v[100:103], v[152:155], v[192:195], v[100:103]
	v_mfma_f32_16x16x32_bf16 v[96:99], v[156:159], v[192:195], v[96:99]
	v_mfma_f32_16x16x32_bf16 v[84:87], v[152:155], v[204:207], v[84:87]
	v_mfma_f32_16x16x32_bf16 v[80:83], v[156:159], v[204:207], v[80:83]
	v_mfma_f32_16x16x32_bf16 v[68:71], v[152:155], v[208:211], v[68:71]
	v_mfma_f32_16x16x32_bf16 v[64:67], v[156:159], v[208:211], v[64:67]
	s_barrier
	s_setprio 0
	v_mov_b32_e32 v160, v171
	s_add_u32 s60, s36, 0x80000
	s_addc_u32 s61, s37, 0
	s_nop 0
	s_nop 0
	s_nop 0
	v_xad_u32 v182, v160, 64, 0
	ds_read_b128 v[160:163], v183 offset:16384
	ds_read_b128 v[174:177], v183 offset:18432
	ds_read_b128 v[178:181], v182 offset:16384
	ds_read_b128 v[192:195], v182 offset:18432
	ds_read_b128 v[196:199], v183 offset:20480
	ds_read_b128 v[200:203], v183 offset:22528
	ds_read_b128 v[204:207], v182 offset:20480
	ds_read_b128 v[208:211], v182 offset:22528
	s_mov_b32 m0, s80
	s_nop 0
	global_load_lds_dwordx4 v167, s[36:37]
	s_mov_b32 m0, s81
	s_nop 0
	global_load_lds_dwordx4 v169, s[36:37]
	s_mov_b32 m0, s29
	s_nop 0
	global_load_lds_dwordx4 v167, s[60:61]
	s_mov_b32 m0, s88
	s_nop 0
	global_load_lds_dwordx4 v169, s[60:61]
	s_mov_b32 m0, s76
	s_nop 0
	global_load_lds_dwordx4 v166, s[40:41]
	s_mov_b32 m0, s89
	s_nop 0
	global_load_lds_dwordx4 v168, s[40:41]
	s_waitcnt vmcnt(8)
	s_waitcnt lgkmcnt(0)
	s_setprio 1
	s_barrier
	v_mfma_f32_16x16x32_bf16 v[60:63], v[128:131], v[160:163], v[60:63]
	v_mfma_f32_16x16x32_bf16 v[56:59], v[132:135], v[160:163], v[56:59]
	v_mfma_f32_16x16x32_bf16 v[44:47], v[128:131], v[174:177], v[44:47]
	v_mfma_f32_16x16x32_bf16 v[40:43], v[132:135], v[174:177], v[40:43]
	v_mfma_f32_16x16x32_bf16 v[28:31], v[128:131], v[196:199], v[28:31]
	v_mfma_f32_16x16x32_bf16 v[24:27], v[132:135], v[196:199], v[24:27]
	v_mfma_f32_16x16x32_bf16 v[12:15], v[128:131], v[200:203], v[12:15]
	v_mfma_f32_16x16x32_bf16 v[8:11], v[132:135], v[200:203], v[8:11]
	v_mfma_f32_16x16x32_bf16 v[60:63], v[136:139], v[178:181], v[60:63]
	v_mfma_f32_16x16x32_bf16 v[56:59], v[140:143], v[178:181], v[56:59]
	v_mfma_f32_16x16x32_bf16 v[44:47], v[136:139], v[192:195], v[44:47]
	v_mfma_f32_16x16x32_bf16 v[40:43], v[140:143], v[192:195], v[40:43]
	v_mfma_f32_16x16x32_bf16 v[28:31], v[136:139], v[204:207], v[28:31]
	v_mfma_f32_16x16x32_bf16 v[24:27], v[140:143], v[204:207], v[24:27]
	v_mfma_f32_16x16x32_bf16 v[12:15], v[136:139], v[208:211], v[12:15]
	v_mfma_f32_16x16x32_bf16 v[8:11], v[140:143], v[208:211], v[8:11]
	v_mfma_f32_16x16x32_bf16 v[52:55], v[144:147], v[160:163], v[52:55]
	v_mfma_f32_16x16x32_bf16 v[48:51], v[148:151], v[160:163], v[48:51]
	v_mfma_f32_16x16x32_bf16 v[36:39], v[144:147], v[174:177], v[36:39]
	v_mfma_f32_16x16x32_bf16 v[32:35], v[148:151], v[174:177], v[32:35]
	v_mfma_f32_16x16x32_bf16 v[20:23], v[144:147], v[196:199], v[20:23]
	v_mfma_f32_16x16x32_bf16 v[16:19], v[148:151], v[196:199], v[16:19]
	v_mfma_f32_16x16x32_bf16 v[4:7], v[144:147], v[200:203], v[4:7]
	v_mfma_f32_16x16x32_bf16 v[0:3], v[148:151], v[200:203], v[0:3]
	v_mfma_f32_16x16x32_bf16 v[52:55], v[152:155], v[178:181], v[52:55]
	v_mfma_f32_16x16x32_bf16 v[48:51], v[156:159], v[178:181], v[48:51]
	v_mfma_f32_16x16x32_bf16 v[36:39], v[152:155], v[192:195], v[36:39]
	v_mfma_f32_16x16x32_bf16 v[32:35], v[156:159], v[192:195], v[32:35]
	v_mfma_f32_16x16x32_bf16 v[20:23], v[152:155], v[204:207], v[20:23]
	v_mfma_f32_16x16x32_bf16 v[16:19], v[156:159], v[204:207], v[16:19]
	v_mfma_f32_16x16x32_bf16 v[4:7], v[152:155], v[208:211], v[4:7]
	v_mfma_f32_16x16x32_bf16 v[0:3], v[156:159], v[208:211], v[0:3]
	s_barrier
; #define PG8_STAGE(bufoff, gbase, voff) do { _Pragma("unroll") for (int _i = 0; _i < 2; ++_i) \
;         dma16((const char*)(gbase), (voff)[_i], ldsb + (bufoff) + ldsw + _i * 8192); } while (0)
; #define PG8_LDA(dst, b, h) do { const int a1_ = opqv(aoff0) ^ 64; _Pragma("unroll") for (int m = 0; m < 4; ++m) { dst[m][0] = *(const LAS bf16x8*)(lds + PG8_SA(b, h) + aoff0 + m * 2048); dst[m][1] = *(const LAS bf16x8*)(lds + PG8_SA(b, h) + a1_ + m * 2048); } } while (0)
; #define PG8_LDB(dst, b, h) do { const int b1_ = opqv(boff0) ^ 64; _Pragma("unroll") for (int n = 0; n < 2; ++n) { dst[n][0] = *(const LAS bf16x8*)(lds + PG8_SB(b, h) + boff0 + n * 2048); dst[n][1] = *(const LAS bf16x8*)(lds + PG8_SB(b, h) + b1_ + n * 2048); } } while (0)
; #define PG8_MMA(ai, bj, At, Bt) do { __builtin_amdgcn_s_setprio(1); _Pragma("unroll") for (int m = 0; m < 4; ++m) _Pragma("unroll") for (int n = 0; n < 2; ++n) _Pragma("unroll") for (int k = 0; k < 2; ++k) \
;         acc[ai][bj][m][n] = __builtin_amdgcn_mfma_f32_16x16x32_bf16(Bt[n][k], At[m][k], acc[ai][bj][m][n], 0, 0, 0); __builtin_amdgcn_s_setprio(0); } while (0)
; #define PG8_WAIT_V(n) asm volatile("s_waitcnt vmcnt(" #n ")" ::: "memory")
; #define PG8_WAIT_L(n) asm volatile("s_waitcnt lgkmcnt(" #n ")" ::: "memory")
; #define PG8_BAR __builtin_amdgcn_s_barrier()
; #define PG8_SCHED __builtin_amdgcn_sched_barrier(0)
; template <class Epi>
; __device__ __forceinline__ void gemm_phase(LAS unsigned char* lds, const Gemm g, const StaticOrder& S, const Epi& E, int wave_) {
;     ...
;             PG8_STAGE(PG8_SA(0, 1), a2 + hstepA, voffA); PG8_LDB(B0, 1, 0); PG8_LDB(B1, 1, 1); PG8_SCHED; PG8_LDA(At, 1, 0);
;             PG8_WAIT_V(8); PG8_WAIT_L(0); PG8_BAR; PG8_MMA(0, 0, At, B0); PG8_MMA(0, 1, At, B1); PG8_BAR; PG8_SCHED;
;             PG8_STAGE(PG8_SB(1, 0), b3, voffB); PG8_STAGE(PG8_SB(1, 1), b3 + hstepB, voffB); PG8_STAGE(PG8_SA(1, 0), a3, voffA); PG8_LDA(At, 1, 1);
;             PG8_WAIT_V(8); PG8_WAIT_L(0); PG8_BAR; PG8_MMA(1, 0, At, B0); PG8_MMA(1, 1, At, B1); PG8_BAR; PG8_SCHED;
	s_setprio 0
	s_add_u32 s40, s40, 0x80000
	s_addc_u32 s41, s41, 0
	s_mov_b32 m0, s1
	s_nop 0
	global_load_lds_dwordx4 v166, s[40:41]
	v_mov_b32_e32 v128, v172
	s_mov_b32 m0, s69
	s_nop 0
	global_load_lds_dwordx4 v168, s[40:41]
	v_add_u32_e32 v132, s34, v172
	v_xad_u32 v140, v128, 64, s34
	v_mov_b32_e32 v144, v172
	s_add_i32 s40, 0, 0x1c000
	ds_read_b128 v[128:131], v132
	ds_read_b128 v[132:135], v132 offset:2048
	ds_read_b128 v[136:139], v140
	ds_read_b128 v[140:143], v140 offset:2048
	v_add_u32_e32 v148, s40, v172
	v_xad_u32 v156, v144, 64, s40
	ds_read_b128 v[144:147], v148
	ds_read_b128 v[148:151], v148 offset:2048
	ds_read_b128 v[152:155], v156
	ds_read_b128 v[156:159], v156 offset:2048
	v_mov_b32_e32 v160, v171
	s_nop 0
	v_xad_u32 v182, v160, 64, 0
	ds_read_b128 v[160:163], v183 offset:32768
	ds_read_b128 v[174:177], v183 offset:34816
	ds_read_b128 v[178:181], v182 offset:32768
	ds_read_b128 v[192:195], v182 offset:34816
	ds_read_b128 v[196:199], v183 offset:36864
	ds_read_b128 v[200:203], v183 offset:38912
	ds_read_b128 v[204:207], v182 offset:36864
	ds_read_b128 v[208:211], v182 offset:38912
	s_waitcnt vmcnt(8)
	s_waitcnt lgkmcnt(0)
	s_setprio 1
	s_barrier
	v_mfma_f32_16x16x32_bf16 v[124:127], v[128:131], v[160:163], v[124:127]
	v_mfma_f32_16x16x32_bf16 v[120:123], v[132:135], v[160:163], v[120:123]
	v_mfma_f32_16x16x32_bf16 v[108:111], v[128:131], v[174:177], v[108:111]
	v_mfma_f32_16x16x32_bf16 v[104:107], v[132:135], v[174:177], v[104:107]
	v_mfma_f32_16x16x32_bf16 v[92:95], v[128:131], v[196:199], v[92:95]
	v_mfma_f32_16x16x32_bf16 v[88:91], v[132:135], v[196:199], v[88:91]
	v_mfma_f32_16x16x32_bf16 v[76:79], v[128:131], v[200:203], v[76:79]
	v_mfma_f32_16x16x32_bf16 v[72:75], v[132:135], v[200:203], v[72:75]
	v_mfma_f32_16x16x32_bf16 v[124:127], v[136:139], v[178:181], v[124:127]
	v_mfma_f32_16x16x32_bf16 v[120:123], v[140:143], v[178:181], v[120:123]
	v_mfma_f32_16x16x32_bf16 v[108:111], v[136:139], v[192:195], v[108:111]
	v_mfma_f32_16x16x32_bf16 v[104:107], v[140:143], v[192:195], v[104:107]
	v_mfma_f32_16x16x32_bf16 v[92:95], v[136:139], v[204:207], v[92:95]
	v_mfma_f32_16x16x32_bf16 v[88:91], v[140:143], v[204:207], v[88:91]
	v_mfma_f32_16x16x32_bf16 v[76:79], v[136:139], v[208:211], v[76:79]
	v_mfma_f32_16x16x32_bf16 v[72:75], v[140:143], v[208:211], v[72:75]
	v_mfma_f32_16x16x32_bf16 v[116:119], v[144:147], v[160:163], v[116:119]
	s_add_u32 s40, s36, 0x80
	s_addc_u32 s41, s37, 0
	v_mfma_f32_16x16x32_bf16 v[112:115], v[148:151], v[160:163], v[112:115]
	v_mfma_f32_16x16x32_bf16 v[100:103], v[144:147], v[174:177], v[100:103]
	v_mfma_f32_16x16x32_bf16 v[96:99], v[148:151], v[174:177], v[96:99]
	v_mfma_f32_16x16x32_bf16 v[84:87], v[144:147], v[196:199], v[84:87]
	v_mfma_f32_16x16x32_bf16 v[80:83], v[148:151], v[196:199], v[80:83]
	v_mfma_f32_16x16x32_bf16 v[68:71], v[144:147], v[200:203], v[68:71]
	v_mfma_f32_16x16x32_bf16 v[64:67], v[148:151], v[200:203], v[64:67]
	v_mfma_f32_16x16x32_bf16 v[116:119], v[152:155], v[178:181], v[116:119]
	v_mfma_f32_16x16x32_bf16 v[112:115], v[156:159], v[178:181], v[112:115]
	v_mfma_f32_16x16x32_bf16 v[100:103], v[152:155], v[192:195], v[100:103]
	v_mfma_f32_16x16x32_bf16 v[96:99], v[156:159], v[192:195], v[96:99]
	v_mfma_f32_16x16x32_bf16 v[84:87], v[152:155], v[204:207], v[84:87]
	v_mfma_f32_16x16x32_bf16 v[80:83], v[156:159], v[204:207], v[80:83]
	v_mfma_f32_16x16x32_bf16 v[68:71], v[152:155], v[208:211], v[68:71]
	v_mfma_f32_16x16x32_bf16 v[64:67], v[156:159], v[208:211], v[64:67]
	s_barrier
	s_setprio 0
	s_add_u32 s36, s36, 0x80080
	s_addc_u32 s37, s37, 0
	v_mov_b32_e32 v160, v171
	s_nop 0
	s_nop 0
	v_xad_u32 v182, v160, 64, 0
	ds_read_b128 v[160:163], v183 offset:49152
	ds_read_b128 v[174:177], v183 offset:51200
	ds_read_b128 v[178:181], v182 offset:49152
	ds_read_b128 v[192:195], v182 offset:51200
	ds_read_b128 v[196:199], v183 offset:53248
	ds_read_b128 v[200:203], v183 offset:55296
	ds_read_b128 v[204:207], v182 offset:53248
	ds_read_b128 v[208:211], v182 offset:55296
	s_mov_b32 m0, s35
	s_nop 0
	global_load_lds_dwordx4 v167, s[40:41]
	s_mov_b32 m0, s33
	s_nop 0
	global_load_lds_dwordx4 v169, s[40:41]
	s_mov_b32 m0, s77
	s_nop 0
	global_load_lds_dwordx4 v167, s[36:37]
	s_mov_b32 m0, s3
	s_nop 0
	global_load_lds_dwordx4 v169, s[36:37]
	s_mov_b32 m0, s22
	s_nop 0
	global_load_lds_dwordx4 v166, s[30:31]
	s_mov_b32 m0, s2
	s_nop 0
	global_load_lds_dwordx4 v168, s[30:31]
	s_waitcnt vmcnt(8)
	s_waitcnt lgkmcnt(0)
	s_setprio 1
	s_barrier
	v_mfma_f32_16x16x32_bf16 v[60:63], v[128:131], v[160:163], v[60:63]
	v_mfma_f32_16x16x32_bf16 v[56:59], v[132:135], v[160:163], v[56:59]
	v_mfma_f32_16x16x32_bf16 v[44:47], v[128:131], v[174:177], v[44:47]
	v_mfma_f32_16x16x32_bf16 v[40:43], v[132:135], v[174:177], v[40:43]
	v_mfma_f32_16x16x32_bf16 v[28:31], v[128:131], v[196:199], v[28:31]
	v_mfma_f32_16x16x32_bf16 v[24:27], v[132:135], v[196:199], v[24:27]
	v_mfma_f32_16x16x32_bf16 v[12:15], v[128:131], v[200:203], v[12:15]
	v_mfma_f32_16x16x32_bf16 v[8:11], v[132:135], v[200:203], v[8:11]
	v_mfma_f32_16x16x32_bf16 v[60:63], v[136:139], v[178:181], v[60:63]
	v_mfma_f32_16x16x32_bf16 v[56:59], v[140:143], v[178:181], v[56:59]
	v_mfma_f32_16x16x32_bf16 v[44:47], v[136:139], v[192:195], v[44:47]
	v_mfma_f32_16x16x32_bf16 v[40:43], v[140:143], v[192:195], v[40:43]
	v_mfma_f32_16x16x32_bf16 v[28:31], v[136:139], v[204:207], v[28:31]
	v_mfma_f32_16x16x32_bf16 v[24:27], v[140:143], v[204:207], v[24:27]
	v_mfma_f32_16x16x32_bf16 v[12:15], v[136:139], v[208:211], v[12:15]
	v_mfma_f32_16x16x32_bf16 v[8:11], v[140:143], v[208:211], v[8:11]
	v_mfma_f32_16x16x32_bf16 v[52:55], v[144:147], v[160:163], v[52:55]
	v_mfma_f32_16x16x32_bf16 v[48:51], v[148:151], v[160:163], v[48:51]
	v_mfma_f32_16x16x32_bf16 v[36:39], v[144:147], v[174:177], v[36:39]
	v_mfma_f32_16x16x32_bf16 v[32:35], v[148:151], v[174:177], v[32:35]
	v_mfma_f32_16x16x32_bf16 v[20:23], v[144:147], v[196:199], v[20:23]
	v_mfma_f32_16x16x32_bf16 v[16:19], v[148:151], v[196:199], v[16:19]
	v_mfma_f32_16x16x32_bf16 v[4:7], v[144:147], v[200:203], v[4:7]
	v_mfma_f32_16x16x32_bf16 v[0:3], v[148:151], v[200:203], v[0:3]
	v_mfma_f32_16x16x32_bf16 v[52:55], v[152:155], v[178:181], v[52:55]
	v_mfma_f32_16x16x32_bf16 v[48:51], v[156:159], v[178:181], v[48:51]
	v_mfma_f32_16x16x32_bf16 v[36:39], v[152:155], v[192:195], v[36:39]
	v_mfma_f32_16x16x32_bf16 v[32:35], v[156:159], v[192:195], v[32:35]
	v_mfma_f32_16x16x32_bf16 v[20:23], v[152:155], v[204:207], v[20:23]
	v_mfma_f32_16x16x32_bf16 v[16:19], v[156:159], v[204:207], v[16:19]
	v_mfma_f32_16x16x32_bf16 v[4:7], v[152:155], v[208:211], v[4:7]
	v_mfma_f32_16x16x32_bf16 v[0:3], v[156:159], v[208:211], v[0:3]
	s_barrier
	s_setprio 0
	s_add_i32 s57, s57, 2
	s_add_u32 s55, s55, 0x100
	s_addc_u32 s56, s56, 0
	s_add_u32 s12, s12, 0x100
	s_addc_u32 s13, s13, 0
	s_cmp_gt_u32 s57, 29
	s_cbranch_scc0 .LBB0_1104

; #define PG8_STAGE(bufoff, gbase, voff) do { _Pragma("unroll") for (int _i = 0; _i < 2; ++_i) \
;         dma16((const char*)(gbase), (voff)[_i], ldsb + (bufoff) + ldsw + _i * 8192); } while (0)
; #define PG8_LDA(dst, b, h) do { const int a1_ = opqv(aoff0) ^ 64; _Pragma("unroll") for (int m = 0; m < 4; ++m) { dst[m][0] = *(const LAS bf16x8*)(lds + PG8_SA(b, h) + aoff0 + m * 2048); dst[m][1] = *(const LAS bf16x8*)(lds + PG8_SA(b, h) + a1_ + m * 2048); } } while (0)
; #define PG8_LDB(dst, b, h) do { const int b1_ = opqv(boff0) ^ 64; _Pragma("unroll") for (int n = 0; n < 2; ++n) { dst[n][0] = *(const LAS bf16x8*)(lds + PG8_SB(b, h) + boff0 + n * 2048); dst[n][1] = *(const LAS bf16x8*)(lds + PG8_SB(b, h) + b1_ + n * 2048); } } while (0)
; #define PG8_MMA(ai, bj, At, Bt) do { __builtin_amdgcn_s_setprio(1); _Pragma("unroll") for (int m = 0; m < 4; ++m) _Pragma("unroll") for (int n = 0; n < 2; ++n) _Pragma("unroll") for (int k = 0; k < 2; ++k) \
;         acc[ai][bj][m][n] = __builtin_amdgcn_mfma_f32_16x16x32_bf16(Bt[n][k], At[m][k], acc[ai][bj][m][n], 0, 0, 0); __builtin_amdgcn_s_setprio(0); } while (0)
; template <class Epi>
; __device__ __forceinline__ void gemm_phase(LAS unsigned char* lds, const Gemm g, const StaticOrder& S, const Epi& E, int wave_) {
;     ...
;         const bool has_next = S.next(ui + 1, nxt);
;         const char* nA = has_next ? (const char*)g.A + (size_t)nxt.pm * tstepA : cA; const char* nB = has_next ? (const char*)g.Bt + (size_t)nxt.pn * tstepB : cB;
; #pragma unroll 1
;         for (int t = 0; t < nt; t += 2) {
;             const bool last = (t == nt - 2);
;             const char* a1 = cA + (size_t)(t + 1) * kstep;
;             const char* a2 = last ? nA : cA + (size_t)(t + 2) * kstep; const char* b2 = last ? nB : cB + (size_t)(t + 2) * kstep;
;             const char* a3 = a2 + kstep; const char* b3 = b2 + kstep;
;             PG8_STAGE(PG8_SA(1, 1), a1 + hstepA, voffA); PG8_LDB(B0, 0, 0); PG8_LDB(B1, 0, 1); PG8_SCHED; PG8_LDA(At, 0, 0);
;             PG8_WAIT_V(8); PG8_WAIT_L(0); PG8_BAR; PG8_MMA(0, 0, At, B0); PG8_MMA(0, 1, At, B1); PG8_BAR; PG8_SCHED;
;             PG8_STAGE(PG8_SB(0, 0), b2, voffB); PG8_STAGE(PG8_SB(0, 1), b2 + hstepB, voffB); PG8_STAGE(PG8_SA(0, 0), a2, voffA); PG8_LDA(At, 0, 1);
;             PG8_WAIT_V(8); PG8_WAIT_L(0); PG8_BAR; PG8_MMA(1, 0, At, B0); PG8_MMA(1, 1, At, B1); PG8_BAR; PG8_SCHED;
.LBB0_1321:
	s_ashr_i32 s25, s24, 31
	s_lshl_b64 s[16:17], s[24:25], 20
	s_add_u32 s26, s21, s16
	s_addc_u32 s27, s46, s17
	s_and_b64 s[16:17], s[42:43], exec
	s_cselect_b32 s16, s27, s37
	s_cselect_b32 s17, s26, s36
	s_ashr_i32 s19, s18, 31
	s_lshl_b64 s[30:31], s[18:19], 20
	s_add_u32 s30, s47, s30
	s_addc_u32 s31, s48, s31
	s_and_b64 s[40:41], s[42:43], exec
	s_cselect_b32 s19, s31, s13
	s_cselect_b32 s25, s30, s12
	s_add_u32 s55, s12, 0x100
	s_addc_u32 s56, s13, 0
	s_add_u32 s12, s36, 0x80080
	s_addc_u32 s13, s37, 0
	s_mov_b32 s57, -2
	s_add_u32 s36, s12, 0xfff80080
	s_addc_u32 s37, s13, -1
	s_cmp_eq_u32 s57, 28
	s_cselect_b32 s44, s17, s36
	s_cselect_b32 s45, s16, s37
	s_cselect_b32 s40, s25, s55
	s_cselect_b32 s41, s19, s56
	s_add_u32 s36, s44, 0x80
	v_mov_b32_e32 v128, v178
	s_addc_u32 s37, s45, 0
	v_add_u32_e32 v132, s23, v178
	v_xad_u32 v140, v128, 64, s23
	v_mov_b32_e32 v144, v178
	s_add_i32 s60, 0, 0x14000
	ds_read_b128 v[128:131], v132
	ds_read_b128 v[132:135], v132 offset:2048
	ds_read_b128 v[136:139], v140
	ds_read_b128 v[140:143], v140 offset:2048
	v_add_u32_e32 v148, s60, v178
	v_xad_u32 v156, v144, 64, s60
	ds_read_b128 v[144:147], v148
	ds_read_b128 v[148:151], v148 offset:2048
	ds_read_b128 v[152:155], v156
	ds_read_b128 v[156:159], v156 offset:2048
	v_mov_b32_e32 v160, v177
	v_add_u32_e32 v169, 0, v177
	v_xad_u32 v168, v160, 64, 0
	ds_read_b128 v[160:163], v169
	ds_read_b128 v[164:167], v169 offset:2048
	ds_read_b128 v[180:183], v168
	ds_read_b128 v[192:195], v168 offset:2048
	ds_read_b128 v[196:199], v169 offset:4096
	ds_read_b128 v[200:203], v169 offset:6144
	ds_read_b128 v[204:207], v168 offset:4096
	ds_read_b128 v[208:211], v168 offset:6144
	s_mov_b32 m0, s14
	s_nop 0
	global_load_lds_dwordx4 v172, s[12:13]
	s_mov_b32 m0, s15
	s_nop 0
	global_load_lds_dwordx4 v174, s[12:13]
	s_waitcnt vmcnt(8)
	s_waitcnt lgkmcnt(0)
	s_setprio 1
	s_barrier
	v_mfma_f32_16x16x32_bf16 v[124:127], v[128:131], v[160:163], 0
	v_mfma_f32_16x16x32_bf16 v[120:123], v[132:135], v[160:163], 0
	v_mfma_f32_16x16x32_bf16 v[108:111], v[128:131], v[164:167], 0
	v_mfma_f32_16x16x32_bf16 v[104:107], v[132:135], v[164:167], 0
	v_mfma_f32_16x16x32_bf16 v[92:95], v[128:131], v[196:199], 0
	v_mfma_f32_16x16x32_bf16 v[88:91], v[132:135], v[196:199], 0
	v_mfma_f32_16x16x32_bf16 v[76:79], v[128:131], v[200:203], 0
	v_mfma_f32_16x16x32_bf16 v[72:75], v[132:135], v[200:203], 0
	v_mfma_f32_16x16x32_bf16 v[124:127], v[136:139], v[180:183], v[124:127]
	v_mfma_f32_16x16x32_bf16 v[120:123], v[140:143], v[180:183], v[120:123]
	v_mfma_f32_16x16x32_bf16 v[108:111], v[136:139], v[192:195], v[108:111]
	v_mfma_f32_16x16x32_bf16 v[104:107], v[140:143], v[192:195], v[104:107]
	v_mfma_f32_16x16x32_bf16 v[92:95], v[136:139], v[204:207], v[92:95]
	v_mfma_f32_16x16x32_bf16 v[88:91], v[140:143], v[204:207], v[88:91]
	v_mfma_f32_16x16x32_bf16 v[76:79], v[136:139], v[208:211], v[76:79]
	v_mfma_f32_16x16x32_bf16 v[72:75], v[140:143], v[208:211], v[72:75]
	v_mfma_f32_16x16x32_bf16 v[116:119], v[144:147], v[160:163], 0
	v_mfma_f32_16x16x32_bf16 v[112:115], v[148:151], v[160:163], 0
	v_mfma_f32_16x16x32_bf16 v[100:103], v[144:147], v[164:167], 0
	v_mfma_f32_16x16x32_bf16 v[96:99], v[148:151], v[164:167], 0
	v_mfma_f32_16x16x32_bf16 v[84:87], v[144:147], v[196:199], 0
	v_mfma_f32_16x16x32_bf16 v[80:83], v[148:151], v[196:199], 0
	v_mfma_f32_16x16x32_bf16 v[68:71], v[144:147], v[200:203], 0
	v_mfma_f32_16x16x32_bf16 v[64:67], v[148:151], v[200:203], 0
	v_mfma_f32_16x16x32_bf16 v[116:119], v[152:155], v[180:183], v[116:119]
	v_mfma_f32_16x16x32_bf16 v[112:115], v[156:159], v[180:183], v[112:115]
	v_mfma_f32_16x16x32_bf16 v[100:103], v[152:155], v[192:195], v[100:103]
	v_mfma_f32_16x16x32_bf16 v[96:99], v[156:159], v[192:195], v[96:99]
	v_mfma_f32_16x16x32_bf16 v[84:87], v[152:155], v[204:207], v[84:87]
	v_mfma_f32_16x16x32_bf16 v[80:83], v[156:159], v[204:207], v[80:83]
	v_mfma_f32_16x16x32_bf16 v[68:71], v[152:155], v[208:211], v[68:71]
	v_mfma_f32_16x16x32_bf16 v[64:67], v[156:159], v[208:211], v[64:67]
	s_barrier
	s_setprio 0
	v_mov_b32_e32 v160, v177
	s_add_u32 s60, s40, 0x80000
	s_addc_u32 s61, s41, 0
	s_nop 0
	s_nop 0
	s_nop 0
	v_xad_u32 v168, v160, 64, 0
	ds_read_b128 v[160:163], v169 offset:16384
	ds_read_b128 v[164:167], v169 offset:18432
	ds_read_b128 v[180:183], v168 offset:16384
	ds_read_b128 v[192:195], v168 offset:18432
	ds_read_b128 v[196:199], v169 offset:20480
	ds_read_b128 v[200:203], v169 offset:22528
	ds_read_b128 v[204:207], v168 offset:20480
	ds_read_b128 v[208:211], v168 offset:22528
	s_mov_b32 m0, s80
	s_nop 0
	global_load_lds_dwordx4 v173, s[40:41]
	s_mov_b32 m0, s81
	s_nop 0
	global_load_lds_dwordx4 v175, s[40:41]
	s_mov_b32 m0, s29
	s_nop 0
	global_load_lds_dwordx4 v173, s[60:61]
	s_mov_b32 m0, s88
	s_nop 0
	global_load_lds_dwordx4 v175, s[60:61]
	s_mov_b32 m0, s76
	s_nop 0
	global_load_lds_dwordx4 v172, s[44:45]
	s_mov_b32 m0, s89
	s_nop 0
	global_load_lds_dwordx4 v174, s[44:45]
	s_waitcnt vmcnt(8)
	s_waitcnt lgkmcnt(0)
	s_setprio 1
	s_barrier
; #define PG8_STAGE(bufoff, gbase, voff) do { _Pragma("unroll") for (int _i = 0; _i < 2; ++_i) \
;         dma16((const char*)(gbase), (voff)[_i], ldsb + (bufoff) + ldsw + _i * 8192); } while (0)
; #define PG8_LDA(dst, b, h) do { const int a1_ = opqv(aoff0) ^ 64; _Pragma("unroll") for (int m = 0; m < 4; ++m) { dst[m][0] = *(const LAS bf16x8*)(lds + PG8_SA(b, h) + aoff0 + m * 2048); dst[m][1] = *(const LAS bf16x8*)(lds + PG8_SA(b, h) + a1_ + m * 2048); } } while (0)
; #define PG8_LDB(dst, b, h) do { const int b1_ = opqv(boff0) ^ 64; _Pragma("unroll") for (int n = 0; n < 2; ++n) { dst[n][0] = *(const LAS bf16x8*)(lds + PG8_SB(b, h) + boff0 + n * 2048); dst[n][1] = *(const LAS bf16x8*)(lds + PG8_SB(b, h) + b1_ + n * 2048); } } while (0)
; #define PG8_MMA(ai, bj, At, Bt) do { __builtin_amdgcn_s_setprio(1); _Pragma("unroll") for (int m = 0; m < 4; ++m) _Pragma("unroll") for (int n = 0; n < 2; ++n) _Pragma("unroll") for (int k = 0; k < 2; ++k) \
;         acc[ai][bj][m][n] = __builtin_amdgcn_mfma_f32_16x16x32_bf16(Bt[n][k], At[m][k], acc[ai][bj][m][n], 0, 0, 0); __builtin_amdgcn_s_setprio(0); } while (0)
; #define PG8_WAIT_V(n) asm volatile("s_waitcnt vmcnt(" #n ")" ::: "memory")
; #define PG8_WAIT_L(n) asm volatile("s_waitcnt lgkmcnt(" #n ")" ::: "memory")
; #define PG8_BAR __builtin_amdgcn_s_barrier()
; #define PG8_SCHED __builtin_amdgcn_sched_barrier(0)
; template <class Epi>
; __device__ __forceinline__ void gemm_phase(LAS unsigned char* lds, const Gemm g, const StaticOrder& S, const Epi& E, int wave_) {
;     ...
;             PG8_WAIT_V(8); PG8_WAIT_L(0); PG8_BAR; PG8_MMA(1, 0, At, B0); PG8_MMA(1, 1, At, B1); PG8_BAR; PG8_SCHED;
;             PG8_STAGE(PG8_SA(0, 1), a2 + hstepA, voffA); PG8_LDB(B0, 1, 0); PG8_LDB(B1, 1, 1); PG8_SCHED; PG8_LDA(At, 1, 0);
;             PG8_WAIT_V(8); PG8_WAIT_L(0); PG8_BAR; PG8_MMA(0, 0, At, B0); PG8_MMA(0, 1, At, B1); PG8_BAR; PG8_SCHED;
	v_mfma_f32_16x16x32_bf16 v[60:63], v[128:131], v[160:163], 0
	v_mfma_f32_16x16x32_bf16 v[56:59], v[132:135], v[160:163], 0
	v_mfma_f32_16x16x32_bf16 v[44:47], v[128:131], v[164:167], 0
	v_mfma_f32_16x16x32_bf16 v[40:43], v[132:135], v[164:167], 0
	v_mfma_f32_16x16x32_bf16 v[28:31], v[128:131], v[196:199], 0
	v_mfma_f32_16x16x32_bf16 v[24:27], v[132:135], v[196:199], 0
	v_mfma_f32_16x16x32_bf16 v[12:15], v[128:131], v[200:203], 0
	v_mfma_f32_16x16x32_bf16 v[8:11], v[132:135], v[200:203], 0
	v_mfma_f32_16x16x32_bf16 v[60:63], v[136:139], v[180:183], v[60:63]
	v_mfma_f32_16x16x32_bf16 v[56:59], v[140:143], v[180:183], v[56:59]
	v_mfma_f32_16x16x32_bf16 v[44:47], v[136:139], v[192:195], v[44:47]
	v_mfma_f32_16x16x32_bf16 v[40:43], v[140:143], v[192:195], v[40:43]
	v_mfma_f32_16x16x32_bf16 v[28:31], v[136:139], v[204:207], v[28:31]
	v_mfma_f32_16x16x32_bf16 v[24:27], v[140:143], v[204:207], v[24:27]
	v_mfma_f32_16x16x32_bf16 v[12:15], v[136:139], v[208:211], v[12:15]
	v_mfma_f32_16x16x32_bf16 v[8:11], v[140:143], v[208:211], v[8:11]
	v_mfma_f32_16x16x32_bf16 v[52:55], v[144:147], v[160:163], 0
	v_mfma_f32_16x16x32_bf16 v[48:51], v[148:151], v[160:163], 0
	v_mfma_f32_16x16x32_bf16 v[36:39], v[144:147], v[164:167], 0
	v_mfma_f32_16x16x32_bf16 v[32:35], v[148:151], v[164:167], 0
	v_mfma_f32_16x16x32_bf16 v[20:23], v[144:147], v[196:199], 0
	v_mfma_f32_16x16x32_bf16 v[16:19], v[148:151], v[196:199], 0
	v_mfma_f32_16x16x32_bf16 v[4:7], v[144:147], v[200:203], 0
	v_mfma_f32_16x16x32_bf16 v[0:3], v[148:151], v[200:203], 0
	v_mfma_f32_16x16x32_bf16 v[52:55], v[152:155], v[180:183], v[52:55]
	v_mfma_f32_16x16x32_bf16 v[48:51], v[156:159], v[180:183], v[48:51]
	v_mfma_f32_16x16x32_bf16 v[36:39], v[152:155], v[192:195], v[36:39]
	v_mfma_f32_16x16x32_bf16 v[32:35], v[156:159], v[192:195], v[32:35]
	v_mfma_f32_16x16x32_bf16 v[20:23], v[152:155], v[204:207], v[20:23]
	v_mfma_f32_16x16x32_bf16 v[16:19], v[156:159], v[204:207], v[16:19]
	v_mfma_f32_16x16x32_bf16 v[4:7], v[152:155], v[208:211], v[4:7]
	v_mfma_f32_16x16x32_bf16 v[0:3], v[156:159], v[208:211], v[0:3]
	s_barrier
	s_setprio 0
	s_add_u32 s44, s44, 0x80000
	s_addc_u32 s45, s45, 0
	s_mov_b32 m0, s1
	s_nop 0
	global_load_lds_dwordx4 v172, s[44:45]
	v_mov_b32_e32 v128, v178
	s_mov_b32 m0, s69
	s_nop 0
	global_load_lds_dwordx4 v174, s[44:45]
	v_add_u32_e32 v132, s34, v178
	v_xad_u32 v140, v128, 64, s34
	v_mov_b32_e32 v144, v178
	s_add_i32 s44, 0, 0x1c000
	ds_read_b128 v[128:131], v132
	ds_read_b128 v[132:135], v132 offset:2048
	ds_read_b128 v[136:139], v140
	ds_read_b128 v[140:143], v140 offset:2048
	v_add_u32_e32 v148, s44, v178
	v_xad_u32 v156, v144, 64, s44
	ds_read_b128 v[144:147], v148
	ds_read_b128 v[148:151], v148 offset:2048
	ds_read_b128 v[152:155], v156
	ds_read_b128 v[156:159], v156 offset:2048
	v_mov_b32_e32 v160, v177
	s_nop 0
	v_xad_u32 v168, v160, 64, 0
	ds_read_b128 v[160:163], v169 offset:32768
	ds_read_b128 v[164:167], v169 offset:34816
	ds_read_b128 v[180:183], v168 offset:32768
	ds_read_b128 v[192:195], v168 offset:34816
	ds_read_b128 v[196:199], v169 offset:36864
	ds_read_b128 v[200:203], v169 offset:38912
	ds_read_b128 v[204:207], v168 offset:36864
	ds_read_b128 v[208:211], v168 offset:38912
	s_waitcnt vmcnt(8)
	s_waitcnt lgkmcnt(0)
	s_setprio 1
	s_barrier
	v_mfma_f32_16x16x32_bf16 v[124:127], v[128:131], v[160:163], v[124:127]
	v_mfma_f32_16x16x32_bf16 v[120:123], v[132:135], v[160:163], v[120:123]
	v_mfma_f32_16x16x32_bf16 v[108:111], v[128:131], v[164:167], v[108:111]
	v_mfma_f32_16x16x32_bf16 v[104:107], v[132:135], v[164:167], v[104:107]
	v_mfma_f32_16x16x32_bf16 v[92:95], v[128:131], v[196:199], v[92:95]
	v_mfma_f32_16x16x32_bf16 v[88:91], v[132:135], v[196:199], v[88:91]
	v_mfma_f32_16x16x32_bf16 v[76:79], v[128:131], v[200:203], v[76:79]
	v_mfma_f32_16x16x32_bf16 v[72:75], v[132:135], v[200:203], v[72:75]
	v_mfma_f32_16x16x32_bf16 v[124:127], v[136:139], v[180:183], v[124:127]
	v_mfma_f32_16x16x32_bf16 v[120:123], v[140:143], v[180:183], v[120:123]
	v_mfma_f32_16x16x32_bf16 v[108:111], v[136:139], v[192:195], v[108:111]
	v_mfma_f32_16x16x32_bf16 v[104:107], v[140:143], v[192:195], v[104:107]
	v_mfma_f32_16x16x32_bf16 v[92:95], v[136:139], v[204:207], v[92:95]
	v_mfma_f32_16x16x32_bf16 v[88:91], v[140:143], v[204:207], v[88:91]
	v_mfma_f32_16x16x32_bf16 v[76:79], v[136:139], v[208:211], v[76:79]
	v_mfma_f32_16x16x32_bf16 v[72:75], v[140:143], v[208:211], v[72:75]
	v_mfma_f32_16x16x32_bf16 v[116:119], v[144:147], v[160:163], v[116:119]
	s_add_u32 s44, s40, 0x80
	s_addc_u32 s45, s41, 0
	v_mfma_f32_16x16x32_bf16 v[112:115], v[148:151], v[160:163], v[112:115]
	v_mfma_f32_16x16x32_bf16 v[100:103], v[144:147], v[164:167], v[100:103]
	v_mfma_f32_16x16x32_bf16 v[96:99], v[148:151], v[164:167], v[96:99]
	v_mfma_f32_16x16x32_bf16 v[84:87], v[144:147], v[196:199], v[84:87]
	v_mfma_f32_16x16x32_bf16 v[80:83], v[148:151], v[196:199], v[80:83]
	v_mfma_f32_16x16x32_bf16 v[68:71], v[144:147], v[200:203], v[68:71]
	v_mfma_f32_16x16x32_bf16 v[64:67], v[148:151], v[200:203], v[64:67]
	v_mfma_f32_16x16x32_bf16 v[116:119], v[152:155], v[180:183], v[116:119]
	v_mfma_f32_16x16x32_bf16 v[112:115], v[156:159], v[180:183], v[112:115]
	v_mfma_f32_16x16x32_bf16 v[100:103], v[152:155], v[192:195], v[100:103]
	v_mfma_f32_16x16x32_bf16 v[96:99], v[156:159], v[192:195], v[96:99]
	v_mfma_f32_16x16x32_bf16 v[84:87], v[152:155], v[204:207], v[84:87]
	v_mfma_f32_16x16x32_bf16 v[80:83], v[156:159], v[204:207], v[80:83]
	v_mfma_f32_16x16x32_bf16 v[68:71], v[152:155], v[208:211], v[68:71]
	v_mfma_f32_16x16x32_bf16 v[64:67], v[156:159], v[208:211], v[64:67]
	s_barrier
; #define PG8_STAGE(bufoff, gbase, voff) do { _Pragma("unroll") for (int _i = 0; _i < 2; ++_i) \
;         dma16((const char*)(gbase), (voff)[_i], ldsb + (bufoff) + ldsw + _i * 8192); } while (0)
; #define PG8_LDA(dst, b, h) do { const int a1_ = opqv(aoff0) ^ 64; _Pragma("unroll") for (int m = 0; m < 4; ++m) { dst[m][0] = *(const LAS bf16x8*)(lds + PG8_SA(b, h) + aoff0 + m * 2048); dst[m][1] = *(const LAS bf16x8*)(lds + PG8_SA(b, h) + a1_ + m * 2048); } } while (0)
; #define PG8_LDB(dst, b, h) do { const int b1_ = opqv(boff0) ^ 64; _Pragma("unroll") for (int n = 0; n < 2; ++n) { dst[n][0] = *(const LAS bf16x8*)(lds + PG8_SB(b, h) + boff0 + n * 2048); dst[n][1] = *(const LAS bf16x8*)(lds + PG8_SB(b, h) + b1_ + n * 2048); } } while (0)
; #define PG8_WAIT_V(n) asm volatile("s_waitcnt vmcnt(" #n ")" ::: "memory")
; template <class Epi>
; __device__ __forceinline__ void gemm_phase(LAS unsigned char* lds, const Gemm g, const StaticOrder& S, const Epi& E, int wave_) {
;     ...
;         for (int t = 0; t < nt; t += 2) {
;             const bool last = (t == nt - 2);
;             const char* a1 = cA + (size_t)(t + 1) * kstep;
;             const char* a2 = last ? nA : cA + (size_t)(t + 2) * kstep; const char* b2 = last ? nB : cB + (size_t)(t + 2) * kstep;
;             const char* a3 = a2 + kstep; const char* b3 = b2 + kstep;
;             PG8_STAGE(PG8_SA(1, 1), a1 + hstepA, voffA); PG8_LDB(B0, 0, 0); PG8_LDB(B1, 0, 1); PG8_SCHED; PG8_LDA(At, 0, 0);
;             PG8_WAIT_V(8); PG8_WAIT_L(0); PG8_BAR; PG8_MMA(0, 0, At, B0); PG8_MMA(0, 1, At, B1); PG8_BAR; PG8_SCHED;
;             PG8_STAGE(PG8_SB(0, 0), b2, voffB); PG8_STAGE(PG8_SB(0, 1), b2 + hstepB, voffB); PG8_STAGE(PG8_SA(0, 0), a2, voffA); PG8_LDA(At, 0, 1);
;             PG8_WAIT_V(8); PG8_WAIT_L(0); PG8_BAR; PG8_MMA(1, 0, At, B0); PG8_MMA(1, 1, At, B1); PG8_BAR; PG8_SCHED;
;             PG8_STAGE(PG8_SA(0, 1), a2 + hstepA, voffA); PG8_LDB(B0, 1, 0); PG8_LDB(B1, 1, 1); PG8_SCHED; PG8_LDA(At, 1, 0);
;             PG8_WAIT_V(8); PG8_WAIT_L(0); PG8_BAR; PG8_MMA(0, 0, At, B0); PG8_MMA(0, 1, At, B1); PG8_BAR; PG8_SCHED;
;             PG8_STAGE(PG8_SB(1, 0), b3, voffB); PG8_STAGE(PG8_SB(1, 1), b3 + hstepB, voffB); PG8_STAGE(PG8_SA(1, 0), a3, voffA); PG8_LDA(At, 1, 1);
;             PG8_WAIT_V(8); PG8_WAIT_L(0); PG8_BAR; PG8_MMA(1, 0, At, B0); PG8_MMA(1, 1, At, B1); PG8_BAR; PG8_SCHED;
	s_setprio 0
	s_add_u32 s40, s40, 0x80080
	s_addc_u32 s41, s41, 0
	v_mov_b32_e32 v160, v177
	s_nop 0
	s_nop 0
	v_xad_u32 v168, v160, 64, 0
	ds_read_b128 v[160:163], v169 offset:49152
	ds_read_b128 v[164:167], v169 offset:51200
	ds_read_b128 v[180:183], v168 offset:49152
	ds_read_b128 v[192:195], v168 offset:51200
	ds_read_b128 v[196:199], v169 offset:53248
	ds_read_b128 v[200:203], v169 offset:55296
	ds_read_b128 v[204:207], v168 offset:53248
	ds_read_b128 v[208:211], v168 offset:55296
	s_mov_b32 m0, s35
	s_nop 0
	global_load_lds_dwordx4 v173, s[44:45]
	s_mov_b32 m0, s33
	s_nop 0
	global_load_lds_dwordx4 v175, s[44:45]
	s_mov_b32 m0, s77
	s_nop 0
	global_load_lds_dwordx4 v173, s[40:41]
	s_mov_b32 m0, s3
	s_nop 0
	global_load_lds_dwordx4 v175, s[40:41]
	s_mov_b32 m0, s22
	s_nop 0
	global_load_lds_dwordx4 v172, s[36:37]
	s_mov_b32 m0, s2
	s_nop 0
	global_load_lds_dwordx4 v174, s[36:37]
	s_waitcnt vmcnt(8)
	s_waitcnt lgkmcnt(0)
	s_setprio 1
	s_barrier
	v_mfma_f32_16x16x32_bf16 v[60:63], v[128:131], v[160:163], v[60:63]
	v_mfma_f32_16x16x32_bf16 v[56:59], v[132:135], v[160:163], v[56:59]
	v_mfma_f32_16x16x32_bf16 v[44:47], v[128:131], v[164:167], v[44:47]
	v_mfma_f32_16x16x32_bf16 v[40:43], v[132:135], v[164:167], v[40:43]
	v_mfma_f32_16x16x32_bf16 v[28:31], v[128:131], v[196:199], v[28:31]
	v_mfma_f32_16x16x32_bf16 v[24:27], v[132:135], v[196:199], v[24:27]
	v_mfma_f32_16x16x32_bf16 v[12:15], v[128:131], v[200:203], v[12:15]
	v_mfma_f32_16x16x32_bf16 v[8:11], v[132:135], v[200:203], v[8:11]
	v_mfma_f32_16x16x32_bf16 v[60:63], v[136:139], v[180:183], v[60:63]
	v_mfma_f32_16x16x32_bf16 v[56:59], v[140:143], v[180:183], v[56:59]
	v_mfma_f32_16x16x32_bf16 v[44:47], v[136:139], v[192:195], v[44:47]
	v_mfma_f32_16x16x32_bf16 v[40:43], v[140:143], v[192:195], v[40:43]
	v_mfma_f32_16x16x32_bf16 v[28:31], v[136:139], v[204:207], v[28:31]
	v_mfma_f32_16x16x32_bf16 v[24:27], v[140:143], v[204:207], v[24:27]
	v_mfma_f32_16x16x32_bf16 v[12:15], v[136:139], v[208:211], v[12:15]
	v_mfma_f32_16x16x32_bf16 v[8:11], v[140:143], v[208:211], v[8:11]
	v_mfma_f32_16x16x32_bf16 v[52:55], v[144:147], v[160:163], v[52:55]
	v_mfma_f32_16x16x32_bf16 v[48:51], v[148:151], v[160:163], v[48:51]
	v_mfma_f32_16x16x32_bf16 v[36:39], v[144:147], v[164:167], v[36:39]
	v_mfma_f32_16x16x32_bf16 v[32:35], v[148:151], v[164:167], v[32:35]
	v_mfma_f32_16x16x32_bf16 v[20:23], v[144:147], v[196:199], v[20:23]
	v_mfma_f32_16x16x32_bf16 v[16:19], v[148:151], v[196:199], v[16:19]
	v_mfma_f32_16x16x32_bf16 v[4:7], v[144:147], v[200:203], v[4:7]
	v_mfma_f32_16x16x32_bf16 v[0:3], v[148:151], v[200:203], v[0:3]
	v_mfma_f32_16x16x32_bf16 v[52:55], v[152:155], v[180:183], v[52:55]
	v_mfma_f32_16x16x32_bf16 v[48:51], v[156:159], v[180:183], v[48:51]
	v_mfma_f32_16x16x32_bf16 v[36:39], v[152:155], v[192:195], v[36:39]
	v_mfma_f32_16x16x32_bf16 v[32:35], v[156:159], v[192:195], v[32:35]
	v_mfma_f32_16x16x32_bf16 v[20:23], v[152:155], v[204:207], v[20:23]
	v_mfma_f32_16x16x32_bf16 v[16:19], v[156:159], v[204:207], v[16:19]
	v_mfma_f32_16x16x32_bf16 v[4:7], v[152:155], v[208:211], v[4:7]
	v_mfma_f32_16x16x32_bf16 v[0:3], v[156:159], v[208:211], v[0:3]
	s_barrier
	s_setprio 0
	s_add_i32 s57, s57, 2
	s_add_u32 s55, s55, 0x100
	s_addc_u32 s56, s56, 0
	s_add_u32 s12, s12, 0x100
	s_addc_u32 s13, s13, 0
	s_cmp_gt_u32 s57, 29
	s_cbranch_scc0 .LBB0_1322
	s_branch .Lpeel_exit_3
.LBB0_1322:
	s_add_u32 s36, s12, 0xfff80080
	s_addc_u32 s37, s13, -1
	s_cmp_eq_u32 s57, 28
	s_cselect_b32 s44, s17, s36
	s_cselect_b32 s45, s16, s37
	s_cselect_b32 s40, s25, s55
	s_cselect_b32 s41, s19, s56
	s_add_u32 s36, s44, 0x80
	v_mov_b32_e32 v128, v178
	s_addc_u32 s37, s45, 0
	v_add_u32_e32 v132, s23, v178
	v_xad_u32 v140, v128, 64, s23
	v_mov_b32_e32 v144, v178
	s_add_i32 s60, 0, 0x14000
	ds_read_b128 v[128:131], v132
	ds_read_b128 v[132:135], v132 offset:2048
	ds_read_b128 v[136:139], v140
	ds_read_b128 v[140:143], v140 offset:2048
	v_add_u32_e32 v148, s60, v178
	v_xad_u32 v156, v144, 64, s60
	ds_read_b128 v[144:147], v148
	ds_read_b128 v[148:151], v148 offset:2048
	ds_read_b128 v[152:155], v156
	ds_read_b128 v[156:159], v156 offset:2048
	v_mov_b32_e32 v160, v177
	v_add_u32_e32 v169, 0, v177
	v_xad_u32 v168, v160, 64, 0
	ds_read_b128 v[160:163], v169
	ds_read_b128 v[164:167], v169 offset:2048
	ds_read_b128 v[180:183], v168
	ds_read_b128 v[192:195], v168 offset:2048
	ds_read_b128 v[196:199], v169 offset:4096
	ds_read_b128 v[200:203], v169 offset:6144
	ds_read_b128 v[204:207], v168 offset:4096
	ds_read_b128 v[208:211], v168 offset:6144
	s_mov_b32 m0, s14
	s_nop 0
	global_load_lds_dwordx4 v172, s[12:13]
	s_mov_b32 m0, s15
	s_nop 0
	global_load_lds_dwordx4 v174, s[12:13]
	s_waitcnt vmcnt(8)
	s_waitcnt lgkmcnt(0)
	s_setprio 1
	s_barrier
; #define PG8_STAGE(bufoff, gbase, voff) do { _Pragma("unroll") for (int _i = 0; _i < 2; ++_i) \
;         dma16((const char*)(gbase), (voff)[_i], ldsb + (bufoff) + ldsw + _i * 8192); } while (0)
; #define PG8_LDA(dst, b, h) do { const int a1_ = opqv(aoff0) ^ 64; _Pragma("unroll") for (int m = 0; m < 4; ++m) { dst[m][0] = *(const LAS bf16x8*)(lds + PG8_SA(b, h) + aoff0 + m * 2048); dst[m][1] = *(const LAS bf16x8*)(lds + PG8_SA(b, h) + a1_ + m * 2048); } } while (0)
; #define PG8_LDB(dst, b, h) do { const int b1_ = opqv(boff0) ^ 64; _Pragma("unroll") for (int n = 0; n < 2; ++n) { dst[n][0] = *(const LAS bf16x8*)(lds + PG8_SB(b, h) + boff0 + n * 2048); dst[n][1] = *(const LAS bf16x8*)(lds + PG8_SB(b, h) + b1_ + n * 2048); } } while (0)
; #define PG8_MMA(ai, bj, At, Bt) do { __builtin_amdgcn_s_setprio(1); _Pragma("unroll") for (int m = 0; m < 4; ++m) _Pragma("unroll") for (int n = 0; n < 2; ++n) _Pragma("unroll") for (int k = 0; k < 2; ++k) \
;         acc[ai][bj][m][n] = __builtin_amdgcn_mfma_f32_16x16x32_bf16(Bt[n][k], At[m][k], acc[ai][bj][m][n], 0, 0, 0); __builtin_amdgcn_s_setprio(0); } while (0)
; #define PG8_WAIT_V(n) asm volatile("s_waitcnt vmcnt(" #n ")" ::: "memory")
; #define PG8_WAIT_L(n) asm volatile("s_waitcnt lgkmcnt(" #n ")" ::: "memory")
; #define PG8_BAR __builtin_amdgcn_s_barrier()
; #define PG8_SCHED __builtin_amdgcn_sched_barrier(0)
; template <class Epi>
; __device__ __forceinline__ void gemm_phase(LAS unsigned char* lds, const Gemm g, const StaticOrder& S, const Epi& E, int wave_) {
;     ...
;             PG8_STAGE(PG8_SA(1, 1), a1 + hstepA, voffA); PG8_LDB(B0, 0, 0); PG8_LDB(B1, 0, 1); PG8_SCHED; PG8_LDA(At, 0, 0);
;             PG8_WAIT_V(8); PG8_WAIT_L(0); PG8_BAR; PG8_MMA(0, 0, At, B0); PG8_MMA(0, 1, At, B1); PG8_BAR; PG8_SCHED;
;             PG8_STAGE(PG8_SB(0, 0), b2, voffB); PG8_STAGE(PG8_SB(0, 1), b2 + hstepB, voffB); PG8_STAGE(PG8_SA(0, 0), a2, voffA); PG8_LDA(At, 0, 1);
;             PG8_WAIT_V(8); PG8_WAIT_L(0); PG8_BAR; PG8_MMA(1, 0, At, B0); PG8_MMA(1, 1, At, B1); PG8_BAR; PG8_SCHED;
	v_mfma_f32_16x16x32_bf16 v[124:127], v[128:131], v[160:163], v[124:127]
	v_mfma_f32_16x16x32_bf16 v[120:123], v[132:135], v[160:163], v[120:123]
	v_mfma_f32_16x16x32_bf16 v[108:111], v[128:131], v[164:167], v[108:111]
	v_mfma_f32_16x16x32_bf16 v[104:107], v[132:135], v[164:167], v[104:107]
	v_mfma_f32_16x16x32_bf16 v[92:95], v[128:131], v[196:199], v[92:95]
	v_mfma_f32_16x16x32_bf16 v[88:91], v[132:135], v[196:199], v[88:91]
	v_mfma_f32_16x16x32_bf16 v[76:79], v[128:131], v[200:203], v[76:79]
	v_mfma_f32_16x16x32_bf16 v[72:75], v[132:135], v[200:203], v[72:75]
	v_mfma_f32_16x16x32_bf16 v[124:127], v[136:139], v[180:183], v[124:127]
	v_mfma_f32_16x16x32_bf16 v[120:123], v[140:143], v[180:183], v[120:123]
	v_mfma_f32_16x16x32_bf16 v[108:111], v[136:139], v[192:195], v[108:111]
	v_mfma_f32_16x16x32_bf16 v[104:107], v[140:143], v[192:195], v[104:107]
	v_mfma_f32_16x16x32_bf16 v[92:95], v[136:139], v[204:207], v[92:95]
	v_mfma_f32_16x16x32_bf16 v[88:91], v[140:143], v[204:207], v[88:91]
	v_mfma_f32_16x16x32_bf16 v[76:79], v[136:139], v[208:211], v[76:79]
	v_mfma_f32_16x16x32_bf16 v[72:75], v[140:143], v[208:211], v[72:75]
	v_mfma_f32_16x16x32_bf16 v[116:119], v[144:147], v[160:163], v[116:119]
	v_mfma_f32_16x16x32_bf16 v[112:115], v[148:151], v[160:163], v[112:115]
	v_mfma_f32_16x16x32_bf16 v[100:103], v[144:147], v[164:167], v[100:103]
	v_mfma_f32_16x16x32_bf16 v[96:99], v[148:151], v[164:167], v[96:99]
	v_mfma_f32_16x16x32_bf16 v[84:87], v[144:147], v[196:199], v[84:87]
	v_mfma_f32_16x16x32_bf16 v[80:83], v[148:151], v[196:199], v[80:83]
	v_mfma_f32_16x16x32_bf16 v[68:71], v[144:147], v[200:203], v[68:71]
	v_mfma_f32_16x16x32_bf16 v[64:67], v[148:151], v[200:203], v[64:67]
	v_mfma_f32_16x16x32_bf16 v[116:119], v[152:155], v[180:183], v[116:119]
	v_mfma_f32_16x16x32_bf16 v[112:115], v[156:159], v[180:183], v[112:115]
	v_mfma_f32_16x16x32_bf16 v[100:103], v[152:155], v[192:195], v[100:103]
	v_mfma_f32_16x16x32_bf16 v[96:99], v[156:159], v[192:195], v[96:99]
	v_mfma_f32_16x16x32_bf16 v[84:87], v[152:155], v[204:207], v[84:87]
	v_mfma_f32_16x16x32_bf16 v[80:83], v[156:159], v[204:207], v[80:83]
	v_mfma_f32_16x16x32_bf16 v[68:71], v[152:155], v[208:211], v[68:71]
	v_mfma_f32_16x16x32_bf16 v[64:67], v[156:159], v[208:211], v[64:67]
	s_barrier
	s_setprio 0
	v_mov_b32_e32 v160, v177
	s_add_u32 s60, s40, 0x80000
	s_addc_u32 s61, s41, 0
	s_nop 0
	s_nop 0
	s_nop 0
	v_xad_u32 v168, v160, 64, 0
	ds_read_b128 v[160:163], v169 offset:16384
	ds_read_b128 v[164:167], v169 offset:18432
	ds_read_b128 v[180:183], v168 offset:16384
	ds_read_b128 v[192:195], v168 offset:18432
	ds_read_b128 v[196:199], v169 offset:20480
	ds_read_b128 v[200:203], v169 offset:22528
	ds_read_b128 v[204:207], v168 offset:20480
	ds_read_b128 v[208:211], v168 offset:22528
	s_mov_b32 m0, s80
	s_nop 0
	global_load_lds_dwordx4 v173, s[40:41]
	s_mov_b32 m0, s81
	s_nop 0
	global_load_lds_dwordx4 v175, s[40:41]
	s_mov_b32 m0, s29
	s_nop 0
	global_load_lds_dwordx4 v173, s[60:61]
	s_mov_b32 m0, s88
	s_nop 0
	global_load_lds_dwordx4 v175, s[60:61]
	s_mov_b32 m0, s76
	s_nop 0
	global_load_lds_dwordx4 v172, s[44:45]
	s_mov_b32 m0, s89
	s_nop 0
	global_load_lds_dwordx4 v174, s[44:45]
	s_waitcnt vmcnt(8)
	s_waitcnt lgkmcnt(0)
	s_setprio 1
	s_barrier
	v_mfma_f32_16x16x32_bf16 v[60:63], v[128:131], v[160:163], v[60:63]
	v_mfma_f32_16x16x32_bf16 v[56:59], v[132:135], v[160:163], v[56:59]
	v_mfma_f32_16x16x32_bf16 v[44:47], v[128:131], v[164:167], v[44:47]
	v_mfma_f32_16x16x32_bf16 v[40:43], v[132:135], v[164:167], v[40:43]
	v_mfma_f32_16x16x32_bf16 v[28:31], v[128:131], v[196:199], v[28:31]
	v_mfma_f32_16x16x32_bf16 v[24:27], v[132:135], v[196:199], v[24:27]
	v_mfma_f32_16x16x32_bf16 v[12:15], v[128:131], v[200:203], v[12:15]
	v_mfma_f32_16x16x32_bf16 v[8:11], v[132:135], v[200:203], v[8:11]
	v_mfma_f32_16x16x32_bf16 v[60:63], v[136:139], v[180:183], v[60:63]
	v_mfma_f32_16x16x32_bf16 v[56:59], v[140:143], v[180:183], v[56:59]
	v_mfma_f32_16x16x32_bf16 v[44:47], v[136:139], v[192:195], v[44:47]
	v_mfma_f32_16x16x32_bf16 v[40:43], v[140:143], v[192:195], v[40:43]
	v_mfma_f32_16x16x32_bf16 v[28:31], v[136:139], v[204:207], v[28:31]
	v_mfma_f32_16x16x32_bf16 v[24:27], v[140:143], v[204:207], v[24:27]
	v_mfma_f32_16x16x32_bf16 v[12:15], v[136:139], v[208:211], v[12:15]
	v_mfma_f32_16x16x32_bf16 v[8:11], v[140:143], v[208:211], v[8:11]
	v_mfma_f32_16x16x32_bf16 v[52:55], v[144:147], v[160:163], v[52:55]
	v_mfma_f32_16x16x32_bf16 v[48:51], v[148:151], v[160:163], v[48:51]
	v_mfma_f32_16x16x32_bf16 v[36:39], v[144:147], v[164:167], v[36:39]
	v_mfma_f32_16x16x32_bf16 v[32:35], v[148:151], v[164:167], v[32:35]
	v_mfma_f32_16x16x32_bf16 v[20:23], v[144:147], v[196:199], v[20:23]
	v_mfma_f32_16x16x32_bf16 v[16:19], v[148:151], v[196:199], v[16:19]
	v_mfma_f32_16x16x32_bf16 v[4:7], v[144:147], v[200:203], v[4:7]
	v_mfma_f32_16x16x32_bf16 v[0:3], v[148:151], v[200:203], v[0:3]
	v_mfma_f32_16x16x32_bf16 v[52:55], v[152:155], v[180:183], v[52:55]
	v_mfma_f32_16x16x32_bf16 v[48:51], v[156:159], v[180:183], v[48:51]
	v_mfma_f32_16x16x32_bf16 v[36:39], v[152:155], v[192:195], v[36:39]
	v_mfma_f32_16x16x32_bf16 v[32:35], v[156:159], v[192:195], v[32:35]
	v_mfma_f32_16x16x32_bf16 v[20:23], v[152:155], v[204:207], v[20:23]
	v_mfma_f32_16x16x32_bf16 v[16:19], v[156:159], v[204:207], v[16:19]
	v_mfma_f32_16x16x32_bf16 v[4:7], v[152:155], v[208:211], v[4:7]
	v_mfma_f32_16x16x32_bf16 v[0:3], v[156:159], v[208:211], v[0:3]
	s_barrier
; #define PG8_STAGE(bufoff, gbase, voff) do { _Pragma("unroll") for (int _i = 0; _i < 2; ++_i) \
;         dma16((const char*)(gbase), (voff)[_i], ldsb + (bufoff) + ldsw + _i * 8192); } while (0)
; #define PG8_LDA(dst, b, h) do { const int a1_ = opqv(aoff0) ^ 64; _Pragma("unroll") for (int m = 0; m < 4; ++m) { dst[m][0] = *(const LAS bf16x8*)(lds + PG8_SA(b, h) + aoff0 + m * 2048); dst[m][1] = *(const LAS bf16x8*)(lds + PG8_SA(b, h) + a1_ + m * 2048); } } while (0)
; #define PG8_LDB(dst, b, h) do { const int b1_ = opqv(boff0) ^ 64; _Pragma("unroll") for (int n = 0; n < 2; ++n) { dst[n][0] = *(const LAS bf16x8*)(lds + PG8_SB(b, h) + boff0 + n * 2048); dst[n][1] = *(const LAS bf16x8*)(lds + PG8_SB(b, h) + b1_ + n * 2048); } } while (0)
; #define PG8_MMA(ai, bj, At, Bt) do { __builtin_amdgcn_s_setprio(1); _Pragma("unroll") for (int m = 0; m < 4; ++m) _Pragma("unroll") for (int n = 0; n < 2; ++n) _Pragma("unroll") for (int k = 0; k < 2; ++k) \
;         acc[ai][bj][m][n] = __builtin_amdgcn_mfma_f32_16x16x32_bf16(Bt[n][k], At[m][k], acc[ai][bj][m][n], 0, 0, 0); __builtin_amdgcn_s_setprio(0); } while (0)
; #define PG8_WAIT_V(n) asm volatile("s_waitcnt vmcnt(" #n ")" ::: "memory")
; #define PG8_WAIT_L(n) asm volatile("s_waitcnt lgkmcnt(" #n ")" ::: "memory")
; #define PG8_BAR __builtin_amdgcn_s_barrier()
; #define PG8_SCHED __builtin_amdgcn_sched_barrier(0)
; template <class Epi>
; __device__ __forceinline__ void gemm_phase(LAS unsigned char* lds, const Gemm g, const StaticOrder& S, const Epi& E, int wave_) {
;     ...
;             PG8_STAGE(PG8_SA(0, 1), a2 + hstepA, voffA); PG8_LDB(B0, 1, 0); PG8_LDB(B1, 1, 1); PG8_SCHED; PG8_LDA(At, 1, 0);
;             PG8_WAIT_V(8); PG8_WAIT_L(0); PG8_BAR; PG8_MMA(0, 0, At, B0); PG8_MMA(0, 1, At, B1); PG8_BAR; PG8_SCHED;
;             PG8_STAGE(PG8_SB(1, 0), b3, voffB); PG8_STAGE(PG8_SB(1, 1), b3 + hstepB, voffB); PG8_STAGE(PG8_SA(1, 0), a3, voffA); PG8_LDA(At, 1, 1);
;             PG8_WAIT_V(8); PG8_WAIT_L(0); PG8_BAR; PG8_MMA(1, 0, At, B0); PG8_MMA(1, 1, At, B1); PG8_BAR; PG8_SCHED;
	s_setprio 0
	s_add_u32 s44, s44, 0x80000
	s_addc_u32 s45, s45, 0
	s_mov_b32 m0, s1
	s_nop 0
	global_load_lds_dwordx4 v172, s[44:45]
	v_mov_b32_e32 v128, v178
	s_mov_b32 m0, s69
	s_nop 0
	global_load_lds_dwordx4 v174, s[44:45]
	v_add_u32_e32 v132, s34, v178
	v_xad_u32 v140, v128, 64, s34
	v_mov_b32_e32 v144, v178
	s_add_i32 s44, 0, 0x1c000
	ds_read_b128 v[128:131], v132
	ds_read_b128 v[132:135], v132 offset:2048
	ds_read_b128 v[136:139], v140
	ds_read_b128 v[140:143], v140 offset:2048
	v_add_u32_e32 v148, s44, v178
	v_xad_u32 v156, v144, 64, s44
	ds_read_b128 v[144:147], v148
	ds_read_b128 v[148:151], v148 offset:2048
	ds_read_b128 v[152:155], v156
	ds_read_b128 v[156:159], v156 offset:2048
	v_mov_b32_e32 v160, v177
	s_nop 0
	v_xad_u32 v168, v160, 64, 0
	ds_read_b128 v[160:163], v169 offset:32768
	ds_read_b128 v[164:167], v169 offset:34816
	ds_read_b128 v[180:183], v168 offset:32768
	ds_read_b128 v[192:195], v168 offset:34816
	ds_read_b128 v[196:199], v169 offset:36864
	ds_read_b128 v[200:203], v169 offset:38912
	ds_read_b128 v[204:207], v168 offset:36864
	ds_read_b128 v[208:211], v168 offset:38912
	s_waitcnt vmcnt(8)
	s_waitcnt lgkmcnt(0)
	s_setprio 1
	s_barrier
	v_mfma_f32_16x16x32_bf16 v[124:127], v[128:131], v[160:163], v[124:127]
	v_mfma_f32_16x16x32_bf16 v[120:123], v[132:135], v[160:163], v[120:123]
	v_mfma_f32_16x16x32_bf16 v[108:111], v[128:131], v[164:167], v[108:111]
	v_mfma_f32_16x16x32_bf16 v[104:107], v[132:135], v[164:167], v[104:107]
	v_mfma_f32_16x16x32_bf16 v[92:95], v[128:131], v[196:199], v[92:95]
	v_mfma_f32_16x16x32_bf16 v[88:91], v[132:135], v[196:199], v[88:91]
	v_mfma_f32_16x16x32_bf16 v[76:79], v[128:131], v[200:203], v[76:79]
	v_mfma_f32_16x16x32_bf16 v[72:75], v[132:135], v[200:203], v[72:75]
	v_mfma_f32_16x16x32_bf16 v[124:127], v[136:139], v[180:183], v[124:127]
	v_mfma_f32_16x16x32_bf16 v[120:123], v[140:143], v[180:183], v[120:123]
	v_mfma_f32_16x16x32_bf16 v[108:111], v[136:139], v[192:195], v[108:111]
	v_mfma_f32_16x16x32_bf16 v[104:107], v[140:143], v[192:195], v[104:107]
	v_mfma_f32_16x16x32_bf16 v[92:95], v[136:139], v[204:207], v[92:95]
	v_mfma_f32_16x16x32_bf16 v[88:91], v[140:143], v[204:207], v[88:91]
	v_mfma_f32_16x16x32_bf16 v[76:79], v[136:139], v[208:211], v[76:79]
	v_mfma_f32_16x16x32_bf16 v[72:75], v[140:143], v[208:211], v[72:75]
	v_mfma_f32_16x16x32_bf16 v[116:119], v[144:147], v[160:163], v[116:119]
	s_add_u32 s44, s40, 0x80
	s_addc_u32 s45, s41, 0
	v_mfma_f32_16x16x32_bf16 v[112:115], v[148:151], v[160:163], v[112:115]
	v_mfma_f32_16x16x32_bf16 v[100:103], v[144:147], v[164:167], v[100:103]
	v_mfma_f32_16x16x32_bf16 v[96:99], v[148:151], v[164:167], v[96:99]
	v_mfma_f32_16x16x32_bf16 v[84:87], v[144:147], v[196:199], v[84:87]
	v_mfma_f32_16x16x32_bf16 v[80:83], v[148:151], v[196:199], v[80:83]
	v_mfma_f32_16x16x32_bf16 v[68:71], v[144:147], v[200:203], v[68:71]
	v_mfma_f32_16x16x32_bf16 v[64:67], v[148:151], v[200:203], v[64:67]
	v_mfma_f32_16x16x32_bf16 v[116:119], v[152:155], v[180:183], v[116:119]
	v_mfma_f32_16x16x32_bf16 v[112:115], v[156:159], v[180:183], v[112:115]
	v_mfma_f32_16x16x32_bf16 v[100:103], v[152:155], v[192:195], v[100:103]
	v_mfma_f32_16x16x32_bf16 v[96:99], v[156:159], v[192:195], v[96:99]
	v_mfma_f32_16x16x32_bf16 v[84:87], v[152:155], v[204:207], v[84:87]
	v_mfma_f32_16x16x32_bf16 v[80:83], v[156:159], v[204:207], v[80:83]
	v_mfma_f32_16x16x32_bf16 v[68:71], v[152:155], v[208:211], v[68:71]
	v_mfma_f32_16x16x32_bf16 v[64:67], v[156:159], v[208:211], v[64:67]
	s_barrier
	s_setprio 0
	s_add_u32 s40, s40, 0x80080
	s_addc_u32 s41, s41, 0
	v_mov_b32_e32 v160, v177
	s_nop 0
	s_nop 0
	v_xad_u32 v168, v160, 64, 0
	ds_read_b128 v[160:163], v169 offset:49152
	ds_read_b128 v[164:167], v169 offset:51200
	ds_read_b128 v[180:183], v168 offset:49152
	ds_read_b128 v[192:195], v168 offset:51200
	ds_read_b128 v[196:199], v169 offset:53248
	ds_read_b128 v[200:203], v169 offset:55296
	ds_read_b128 v[204:207], v168 offset:53248
	ds_read_b128 v[208:211], v168 offset:55296
	s_mov_b32 m0, s35
	s_nop 0
	global_load_lds_dwordx4 v173, s[44:45]
	s_mov_b32 m0, s33
	s_nop 0
	global_load_lds_dwordx4 v175, s[44:45]
	s_mov_b32 m0, s77
	s_nop 0
	global_load_lds_dwordx4 v173, s[40:41]
	s_mov_b32 m0, s3
	s_nop 0
	global_load_lds_dwordx4 v175, s[40:41]
	s_mov_b32 m0, s22
	s_nop 0
	global_load_lds_dwordx4 v172, s[36:37]
	s_mov_b32 m0, s2
	s_nop 0
	global_load_lds_dwordx4 v174, s[36:37]
	s_waitcnt vmcnt(8)
	s_waitcnt lgkmcnt(0)
	s_setprio 1
	s_barrier
	v_mfma_f32_16x16x32_bf16 v[60:63], v[128:131], v[160:163], v[60:63]
	v_mfma_f32_16x16x32_bf16 v[56:59], v[132:135], v[160:163], v[56:59]
	v_mfma_f32_16x16x32_bf16 v[44:47], v[128:131], v[164:167], v[44:47]
	v_mfma_f32_16x16x32_bf16 v[40:43], v[132:135], v[164:167], v[40:43]
	v_mfma_f32_16x16x32_bf16 v[28:31], v[128:131], v[196:199], v[28:31]
	v_mfma_f32_16x16x32_bf16 v[24:27], v[132:135], v[196:199], v[24:27]
	v_mfma_f32_16x16x32_bf16 v[12:15], v[128:131], v[200:203], v[12:15]
	v_mfma_f32_16x16x32_bf16 v[8:11], v[132:135], v[200:203], v[8:11]
	v_mfma_f32_16x16x32_bf16 v[60:63], v[136:139], v[180:183], v[60:63]
	v_mfma_f32_16x16x32_bf16 v[56:59], v[140:143], v[180:183], v[56:59]
	v_mfma_f32_16x16x32_bf16 v[44:47], v[136:139], v[192:195], v[44:47]
	v_mfma_f32_16x16x32_bf16 v[40:43], v[140:143], v[192:195], v[40:43]
	v_mfma_f32_16x16x32_bf16 v[28:31], v[136:139], v[204:207], v[28:31]
	v_mfma_f32_16x16x32_bf16 v[24:27], v[140:143], v[204:207], v[24:27]
	v_mfma_f32_16x16x32_bf16 v[12:15], v[136:139], v[208:211], v[12:15]
	v_mfma_f32_16x16x32_bf16 v[8:11], v[140:143], v[208:211], v[8:11]
	v_mfma_f32_16x16x32_bf16 v[52:55], v[144:147], v[160:163], v[52:55]
	v_mfma_f32_16x16x32_bf16 v[48:51], v[148:151], v[160:163], v[48:51]
	v_mfma_f32_16x16x32_bf16 v[36:39], v[144:147], v[164:167], v[36:39]
	v_mfma_f32_16x16x32_bf16 v[32:35], v[148:151], v[164:167], v[32:35]
	v_mfma_f32_16x16x32_bf16 v[20:23], v[144:147], v[196:199], v[20:23]
	v_mfma_f32_16x16x32_bf16 v[16:19], v[148:151], v[196:199], v[16:19]
	v_mfma_f32_16x16x32_bf16 v[4:7], v[144:147], v[200:203], v[4:7]
	v_mfma_f32_16x16x32_bf16 v[0:3], v[148:151], v[200:203], v[0:3]
	v_mfma_f32_16x16x32_bf16 v[52:55], v[152:155], v[180:183], v[52:55]
	v_mfma_f32_16x16x32_bf16 v[48:51], v[156:159], v[180:183], v[48:51]
	v_mfma_f32_16x16x32_bf16 v[36:39], v[152:155], v[192:195], v[36:39]
	v_mfma_f32_16x16x32_bf16 v[32:35], v[156:159], v[192:195], v[32:35]
	v_mfma_f32_16x16x32_bf16 v[20:23], v[152:155], v[204:207], v[20:23]
	v_mfma_f32_16x16x32_bf16 v[16:19], v[156:159], v[204:207], v[16:19]
	v_mfma_f32_16x16x32_bf16 v[4:7], v[152:155], v[208:211], v[4:7]
	v_mfma_f32_16x16x32_bf16 v[0:3], v[156:159], v[208:211], v[0:3]
	s_barrier
	s_setprio 0
	s_add_i32 s57, s57, 2
	s_add_u32 s55, s55, 0x100
	s_addc_u32 s56, s56, 0
	s_add_u32 s12, s12, 0x100
	s_addc_u32 s13, s13, 0
	s_cmp_gt_u32 s57, 29
	s_cbranch_scc0 .LBB0_1322

; #define PG8_STAGE(bufoff, gbase, voff) do { _Pragma("unroll") for (int _i = 0; _i < 2; ++_i) \
;         dma16((const char*)(gbase), (voff)[_i], ldsb + (bufoff) + ldsw + _i * 8192); } while (0)
; #define PG8_LDA(dst, b, h) do { const int a1_ = opqv(aoff0) ^ 64; _Pragma("unroll") for (int m = 0; m < 4; ++m) { dst[m][0] = *(const LAS bf16x8*)(lds + PG8_SA(b, h) + aoff0 + m * 2048); dst[m][1] = *(const LAS bf16x8*)(lds + PG8_SA(b, h) + a1_ + m * 2048); } } while (0)
; #define PG8_WAIT_V(n) asm volatile("s_waitcnt vmcnt(" #n ")" ::: "memory")
; #define PG8_BAR __builtin_amdgcn_s_barrier()
; template <class Epi>
; __device__ __forceinline__ void gemm_phase(LAS unsigned char* lds, const Gemm g, const StaticOrder& S, const Epi& E, int wave_) {
;     ...
;         const bool has_next = S.next(ui + 1, nxt);
;         const char* nA = has_next ? (const char*)g.A + (size_t)nxt.pm * tstepA : cA; const char* nB = has_next ? (const char*)g.Bt + (size_t)nxt.pn * tstepB : cB;
; #pragma unroll 1
;         for (int t = 0; t < nt; t += 2) {
;             const bool last = (t == nt - 2);
;             const char* a1 = cA + (size_t)(t + 1) * kstep;
;             const char* a2 = last ? nA : cA + (size_t)(t + 2) * kstep; const char* b2 = last ? nB : cB + (size_t)(t + 2) * kstep;
;             const char* a3 = a2 + kstep; const char* b3 = b2 + kstep;
;             PG8_STAGE(PG8_SA(1, 1), a1 + hstepA, voffA); PG8_LDB(B0, 0, 0); PG8_LDB(B1, 0, 1); PG8_SCHED; PG8_LDA(At, 0, 0);
;             PG8_WAIT_V(8); PG8_WAIT_L(0); PG8_BAR; PG8_MMA(0, 0, At, B0); PG8_MMA(0, 1, At, B1); PG8_BAR; PG8_SCHED;
;             PG8_STAGE(PG8_SB(0, 0), b2, voffB); PG8_STAGE(PG8_SB(0, 1), b2 + hstepB, voffB); PG8_STAGE(PG8_SA(0, 0), a2, voffA); PG8_LDA(At, 0, 1);
;             PG8_WAIT_V(8); PG8_WAIT_L(0); PG8_BAR; PG8_MMA(1, 0, At, B0); PG8_MMA(1, 1, At, B1); PG8_BAR; PG8_SCHED;
;             PG8_STAGE(PG8_SA(0, 1), a2 + hstepA, voffA); PG8_LDB(B0, 1, 0); PG8_LDB(B1, 1, 1); PG8_SCHED; PG8_LDA(At, 1, 0);
;             PG8_WAIT_V(8); PG8_WAIT_L(0); PG8_BAR; PG8_MMA(0, 0, At, B0); PG8_MMA(0, 1, At, B1); PG8_BAR; PG8_SCHED;
;             PG8_STAGE(PG8_SB(1, 0), b3, voffB); PG8_STAGE(PG8_SB(1, 1), b3 + hstepB, voffB); PG8_STAGE(PG8_SA(1, 0), a3, voffA); PG8_LDA(At, 1, 1);
;             PG8_WAIT_V(8); PG8_WAIT_L(0); PG8_BAR; PG8_MMA(1, 0, At, B0); PG8_MMA(1, 1, At, B1); PG8_BAR; PG8_SCHED;
.LBB0_1341:
	s_ashr_i32 s9, s8, 31
	s_lshl_b64 s[10:11], s[8:9], 17
	s_add_u32 s10, s16, s10
	s_addc_u32 s11, s17, s11
	s_and_b64 s[12:13], s[42:43], exec
	s_cselect_b32 s9, s11, s27
	s_cselect_b32 s61, s10, s26
	s_ashr_i32 s7, s6, 31
	s_lshl_b64 s[12:13], s[6:7], 17
	s_add_u32 s18, s21, s12
	s_addc_u32 s19, s52, s13
	s_and_b64 s[12:13], s[42:43], exec
	s_cselect_b32 s7, s19, s25
	s_cselect_b32 s62, s18, s24
	s_mov_b64 s[30:31], 0
	s_mov_b64 s[12:13], -1
	s_mov_b64 s[36:37], 0
	s_add_u32 s46, s26, s30
	s_addc_u32 s47, s27, s31
	s_add_u32 s44, s46, 0x100
	s_addc_u32 s45, s47, 0
	s_and_b64 s[40:41], s[36:37], exec
	s_cselect_b32 s45, s9, s45
	s_cselect_b32 s44, s61, s44
	s_add_u32 s30, s24, s30
	s_addc_u32 s31, s25, s31
	s_add_u32 s40, s30, 0x100
	s_addc_u32 s41, s31, 0
	s_add_u32 s30, s44, 0x80
	s_addc_u32 s31, s45, 0
	s_add_u32 s56, s46, 0x10080
	s_addc_u32 s57, s47, 0
	s_mov_b32 m0, s14
	s_nop 0
	global_load_lds_dwordx4 v130, s[56:57]
	v_mov_b32_e32 v128, v136
	s_mov_b32 m0, s15
	s_nop 0
	global_load_lds_dwordx4 v132, s[56:57]
	s_and_b64 s[36:37], s[36:37], exec
	v_xad_u32 v128, v128, 64, s23
	v_add_u32_e32 v129, s23, v136
	s_cselect_b32 s49, s7, s41
	s_cselect_b32 s48, s62, s40
	s_add_i32 s37, 0, 0x14000
	ds_read_b128 v[138:141], v129
	ds_read_b128 v[142:145], v129 offset:2048
	ds_read_b128 v[146:149], v128
	ds_read_b128 v[150:153], v128 offset:2048
	v_mov_b32_e32 v128, v136
	v_add_u32_e32 v129, s37, v136
	s_add_u32 s46, s48, 0x10000
	v_xad_u32 v128, v128, 64, s37
	ds_read_b128 v[154:157], v129
	ds_read_b128 v[158:161], v129 offset:2048
	ds_read_b128 v[162:165], v128
	ds_read_b128 v[166:169], v128 offset:2048
	s_addc_u32 s47, s49, 0
	s_add_u32 s40, s44, 0x10000
	s_addc_u32 s41, s45, 0
	s_add_i32 s63, 0, 0x1c000
	s_add_u32 s36, s48, 0x80
	s_addc_u32 s37, s49, 0
	s_add_u32 s56, s48, 0x10080
	s_addc_u32 s57, s49, 0
	v_mov_b32_e32 v128, v135
	v_add_u32_e32 v129, 0, v135
	v_xad_u32 v128, v128, 64, 0
	ds_read_b128 v[172:175], v129
	ds_read_b128 v[176:179], v129 offset:2048
	ds_read_b128 v[180:183], v128
	ds_read_b128 v[192:195], v128 offset:2048
	ds_read_b128 v[196:199], v129 offset:4096
	ds_read_b128 v[200:203], v129 offset:6144
	ds_read_b128 v[204:207], v128 offset:4096
	ds_read_b128 v[208:211], v128 offset:6144
	s_waitcnt vmcnt(8)
	s_waitcnt lgkmcnt(0)
	s_setprio 1
	s_barrier
	v_mfma_f32_16x16x32_bf16 v[124:127], v[138:141], v[172:175], 0
	v_mfma_f32_16x16x32_bf16 v[120:123], v[142:145], v[172:175], 0
	v_mfma_f32_16x16x32_bf16 v[116:119], v[138:141], v[176:179], 0
	v_mfma_f32_16x16x32_bf16 v[108:111], v[142:145], v[176:179], 0
	v_mfma_f32_16x16x32_bf16 v[100:103], v[138:141], v[196:199], 0
	v_mfma_f32_16x16x32_bf16 v[92:95], v[142:145], v[196:199], 0
	v_mfma_f32_16x16x32_bf16 v[84:87], v[138:141], v[200:203], 0
	v_mfma_f32_16x16x32_bf16 v[76:79], v[142:145], v[200:203], 0
	v_mfma_f32_16x16x32_bf16 v[124:127], v[146:149], v[180:183], v[124:127]
	v_mfma_f32_16x16x32_bf16 v[120:123], v[150:153], v[180:183], v[120:123]
	v_mfma_f32_16x16x32_bf16 v[116:119], v[146:149], v[192:195], v[116:119]
	v_mfma_f32_16x16x32_bf16 v[108:111], v[150:153], v[192:195], v[108:111]
	v_mfma_f32_16x16x32_bf16 v[100:103], v[146:149], v[204:207], v[100:103]
	v_mfma_f32_16x16x32_bf16 v[92:95], v[150:153], v[204:207], v[92:95]
	v_mfma_f32_16x16x32_bf16 v[84:87], v[146:149], v[208:211], v[84:87]
	v_mfma_f32_16x16x32_bf16 v[76:79], v[150:153], v[208:211], v[76:79]
	v_mfma_f32_16x16x32_bf16 v[112:115], v[154:157], v[172:175], 0
	v_mfma_f32_16x16x32_bf16 v[104:107], v[158:161], v[172:175], 0
	v_mfma_f32_16x16x32_bf16 v[96:99], v[154:157], v[176:179], 0
	v_mfma_f32_16x16x32_bf16 v[88:91], v[158:161], v[176:179], 0
	v_mfma_f32_16x16x32_bf16 v[80:83], v[154:157], v[196:199], 0
	v_mfma_f32_16x16x32_bf16 v[72:75], v[158:161], v[196:199], 0
	v_mfma_f32_16x16x32_bf16 v[68:71], v[154:157], v[200:203], 0
	v_mfma_f32_16x16x32_bf16 v[64:67], v[158:161], v[200:203], 0
	v_mfma_f32_16x16x32_bf16 v[112:115], v[162:165], v[180:183], v[112:115]
	v_mfma_f32_16x16x32_bf16 v[104:107], v[166:169], v[180:183], v[104:107]
	v_mfma_f32_16x16x32_bf16 v[96:99], v[162:165], v[192:195], v[96:99]
	v_mfma_f32_16x16x32_bf16 v[88:91], v[166:169], v[192:195], v[88:91]
	v_mfma_f32_16x16x32_bf16 v[80:83], v[162:165], v[204:207], v[80:83]
	v_mfma_f32_16x16x32_bf16 v[72:75], v[166:169], v[204:207], v[72:75]
	v_mfma_f32_16x16x32_bf16 v[68:71], v[162:165], v[208:211], v[68:71]
	v_mfma_f32_16x16x32_bf16 v[64:67], v[166:169], v[208:211], v[64:67]
	s_barrier
	s_setprio 0
	v_mov_b32_e32 v128, v135
	s_nop 0
	s_nop 0
	s_nop 0
	v_xad_u32 v128, v128, 64, 0
	ds_read_b128 v[172:175], v129 offset:16384
	ds_read_b128 v[176:179], v129 offset:18432
	ds_read_b128 v[180:183], v128 offset:16384
	ds_read_b128 v[192:195], v128 offset:18432
	ds_read_b128 v[196:199], v129 offset:20480
	ds_read_b128 v[200:203], v129 offset:22528
	ds_read_b128 v[204:207], v128 offset:20480
	ds_read_b128 v[208:211], v128 offset:22528
	s_mov_b32 m0, s80
	s_nop 0
	global_load_lds_dwordx4 v131, s[48:49]
	s_mov_b32 m0, s81
	s_nop 0
	global_load_lds_dwordx4 v133, s[48:49]
	s_mov_b32 m0, s29
	s_nop 0
	global_load_lds_dwordx4 v131, s[46:47]
	s_mov_b32 m0, s88
	s_nop 0
	global_load_lds_dwordx4 v133, s[46:47]
	s_mov_b32 m0, s76
	s_nop 0
	global_load_lds_dwordx4 v130, s[44:45]
	s_mov_b32 m0, s89
	s_nop 0
	global_load_lds_dwordx4 v132, s[44:45]
	s_waitcnt vmcnt(8)
	s_waitcnt lgkmcnt(0)
	s_setprio 1
	s_barrier
; #define PG8_STAGE(bufoff, gbase, voff) do { _Pragma("unroll") for (int _i = 0; _i < 2; ++_i) \
;         dma16((const char*)(gbase), (voff)[_i], ldsb + (bufoff) + ldsw + _i * 8192); } while (0)
; #define PG8_LDA(dst, b, h) do { const int a1_ = opqv(aoff0) ^ 64; _Pragma("unroll") for (int m = 0; m < 4; ++m) { dst[m][0] = *(const LAS bf16x8*)(lds + PG8_SA(b, h) + aoff0 + m * 2048); dst[m][1] = *(const LAS bf16x8*)(lds + PG8_SA(b, h) + a1_ + m * 2048); } } while (0)
; #define PG8_LDB(dst, b, h) do { const int b1_ = opqv(boff0) ^ 64; _Pragma("unroll") for (int n = 0; n < 2; ++n) { dst[n][0] = *(const LAS bf16x8*)(lds + PG8_SB(b, h) + boff0 + n * 2048); dst[n][1] = *(const LAS bf16x8*)(lds + PG8_SB(b, h) + b1_ + n * 2048); } } while (0)
; #define PG8_MMA(ai, bj, At, Bt) do { __builtin_amdgcn_s_setprio(1); _Pragma("unroll") for (int m = 0; m < 4; ++m) _Pragma("unroll") for (int n = 0; n < 2; ++n) _Pragma("unroll") for (int k = 0; k < 2; ++k) \
;         acc[ai][bj][m][n] = __builtin_amdgcn_mfma_f32_16x16x32_bf16(Bt[n][k], At[m][k], acc[ai][bj][m][n], 0, 0, 0); __builtin_amdgcn_s_setprio(0); } while (0)
; #define PG8_WAIT_V(n) asm volatile("s_waitcnt vmcnt(" #n ")" ::: "memory")
; #define PG8_WAIT_L(n) asm volatile("s_waitcnt lgkmcnt(" #n ")" ::: "memory")
; #define PG8_BAR __builtin_amdgcn_s_barrier()
; #define PG8_SCHED __builtin_amdgcn_sched_barrier(0)
; template <class Epi>
; __device__ __forceinline__ void gemm_phase(LAS unsigned char* lds, const Gemm g, const StaticOrder& S, const Epi& E, int wave_) {
;     ...
;             PG8_WAIT_V(8); PG8_WAIT_L(0); PG8_BAR; PG8_MMA(0, 0, At, B0); PG8_MMA(0, 1, At, B1); PG8_BAR; PG8_SCHED;
;             PG8_STAGE(PG8_SB(0, 0), b2, voffB); PG8_STAGE(PG8_SB(0, 1), b2 + hstepB, voffB); PG8_STAGE(PG8_SA(0, 0), a2, voffA); PG8_LDA(At, 0, 1);
;             PG8_WAIT_V(8); PG8_WAIT_L(0); PG8_BAR; PG8_MMA(1, 0, At, B0); PG8_MMA(1, 1, At, B1); PG8_BAR; PG8_SCHED;
;             PG8_STAGE(PG8_SA(0, 1), a2 + hstepA, voffA); PG8_LDB(B0, 1, 0); PG8_LDB(B1, 1, 1); PG8_SCHED; PG8_LDA(At, 1, 0);
;             PG8_WAIT_V(8); PG8_WAIT_L(0); PG8_BAR; PG8_MMA(0, 0, At, B0); PG8_MMA(0, 1, At, B1); PG8_BAR; PG8_SCHED;
	v_mfma_f32_16x16x32_bf16 v[60:63], v[138:141], v[172:175], 0
	v_mfma_f32_16x16x32_bf16 v[56:59], v[142:145], v[172:175], 0
	v_mfma_f32_16x16x32_bf16 v[52:55], v[138:141], v[176:179], 0
	v_mfma_f32_16x16x32_bf16 v[44:47], v[142:145], v[176:179], 0
	v_mfma_f32_16x16x32_bf16 v[36:39], v[138:141], v[196:199], 0
	v_mfma_f32_16x16x32_bf16 v[28:31], v[142:145], v[196:199], 0
	v_mfma_f32_16x16x32_bf16 v[20:23], v[138:141], v[200:203], 0
	v_mfma_f32_16x16x32_bf16 v[12:15], v[142:145], v[200:203], 0
	v_mfma_f32_16x16x32_bf16 v[60:63], v[146:149], v[180:183], v[60:63]
	v_mfma_f32_16x16x32_bf16 v[56:59], v[150:153], v[180:183], v[56:59]
	v_mfma_f32_16x16x32_bf16 v[52:55], v[146:149], v[192:195], v[52:55]
	v_mfma_f32_16x16x32_bf16 v[44:47], v[150:153], v[192:195], v[44:47]
	v_mfma_f32_16x16x32_bf16 v[36:39], v[146:149], v[204:207], v[36:39]
	v_mfma_f32_16x16x32_bf16 v[28:31], v[150:153], v[204:207], v[28:31]
	v_mfma_f32_16x16x32_bf16 v[20:23], v[146:149], v[208:211], v[20:23]
	v_mfma_f32_16x16x32_bf16 v[12:15], v[150:153], v[208:211], v[12:15]
	v_mfma_f32_16x16x32_bf16 v[48:51], v[154:157], v[172:175], 0
	v_mfma_f32_16x16x32_bf16 v[40:43], v[158:161], v[172:175], 0
	v_mfma_f32_16x16x32_bf16 v[32:35], v[154:157], v[176:179], 0
	v_mfma_f32_16x16x32_bf16 v[24:27], v[158:161], v[176:179], 0
	v_mfma_f32_16x16x32_bf16 v[16:19], v[154:157], v[196:199], 0
	v_mfma_f32_16x16x32_bf16 v[8:11], v[158:161], v[196:199], 0
	v_mfma_f32_16x16x32_bf16 v[4:7], v[154:157], v[200:203], 0
	v_mfma_f32_16x16x32_bf16 v[0:3], v[158:161], v[200:203], 0
	v_mfma_f32_16x16x32_bf16 v[48:51], v[162:165], v[180:183], v[48:51]
	v_mfma_f32_16x16x32_bf16 v[40:43], v[166:169], v[180:183], v[40:43]
	v_mfma_f32_16x16x32_bf16 v[32:35], v[162:165], v[192:195], v[32:35]
	v_mfma_f32_16x16x32_bf16 v[24:27], v[166:169], v[192:195], v[24:27]
	v_mfma_f32_16x16x32_bf16 v[16:19], v[162:165], v[204:207], v[16:19]
	v_mfma_f32_16x16x32_bf16 v[8:11], v[166:169], v[204:207], v[8:11]
	v_mfma_f32_16x16x32_bf16 v[4:7], v[162:165], v[208:211], v[4:7]
	v_mfma_f32_16x16x32_bf16 v[0:3], v[166:169], v[208:211], v[0:3]
	s_barrier
	s_setprio 0
	v_mov_b32_e32 v128, v136
	v_add_u32_e32 v142, s34, v136
	v_xad_u32 v128, v128, 64, s34
	ds_read_b128 v[138:141], v142
	ds_read_b128 v[142:145], v142 offset:2048
	ds_read_b128 v[146:149], v128
	ds_read_b128 v[150:153], v128 offset:2048
	v_mov_b32_e32 v128, v136
	v_add_u32_e32 v158, s63, v136
	v_xad_u32 v128, v128, 64, s63
	ds_read_b128 v[154:157], v158
	ds_read_b128 v[158:161], v158 offset:2048
	ds_read_b128 v[162:165], v128
	ds_read_b128 v[166:169], v128 offset:2048
	v_mov_b32_e32 v128, v135
	s_nop 0
	v_xad_u32 v128, v128, 64, 0
	ds_read_b128 v[172:175], v129 offset:32768
	ds_read_b128 v[176:179], v129 offset:34816
	ds_read_b128 v[180:183], v128 offset:32768
	ds_read_b128 v[192:195], v128 offset:34816
	ds_read_b128 v[196:199], v129 offset:36864
	ds_read_b128 v[200:203], v129 offset:38912
	ds_read_b128 v[204:207], v128 offset:36864
	ds_read_b128 v[208:211], v128 offset:38912
	s_mov_b32 m0, s1
	s_nop 0
	global_load_lds_dwordx4 v130, s[40:41]
	s_mov_b32 m0, s69
	s_nop 0
	global_load_lds_dwordx4 v132, s[40:41]
	s_waitcnt vmcnt(8)
	s_waitcnt lgkmcnt(0)
	s_setprio 1
	s_barrier
	v_mfma_f32_16x16x32_bf16 v[124:127], v[138:141], v[172:175], v[124:127]
	v_mfma_f32_16x16x32_bf16 v[120:123], v[142:145], v[172:175], v[120:123]
	v_mfma_f32_16x16x32_bf16 v[116:119], v[138:141], v[176:179], v[116:119]
	v_mfma_f32_16x16x32_bf16 v[108:111], v[142:145], v[176:179], v[108:111]
	v_mfma_f32_16x16x32_bf16 v[100:103], v[138:141], v[196:199], v[100:103]
	v_mfma_f32_16x16x32_bf16 v[92:95], v[142:145], v[196:199], v[92:95]
	v_mfma_f32_16x16x32_bf16 v[84:87], v[138:141], v[200:203], v[84:87]
	v_mfma_f32_16x16x32_bf16 v[76:79], v[142:145], v[200:203], v[76:79]
	v_mfma_f32_16x16x32_bf16 v[124:127], v[146:149], v[180:183], v[124:127]
	v_mfma_f32_16x16x32_bf16 v[120:123], v[150:153], v[180:183], v[120:123]
	v_mfma_f32_16x16x32_bf16 v[116:119], v[146:149], v[192:195], v[116:119]
	v_mfma_f32_16x16x32_bf16 v[108:111], v[150:153], v[192:195], v[108:111]
	v_mfma_f32_16x16x32_bf16 v[100:103], v[146:149], v[204:207], v[100:103]
	v_mfma_f32_16x16x32_bf16 v[92:95], v[150:153], v[204:207], v[92:95]
	v_mfma_f32_16x16x32_bf16 v[84:87], v[146:149], v[208:211], v[84:87]
	v_mfma_f32_16x16x32_bf16 v[76:79], v[150:153], v[208:211], v[76:79]
	v_mfma_f32_16x16x32_bf16 v[112:115], v[154:157], v[172:175], v[112:115]
	v_mfma_f32_16x16x32_bf16 v[104:107], v[158:161], v[172:175], v[104:107]
	v_mfma_f32_16x16x32_bf16 v[96:99], v[154:157], v[176:179], v[96:99]
	v_mfma_f32_16x16x32_bf16 v[88:91], v[158:161], v[176:179], v[88:91]
	v_mfma_f32_16x16x32_bf16 v[80:83], v[154:157], v[196:199], v[80:83]
	v_mfma_f32_16x16x32_bf16 v[72:75], v[158:161], v[196:199], v[72:75]
	v_mfma_f32_16x16x32_bf16 v[68:71], v[154:157], v[200:203], v[68:71]
	v_mfma_f32_16x16x32_bf16 v[64:67], v[158:161], v[200:203], v[64:67]
	v_mfma_f32_16x16x32_bf16 v[112:115], v[162:165], v[180:183], v[112:115]
	v_mfma_f32_16x16x32_bf16 v[104:107], v[166:169], v[180:183], v[104:107]
	v_mfma_f32_16x16x32_bf16 v[96:99], v[162:165], v[192:195], v[96:99]
	v_mfma_f32_16x16x32_bf16 v[88:91], v[166:169], v[192:195], v[88:91]
	v_mfma_f32_16x16x32_bf16 v[80:83], v[162:165], v[204:207], v[80:83]
	v_mfma_f32_16x16x32_bf16 v[72:75], v[166:169], v[204:207], v[72:75]
	v_mfma_f32_16x16x32_bf16 v[68:71], v[162:165], v[208:211], v[68:71]
	v_mfma_f32_16x16x32_bf16 v[64:67], v[166:169], v[208:211], v[64:67]
	s_barrier
; #define PG8_STAGE(bufoff, gbase, voff) do { _Pragma("unroll") for (int _i = 0; _i < 2; ++_i) \
;         dma16((const char*)(gbase), (voff)[_i], ldsb + (bufoff) + ldsw + _i * 8192); } while (0)
; #define PG8_LDA(dst, b, h) do { const int a1_ = opqv(aoff0) ^ 64; _Pragma("unroll") for (int m = 0; m < 4; ++m) { dst[m][0] = *(const LAS bf16x8*)(lds + PG8_SA(b, h) + aoff0 + m * 2048); dst[m][1] = *(const LAS bf16x8*)(lds + PG8_SA(b, h) + a1_ + m * 2048); } } while (0)
; #define PG8_WAIT_V(n) asm volatile("s_waitcnt vmcnt(" #n ")" ::: "memory")
; #define PG8_BAR __builtin_amdgcn_s_barrier()
; template <class Epi>
; __device__ __forceinline__ void gemm_phase(LAS unsigned char* lds, const Gemm g, const StaticOrder& S, const Epi& E, int wave_) {
;     ...
;         const bool has_next = S.next(ui + 1, nxt);
;         const char* nA = has_next ? (const char*)g.A + (size_t)nxt.pm * tstepA : cA; const char* nB = has_next ? (const char*)g.Bt + (size_t)nxt.pn * tstepB : cB;
; #pragma unroll 1
;         for (int t = 0; t < nt; t += 2) {
;             const bool last = (t == nt - 2);
;             const char* a1 = cA + (size_t)(t + 1) * kstep;
;             const char* a2 = last ? nA : cA + (size_t)(t + 2) * kstep; const char* b2 = last ? nB : cB + (size_t)(t + 2) * kstep;
;             const char* a3 = a2 + kstep; const char* b3 = b2 + kstep;
;             PG8_STAGE(PG8_SA(1, 1), a1 + hstepA, voffA); PG8_LDB(B0, 0, 0); PG8_LDB(B1, 0, 1); PG8_SCHED; PG8_LDA(At, 0, 0);
;             PG8_WAIT_V(8); PG8_WAIT_L(0); PG8_BAR; PG8_MMA(0, 0, At, B0); PG8_MMA(0, 1, At, B1); PG8_BAR; PG8_SCHED;
;             PG8_STAGE(PG8_SB(0, 0), b2, voffB); PG8_STAGE(PG8_SB(0, 1), b2 + hstepB, voffB); PG8_STAGE(PG8_SA(0, 0), a2, voffA); PG8_LDA(At, 0, 1);
;             PG8_WAIT_V(8); PG8_WAIT_L(0); PG8_BAR; PG8_MMA(1, 0, At, B0); PG8_MMA(1, 1, At, B1); PG8_BAR; PG8_SCHED;
;             PG8_STAGE(PG8_SA(0, 1), a2 + hstepA, voffA); PG8_LDB(B0, 1, 0); PG8_LDB(B1, 1, 1); PG8_SCHED; PG8_LDA(At, 1, 0);
;             PG8_WAIT_V(8); PG8_WAIT_L(0); PG8_BAR; PG8_MMA(0, 0, At, B0); PG8_MMA(0, 1, At, B1); PG8_BAR; PG8_SCHED;
;             PG8_STAGE(PG8_SB(1, 0), b3, voffB); PG8_STAGE(PG8_SB(1, 1), b3 + hstepB, voffB); PG8_STAGE(PG8_SA(1, 0), a3, voffA); PG8_LDA(At, 1, 1);
;             PG8_WAIT_V(8); PG8_WAIT_L(0); PG8_BAR; PG8_MMA(1, 0, At, B0); PG8_MMA(1, 1, At, B1); PG8_BAR; PG8_SCHED;
	s_setprio 0
	v_mov_b32_e32 v128, v135
	s_nop 0
	s_nop 0
	s_nop 0
	s_nop 0
	v_xad_u32 v128, v128, 64, 0
	ds_read_b128 v[172:175], v129 offset:49152
	ds_read_b128 v[176:179], v129 offset:51200
	ds_read_b128 v[180:183], v128 offset:49152
	ds_read_b128 v[192:195], v128 offset:51200
	ds_read_b128 v[196:199], v129 offset:53248
	ds_read_b128 v[200:203], v129 offset:55296
	ds_read_b128 v[204:207], v128 offset:53248
	ds_read_b128 v[208:211], v128 offset:55296
	s_mov_b32 m0, s35
	s_nop 0
	global_load_lds_dwordx4 v131, s[36:37]
	s_mov_b32 m0, s33
	s_nop 0
	global_load_lds_dwordx4 v133, s[36:37]
	s_mov_b32 m0, s77
	s_nop 0
	global_load_lds_dwordx4 v131, s[56:57]
	s_mov_b32 m0, s3
	s_nop 0
	global_load_lds_dwordx4 v133, s[56:57]
	s_mov_b32 m0, s22
	s_nop 0
	global_load_lds_dwordx4 v130, s[30:31]
	s_mov_b32 m0, s2
	s_nop 0
	global_load_lds_dwordx4 v132, s[30:31]
	s_waitcnt vmcnt(8)
	s_waitcnt lgkmcnt(0)
	s_setprio 1
	s_barrier
	v_mfma_f32_16x16x32_bf16 v[60:63], v[138:141], v[172:175], v[60:63]
	v_mfma_f32_16x16x32_bf16 v[56:59], v[142:145], v[172:175], v[56:59]
	v_mfma_f32_16x16x32_bf16 v[52:55], v[138:141], v[176:179], v[52:55]
	v_mfma_f32_16x16x32_bf16 v[44:47], v[142:145], v[176:179], v[44:47]
	v_mfma_f32_16x16x32_bf16 v[36:39], v[138:141], v[196:199], v[36:39]
	v_mfma_f32_16x16x32_bf16 v[28:31], v[142:145], v[196:199], v[28:31]
	v_mfma_f32_16x16x32_bf16 v[20:23], v[138:141], v[200:203], v[20:23]
	v_mfma_f32_16x16x32_bf16 v[12:15], v[142:145], v[200:203], v[12:15]
	v_mfma_f32_16x16x32_bf16 v[60:63], v[146:149], v[180:183], v[60:63]
	v_mfma_f32_16x16x32_bf16 v[56:59], v[150:153], v[180:183], v[56:59]
	v_mfma_f32_16x16x32_bf16 v[52:55], v[146:149], v[192:195], v[52:55]
	v_mfma_f32_16x16x32_bf16 v[44:47], v[150:153], v[192:195], v[44:47]
	v_mfma_f32_16x16x32_bf16 v[36:39], v[146:149], v[204:207], v[36:39]
	v_mfma_f32_16x16x32_bf16 v[28:31], v[150:153], v[204:207], v[28:31]
	v_mfma_f32_16x16x32_bf16 v[20:23], v[146:149], v[208:211], v[20:23]
	v_mfma_f32_16x16x32_bf16 v[12:15], v[150:153], v[208:211], v[12:15]
	v_mfma_f32_16x16x32_bf16 v[48:51], v[154:157], v[172:175], v[48:51]
	v_mfma_f32_16x16x32_bf16 v[40:43], v[158:161], v[172:175], v[40:43]
	v_mfma_f32_16x16x32_bf16 v[32:35], v[154:157], v[176:179], v[32:35]
	v_mfma_f32_16x16x32_bf16 v[24:27], v[158:161], v[176:179], v[24:27]
	v_mfma_f32_16x16x32_bf16 v[16:19], v[154:157], v[196:199], v[16:19]
	v_mfma_f32_16x16x32_bf16 v[8:11], v[158:161], v[196:199], v[8:11]
	v_mfma_f32_16x16x32_bf16 v[4:7], v[154:157], v[200:203], v[4:7]
	v_mfma_f32_16x16x32_bf16 v[0:3], v[158:161], v[200:203], v[0:3]
	v_mfma_f32_16x16x32_bf16 v[48:51], v[162:165], v[180:183], v[48:51]
	v_mfma_f32_16x16x32_bf16 v[40:43], v[166:169], v[180:183], v[40:43]
	v_mfma_f32_16x16x32_bf16 v[32:35], v[162:165], v[192:195], v[32:35]
	v_mfma_f32_16x16x32_bf16 v[24:27], v[166:169], v[192:195], v[24:27]
	v_mfma_f32_16x16x32_bf16 v[16:19], v[162:165], v[204:207], v[16:19]
	v_mfma_f32_16x16x32_bf16 v[8:11], v[166:169], v[204:207], v[8:11]
	v_mfma_f32_16x16x32_bf16 v[4:7], v[162:165], v[208:211], v[4:7]
	v_mfma_f32_16x16x32_bf16 v[0:3], v[166:169], v[208:211], v[0:3]
	s_barrier
	s_setprio 0
	s_andn2_b64 vcc, exec, s[12:13]
	s_mov_b64 s[36:37], -1
	s_mov_b64 s[12:13], 0
	s_mov_b64 s[30:31], 0x100
	s_cbranch_vccz .LBB0_1342
	s_branch .Lpeel_exit_2
.LBB0_1342:
	s_add_u32 s46, s26, s30
	s_addc_u32 s47, s27, s31
	s_add_u32 s44, s46, 0x100
	s_addc_u32 s45, s47, 0
	s_and_b64 s[40:41], s[36:37], exec
	s_cselect_b32 s45, s9, s45
	s_cselect_b32 s44, s61, s44
	s_add_u32 s30, s24, s30
	s_addc_u32 s31, s25, s31
	s_add_u32 s40, s30, 0x100
	s_addc_u32 s41, s31, 0
	s_add_u32 s30, s44, 0x80
	s_addc_u32 s31, s45, 0
	s_add_u32 s56, s46, 0x10080
	s_addc_u32 s57, s47, 0
	s_mov_b32 m0, s14
	s_nop 0
	global_load_lds_dwordx4 v130, s[56:57]
	v_mov_b32_e32 v128, v136
	s_mov_b32 m0, s15
	s_nop 0
	global_load_lds_dwordx4 v132, s[56:57]
	s_and_b64 s[36:37], s[36:37], exec
	v_xad_u32 v128, v128, 64, s23
	v_add_u32_e32 v129, s23, v136
	s_cselect_b32 s49, s7, s41
	s_cselect_b32 s48, s62, s40
	s_add_i32 s37, 0, 0x14000
	ds_read_b128 v[138:141], v129
	ds_read_b128 v[142:145], v129 offset:2048
	ds_read_b128 v[146:149], v128
	ds_read_b128 v[150:153], v128 offset:2048
	v_mov_b32_e32 v128, v136
	v_add_u32_e32 v129, s37, v136
	s_add_u32 s46, s48, 0x10000
	v_xad_u32 v128, v128, 64, s37
	ds_read_b128 v[154:157], v129
	ds_read_b128 v[158:161], v129 offset:2048
	ds_read_b128 v[162:165], v128
	ds_read_b128 v[166:169], v128 offset:2048
	s_addc_u32 s47, s49, 0
	s_add_u32 s40, s44, 0x10000
	s_addc_u32 s41, s45, 0
	s_add_i32 s63, 0, 0x1c000
	s_add_u32 s36, s48, 0x80
	s_addc_u32 s37, s49, 0
	s_add_u32 s56, s48, 0x10080
	s_addc_u32 s57, s49, 0
	v_mov_b32_e32 v128, v135
	v_add_u32_e32 v129, 0, v135
	v_xad_u32 v128, v128, 64, 0
	ds_read_b128 v[172:175], v129
	ds_read_b128 v[176:179], v129 offset:2048
	ds_read_b128 v[180:183], v128
	ds_read_b128 v[192:195], v128 offset:2048
	ds_read_b128 v[196:199], v129 offset:4096
	ds_read_b128 v[200:203], v129 offset:6144
	ds_read_b128 v[204:207], v128 offset:4096
	ds_read_b128 v[208:211], v128 offset:6144
	s_waitcnt vmcnt(8)
	s_waitcnt lgkmcnt(0)
	s_setprio 1
	s_barrier
; #define PG8_STAGE(bufoff, gbase, voff) do { _Pragma("unroll") for (int _i = 0; _i < 2; ++_i) \
;         dma16((const char*)(gbase), (voff)[_i], ldsb + (bufoff) + ldsw + _i * 8192); } while (0)
; #define PG8_LDA(dst, b, h) do { const int a1_ = opqv(aoff0) ^ 64; _Pragma("unroll") for (int m = 0; m < 4; ++m) { dst[m][0] = *(const LAS bf16x8*)(lds + PG8_SA(b, h) + aoff0 + m * 2048); dst[m][1] = *(const LAS bf16x8*)(lds + PG8_SA(b, h) + a1_ + m * 2048); } } while (0)
; #define PG8_MMA(ai, bj, At, Bt) do { __builtin_amdgcn_s_setprio(1); _Pragma("unroll") for (int m = 0; m < 4; ++m) _Pragma("unroll") for (int n = 0; n < 2; ++n) _Pragma("unroll") for (int k = 0; k < 2; ++k) \
;         acc[ai][bj][m][n] = __builtin_amdgcn_mfma_f32_16x16x32_bf16(Bt[n][k], At[m][k], acc[ai][bj][m][n], 0, 0, 0); __builtin_amdgcn_s_setprio(0); } while (0)
; #define PG8_WAIT_V(n) asm volatile("s_waitcnt vmcnt(" #n ")" ::: "memory")
; #define PG8_WAIT_L(n) asm volatile("s_waitcnt lgkmcnt(" #n ")" ::: "memory")
; #define PG8_BAR __builtin_amdgcn_s_barrier()
; #define PG8_SCHED __builtin_amdgcn_sched_barrier(0)
; template <class Epi>
; __device__ __forceinline__ void gemm_phase(LAS unsigned char* lds, const Gemm g, const StaticOrder& S, const Epi& E, int wave_) {
;     ...
;             PG8_WAIT_V(8); PG8_WAIT_L(0); PG8_BAR; PG8_MMA(0, 0, At, B0); PG8_MMA(0, 1, At, B1); PG8_BAR; PG8_SCHED;
;             PG8_STAGE(PG8_SB(0, 0), b2, voffB); PG8_STAGE(PG8_SB(0, 1), b2 + hstepB, voffB); PG8_STAGE(PG8_SA(0, 0), a2, voffA); PG8_LDA(At, 0, 1);
;             PG8_WAIT_V(8); PG8_WAIT_L(0); PG8_BAR; PG8_MMA(1, 0, At, B0); PG8_MMA(1, 1, At, B1); PG8_BAR; PG8_SCHED;
	v_mfma_f32_16x16x32_bf16 v[124:127], v[138:141], v[172:175], v[124:127]
	v_mfma_f32_16x16x32_bf16 v[120:123], v[142:145], v[172:175], v[120:123]
	v_mfma_f32_16x16x32_bf16 v[116:119], v[138:141], v[176:179], v[116:119]
	v_mfma_f32_16x16x32_bf16 v[108:111], v[142:145], v[176:179], v[108:111]
	v_mfma_f32_16x16x32_bf16 v[100:103], v[138:141], v[196:199], v[100:103]
	v_mfma_f32_16x16x32_bf16 v[92:95], v[142:145], v[196:199], v[92:95]
	v_mfma_f32_16x16x32_bf16 v[84:87], v[138:141], v[200:203], v[84:87]
	v_mfma_f32_16x16x32_bf16 v[76:79], v[142:145], v[200:203], v[76:79]
	v_mfma_f32_16x16x32_bf16 v[124:127], v[146:149], v[180:183], v[124:127]
	v_mfma_f32_16x16x32_bf16 v[120:123], v[150:153], v[180:183], v[120:123]
	v_mfma_f32_16x16x32_bf16 v[116:119], v[146:149], v[192:195], v[116:119]
	v_mfma_f32_16x16x32_bf16 v[108:111], v[150:153], v[192:195], v[108:111]
	v_mfma_f32_16x16x32_bf16 v[100:103], v[146:149], v[204:207], v[100:103]
	v_mfma_f32_16x16x32_bf16 v[92:95], v[150:153], v[204:207], v[92:95]
	v_mfma_f32_16x16x32_bf16 v[84:87], v[146:149], v[208:211], v[84:87]
	v_mfma_f32_16x16x32_bf16 v[76:79], v[150:153], v[208:211], v[76:79]
	v_mfma_f32_16x16x32_bf16 v[112:115], v[154:157], v[172:175], v[112:115]
	v_mfma_f32_16x16x32_bf16 v[104:107], v[158:161], v[172:175], v[104:107]
	v_mfma_f32_16x16x32_bf16 v[96:99], v[154:157], v[176:179], v[96:99]
	v_mfma_f32_16x16x32_bf16 v[88:91], v[158:161], v[176:179], v[88:91]
	v_mfma_f32_16x16x32_bf16 v[80:83], v[154:157], v[196:199], v[80:83]
	v_mfma_f32_16x16x32_bf16 v[72:75], v[158:161], v[196:199], v[72:75]
	v_mfma_f32_16x16x32_bf16 v[68:71], v[154:157], v[200:203], v[68:71]
	v_mfma_f32_16x16x32_bf16 v[64:67], v[158:161], v[200:203], v[64:67]
	v_mfma_f32_16x16x32_bf16 v[112:115], v[162:165], v[180:183], v[112:115]
	v_mfma_f32_16x16x32_bf16 v[104:107], v[166:169], v[180:183], v[104:107]
	v_mfma_f32_16x16x32_bf16 v[96:99], v[162:165], v[192:195], v[96:99]
	v_mfma_f32_16x16x32_bf16 v[88:91], v[166:169], v[192:195], v[88:91]
	v_mfma_f32_16x16x32_bf16 v[80:83], v[162:165], v[204:207], v[80:83]
	v_mfma_f32_16x16x32_bf16 v[72:75], v[166:169], v[204:207], v[72:75]
	v_mfma_f32_16x16x32_bf16 v[68:71], v[162:165], v[208:211], v[68:71]
	v_mfma_f32_16x16x32_bf16 v[64:67], v[166:169], v[208:211], v[64:67]
	s_barrier
	s_setprio 0
	v_mov_b32_e32 v128, v135
	s_nop 0
	s_nop 0
	s_nop 0
	v_xad_u32 v128, v128, 64, 0
	ds_read_b128 v[172:175], v129 offset:16384
	ds_read_b128 v[176:179], v129 offset:18432
	ds_read_b128 v[180:183], v128 offset:16384
	ds_read_b128 v[192:195], v128 offset:18432
	ds_read_b128 v[196:199], v129 offset:20480
	ds_read_b128 v[200:203], v129 offset:22528
	ds_read_b128 v[204:207], v128 offset:20480
	ds_read_b128 v[208:211], v128 offset:22528
	s_mov_b32 m0, s80
	s_nop 0
	global_load_lds_dwordx4 v131, s[48:49]
	s_mov_b32 m0, s81
	s_nop 0
	global_load_lds_dwordx4 v133, s[48:49]
	s_mov_b32 m0, s29
	s_nop 0
	global_load_lds_dwordx4 v131, s[46:47]
	s_mov_b32 m0, s88
	s_nop 0
	global_load_lds_dwordx4 v133, s[46:47]
	s_mov_b32 m0, s76
	s_nop 0
	global_load_lds_dwordx4 v130, s[44:45]
	s_mov_b32 m0, s89
	s_nop 0
	global_load_lds_dwordx4 v132, s[44:45]
	s_waitcnt vmcnt(8)
	s_waitcnt lgkmcnt(0)
	s_setprio 1
	s_barrier
	v_mfma_f32_16x16x32_bf16 v[60:63], v[138:141], v[172:175], v[60:63]
	v_mfma_f32_16x16x32_bf16 v[56:59], v[142:145], v[172:175], v[56:59]
	v_mfma_f32_16x16x32_bf16 v[52:55], v[138:141], v[176:179], v[52:55]
	v_mfma_f32_16x16x32_bf16 v[44:47], v[142:145], v[176:179], v[44:47]
	v_mfma_f32_16x16x32_bf16 v[36:39], v[138:141], v[196:199], v[36:39]
	v_mfma_f32_16x16x32_bf16 v[28:31], v[142:145], v[196:199], v[28:31]
	v_mfma_f32_16x16x32_bf16 v[20:23], v[138:141], v[200:203], v[20:23]
	v_mfma_f32_16x16x32_bf16 v[12:15], v[142:145], v[200:203], v[12:15]
	v_mfma_f32_16x16x32_bf16 v[60:63], v[146:149], v[180:183], v[60:63]
	v_mfma_f32_16x16x32_bf16 v[56:59], v[150:153], v[180:183], v[56:59]
	v_mfma_f32_16x16x32_bf16 v[52:55], v[146:149], v[192:195], v[52:55]
	v_mfma_f32_16x16x32_bf16 v[44:47], v[150:153], v[192:195], v[44:47]
	v_mfma_f32_16x16x32_bf16 v[36:39], v[146:149], v[204:207], v[36:39]
	v_mfma_f32_16x16x32_bf16 v[28:31], v[150:153], v[204:207], v[28:31]
	v_mfma_f32_16x16x32_bf16 v[20:23], v[146:149], v[208:211], v[20:23]
	v_mfma_f32_16x16x32_bf16 v[12:15], v[150:153], v[208:211], v[12:15]
	v_mfma_f32_16x16x32_bf16 v[48:51], v[154:157], v[172:175], v[48:51]
	v_mfma_f32_16x16x32_bf16 v[40:43], v[158:161], v[172:175], v[40:43]
	v_mfma_f32_16x16x32_bf16 v[32:35], v[154:157], v[176:179], v[32:35]
	v_mfma_f32_16x16x32_bf16 v[24:27], v[158:161], v[176:179], v[24:27]
	v_mfma_f32_16x16x32_bf16 v[16:19], v[154:157], v[196:199], v[16:19]
	v_mfma_f32_16x16x32_bf16 v[8:11], v[158:161], v[196:199], v[8:11]
	v_mfma_f32_16x16x32_bf16 v[4:7], v[154:157], v[200:203], v[4:7]
	v_mfma_f32_16x16x32_bf16 v[0:3], v[158:161], v[200:203], v[0:3]
	v_mfma_f32_16x16x32_bf16 v[48:51], v[162:165], v[180:183], v[48:51]
	v_mfma_f32_16x16x32_bf16 v[40:43], v[166:169], v[180:183], v[40:43]
	v_mfma_f32_16x16x32_bf16 v[32:35], v[162:165], v[192:195], v[32:35]
	v_mfma_f32_16x16x32_bf16 v[24:27], v[166:169], v[192:195], v[24:27]
	v_mfma_f32_16x16x32_bf16 v[16:19], v[162:165], v[204:207], v[16:19]
	v_mfma_f32_16x16x32_bf16 v[8:11], v[166:169], v[204:207], v[8:11]
	v_mfma_f32_16x16x32_bf16 v[4:7], v[162:165], v[208:211], v[4:7]
	v_mfma_f32_16x16x32_bf16 v[0:3], v[166:169], v[208:211], v[0:3]
	s_barrier
; #define PG8_STAGE(bufoff, gbase, voff) do { _Pragma("unroll") for (int _i = 0; _i < 2; ++_i) \
;         dma16((const char*)(gbase), (voff)[_i], ldsb + (bufoff) + ldsw + _i * 8192); } while (0)
; #define PG8_LDA(dst, b, h) do { const int a1_ = opqv(aoff0) ^ 64; _Pragma("unroll") for (int m = 0; m < 4; ++m) { dst[m][0] = *(const LAS bf16x8*)(lds + PG8_SA(b, h) + aoff0 + m * 2048); dst[m][1] = *(const LAS bf16x8*)(lds + PG8_SA(b, h) + a1_ + m * 2048); } } while (0)
; #define PG8_LDB(dst, b, h) do { const int b1_ = opqv(boff0) ^ 64; _Pragma("unroll") for (int n = 0; n < 2; ++n) { dst[n][0] = *(const LAS bf16x8*)(lds + PG8_SB(b, h) + boff0 + n * 2048); dst[n][1] = *(const LAS bf16x8*)(lds + PG8_SB(b, h) + b1_ + n * 2048); } } while (0)
; #define PG8_MMA(ai, bj, At, Bt) do { __builtin_amdgcn_s_setprio(1); _Pragma("unroll") for (int m = 0; m < 4; ++m) _Pragma("unroll") for (int n = 0; n < 2; ++n) _Pragma("unroll") for (int k = 0; k < 2; ++k) \
;         acc[ai][bj][m][n] = __builtin_amdgcn_mfma_f32_16x16x32_bf16(Bt[n][k], At[m][k], acc[ai][bj][m][n], 0, 0, 0); __builtin_amdgcn_s_setprio(0); } while (0)
; #define PG8_WAIT_V(n) asm volatile("s_waitcnt vmcnt(" #n ")" ::: "memory")
; #define PG8_WAIT_L(n) asm volatile("s_waitcnt lgkmcnt(" #n ")" ::: "memory")
; #define PG8_BAR __builtin_amdgcn_s_barrier()
; #define PG8_SCHED __builtin_amdgcn_sched_barrier(0)
; template <class Epi>
; __device__ __forceinline__ void gemm_phase(LAS unsigned char* lds, const Gemm g, const StaticOrder& S, const Epi& E, int wave_) {
;     ...
;             PG8_STAGE(PG8_SA(0, 1), a2 + hstepA, voffA); PG8_LDB(B0, 1, 0); PG8_LDB(B1, 1, 1); PG8_SCHED; PG8_LDA(At, 1, 0);
;             PG8_WAIT_V(8); PG8_WAIT_L(0); PG8_BAR; PG8_MMA(0, 0, At, B0); PG8_MMA(0, 1, At, B1); PG8_BAR; PG8_SCHED;
;             PG8_STAGE(PG8_SB(1, 0), b3, voffB); PG8_STAGE(PG8_SB(1, 1), b3 + hstepB, voffB); PG8_STAGE(PG8_SA(1, 0), a3, voffA); PG8_LDA(At, 1, 1);
;             PG8_WAIT_V(8); PG8_WAIT_L(0); PG8_BAR; PG8_MMA(1, 0, At, B0); PG8_MMA(1, 1, At, B1); PG8_BAR; PG8_SCHED;
	s_setprio 0
	v_mov_b32_e32 v128, v136
	v_add_u32_e32 v142, s34, v136
	v_xad_u32 v128, v128, 64, s34
	ds_read_b128 v[138:141], v142
	ds_read_b128 v[142:145], v142 offset:2048
	ds_read_b128 v[146:149], v128
	ds_read_b128 v[150:153], v128 offset:2048
	v_mov_b32_e32 v128, v136
	v_add_u32_e32 v158, s63, v136
	v_xad_u32 v128, v128, 64, s63
	ds_read_b128 v[154:157], v158
	ds_read_b128 v[158:161], v158 offset:2048
	ds_read_b128 v[162:165], v128
	ds_read_b128 v[166:169], v128 offset:2048
	v_mov_b32_e32 v128, v135
	s_nop 0
	v_xad_u32 v128, v128, 64, 0
	ds_read_b128 v[172:175], v129 offset:32768
	ds_read_b128 v[176:179], v129 offset:34816
	ds_read_b128 v[180:183], v128 offset:32768
	ds_read_b128 v[192:195], v128 offset:34816
	ds_read_b128 v[196:199], v129 offset:36864
	ds_read_b128 v[200:203], v129 offset:38912
	ds_read_b128 v[204:207], v128 offset:36864
	ds_read_b128 v[208:211], v128 offset:38912
	s_mov_b32 m0, s1
	s_nop 0
	global_load_lds_dwordx4 v130, s[40:41]
	s_mov_b32 m0, s69
	s_nop 0
	global_load_lds_dwordx4 v132, s[40:41]
	s_waitcnt vmcnt(8)
	s_waitcnt lgkmcnt(0)
	s_setprio 1
	s_barrier
	v_mfma_f32_16x16x32_bf16 v[124:127], v[138:141], v[172:175], v[124:127]
	v_mfma_f32_16x16x32_bf16 v[120:123], v[142:145], v[172:175], v[120:123]
	v_mfma_f32_16x16x32_bf16 v[116:119], v[138:141], v[176:179], v[116:119]
	v_mfma_f32_16x16x32_bf16 v[108:111], v[142:145], v[176:179], v[108:111]
	v_mfma_f32_16x16x32_bf16 v[100:103], v[138:141], v[196:199], v[100:103]
	v_mfma_f32_16x16x32_bf16 v[92:95], v[142:145], v[196:199], v[92:95]
	v_mfma_f32_16x16x32_bf16 v[84:87], v[138:141], v[200:203], v[84:87]
	v_mfma_f32_16x16x32_bf16 v[76:79], v[142:145], v[200:203], v[76:79]
	v_mfma_f32_16x16x32_bf16 v[124:127], v[146:149], v[180:183], v[124:127]
	v_mfma_f32_16x16x32_bf16 v[120:123], v[150:153], v[180:183], v[120:123]
	v_mfma_f32_16x16x32_bf16 v[116:119], v[146:149], v[192:195], v[116:119]
	v_mfma_f32_16x16x32_bf16 v[108:111], v[150:153], v[192:195], v[108:111]
	v_mfma_f32_16x16x32_bf16 v[100:103], v[146:149], v[204:207], v[100:103]
	v_mfma_f32_16x16x32_bf16 v[92:95], v[150:153], v[204:207], v[92:95]
	v_mfma_f32_16x16x32_bf16 v[84:87], v[146:149], v[208:211], v[84:87]
	v_mfma_f32_16x16x32_bf16 v[76:79], v[150:153], v[208:211], v[76:79]
	v_mfma_f32_16x16x32_bf16 v[112:115], v[154:157], v[172:175], v[112:115]
	v_mfma_f32_16x16x32_bf16 v[104:107], v[158:161], v[172:175], v[104:107]
	v_mfma_f32_16x16x32_bf16 v[96:99], v[154:157], v[176:179], v[96:99]
	v_mfma_f32_16x16x32_bf16 v[88:91], v[158:161], v[176:179], v[88:91]
	v_mfma_f32_16x16x32_bf16 v[80:83], v[154:157], v[196:199], v[80:83]
	v_mfma_f32_16x16x32_bf16 v[72:75], v[158:161], v[196:199], v[72:75]
	v_mfma_f32_16x16x32_bf16 v[68:71], v[154:157], v[200:203], v[68:71]
	v_mfma_f32_16x16x32_bf16 v[64:67], v[158:161], v[200:203], v[64:67]
	v_mfma_f32_16x16x32_bf16 v[112:115], v[162:165], v[180:183], v[112:115]
	v_mfma_f32_16x16x32_bf16 v[104:107], v[166:169], v[180:183], v[104:107]
	v_mfma_f32_16x16x32_bf16 v[96:99], v[162:165], v[192:195], v[96:99]
	v_mfma_f32_16x16x32_bf16 v[88:91], v[166:169], v[192:195], v[88:91]
	v_mfma_f32_16x16x32_bf16 v[80:83], v[162:165], v[204:207], v[80:83]
	v_mfma_f32_16x16x32_bf16 v[72:75], v[166:169], v[204:207], v[72:75]
	v_mfma_f32_16x16x32_bf16 v[68:71], v[162:165], v[208:211], v[68:71]
	v_mfma_f32_16x16x32_bf16 v[64:67], v[166:169], v[208:211], v[64:67]
	s_barrier
	s_setprio 0
	v_mov_b32_e32 v128, v135
	s_nop 0
	s_nop 0
	s_nop 0
	s_nop 0
	v_xad_u32 v128, v128, 64, 0
	ds_read_b128 v[172:175], v129 offset:49152
	ds_read_b128 v[176:179], v129 offset:51200
	ds_read_b128 v[180:183], v128 offset:49152
	ds_read_b128 v[192:195], v128 offset:51200
	ds_read_b128 v[196:199], v129 offset:53248
	ds_read_b128 v[200:203], v129 offset:55296
	ds_read_b128 v[204:207], v128 offset:53248
	ds_read_b128 v[208:211], v128 offset:55296
	s_mov_b32 m0, s35
	s_nop 0
	global_load_lds_dwordx4 v131, s[36:37]
	s_mov_b32 m0, s33
	s_nop 0
	global_load_lds_dwordx4 v133, s[36:37]
	s_mov_b32 m0, s77
	s_nop 0
	global_load_lds_dwordx4 v131, s[56:57]
	s_mov_b32 m0, s3
	s_nop 0
	global_load_lds_dwordx4 v133, s[56:57]
	s_mov_b32 m0, s22
	s_nop 0
	global_load_lds_dwordx4 v130, s[30:31]
	s_mov_b32 m0, s2
	s_nop 0
	global_load_lds_dwordx4 v132, s[30:31]
	s_waitcnt vmcnt(8)
	s_waitcnt lgkmcnt(0)
	s_setprio 1
	s_barrier
	v_mfma_f32_16x16x32_bf16 v[60:63], v[138:141], v[172:175], v[60:63]
	v_mfma_f32_16x16x32_bf16 v[56:59], v[142:145], v[172:175], v[56:59]
	v_mfma_f32_16x16x32_bf16 v[52:55], v[138:141], v[176:179], v[52:55]
	v_mfma_f32_16x16x32_bf16 v[44:47], v[142:145], v[176:179], v[44:47]
	v_mfma_f32_16x16x32_bf16 v[36:39], v[138:141], v[196:199], v[36:39]
	v_mfma_f32_16x16x32_bf16 v[28:31], v[142:145], v[196:199], v[28:31]
	v_mfma_f32_16x16x32_bf16 v[20:23], v[138:141], v[200:203], v[20:23]
	v_mfma_f32_16x16x32_bf16 v[12:15], v[142:145], v[200:203], v[12:15]
	v_mfma_f32_16x16x32_bf16 v[60:63], v[146:149], v[180:183], v[60:63]
	v_mfma_f32_16x16x32_bf16 v[56:59], v[150:153], v[180:183], v[56:59]
	v_mfma_f32_16x16x32_bf16 v[52:55], v[146:149], v[192:195], v[52:55]
	v_mfma_f32_16x16x32_bf16 v[44:47], v[150:153], v[192:195], v[44:47]
	v_mfma_f32_16x16x32_bf16 v[36:39], v[146:149], v[204:207], v[36:39]
	v_mfma_f32_16x16x32_bf16 v[28:31], v[150:153], v[204:207], v[28:31]
	v_mfma_f32_16x16x32_bf16 v[20:23], v[146:149], v[208:211], v[20:23]
	v_mfma_f32_16x16x32_bf16 v[12:15], v[150:153], v[208:211], v[12:15]
	v_mfma_f32_16x16x32_bf16 v[48:51], v[154:157], v[172:175], v[48:51]
	v_mfma_f32_16x16x32_bf16 v[40:43], v[158:161], v[172:175], v[40:43]
	v_mfma_f32_16x16x32_bf16 v[32:35], v[154:157], v[176:179], v[32:35]
	v_mfma_f32_16x16x32_bf16 v[24:27], v[158:161], v[176:179], v[24:27]
	v_mfma_f32_16x16x32_bf16 v[16:19], v[154:157], v[196:199], v[16:19]
	v_mfma_f32_16x16x32_bf16 v[8:11], v[158:161], v[196:199], v[8:11]
	v_mfma_f32_16x16x32_bf16 v[4:7], v[154:157], v[200:203], v[4:7]
	v_mfma_f32_16x16x32_bf16 v[0:3], v[158:161], v[200:203], v[0:3]
	v_mfma_f32_16x16x32_bf16 v[48:51], v[162:165], v[180:183], v[48:51]
	v_mfma_f32_16x16x32_bf16 v[40:43], v[166:169], v[180:183], v[40:43]
	v_mfma_f32_16x16x32_bf16 v[32:35], v[162:165], v[192:195], v[32:35]
	v_mfma_f32_16x16x32_bf16 v[24:27], v[166:169], v[192:195], v[24:27]
	v_mfma_f32_16x16x32_bf16 v[16:19], v[162:165], v[204:207], v[16:19]
	v_mfma_f32_16x16x32_bf16 v[8:11], v[166:169], v[204:207], v[8:11]
	v_mfma_f32_16x16x32_bf16 v[4:7], v[162:165], v[208:211], v[4:7]
	v_mfma_f32_16x16x32_bf16 v[0:3], v[166:169], v[208:211], v[0:3]
	s_barrier
	s_setprio 0
	s_andn2_b64 vcc, exec, s[12:13]
	s_mov_b64 s[36:37], -1
	s_mov_b64 s[12:13], 0
	s_mov_b64 s[30:31], 0x100
	s_cbranch_vccz .LBB0_1342

; #define PG8_STAGE(bufoff, gbase, voff) do { _Pragma("unroll") for (int _i = 0; _i < 2; ++_i) \
;         dma16((const char*)(gbase), (voff)[_i], ldsb + (bufoff) + ldsw + _i * 8192); } while (0)
; #define PG8_LDA(dst, b, h) do { const int a1_ = opqv(aoff0) ^ 64; _Pragma("unroll") for (int m = 0; m < 4; ++m) { dst[m][0] = *(const LAS bf16x8*)(lds + PG8_SA(b, h) + aoff0 + m * 2048); dst[m][1] = *(const LAS bf16x8*)(lds + PG8_SA(b, h) + a1_ + m * 2048); } } while (0)
; #define PG8_WAIT_V(n) asm volatile("s_waitcnt vmcnt(" #n ")" ::: "memory")
; #define PG8_BAR __builtin_amdgcn_s_barrier()
; template <class Epi>
; __device__ __forceinline__ void gemm_phase(LAS unsigned char* lds, const Gemm g, const StaticOrder& S, const Epi& E, int wave_) {
;     ...
;         const bool has_next = S.next(ui + 1, nxt);
;         const char* nA = has_next ? (const char*)g.A + (size_t)nxt.pm * tstepA : cA; const char* nB = has_next ? (const char*)g.Bt + (size_t)nxt.pn * tstepB : cB;
; #pragma unroll 1
;         for (int t = 0; t < nt; t += 2) {
;             const bool last = (t == nt - 2);
;             const char* a1 = cA + (size_t)(t + 1) * kstep;
;             const char* a2 = last ? nA : cA + (size_t)(t + 2) * kstep; const char* b2 = last ? nB : cB + (size_t)(t + 2) * kstep;
;             const char* a3 = a2 + kstep; const char* b3 = b2 + kstep;
;             PG8_STAGE(PG8_SA(1, 1), a1 + hstepA, voffA); PG8_LDB(B0, 0, 0); PG8_LDB(B1, 0, 1); PG8_SCHED; PG8_LDA(At, 0, 0);
;             PG8_WAIT_V(8); PG8_WAIT_L(0); PG8_BAR; PG8_MMA(0, 0, At, B0); PG8_MMA(0, 1, At, B1); PG8_BAR; PG8_SCHED;
;             PG8_STAGE(PG8_SB(0, 0), b2, voffB); PG8_STAGE(PG8_SB(0, 1), b2 + hstepB, voffB); PG8_STAGE(PG8_SA(0, 0), a2, voffA); PG8_LDA(At, 0, 1);
;             PG8_WAIT_V(8); PG8_WAIT_L(0); PG8_BAR; PG8_MMA(1, 0, At, B0); PG8_MMA(1, 1, At, B1); PG8_BAR; PG8_SCHED;
;             PG8_STAGE(PG8_SA(0, 1), a2 + hstepA, voffA); PG8_LDB(B0, 1, 0); PG8_LDB(B1, 1, 1); PG8_SCHED; PG8_LDA(At, 1, 0);
;             PG8_WAIT_V(8); PG8_WAIT_L(0); PG8_BAR; PG8_MMA(0, 0, At, B0); PG8_MMA(0, 1, At, B1); PG8_BAR; PG8_SCHED;
;             PG8_STAGE(PG8_SB(1, 0), b3, voffB); PG8_STAGE(PG8_SB(1, 1), b3 + hstepB, voffB); PG8_STAGE(PG8_SA(1, 0), a3, voffA); PG8_LDA(At, 1, 1);
;             PG8_WAIT_V(8); PG8_WAIT_L(0); PG8_BAR; PG8_MMA(1, 0, At, B0); PG8_MMA(1, 1, At, B1); PG8_BAR; PG8_SCHED;
.LBB0_1551:
	s_add_u32 s16, s12, 0x100
	s_addc_u32 s17, s13, 0
	s_add_u32 s12, s36, 0x160080
	s_addc_u32 s13, s37, 0
	s_mov_b32 s59, -2
	s_add_u32 s36, s12, 0xffea0080
	s_addc_u32 s37, s13, -1
	s_cmpk_eq_i32 s59, 0x54
	s_cselect_b32 s46, s26, s36
	s_cselect_b32 s47, s27, s37
	s_cselect_b32 s40, s30, s16
	s_cselect_b32 s41, s31, s17
	s_add_u32 s36, s46, 0x80
	v_mov_b32_e32 v64, v219
	s_addc_u32 s37, s47, 0
	v_add_u32_e32 v68, s23, v219
	v_xad_u32 v76, v64, 64, s23
	v_mov_b32_e32 v80, v219
	s_add_i32 s60, 0, 0x14000
	ds_read_b128 v[64:67], v68
	ds_read_b128 v[68:71], v68 offset:2048
	ds_read_b128 v[72:75], v76
	ds_read_b128 v[76:79], v76 offset:2048
	v_add_u32_e32 v84, s60, v219
	v_xad_u32 v92, v80, 64, s60
	ds_read_b128 v[80:83], v84
	ds_read_b128 v[84:87], v84 offset:2048
	ds_read_b128 v[88:91], v92
	ds_read_b128 v[92:95], v92 offset:2048
	v_mov_b32_e32 v160, v218
	v_add_u32_e32 v191, 0, v218
	v_xad_u32 v190, v160, 64, 0
	ds_read_b128 v[160:163], v191
	ds_read_b128 v[164:167], v191 offset:2048
	ds_read_b128 v[168:171], v190
	ds_read_b128 v[172:175], v190 offset:2048
	ds_read_b128 v[176:179], v191 offset:4096
	ds_read_b128 v[180:183], v191 offset:6144
	ds_read_b128 v[192:195], v190 offset:4096
	ds_read_b128 v[196:199], v190 offset:6144
	s_mov_b32 m0, s14
	s_nop 0
	global_load_lds_dwordx4 v184, s[12:13]
	s_mov_b32 m0, s15
	s_nop 0
	global_load_lds_dwordx4 v215, s[12:13]
	s_waitcnt vmcnt(8)
	s_waitcnt lgkmcnt(0)
	s_setprio 1
	s_barrier
	v_mfma_f32_16x16x32_bf16 v[156:159], v[64:67], v[160:163], 0
	v_mfma_f32_16x16x32_bf16 v[152:155], v[68:71], v[160:163], 0
	v_mfma_f32_16x16x32_bf16 v[140:143], v[64:67], v[164:167], 0
	v_mfma_f32_16x16x32_bf16 v[136:139], v[68:71], v[164:167], 0
	v_mfma_f32_16x16x32_bf16 v[124:127], v[64:67], v[176:179], 0
	v_mfma_f32_16x16x32_bf16 v[120:123], v[68:71], v[176:179], 0
	v_mfma_f32_16x16x32_bf16 v[108:111], v[64:67], v[180:183], 0
	v_mfma_f32_16x16x32_bf16 v[104:107], v[68:71], v[180:183], 0
	v_mfma_f32_16x16x32_bf16 v[156:159], v[72:75], v[168:171], v[156:159]
	v_mfma_f32_16x16x32_bf16 v[152:155], v[76:79], v[168:171], v[152:155]
	v_mfma_f32_16x16x32_bf16 v[140:143], v[72:75], v[172:175], v[140:143]
	v_mfma_f32_16x16x32_bf16 v[136:139], v[76:79], v[172:175], v[136:139]
	v_mfma_f32_16x16x32_bf16 v[124:127], v[72:75], v[192:195], v[124:127]
	v_mfma_f32_16x16x32_bf16 v[120:123], v[76:79], v[192:195], v[120:123]
	v_mfma_f32_16x16x32_bf16 v[108:111], v[72:75], v[196:199], v[108:111]
	v_mfma_f32_16x16x32_bf16 v[104:107], v[76:79], v[196:199], v[104:107]
	v_mfma_f32_16x16x32_bf16 v[148:151], v[80:83], v[160:163], 0
	v_mfma_f32_16x16x32_bf16 v[144:147], v[84:87], v[160:163], 0
	v_mfma_f32_16x16x32_bf16 v[132:135], v[80:83], v[164:167], 0
	v_mfma_f32_16x16x32_bf16 v[128:131], v[84:87], v[164:167], 0
	v_mfma_f32_16x16x32_bf16 v[116:119], v[80:83], v[176:179], 0
	v_mfma_f32_16x16x32_bf16 v[112:115], v[84:87], v[176:179], 0
	v_mfma_f32_16x16x32_bf16 v[100:103], v[80:83], v[180:183], 0
	v_mfma_f32_16x16x32_bf16 v[96:99], v[84:87], v[180:183], 0
	v_mfma_f32_16x16x32_bf16 v[148:151], v[88:91], v[168:171], v[148:151]
	v_mfma_f32_16x16x32_bf16 v[144:147], v[92:95], v[168:171], v[144:147]
	v_mfma_f32_16x16x32_bf16 v[132:135], v[88:91], v[172:175], v[132:135]
	v_mfma_f32_16x16x32_bf16 v[128:131], v[92:95], v[172:175], v[128:131]
	v_mfma_f32_16x16x32_bf16 v[116:119], v[88:91], v[192:195], v[116:119]
	v_mfma_f32_16x16x32_bf16 v[112:115], v[92:95], v[192:195], v[112:115]
	v_mfma_f32_16x16x32_bf16 v[100:103], v[88:91], v[196:199], v[100:103]
	v_mfma_f32_16x16x32_bf16 v[96:99], v[92:95], v[196:199], v[96:99]
	s_barrier
	s_setprio 0
	v_mov_b32_e32 v160, v218
	s_add_u32 s60, s40, 0x160000
	s_addc_u32 s61, s41, 0
	s_nop 0
	s_nop 0
	s_nop 0
	v_xad_u32 v190, v160, 64, 0
	ds_read_b128 v[160:163], v191 offset:16384
	ds_read_b128 v[164:167], v191 offset:18432
	ds_read_b128 v[168:171], v190 offset:16384
	ds_read_b128 v[172:175], v190 offset:18432
	ds_read_b128 v[176:179], v191 offset:20480
	ds_read_b128 v[180:183], v191 offset:22528
	ds_read_b128 v[192:195], v190 offset:20480
	ds_read_b128 v[196:199], v190 offset:22528
	s_mov_b32 m0, s80
	s_nop 0
	global_load_lds_dwordx4 v214, s[40:41]
	s_mov_b32 m0, s81
	s_nop 0
	global_load_lds_dwordx4 v216, s[40:41]
	s_mov_b32 m0, s29
	s_nop 0
	global_load_lds_dwordx4 v214, s[60:61]
	s_mov_b32 m0, s88
	s_nop 0
	global_load_lds_dwordx4 v216, s[60:61]
	s_mov_b32 m0, s76
	s_nop 0
	global_load_lds_dwordx4 v184, s[46:47]
	s_mov_b32 m0, s89
	s_nop 0
	global_load_lds_dwordx4 v215, s[46:47]
	s_waitcnt vmcnt(8)
	s_waitcnt lgkmcnt(0)
	s_setprio 1
	s_barrier
	v_mfma_f32_16x16x32_bf16 v[60:63], v[64:67], v[160:163], 0
	v_mfma_f32_16x16x32_bf16 v[56:59], v[68:71], v[160:163], 0
	v_mfma_f32_16x16x32_bf16 v[44:47], v[64:67], v[164:167], 0
	v_mfma_f32_16x16x32_bf16 v[40:43], v[68:71], v[164:167], 0
	v_mfma_f32_16x16x32_bf16 v[28:31], v[64:67], v[176:179], 0
	v_mfma_f32_16x16x32_bf16 v[24:27], v[68:71], v[176:179], 0
	v_mfma_f32_16x16x32_bf16 v[12:15], v[64:67], v[180:183], 0
	v_mfma_f32_16x16x32_bf16 v[8:11], v[68:71], v[180:183], 0
	v_mfma_f32_16x16x32_bf16 v[60:63], v[72:75], v[168:171], v[60:63]
	v_mfma_f32_16x16x32_bf16 v[56:59], v[76:79], v[168:171], v[56:59]
	v_mfma_f32_16x16x32_bf16 v[44:47], v[72:75], v[172:175], v[44:47]
	v_mfma_f32_16x16x32_bf16 v[40:43], v[76:79], v[172:175], v[40:43]
	v_mfma_f32_16x16x32_bf16 v[28:31], v[72:75], v[192:195], v[28:31]
	v_mfma_f32_16x16x32_bf16 v[24:27], v[76:79], v[192:195], v[24:27]
	v_mfma_f32_16x16x32_bf16 v[12:15], v[72:75], v[196:199], v[12:15]
	v_mfma_f32_16x16x32_bf16 v[8:11], v[76:79], v[196:199], v[8:11]
	v_mfma_f32_16x16x32_bf16 v[52:55], v[80:83], v[160:163], 0
	v_mfma_f32_16x16x32_bf16 v[48:51], v[84:87], v[160:163], 0
	v_mfma_f32_16x16x32_bf16 v[36:39], v[80:83], v[164:167], 0
	v_mfma_f32_16x16x32_bf16 v[32:35], v[84:87], v[164:167], 0
	v_mfma_f32_16x16x32_bf16 v[20:23], v[80:83], v[176:179], 0
	v_mfma_f32_16x16x32_bf16 v[16:19], v[84:87], v[176:179], 0
	v_mfma_f32_16x16x32_bf16 v[4:7], v[80:83], v[180:183], 0
	v_mfma_f32_16x16x32_bf16 v[0:3], v[84:87], v[180:183], 0
	v_mfma_f32_16x16x32_bf16 v[52:55], v[88:91], v[168:171], v[52:55]
	v_mfma_f32_16x16x32_bf16 v[48:51], v[92:95], v[168:171], v[48:51]
	v_mfma_f32_16x16x32_bf16 v[36:39], v[88:91], v[172:175], v[36:39]
	v_mfma_f32_16x16x32_bf16 v[32:35], v[92:95], v[172:175], v[32:35]
	v_mfma_f32_16x16x32_bf16 v[20:23], v[88:91], v[192:195], v[20:23]
	v_mfma_f32_16x16x32_bf16 v[16:19], v[92:95], v[192:195], v[16:19]
	v_mfma_f32_16x16x32_bf16 v[4:7], v[88:91], v[196:199], v[4:7]
	v_mfma_f32_16x16x32_bf16 v[0:3], v[92:95], v[196:199], v[0:3]
	s_barrier
; #define PG8_STAGE(bufoff, gbase, voff) do { _Pragma("unroll") for (int _i = 0; _i < 2; ++_i) \
;         dma16((const char*)(gbase), (voff)[_i], ldsb + (bufoff) + ldsw + _i * 8192); } while (0)
; #define PG8_LDA(dst, b, h) do { const int a1_ = opqv(aoff0) ^ 64; _Pragma("unroll") for (int m = 0; m < 4; ++m) { dst[m][0] = *(const LAS bf16x8*)(lds + PG8_SA(b, h) + aoff0 + m * 2048); dst[m][1] = *(const LAS bf16x8*)(lds + PG8_SA(b, h) + a1_ + m * 2048); } } while (0)
; #define PG8_LDB(dst, b, h) do { const int b1_ = opqv(boff0) ^ 64; _Pragma("unroll") for (int n = 0; n < 2; ++n) { dst[n][0] = *(const LAS bf16x8*)(lds + PG8_SB(b, h) + boff0 + n * 2048); dst[n][1] = *(const LAS bf16x8*)(lds + PG8_SB(b, h) + b1_ + n * 2048); } } while (0)
; #define PG8_MMA(ai, bj, At, Bt) do { __builtin_amdgcn_s_setprio(1); _Pragma("unroll") for (int m = 0; m < 4; ++m) _Pragma("unroll") for (int n = 0; n < 2; ++n) _Pragma("unroll") for (int k = 0; k < 2; ++k) \
;         acc[ai][bj][m][n] = __builtin_amdgcn_mfma_f32_16x16x32_bf16(Bt[n][k], At[m][k], acc[ai][bj][m][n], 0, 0, 0); __builtin_amdgcn_s_setprio(0); } while (0)
; #define PG8_WAIT_V(n) asm volatile("s_waitcnt vmcnt(" #n ")" ::: "memory")
; #define PG8_WAIT_L(n) asm volatile("s_waitcnt lgkmcnt(" #n ")" ::: "memory")
; #define PG8_BAR __builtin_amdgcn_s_barrier()
; #define PG8_SCHED __builtin_amdgcn_sched_barrier(0)
; template <class Epi>
; __device__ __forceinline__ void gemm_phase(LAS unsigned char* lds, const Gemm g, const StaticOrder& S, const Epi& E, int wave_) {
;     ...
;             PG8_STAGE(PG8_SA(0, 1), a2 + hstepA, voffA); PG8_LDB(B0, 1, 0); PG8_LDB(B1, 1, 1); PG8_SCHED; PG8_LDA(At, 1, 0);
;             PG8_WAIT_V(8); PG8_WAIT_L(0); PG8_BAR; PG8_MMA(0, 0, At, B0); PG8_MMA(0, 1, At, B1); PG8_BAR; PG8_SCHED;
;             PG8_STAGE(PG8_SB(1, 0), b3, voffB); PG8_STAGE(PG8_SB(1, 1), b3 + hstepB, voffB); PG8_STAGE(PG8_SA(1, 0), a3, voffA); PG8_LDA(At, 1, 1);
;             PG8_WAIT_V(8); PG8_WAIT_L(0); PG8_BAR; PG8_MMA(1, 0, At, B0); PG8_MMA(1, 1, At, B1); PG8_BAR; PG8_SCHED;
	s_setprio 0
	s_add_u32 s46, s46, 0x160000
	s_addc_u32 s47, s47, 0
	s_mov_b32 m0, s1
	s_nop 0
	global_load_lds_dwordx4 v184, s[46:47]
	v_mov_b32_e32 v64, v219
	s_mov_b32 m0, s69
	s_nop 0
	global_load_lds_dwordx4 v215, s[46:47]
	v_add_u32_e32 v68, s34, v219
	v_xad_u32 v76, v64, 64, s34
	v_mov_b32_e32 v80, v219
	s_add_i32 s46, 0, 0x1c000
	ds_read_b128 v[64:67], v68
	ds_read_b128 v[68:71], v68 offset:2048
	ds_read_b128 v[72:75], v76
	ds_read_b128 v[76:79], v76 offset:2048
	v_add_u32_e32 v84, s46, v219
	v_xad_u32 v92, v80, 64, s46
	ds_read_b128 v[80:83], v84
	ds_read_b128 v[84:87], v84 offset:2048
	ds_read_b128 v[88:91], v92
	ds_read_b128 v[92:95], v92 offset:2048
	v_mov_b32_e32 v160, v218
	s_nop 0
	v_xad_u32 v190, v160, 64, 0
	ds_read_b128 v[160:163], v191 offset:32768
	ds_read_b128 v[164:167], v191 offset:34816
	ds_read_b128 v[168:171], v190 offset:32768
	ds_read_b128 v[172:175], v190 offset:34816
	ds_read_b128 v[176:179], v191 offset:36864
	ds_read_b128 v[180:183], v191 offset:38912
	ds_read_b128 v[192:195], v190 offset:36864
	ds_read_b128 v[196:199], v190 offset:38912
	s_waitcnt vmcnt(8)
	s_waitcnt lgkmcnt(0)
	s_setprio 1
	s_barrier
	v_mfma_f32_16x16x32_bf16 v[156:159], v[64:67], v[160:163], v[156:159]
	v_mfma_f32_16x16x32_bf16 v[152:155], v[68:71], v[160:163], v[152:155]
	v_mfma_f32_16x16x32_bf16 v[140:143], v[64:67], v[164:167], v[140:143]
	v_mfma_f32_16x16x32_bf16 v[136:139], v[68:71], v[164:167], v[136:139]
	v_mfma_f32_16x16x32_bf16 v[124:127], v[64:67], v[176:179], v[124:127]
	v_mfma_f32_16x16x32_bf16 v[120:123], v[68:71], v[176:179], v[120:123]
	v_mfma_f32_16x16x32_bf16 v[108:111], v[64:67], v[180:183], v[108:111]
	v_mfma_f32_16x16x32_bf16 v[104:107], v[68:71], v[180:183], v[104:107]
	v_mfma_f32_16x16x32_bf16 v[156:159], v[72:75], v[168:171], v[156:159]
	v_mfma_f32_16x16x32_bf16 v[152:155], v[76:79], v[168:171], v[152:155]
	v_mfma_f32_16x16x32_bf16 v[140:143], v[72:75], v[172:175], v[140:143]
	v_mfma_f32_16x16x32_bf16 v[136:139], v[76:79], v[172:175], v[136:139]
	v_mfma_f32_16x16x32_bf16 v[124:127], v[72:75], v[192:195], v[124:127]
	v_mfma_f32_16x16x32_bf16 v[120:123], v[76:79], v[192:195], v[120:123]
	v_mfma_f32_16x16x32_bf16 v[108:111], v[72:75], v[196:199], v[108:111]
	v_mfma_f32_16x16x32_bf16 v[104:107], v[76:79], v[196:199], v[104:107]
	v_mfma_f32_16x16x32_bf16 v[148:151], v[80:83], v[160:163], v[148:151]
	s_add_u32 s46, s40, 0x80
	s_addc_u32 s47, s41, 0
	v_mfma_f32_16x16x32_bf16 v[144:147], v[84:87], v[160:163], v[144:147]
	v_mfma_f32_16x16x32_bf16 v[132:135], v[80:83], v[164:167], v[132:135]
	v_mfma_f32_16x16x32_bf16 v[128:131], v[84:87], v[164:167], v[128:131]
	v_mfma_f32_16x16x32_bf16 v[116:119], v[80:83], v[176:179], v[116:119]
	v_mfma_f32_16x16x32_bf16 v[112:115], v[84:87], v[176:179], v[112:115]
	v_mfma_f32_16x16x32_bf16 v[100:103], v[80:83], v[180:183], v[100:103]
	v_mfma_f32_16x16x32_bf16 v[96:99], v[84:87], v[180:183], v[96:99]
	v_mfma_f32_16x16x32_bf16 v[148:151], v[88:91], v[168:171], v[148:151]
	v_mfma_f32_16x16x32_bf16 v[144:147], v[92:95], v[168:171], v[144:147]
	v_mfma_f32_16x16x32_bf16 v[132:135], v[88:91], v[172:175], v[132:135]
	v_mfma_f32_16x16x32_bf16 v[128:131], v[92:95], v[172:175], v[128:131]
	v_mfma_f32_16x16x32_bf16 v[116:119], v[88:91], v[192:195], v[116:119]
	v_mfma_f32_16x16x32_bf16 v[112:115], v[92:95], v[192:195], v[112:115]
	v_mfma_f32_16x16x32_bf16 v[100:103], v[88:91], v[196:199], v[100:103]
	v_mfma_f32_16x16x32_bf16 v[96:99], v[92:95], v[196:199], v[96:99]
	s_barrier
	s_setprio 0
	s_add_u32 s40, s40, 0x160080
	s_addc_u32 s41, s41, 0
	v_mov_b32_e32 v160, v218
	s_nop 0
	s_nop 0
	v_xad_u32 v190, v160, 64, 0
	ds_read_b128 v[160:163], v191 offset:49152
	ds_read_b128 v[164:167], v191 offset:51200
	ds_read_b128 v[168:171], v190 offset:49152
	ds_read_b128 v[172:175], v190 offset:51200
	ds_read_b128 v[176:179], v191 offset:53248
	ds_read_b128 v[180:183], v191 offset:55296
	ds_read_b128 v[192:195], v190 offset:53248
	ds_read_b128 v[196:199], v190 offset:55296
	s_mov_b32 m0, s35
	s_nop 0
	global_load_lds_dwordx4 v214, s[46:47]
	s_mov_b32 m0, s33
	s_nop 0
	global_load_lds_dwordx4 v216, s[46:47]
	s_mov_b32 m0, s77
	s_nop 0
	global_load_lds_dwordx4 v214, s[40:41]
	s_mov_b32 m0, s3
	s_nop 0
	global_load_lds_dwordx4 v216, s[40:41]
	s_mov_b32 m0, s22
	s_nop 0
	global_load_lds_dwordx4 v184, s[36:37]
	s_mov_b32 m0, s2
	s_nop 0
	global_load_lds_dwordx4 v215, s[36:37]
	s_waitcnt vmcnt(8)
	s_waitcnt lgkmcnt(0)
	s_setprio 1
	s_barrier
	v_mfma_f32_16x16x32_bf16 v[60:63], v[64:67], v[160:163], v[60:63]
	v_mfma_f32_16x16x32_bf16 v[56:59], v[68:71], v[160:163], v[56:59]
	v_mfma_f32_16x16x32_bf16 v[44:47], v[64:67], v[164:167], v[44:47]
	v_mfma_f32_16x16x32_bf16 v[40:43], v[68:71], v[164:167], v[40:43]
	v_mfma_f32_16x16x32_bf16 v[28:31], v[64:67], v[176:179], v[28:31]
	v_mfma_f32_16x16x32_bf16 v[24:27], v[68:71], v[176:179], v[24:27]
	v_mfma_f32_16x16x32_bf16 v[12:15], v[64:67], v[180:183], v[12:15]
	v_mfma_f32_16x16x32_bf16 v[8:11], v[68:71], v[180:183], v[8:11]
	v_mfma_f32_16x16x32_bf16 v[60:63], v[72:75], v[168:171], v[60:63]
	v_mfma_f32_16x16x32_bf16 v[56:59], v[76:79], v[168:171], v[56:59]
	v_mfma_f32_16x16x32_bf16 v[44:47], v[72:75], v[172:175], v[44:47]
	v_mfma_f32_16x16x32_bf16 v[40:43], v[76:79], v[172:175], v[40:43]
	v_mfma_f32_16x16x32_bf16 v[28:31], v[72:75], v[192:195], v[28:31]
	v_mfma_f32_16x16x32_bf16 v[24:27], v[76:79], v[192:195], v[24:27]
	v_mfma_f32_16x16x32_bf16 v[12:15], v[72:75], v[196:199], v[12:15]
	v_mfma_f32_16x16x32_bf16 v[8:11], v[76:79], v[196:199], v[8:11]
	v_mfma_f32_16x16x32_bf16 v[52:55], v[80:83], v[160:163], v[52:55]
	v_mfma_f32_16x16x32_bf16 v[48:51], v[84:87], v[160:163], v[48:51]
	v_mfma_f32_16x16x32_bf16 v[36:39], v[80:83], v[164:167], v[36:39]
	v_mfma_f32_16x16x32_bf16 v[32:35], v[84:87], v[164:167], v[32:35]
	v_mfma_f32_16x16x32_bf16 v[20:23], v[80:83], v[176:179], v[20:23]
	v_mfma_f32_16x16x32_bf16 v[16:19], v[84:87], v[176:179], v[16:19]
	v_mfma_f32_16x16x32_bf16 v[4:7], v[80:83], v[180:183], v[4:7]
	v_mfma_f32_16x16x32_bf16 v[0:3], v[84:87], v[180:183], v[0:3]
	v_mfma_f32_16x16x32_bf16 v[52:55], v[88:91], v[168:171], v[52:55]
	v_mfma_f32_16x16x32_bf16 v[48:51], v[92:95], v[168:171], v[48:51]
	v_mfma_f32_16x16x32_bf16 v[36:39], v[88:91], v[172:175], v[36:39]
	v_mfma_f32_16x16x32_bf16 v[32:35], v[92:95], v[172:175], v[32:35]
	v_mfma_f32_16x16x32_bf16 v[20:23], v[88:91], v[192:195], v[20:23]
	v_mfma_f32_16x16x32_bf16 v[16:19], v[92:95], v[192:195], v[16:19]
	v_mfma_f32_16x16x32_bf16 v[4:7], v[88:91], v[196:199], v[4:7]
	v_mfma_f32_16x16x32_bf16 v[0:3], v[92:95], v[196:199], v[0:3]
	s_barrier
	s_setprio 0
	s_add_i32 s59, s59, 2
	s_add_u32 s16, s16, 0x100
	s_addc_u32 s17, s17, 0
	s_add_u32 s12, s12, 0x100
	s_addc_u32 s13, s13, 0
	s_cmpk_gt_u32 s59, 0x55
	s_cbranch_scc0 .LBB0_1552
	s_branch .Lpeel_exit_1
; #define PG8_STAGE(bufoff, gbase, voff) do { _Pragma("unroll") for (int _i = 0; _i < 2; ++_i) \
;         dma16((const char*)(gbase), (voff)[_i], ldsb + (bufoff) + ldsw + _i * 8192); } while (0)
; #define PG8_LDA(dst, b, h) do { const int a1_ = opqv(aoff0) ^ 64; _Pragma("unroll") for (int m = 0; m < 4; ++m) { dst[m][0] = *(const LAS bf16x8*)(lds + PG8_SA(b, h) + aoff0 + m * 2048); dst[m][1] = *(const LAS bf16x8*)(lds + PG8_SA(b, h) + a1_ + m * 2048); } } while (0)
; #define PG8_LDB(dst, b, h) do { const int b1_ = opqv(boff0) ^ 64; _Pragma("unroll") for (int n = 0; n < 2; ++n) { dst[n][0] = *(const LAS bf16x8*)(lds + PG8_SB(b, h) + boff0 + n * 2048); dst[n][1] = *(const LAS bf16x8*)(lds + PG8_SB(b, h) + b1_ + n * 2048); } } while (0)
; #define PG8_MMA(ai, bj, At, Bt) do { __builtin_amdgcn_s_setprio(1); _Pragma("unroll") for (int m = 0; m < 4; ++m) _Pragma("unroll") for (int n = 0; n < 2; ++n) _Pragma("unroll") for (int k = 0; k < 2; ++k) \
;         acc[ai][bj][m][n] = __builtin_amdgcn_mfma_f32_16x16x32_bf16(Bt[n][k], At[m][k], acc[ai][bj][m][n], 0, 0, 0); __builtin_amdgcn_s_setprio(0); } while (0)
; #define PG8_WAIT_V(n) asm volatile("s_waitcnt vmcnt(" #n ")" ::: "memory")
; #define PG8_WAIT_L(n) asm volatile("s_waitcnt lgkmcnt(" #n ")" ::: "memory")
; #define PG8_BAR __builtin_amdgcn_s_barrier()
; #define PG8_SCHED __builtin_amdgcn_sched_barrier(0)
; template <class Epi>
; __device__ __forceinline__ void gemm_phase(LAS unsigned char* lds, const Gemm g, const StaticOrder& S, const Epi& E, int wave_) {
;     ...
;             const char* a2 = last ? nA : cA + (size_t)(t + 2) * kstep; const char* b2 = last ? nB : cB + (size_t)(t + 2) * kstep;
;             const char* a3 = a2 + kstep; const char* b3 = b2 + kstep;
;             PG8_STAGE(PG8_SA(1, 1), a1 + hstepA, voffA); PG8_LDB(B0, 0, 0); PG8_LDB(B1, 0, 1); PG8_SCHED; PG8_LDA(At, 0, 0);
;             PG8_WAIT_V(8); PG8_WAIT_L(0); PG8_BAR; PG8_MMA(0, 0, At, B0); PG8_MMA(0, 1, At, B1); PG8_BAR; PG8_SCHED;
.LBB0_1552:
	s_add_u32 s36, s12, 0xffea0080
	s_addc_u32 s37, s13, -1
	s_cmpk_eq_i32 s59, 0x54
	s_cselect_b32 s46, s26, s36
	s_cselect_b32 s47, s27, s37
	s_cselect_b32 s40, s30, s16
	s_cselect_b32 s41, s31, s17
	s_add_u32 s36, s46, 0x80
	v_mov_b32_e32 v64, v219
	s_addc_u32 s37, s47, 0
	v_add_u32_e32 v68, s23, v219
	v_xad_u32 v76, v64, 64, s23
	v_mov_b32_e32 v80, v219
	s_add_i32 s60, 0, 0x14000
	ds_read_b128 v[64:67], v68
	ds_read_b128 v[68:71], v68 offset:2048
	ds_read_b128 v[72:75], v76
	ds_read_b128 v[76:79], v76 offset:2048
	v_add_u32_e32 v84, s60, v219
	v_xad_u32 v92, v80, 64, s60
	ds_read_b128 v[80:83], v84
	ds_read_b128 v[84:87], v84 offset:2048
	ds_read_b128 v[88:91], v92
	ds_read_b128 v[92:95], v92 offset:2048
	v_mov_b32_e32 v160, v218
	v_add_u32_e32 v191, 0, v218
	v_xad_u32 v190, v160, 64, 0
	ds_read_b128 v[160:163], v191
	ds_read_b128 v[164:167], v191 offset:2048
	ds_read_b128 v[168:171], v190
	ds_read_b128 v[172:175], v190 offset:2048
	ds_read_b128 v[176:179], v191 offset:4096
	ds_read_b128 v[180:183], v191 offset:6144
	ds_read_b128 v[192:195], v190 offset:4096
	ds_read_b128 v[196:199], v190 offset:6144
	s_mov_b32 m0, s14
	s_nop 0
	global_load_lds_dwordx4 v184, s[12:13]
	s_mov_b32 m0, s15
	s_nop 0
	global_load_lds_dwordx4 v215, s[12:13]
	s_waitcnt vmcnt(8)
	s_waitcnt lgkmcnt(0)
	s_setprio 1
	s_barrier
	v_mfma_f32_16x16x32_bf16 v[156:159], v[64:67], v[160:163], v[156:159]
	v_mfma_f32_16x16x32_bf16 v[152:155], v[68:71], v[160:163], v[152:155]
	v_mfma_f32_16x16x32_bf16 v[140:143], v[64:67], v[164:167], v[140:143]
	v_mfma_f32_16x16x32_bf16 v[136:139], v[68:71], v[164:167], v[136:139]
	v_mfma_f32_16x16x32_bf16 v[124:127], v[64:67], v[176:179], v[124:127]
	v_mfma_f32_16x16x32_bf16 v[120:123], v[68:71], v[176:179], v[120:123]
	v_mfma_f32_16x16x32_bf16 v[108:111], v[64:67], v[180:183], v[108:111]
	v_mfma_f32_16x16x32_bf16 v[104:107], v[68:71], v[180:183], v[104:107]
	v_mfma_f32_16x16x32_bf16 v[156:159], v[72:75], v[168:171], v[156:159]
	v_mfma_f32_16x16x32_bf16 v[152:155], v[76:79], v[168:171], v[152:155]
	v_mfma_f32_16x16x32_bf16 v[140:143], v[72:75], v[172:175], v[140:143]
	v_mfma_f32_16x16x32_bf16 v[136:139], v[76:79], v[172:175], v[136:139]
	v_mfma_f32_16x16x32_bf16 v[124:127], v[72:75], v[192:195], v[124:127]
	v_mfma_f32_16x16x32_bf16 v[120:123], v[76:79], v[192:195], v[120:123]
	v_mfma_f32_16x16x32_bf16 v[108:111], v[72:75], v[196:199], v[108:111]
	v_mfma_f32_16x16x32_bf16 v[104:107], v[76:79], v[196:199], v[104:107]
	v_mfma_f32_16x16x32_bf16 v[148:151], v[80:83], v[160:163], v[148:151]
	v_mfma_f32_16x16x32_bf16 v[144:147], v[84:87], v[160:163], v[144:147]
	v_mfma_f32_16x16x32_bf16 v[132:135], v[80:83], v[164:167], v[132:135]
	v_mfma_f32_16x16x32_bf16 v[128:131], v[84:87], v[164:167], v[128:131]
	v_mfma_f32_16x16x32_bf16 v[116:119], v[80:83], v[176:179], v[116:119]
	v_mfma_f32_16x16x32_bf16 v[112:115], v[84:87], v[176:179], v[112:115]
	v_mfma_f32_16x16x32_bf16 v[100:103], v[80:83], v[180:183], v[100:103]
	v_mfma_f32_16x16x32_bf16 v[96:99], v[84:87], v[180:183], v[96:99]
	v_mfma_f32_16x16x32_bf16 v[148:151], v[88:91], v[168:171], v[148:151]
	v_mfma_f32_16x16x32_bf16 v[144:147], v[92:95], v[168:171], v[144:147]
	v_mfma_f32_16x16x32_bf16 v[132:135], v[88:91], v[172:175], v[132:135]
	v_mfma_f32_16x16x32_bf16 v[128:131], v[92:95], v[172:175], v[128:131]
	v_mfma_f32_16x16x32_bf16 v[116:119], v[88:91], v[192:195], v[116:119]
	v_mfma_f32_16x16x32_bf16 v[112:115], v[92:95], v[192:195], v[112:115]
	v_mfma_f32_16x16x32_bf16 v[100:103], v[88:91], v[196:199], v[100:103]
	v_mfma_f32_16x16x32_bf16 v[96:99], v[92:95], v[196:199], v[96:99]
	s_barrier
	s_setprio 0
	v_mov_b32_e32 v160, v218
	s_add_u32 s60, s40, 0x160000
	s_addc_u32 s61, s41, 0
	s_nop 0
	s_nop 0
	s_nop 0
	v_xad_u32 v190, v160, 64, 0
	ds_read_b128 v[160:163], v191 offset:16384
	ds_read_b128 v[164:167], v191 offset:18432
	ds_read_b128 v[168:171], v190 offset:16384
	ds_read_b128 v[172:175], v190 offset:18432
	ds_read_b128 v[176:179], v191 offset:20480
	ds_read_b128 v[180:183], v191 offset:22528
	ds_read_b128 v[192:195], v190 offset:20480
	ds_read_b128 v[196:199], v190 offset:22528
	s_mov_b32 m0, s80
	s_nop 0
	global_load_lds_dwordx4 v214, s[40:41]
	s_mov_b32 m0, s81
	s_nop 0
	global_load_lds_dwordx4 v216, s[40:41]
	s_mov_b32 m0, s29
	s_nop 0
	global_load_lds_dwordx4 v214, s[60:61]
	s_mov_b32 m0, s88
	s_nop 0
	global_load_lds_dwordx4 v216, s[60:61]
	s_mov_b32 m0, s76
	s_nop 0
	global_load_lds_dwordx4 v184, s[46:47]
	s_mov_b32 m0, s89
	s_nop 0
	global_load_lds_dwordx4 v215, s[46:47]
	s_waitcnt vmcnt(8)
	s_waitcnt lgkmcnt(0)
	s_setprio 1
	s_barrier
; #define PG8_STAGE(bufoff, gbase, voff) do { _Pragma("unroll") for (int _i = 0; _i < 2; ++_i) \
;         dma16((const char*)(gbase), (voff)[_i], ldsb + (bufoff) + ldsw + _i * 8192); } while (0)
; #define PG8_LDA(dst, b, h) do { const int a1_ = opqv(aoff0) ^ 64; _Pragma("unroll") for (int m = 0; m < 4; ++m) { dst[m][0] = *(const LAS bf16x8*)(lds + PG8_SA(b, h) + aoff0 + m * 2048); dst[m][1] = *(const LAS bf16x8*)(lds + PG8_SA(b, h) + a1_ + m * 2048); } } while (0)
; #define PG8_LDB(dst, b, h) do { const int b1_ = opqv(boff0) ^ 64; _Pragma("unroll") for (int n = 0; n < 2; ++n) { dst[n][0] = *(const LAS bf16x8*)(lds + PG8_SB(b, h) + boff0 + n * 2048); dst[n][1] = *(const LAS bf16x8*)(lds + PG8_SB(b, h) + b1_ + n * 2048); } } while (0)
; #define PG8_MMA(ai, bj, At, Bt) do { __builtin_amdgcn_s_setprio(1); _Pragma("unroll") for (int m = 0; m < 4; ++m) _Pragma("unroll") for (int n = 0; n < 2; ++n) _Pragma("unroll") for (int k = 0; k < 2; ++k) \
;         acc[ai][bj][m][n] = __builtin_amdgcn_mfma_f32_16x16x32_bf16(Bt[n][k], At[m][k], acc[ai][bj][m][n], 0, 0, 0); __builtin_amdgcn_s_setprio(0); } while (0)
; #define PG8_WAIT_V(n) asm volatile("s_waitcnt vmcnt(" #n ")" ::: "memory")
; #define PG8_WAIT_L(n) asm volatile("s_waitcnt lgkmcnt(" #n ")" ::: "memory")
; #define PG8_BAR __builtin_amdgcn_s_barrier()
; #define PG8_SCHED __builtin_amdgcn_sched_barrier(0)
; template <class Epi>
; __device__ __forceinline__ void gemm_phase(LAS unsigned char* lds, const Gemm g, const StaticOrder& S, const Epi& E, int wave_) {
;     ...
;             PG8_WAIT_V(8); PG8_WAIT_L(0); PG8_BAR; PG8_MMA(1, 0, At, B0); PG8_MMA(1, 1, At, B1); PG8_BAR; PG8_SCHED;
;             PG8_STAGE(PG8_SA(0, 1), a2 + hstepA, voffA); PG8_LDB(B0, 1, 0); PG8_LDB(B1, 1, 1); PG8_SCHED; PG8_LDA(At, 1, 0);
;             PG8_WAIT_V(8); PG8_WAIT_L(0); PG8_BAR; PG8_MMA(0, 0, At, B0); PG8_MMA(0, 1, At, B1); PG8_BAR; PG8_SCHED;
	v_mfma_f32_16x16x32_bf16 v[60:63], v[64:67], v[160:163], v[60:63]
	v_mfma_f32_16x16x32_bf16 v[56:59], v[68:71], v[160:163], v[56:59]
	v_mfma_f32_16x16x32_bf16 v[44:47], v[64:67], v[164:167], v[44:47]
	v_mfma_f32_16x16x32_bf16 v[40:43], v[68:71], v[164:167], v[40:43]
	v_mfma_f32_16x16x32_bf16 v[28:31], v[64:67], v[176:179], v[28:31]
	v_mfma_f32_16x16x32_bf16 v[24:27], v[68:71], v[176:179], v[24:27]
	v_mfma_f32_16x16x32_bf16 v[12:15], v[64:67], v[180:183], v[12:15]
	v_mfma_f32_16x16x32_bf16 v[8:11], v[68:71], v[180:183], v[8:11]
	v_mfma_f32_16x16x32_bf16 v[60:63], v[72:75], v[168:171], v[60:63]
	v_mfma_f32_16x16x32_bf16 v[56:59], v[76:79], v[168:171], v[56:59]
	v_mfma_f32_16x16x32_bf16 v[44:47], v[72:75], v[172:175], v[44:47]
	v_mfma_f32_16x16x32_bf16 v[40:43], v[76:79], v[172:175], v[40:43]
	v_mfma_f32_16x16x32_bf16 v[28:31], v[72:75], v[192:195], v[28:31]
	v_mfma_f32_16x16x32_bf16 v[24:27], v[76:79], v[192:195], v[24:27]
	v_mfma_f32_16x16x32_bf16 v[12:15], v[72:75], v[196:199], v[12:15]
	v_mfma_f32_16x16x32_bf16 v[8:11], v[76:79], v[196:199], v[8:11]
	v_mfma_f32_16x16x32_bf16 v[52:55], v[80:83], v[160:163], v[52:55]
	v_mfma_f32_16x16x32_bf16 v[48:51], v[84:87], v[160:163], v[48:51]
	v_mfma_f32_16x16x32_bf16 v[36:39], v[80:83], v[164:167], v[36:39]
	v_mfma_f32_16x16x32_bf16 v[32:35], v[84:87], v[164:167], v[32:35]
	v_mfma_f32_16x16x32_bf16 v[20:23], v[80:83], v[176:179], v[20:23]
	v_mfma_f32_16x16x32_bf16 v[16:19], v[84:87], v[176:179], v[16:19]
	v_mfma_f32_16x16x32_bf16 v[4:7], v[80:83], v[180:183], v[4:7]
	v_mfma_f32_16x16x32_bf16 v[0:3], v[84:87], v[180:183], v[0:3]
	v_mfma_f32_16x16x32_bf16 v[52:55], v[88:91], v[168:171], v[52:55]
	v_mfma_f32_16x16x32_bf16 v[48:51], v[92:95], v[168:171], v[48:51]
	v_mfma_f32_16x16x32_bf16 v[36:39], v[88:91], v[172:175], v[36:39]
	v_mfma_f32_16x16x32_bf16 v[32:35], v[92:95], v[172:175], v[32:35]
	v_mfma_f32_16x16x32_bf16 v[20:23], v[88:91], v[192:195], v[20:23]
	v_mfma_f32_16x16x32_bf16 v[16:19], v[92:95], v[192:195], v[16:19]
	v_mfma_f32_16x16x32_bf16 v[4:7], v[88:91], v[196:199], v[4:7]
	v_mfma_f32_16x16x32_bf16 v[0:3], v[92:95], v[196:199], v[0:3]
	s_barrier
	s_setprio 0
	s_add_u32 s46, s46, 0x160000
	s_addc_u32 s47, s47, 0
	s_mov_b32 m0, s1
	s_nop 0
	global_load_lds_dwordx4 v184, s[46:47]
	v_mov_b32_e32 v64, v219
	s_mov_b32 m0, s69
	s_nop 0
	global_load_lds_dwordx4 v215, s[46:47]
	v_add_u32_e32 v68, s34, v219
	v_xad_u32 v76, v64, 64, s34
	v_mov_b32_e32 v80, v219
	s_add_i32 s46, 0, 0x1c000
	ds_read_b128 v[64:67], v68
	ds_read_b128 v[68:71], v68 offset:2048
	ds_read_b128 v[72:75], v76
	ds_read_b128 v[76:79], v76 offset:2048
	v_add_u32_e32 v84, s46, v219
	v_xad_u32 v92, v80, 64, s46
	ds_read_b128 v[80:83], v84
	ds_read_b128 v[84:87], v84 offset:2048
	ds_read_b128 v[88:91], v92
	ds_read_b128 v[92:95], v92 offset:2048
	v_mov_b32_e32 v160, v218
	s_nop 0
	v_xad_u32 v190, v160, 64, 0
	ds_read_b128 v[160:163], v191 offset:32768
	ds_read_b128 v[164:167], v191 offset:34816
	ds_read_b128 v[168:171], v190 offset:32768
	ds_read_b128 v[172:175], v190 offset:34816
	ds_read_b128 v[176:179], v191 offset:36864
	ds_read_b128 v[180:183], v191 offset:38912
	ds_read_b128 v[192:195], v190 offset:36864
	ds_read_b128 v[196:199], v190 offset:38912
	s_waitcnt vmcnt(8)
	s_waitcnt lgkmcnt(0)
	s_setprio 1
	s_barrier
	v_mfma_f32_16x16x32_bf16 v[156:159], v[64:67], v[160:163], v[156:159]
	v_mfma_f32_16x16x32_bf16 v[152:155], v[68:71], v[160:163], v[152:155]
	v_mfma_f32_16x16x32_bf16 v[140:143], v[64:67], v[164:167], v[140:143]
	v_mfma_f32_16x16x32_bf16 v[136:139], v[68:71], v[164:167], v[136:139]
	v_mfma_f32_16x16x32_bf16 v[124:127], v[64:67], v[176:179], v[124:127]
	v_mfma_f32_16x16x32_bf16 v[120:123], v[68:71], v[176:179], v[120:123]
	v_mfma_f32_16x16x32_bf16 v[108:111], v[64:67], v[180:183], v[108:111]
	v_mfma_f32_16x16x32_bf16 v[104:107], v[68:71], v[180:183], v[104:107]
	v_mfma_f32_16x16x32_bf16 v[156:159], v[72:75], v[168:171], v[156:159]
	v_mfma_f32_16x16x32_bf16 v[152:155], v[76:79], v[168:171], v[152:155]
	v_mfma_f32_16x16x32_bf16 v[140:143], v[72:75], v[172:175], v[140:143]
	v_mfma_f32_16x16x32_bf16 v[136:139], v[76:79], v[172:175], v[136:139]
	v_mfma_f32_16x16x32_bf16 v[124:127], v[72:75], v[192:195], v[124:127]
	v_mfma_f32_16x16x32_bf16 v[120:123], v[76:79], v[192:195], v[120:123]
	v_mfma_f32_16x16x32_bf16 v[108:111], v[72:75], v[196:199], v[108:111]
	v_mfma_f32_16x16x32_bf16 v[104:107], v[76:79], v[196:199], v[104:107]
	v_mfma_f32_16x16x32_bf16 v[148:151], v[80:83], v[160:163], v[148:151]
	s_add_u32 s46, s40, 0x80
	s_addc_u32 s47, s41, 0
	v_mfma_f32_16x16x32_bf16 v[144:147], v[84:87], v[160:163], v[144:147]
	v_mfma_f32_16x16x32_bf16 v[132:135], v[80:83], v[164:167], v[132:135]
	v_mfma_f32_16x16x32_bf16 v[128:131], v[84:87], v[164:167], v[128:131]
	v_mfma_f32_16x16x32_bf16 v[116:119], v[80:83], v[176:179], v[116:119]
	v_mfma_f32_16x16x32_bf16 v[112:115], v[84:87], v[176:179], v[112:115]
	v_mfma_f32_16x16x32_bf16 v[100:103], v[80:83], v[180:183], v[100:103]
	v_mfma_f32_16x16x32_bf16 v[96:99], v[84:87], v[180:183], v[96:99]
	v_mfma_f32_16x16x32_bf16 v[148:151], v[88:91], v[168:171], v[148:151]
	v_mfma_f32_16x16x32_bf16 v[144:147], v[92:95], v[168:171], v[144:147]
	v_mfma_f32_16x16x32_bf16 v[132:135], v[88:91], v[172:175], v[132:135]
	v_mfma_f32_16x16x32_bf16 v[128:131], v[92:95], v[172:175], v[128:131]
	v_mfma_f32_16x16x32_bf16 v[116:119], v[88:91], v[192:195], v[116:119]
	v_mfma_f32_16x16x32_bf16 v[112:115], v[92:95], v[192:195], v[112:115]
	v_mfma_f32_16x16x32_bf16 v[100:103], v[88:91], v[196:199], v[100:103]
	v_mfma_f32_16x16x32_bf16 v[96:99], v[92:95], v[196:199], v[96:99]
	s_barrier
; #define PG8_STAGE(bufoff, gbase, voff) do { _Pragma("unroll") for (int _i = 0; _i < 2; ++_i) \
;         dma16((const char*)(gbase), (voff)[_i], ldsb + (bufoff) + ldsw + _i * 8192); } while (0)
; #define PG8_LDA(dst, b, h) do { const int a1_ = opqv(aoff0) ^ 64; _Pragma("unroll") for (int m = 0; m < 4; ++m) { dst[m][0] = *(const LAS bf16x8*)(lds + PG8_SA(b, h) + aoff0 + m * 2048); dst[m][1] = *(const LAS bf16x8*)(lds + PG8_SA(b, h) + a1_ + m * 2048); } } while (0)
; #define PG8_MMA(ai, bj, At, Bt) do { __builtin_amdgcn_s_setprio(1); _Pragma("unroll") for (int m = 0; m < 4; ++m) _Pragma("unroll") for (int n = 0; n < 2; ++n) _Pragma("unroll") for (int k = 0; k < 2; ++k) \
;         acc[ai][bj][m][n] = __builtin_amdgcn_mfma_f32_16x16x32_bf16(Bt[n][k], At[m][k], acc[ai][bj][m][n], 0, 0, 0); __builtin_amdgcn_s_setprio(0); } while (0)
; #define PG8_WAIT_V(n) asm volatile("s_waitcnt vmcnt(" #n ")" ::: "memory")
; #define PG8_WAIT_L(n) asm volatile("s_waitcnt lgkmcnt(" #n ")" ::: "memory")
; #define PG8_BAR __builtin_amdgcn_s_barrier()
; #define PG8_SCHED __builtin_amdgcn_sched_barrier(0)
; template <class Epi>
; __device__ __forceinline__ void gemm_phase(LAS unsigned char* lds, const Gemm g, const StaticOrder& S, const Epi& E, int wave_) {
;     ...
;             PG8_STAGE(PG8_SB(1, 0), b3, voffB); PG8_STAGE(PG8_SB(1, 1), b3 + hstepB, voffB); PG8_STAGE(PG8_SA(1, 0), a3, voffA); PG8_LDA(At, 1, 1);
;             PG8_WAIT_V(8); PG8_WAIT_L(0); PG8_BAR; PG8_MMA(1, 0, At, B0); PG8_MMA(1, 1, At, B1); PG8_BAR; PG8_SCHED;
	s_setprio 0
	s_add_u32 s40, s40, 0x160080
	s_addc_u32 s41, s41, 0
	v_mov_b32_e32 v160, v218
	s_nop 0
	s_nop 0
	v_xad_u32 v190, v160, 64, 0
	ds_read_b128 v[160:163], v191 offset:49152
	ds_read_b128 v[164:167], v191 offset:51200
	ds_read_b128 v[168:171], v190 offset:49152
	ds_read_b128 v[172:175], v190 offset:51200
	ds_read_b128 v[176:179], v191 offset:53248
	ds_read_b128 v[180:183], v191 offset:55296
	ds_read_b128 v[192:195], v190 offset:53248
	ds_read_b128 v[196:199], v190 offset:55296
	s_mov_b32 m0, s35
	s_nop 0
	global_load_lds_dwordx4 v214, s[46:47]
	s_mov_b32 m0, s33
	s_nop 0
	global_load_lds_dwordx4 v216, s[46:47]
	s_mov_b32 m0, s77
	s_nop 0
	global_load_lds_dwordx4 v214, s[40:41]
	s_mov_b32 m0, s3
	s_nop 0
	global_load_lds_dwordx4 v216, s[40:41]
	s_mov_b32 m0, s22
	s_nop 0
	global_load_lds_dwordx4 v184, s[36:37]
	s_mov_b32 m0, s2
	s_nop 0
	global_load_lds_dwordx4 v215, s[36:37]
	s_waitcnt vmcnt(8)
	s_waitcnt lgkmcnt(0)
	s_setprio 1
	s_barrier
	v_mfma_f32_16x16x32_bf16 v[60:63], v[64:67], v[160:163], v[60:63]
	v_mfma_f32_16x16x32_bf16 v[56:59], v[68:71], v[160:163], v[56:59]
	v_mfma_f32_16x16x32_bf16 v[44:47], v[64:67], v[164:167], v[44:47]
	v_mfma_f32_16x16x32_bf16 v[40:43], v[68:71], v[164:167], v[40:43]
	v_mfma_f32_16x16x32_bf16 v[28:31], v[64:67], v[176:179], v[28:31]
	v_mfma_f32_16x16x32_bf16 v[24:27], v[68:71], v[176:179], v[24:27]
	v_mfma_f32_16x16x32_bf16 v[12:15], v[64:67], v[180:183], v[12:15]
	v_mfma_f32_16x16x32_bf16 v[8:11], v[68:71], v[180:183], v[8:11]
	v_mfma_f32_16x16x32_bf16 v[60:63], v[72:75], v[168:171], v[60:63]
	v_mfma_f32_16x16x32_bf16 v[56:59], v[76:79], v[168:171], v[56:59]
	v_mfma_f32_16x16x32_bf16 v[44:47], v[72:75], v[172:175], v[44:47]
	v_mfma_f32_16x16x32_bf16 v[40:43], v[76:79], v[172:175], v[40:43]
	v_mfma_f32_16x16x32_bf16 v[28:31], v[72:75], v[192:195], v[28:31]
	v_mfma_f32_16x16x32_bf16 v[24:27], v[76:79], v[192:195], v[24:27]
	v_mfma_f32_16x16x32_bf16 v[12:15], v[72:75], v[196:199], v[12:15]
	v_mfma_f32_16x16x32_bf16 v[8:11], v[76:79], v[196:199], v[8:11]
	v_mfma_f32_16x16x32_bf16 v[52:55], v[80:83], v[160:163], v[52:55]
	v_mfma_f32_16x16x32_bf16 v[48:51], v[84:87], v[160:163], v[48:51]
	v_mfma_f32_16x16x32_bf16 v[36:39], v[80:83], v[164:167], v[36:39]
	v_mfma_f32_16x16x32_bf16 v[32:35], v[84:87], v[164:167], v[32:35]
	v_mfma_f32_16x16x32_bf16 v[20:23], v[80:83], v[176:179], v[20:23]
	v_mfma_f32_16x16x32_bf16 v[16:19], v[84:87], v[176:179], v[16:19]
	v_mfma_f32_16x16x32_bf16 v[4:7], v[80:83], v[180:183], v[4:7]
	v_mfma_f32_16x16x32_bf16 v[0:3], v[84:87], v[180:183], v[0:3]
	v_mfma_f32_16x16x32_bf16 v[52:55], v[88:91], v[168:171], v[52:55]
	v_mfma_f32_16x16x32_bf16 v[48:51], v[92:95], v[168:171], v[48:51]
	v_mfma_f32_16x16x32_bf16 v[36:39], v[88:91], v[172:175], v[36:39]
	v_mfma_f32_16x16x32_bf16 v[32:35], v[92:95], v[172:175], v[32:35]
	v_mfma_f32_16x16x32_bf16 v[20:23], v[88:91], v[192:195], v[20:23]
	v_mfma_f32_16x16x32_bf16 v[16:19], v[92:95], v[192:195], v[16:19]
	v_mfma_f32_16x16x32_bf16 v[4:7], v[88:91], v[196:199], v[4:7]
	v_mfma_f32_16x16x32_bf16 v[0:3], v[92:95], v[196:199], v[0:3]
	s_barrier
	s_setprio 0
	s_add_i32 s59, s59, 2
	s_add_u32 s16, s16, 0x100
	s_addc_u32 s17, s17, 0
	s_add_u32 s12, s12, 0x100
	s_addc_u32 s13, s13, 0
	s_cmpk_gt_u32 s59, 0x55
	s_cbranch_scc0 .LBB0_1552

; #define PG8_STAGE(bufoff, gbase, voff) do { _Pragma("unroll") for (int _i = 0; _i < 2; ++_i) \
;         dma16((const char*)(gbase), (voff)[_i], ldsb + (bufoff) + ldsw + _i * 8192); } while (0)
; #define PG8_LDA(dst, b, h) do { const int a1_ = opqv(aoff0) ^ 64; _Pragma("unroll") for (int m = 0; m < 4; ++m) { dst[m][0] = *(const LAS bf16x8*)(lds + PG8_SA(b, h) + aoff0 + m * 2048); dst[m][1] = *(const LAS bf16x8*)(lds + PG8_SA(b, h) + a1_ + m * 2048); } } while (0)
; #define PG8_WAIT_V(n) asm volatile("s_waitcnt vmcnt(" #n ")" ::: "memory")
; #define PG8_BAR __builtin_amdgcn_s_barrier()
; template <class Epi>
; __device__ __forceinline__ void gemm_phase(LAS unsigned char* lds, const Gemm g, const StaticOrder& S, const Epi& E, int wave_) {
;     ...
;         const bool has_next = S.next(ui + 1, nxt);
;         const char* nA = has_next ? (const char*)g.A + (size_t)nxt.pm * tstepA : cA; const char* nB = has_next ? (const char*)g.Bt + (size_t)nxt.pn * tstepB : cB;
; #pragma unroll 1
;         for (int t = 0; t < nt; t += 2) {
;             const bool last = (t == nt - 2);
;             const char* a1 = cA + (size_t)(t + 1) * kstep;
;             const char* a2 = last ? nA : cA + (size_t)(t + 2) * kstep; const char* b2 = last ? nB : cB + (size_t)(t + 2) * kstep;
;             const char* a3 = a2 + kstep; const char* b3 = b2 + kstep;
;             PG8_STAGE(PG8_SA(1, 1), a1 + hstepA, voffA); PG8_LDB(B0, 0, 0); PG8_LDB(B1, 0, 1); PG8_SCHED; PG8_LDA(At, 0, 0);
;             PG8_WAIT_V(8); PG8_WAIT_L(0); PG8_BAR; PG8_MMA(0, 0, At, B0); PG8_MMA(0, 1, At, B1); PG8_BAR; PG8_SCHED;
;             PG8_STAGE(PG8_SB(0, 0), b2, voffB); PG8_STAGE(PG8_SB(0, 1), b2 + hstepB, voffB); PG8_STAGE(PG8_SA(0, 0), a2, voffA); PG8_LDA(At, 0, 1);
;             PG8_WAIT_V(8); PG8_WAIT_L(0); PG8_BAR; PG8_MMA(1, 0, At, B0); PG8_MMA(1, 1, At, B1); PG8_BAR; PG8_SCHED;
;             PG8_STAGE(PG8_SA(0, 1), a2 + hstepA, voffA); PG8_LDB(B0, 1, 0); PG8_LDB(B1, 1, 1); PG8_SCHED; PG8_LDA(At, 1, 0);
;             PG8_WAIT_V(8); PG8_WAIT_L(0); PG8_BAR; PG8_MMA(0, 0, At, B0); PG8_MMA(0, 1, At, B1); PG8_BAR; PG8_SCHED;
;             PG8_STAGE(PG8_SB(1, 0), b3, voffB); PG8_STAGE(PG8_SB(1, 1), b3 + hstepB, voffB); PG8_STAGE(PG8_SA(1, 0), a3, voffA); PG8_LDA(At, 1, 1);
;             PG8_WAIT_V(8); PG8_WAIT_L(0); PG8_BAR; PG8_MMA(1, 0, At, B0); PG8_MMA(1, 1, At, B1); PG8_BAR; PG8_SCHED;
.LBB0_1775:
	s_ashr_i32 s59, s58, 31
	s_lshl_b64 s[16:17], s[58:59], 20
	s_add_u32 s60, s21, s16
	s_addc_u32 s61, s52, s17
	s_and_b64 s[16:17], s[44:45], exec
	s_cselect_b32 s16, s61, s47
	s_cselect_b32 s17, s60, s46
	s_ashr_i32 s57, s56, 31
	s_lshl_b64 s[48:49], s[56:57], 20
	s_add_u32 s62, s66, s48
	s_addc_u32 s63, s67, s49
	s_and_b64 s[48:49], s[44:45], exec
	s_cselect_b32 s57, s63, s13
	s_cselect_b32 s59, s62, s12
	s_add_u32 s75, s12, 0x100
	s_addc_u32 s78, s13, 0
	s_add_u32 s12, s46, 0x80080
	s_addc_u32 s13, s47, 0
	s_mov_b32 s79, -2
	s_add_u32 s46, s12, 0xfff80080
	s_addc_u32 s47, s13, -1
	s_cmp_eq_u32 s79, 28
	s_cselect_b32 s64, s17, s46
	s_cselect_b32 s65, s16, s47
	s_cselect_b32 s48, s59, s75
	s_cselect_b32 s49, s57, s78
	s_add_u32 s46, s64, 0x80
	v_mov_b32_e32 v88, v238
	s_addc_u32 s47, s65, 0
	v_add_u32_e32 v92, s23, v238
	v_xad_u32 v100, v88, 64, s23
	v_mov_b32_e32 v108, v238
	s_add_i32 s82, 0, 0x14000
	ds_read_b128 v[88:91], v92
	ds_read_b128 v[92:95], v92 offset:2048
	ds_read_b128 v[96:99], v100
	ds_read_b128 v[100:103], v100 offset:2048
	v_add_u32_e32 v112, s82, v238
	v_xad_u32 v124, v108, 64, s82
	ds_read_b128 v[108:111], v112
	ds_read_b128 v[112:115], v112 offset:2048
	ds_read_b128 v[120:123], v124
	ds_read_b128 v[124:127], v124 offset:2048
	v_mov_b32_e32 v160, v237
	v_add_u32_e32 v191, 0, v237
	v_xad_u32 v190, v160, 64, 0
	ds_read_b128 v[160:163], v191
	ds_read_b128 v[164:167], v191 offset:2048
	ds_read_b128 v[168:171], v190
	ds_read_b128 v[172:175], v190 offset:2048
	ds_read_b128 v[176:179], v191 offset:4096
	ds_read_b128 v[180:183], v191 offset:6144
	ds_read_b128 v[192:195], v190 offset:4096
	ds_read_b128 v[196:199], v190 offset:6144
	s_mov_b32 m0, s14
	s_nop 0
	global_load_lds_dwordx4 v184, s[12:13]
	s_mov_b32 m0, s15
	s_nop 0
	global_load_lds_dwordx4 v234, s[12:13]
	s_waitcnt vmcnt(8)
	s_waitcnt lgkmcnt(0)
	s_setprio 1
	s_barrier
	v_mfma_f32_16x16x32_bf16 v[156:159], v[88:91], v[160:163], 0
	v_mfma_f32_16x16x32_bf16 v[152:155], v[92:95], v[160:163], 0
	v_mfma_f32_16x16x32_bf16 v[148:151], v[88:91], v[164:167], 0
	v_mfma_f32_16x16x32_bf16 v[144:147], v[92:95], v[164:167], 0
	v_mfma_f32_16x16x32_bf16 v[140:143], v[88:91], v[176:179], 0
	v_mfma_f32_16x16x32_bf16 v[136:139], v[92:95], v[176:179], 0
	v_mfma_f32_16x16x32_bf16 v[132:135], v[88:91], v[180:183], 0
	v_mfma_f32_16x16x32_bf16 v[128:131], v[92:95], v[180:183], 0
	v_mfma_f32_16x16x32_bf16 v[156:159], v[96:99], v[168:171], v[156:159]
	v_mfma_f32_16x16x32_bf16 v[152:155], v[100:103], v[168:171], v[152:155]
	v_mfma_f32_16x16x32_bf16 v[148:151], v[96:99], v[172:175], v[148:151]
	v_mfma_f32_16x16x32_bf16 v[144:147], v[100:103], v[172:175], v[144:147]
	v_mfma_f32_16x16x32_bf16 v[140:143], v[96:99], v[192:195], v[140:143]
	v_mfma_f32_16x16x32_bf16 v[136:139], v[100:103], v[192:195], v[136:139]
	v_mfma_f32_16x16x32_bf16 v[132:135], v[96:99], v[196:199], v[132:135]
	v_mfma_f32_16x16x32_bf16 v[128:131], v[100:103], v[196:199], v[128:131]
	v_mfma_f32_16x16x32_bf16 v[60:63], v[108:111], v[160:163], 0
	v_mfma_f32_16x16x32_bf16 v[56:59], v[112:115], v[160:163], 0
	v_mfma_f32_16x16x32_bf16 v[52:55], v[108:111], v[164:167], 0
	v_mfma_f32_16x16x32_bf16 v[48:51], v[112:115], v[164:167], 0
	v_mfma_f32_16x16x32_bf16 v[44:47], v[108:111], v[176:179], 0
	v_mfma_f32_16x16x32_bf16 v[40:43], v[112:115], v[176:179], 0
	v_mfma_f32_16x16x32_bf16 v[36:39], v[108:111], v[180:183], 0
	v_mfma_f32_16x16x32_bf16 v[32:35], v[112:115], v[180:183], 0
	v_mfma_f32_16x16x32_bf16 v[60:63], v[120:123], v[168:171], v[60:63]
	v_mfma_f32_16x16x32_bf16 v[56:59], v[124:127], v[168:171], v[56:59]
	v_mfma_f32_16x16x32_bf16 v[52:55], v[120:123], v[172:175], v[52:55]
	v_mfma_f32_16x16x32_bf16 v[48:51], v[124:127], v[172:175], v[48:51]
	v_mfma_f32_16x16x32_bf16 v[44:47], v[120:123], v[192:195], v[44:47]
	v_mfma_f32_16x16x32_bf16 v[40:43], v[124:127], v[192:195], v[40:43]
	v_mfma_f32_16x16x32_bf16 v[36:39], v[120:123], v[196:199], v[36:39]
	v_mfma_f32_16x16x32_bf16 v[32:35], v[124:127], v[196:199], v[32:35]
	s_barrier
	s_setprio 0
	v_mov_b32_e32 v160, v237
	s_add_u32 s82, s48, 0x80000
	s_addc_u32 s83, s49, 0
	s_nop 0
	s_nop 0
	s_nop 0
	v_xad_u32 v190, v160, 64, 0
	ds_read_b128 v[160:163], v191 offset:16384
	ds_read_b128 v[164:167], v191 offset:18432
	ds_read_b128 v[168:171], v190 offset:16384
	ds_read_b128 v[172:175], v190 offset:18432
	ds_read_b128 v[176:179], v191 offset:20480
	ds_read_b128 v[180:183], v191 offset:22528
	ds_read_b128 v[192:195], v190 offset:20480
	ds_read_b128 v[196:199], v190 offset:22528
	s_mov_b32 m0, s80
	s_nop 0
	global_load_lds_dwordx4 v233, s[48:49]
	s_mov_b32 m0, s81
	s_nop 0
	global_load_lds_dwordx4 v235, s[48:49]
	s_mov_b32 m0, s29
	s_nop 0
	global_load_lds_dwordx4 v233, s[82:83]
	s_mov_b32 m0, s88
	s_nop 0
	global_load_lds_dwordx4 v235, s[82:83]
	s_mov_b32 m0, s76
	s_nop 0
	global_load_lds_dwordx4 v184, s[64:65]
	s_mov_b32 m0, s89
	s_nop 0
	global_load_lds_dwordx4 v234, s[64:65]
	s_waitcnt vmcnt(8)
	s_waitcnt lgkmcnt(0)
	s_setprio 1
	s_barrier
; #define PG8_STAGE(bufoff, gbase, voff) do { _Pragma("unroll") for (int _i = 0; _i < 2; ++_i) \
;         dma16((const char*)(gbase), (voff)[_i], ldsb + (bufoff) + ldsw + _i * 8192); } while (0)
; #define PG8_LDA(dst, b, h) do { const int a1_ = opqv(aoff0) ^ 64; _Pragma("unroll") for (int m = 0; m < 4; ++m) { dst[m][0] = *(const LAS bf16x8*)(lds + PG8_SA(b, h) + aoff0 + m * 2048); dst[m][1] = *(const LAS bf16x8*)(lds + PG8_SA(b, h) + a1_ + m * 2048); } } while (0)
; #define PG8_LDB(dst, b, h) do { const int b1_ = opqv(boff0) ^ 64; _Pragma("unroll") for (int n = 0; n < 2; ++n) { dst[n][0] = *(const LAS bf16x8*)(lds + PG8_SB(b, h) + boff0 + n * 2048); dst[n][1] = *(const LAS bf16x8*)(lds + PG8_SB(b, h) + b1_ + n * 2048); } } while (0)
; #define PG8_MMA(ai, bj, At, Bt) do { __builtin_amdgcn_s_setprio(1); _Pragma("unroll") for (int m = 0; m < 4; ++m) _Pragma("unroll") for (int n = 0; n < 2; ++n) _Pragma("unroll") for (int k = 0; k < 2; ++k) \
;         acc[ai][bj][m][n] = __builtin_amdgcn_mfma_f32_16x16x32_bf16(Bt[n][k], At[m][k], acc[ai][bj][m][n], 0, 0, 0); __builtin_amdgcn_s_setprio(0); } while (0)
; #define PG8_WAIT_V(n) asm volatile("s_waitcnt vmcnt(" #n ")" ::: "memory")
; #define PG8_WAIT_L(n) asm volatile("s_waitcnt lgkmcnt(" #n ")" ::: "memory")
; #define PG8_BAR __builtin_amdgcn_s_barrier()
; #define PG8_SCHED __builtin_amdgcn_sched_barrier(0)
; template <class Epi>
; __device__ __forceinline__ void gemm_phase(LAS unsigned char* lds, const Gemm g, const StaticOrder& S, const Epi& E, int wave_) {
;     ...
;             PG8_WAIT_V(8); PG8_WAIT_L(0); PG8_BAR; PG8_MMA(1, 0, At, B0); PG8_MMA(1, 1, At, B1); PG8_BAR; PG8_SCHED;
;             PG8_STAGE(PG8_SA(0, 1), a2 + hstepA, voffA); PG8_LDB(B0, 1, 0); PG8_LDB(B1, 1, 1); PG8_SCHED; PG8_LDA(At, 1, 0);
;             PG8_WAIT_V(8); PG8_WAIT_L(0); PG8_BAR; PG8_MMA(0, 0, At, B0); PG8_MMA(0, 1, At, B1); PG8_BAR; PG8_SCHED;
	v_mfma_f32_16x16x32_bf16 v[116:119], v[88:91], v[160:163], 0
	v_mfma_f32_16x16x32_bf16 v[104:107], v[92:95], v[160:163], 0
	v_mfma_f32_16x16x32_bf16 v[84:87], v[88:91], v[164:167], 0
	v_mfma_f32_16x16x32_bf16 v[80:83], v[92:95], v[164:167], 0
	v_mfma_f32_16x16x32_bf16 v[76:79], v[88:91], v[176:179], 0
	v_mfma_f32_16x16x32_bf16 v[72:75], v[92:95], v[176:179], 0
	v_mfma_f32_16x16x32_bf16 v[68:71], v[88:91], v[180:183], 0
	v_mfma_f32_16x16x32_bf16 v[64:67], v[92:95], v[180:183], 0
	v_mfma_f32_16x16x32_bf16 v[116:119], v[96:99], v[168:171], v[116:119]
	v_mfma_f32_16x16x32_bf16 v[104:107], v[100:103], v[168:171], v[104:107]
	v_mfma_f32_16x16x32_bf16 v[84:87], v[96:99], v[172:175], v[84:87]
	v_mfma_f32_16x16x32_bf16 v[80:83], v[100:103], v[172:175], v[80:83]
	v_mfma_f32_16x16x32_bf16 v[76:79], v[96:99], v[192:195], v[76:79]
	v_mfma_f32_16x16x32_bf16 v[72:75], v[100:103], v[192:195], v[72:75]
	v_mfma_f32_16x16x32_bf16 v[68:71], v[96:99], v[196:199], v[68:71]
	v_mfma_f32_16x16x32_bf16 v[64:67], v[100:103], v[196:199], v[64:67]
	v_mfma_f32_16x16x32_bf16 v[28:31], v[108:111], v[160:163], 0
	v_mfma_f32_16x16x32_bf16 v[24:27], v[112:115], v[160:163], 0
	v_mfma_f32_16x16x32_bf16 v[20:23], v[108:111], v[164:167], 0
	v_mfma_f32_16x16x32_bf16 v[16:19], v[112:115], v[164:167], 0
	v_mfma_f32_16x16x32_bf16 v[12:15], v[108:111], v[176:179], 0
	v_mfma_f32_16x16x32_bf16 v[8:11], v[112:115], v[176:179], 0
	v_mfma_f32_16x16x32_bf16 v[4:7], v[108:111], v[180:183], 0
	v_mfma_f32_16x16x32_bf16 v[0:3], v[112:115], v[180:183], 0
	v_mfma_f32_16x16x32_bf16 v[28:31], v[120:123], v[168:171], v[28:31]
	v_mfma_f32_16x16x32_bf16 v[24:27], v[124:127], v[168:171], v[24:27]
	v_mfma_f32_16x16x32_bf16 v[20:23], v[120:123], v[172:175], v[20:23]
	v_mfma_f32_16x16x32_bf16 v[16:19], v[124:127], v[172:175], v[16:19]
	v_mfma_f32_16x16x32_bf16 v[12:15], v[120:123], v[192:195], v[12:15]
	v_mfma_f32_16x16x32_bf16 v[8:11], v[124:127], v[192:195], v[8:11]
	v_mfma_f32_16x16x32_bf16 v[4:7], v[120:123], v[196:199], v[4:7]
	v_mfma_f32_16x16x32_bf16 v[0:3], v[124:127], v[196:199], v[0:3]
	s_barrier
	s_setprio 0
	s_add_u32 s64, s64, 0x80000
	s_addc_u32 s65, s65, 0
	s_mov_b32 m0, s1
	s_nop 0
	global_load_lds_dwordx4 v184, s[64:65]
	v_mov_b32_e32 v88, v238
	s_mov_b32 m0, s69
	s_nop 0
	global_load_lds_dwordx4 v234, s[64:65]
	v_add_u32_e32 v92, s34, v238
	v_xad_u32 v100, v88, 64, s34
	v_mov_b32_e32 v108, v238
	s_add_i32 s64, 0, 0x1c000
	ds_read_b128 v[88:91], v92
	ds_read_b128 v[92:95], v92 offset:2048
	ds_read_b128 v[96:99], v100
	ds_read_b128 v[100:103], v100 offset:2048
	v_add_u32_e32 v112, s64, v238
	v_xad_u32 v124, v108, 64, s64
	ds_read_b128 v[108:111], v112
	ds_read_b128 v[112:115], v112 offset:2048
	ds_read_b128 v[120:123], v124
	ds_read_b128 v[124:127], v124 offset:2048
	v_mov_b32_e32 v160, v237
	s_nop 0
	v_xad_u32 v190, v160, 64, 0
	ds_read_b128 v[160:163], v191 offset:32768
	ds_read_b128 v[164:167], v191 offset:34816
	ds_read_b128 v[168:171], v190 offset:32768
	ds_read_b128 v[172:175], v190 offset:34816
	ds_read_b128 v[176:179], v191 offset:36864
	ds_read_b128 v[180:183], v191 offset:38912
	ds_read_b128 v[192:195], v190 offset:36864
	ds_read_b128 v[196:199], v190 offset:38912
	s_waitcnt vmcnt(8)
	s_waitcnt lgkmcnt(0)
	s_setprio 1
	s_barrier
	v_mfma_f32_16x16x32_bf16 v[156:159], v[88:91], v[160:163], v[156:159]
	v_mfma_f32_16x16x32_bf16 v[152:155], v[92:95], v[160:163], v[152:155]
	v_mfma_f32_16x16x32_bf16 v[148:151], v[88:91], v[164:167], v[148:151]
	v_mfma_f32_16x16x32_bf16 v[144:147], v[92:95], v[164:167], v[144:147]
	v_mfma_f32_16x16x32_bf16 v[140:143], v[88:91], v[176:179], v[140:143]
	v_mfma_f32_16x16x32_bf16 v[136:139], v[92:95], v[176:179], v[136:139]
	v_mfma_f32_16x16x32_bf16 v[132:135], v[88:91], v[180:183], v[132:135]
	v_mfma_f32_16x16x32_bf16 v[128:131], v[92:95], v[180:183], v[128:131]
	v_mfma_f32_16x16x32_bf16 v[156:159], v[96:99], v[168:171], v[156:159]
	v_mfma_f32_16x16x32_bf16 v[152:155], v[100:103], v[168:171], v[152:155]
	v_mfma_f32_16x16x32_bf16 v[148:151], v[96:99], v[172:175], v[148:151]
	v_mfma_f32_16x16x32_bf16 v[144:147], v[100:103], v[172:175], v[144:147]
	v_mfma_f32_16x16x32_bf16 v[140:143], v[96:99], v[192:195], v[140:143]
	v_mfma_f32_16x16x32_bf16 v[136:139], v[100:103], v[192:195], v[136:139]
	v_mfma_f32_16x16x32_bf16 v[132:135], v[96:99], v[196:199], v[132:135]
	v_mfma_f32_16x16x32_bf16 v[128:131], v[100:103], v[196:199], v[128:131]
	v_mfma_f32_16x16x32_bf16 v[60:63], v[108:111], v[160:163], v[60:63]
	s_add_u32 s64, s48, 0x80
	s_addc_u32 s65, s49, 0
	v_mfma_f32_16x16x32_bf16 v[56:59], v[112:115], v[160:163], v[56:59]
	v_mfma_f32_16x16x32_bf16 v[52:55], v[108:111], v[164:167], v[52:55]
	v_mfma_f32_16x16x32_bf16 v[48:51], v[112:115], v[164:167], v[48:51]
	v_mfma_f32_16x16x32_bf16 v[44:47], v[108:111], v[176:179], v[44:47]
	v_mfma_f32_16x16x32_bf16 v[40:43], v[112:115], v[176:179], v[40:43]
	v_mfma_f32_16x16x32_bf16 v[36:39], v[108:111], v[180:183], v[36:39]
	v_mfma_f32_16x16x32_bf16 v[32:35], v[112:115], v[180:183], v[32:35]
	v_mfma_f32_16x16x32_bf16 v[60:63], v[120:123], v[168:171], v[60:63]
	v_mfma_f32_16x16x32_bf16 v[56:59], v[124:127], v[168:171], v[56:59]
	v_mfma_f32_16x16x32_bf16 v[52:55], v[120:123], v[172:175], v[52:55]
	v_mfma_f32_16x16x32_bf16 v[48:51], v[124:127], v[172:175], v[48:51]
	v_mfma_f32_16x16x32_bf16 v[44:47], v[120:123], v[192:195], v[44:47]
	v_mfma_f32_16x16x32_bf16 v[40:43], v[124:127], v[192:195], v[40:43]
	v_mfma_f32_16x16x32_bf16 v[36:39], v[120:123], v[196:199], v[36:39]
	v_mfma_f32_16x16x32_bf16 v[32:35], v[124:127], v[196:199], v[32:35]
	s_barrier
; #define PG8_STAGE(bufoff, gbase, voff) do { _Pragma("unroll") for (int _i = 0; _i < 2; ++_i) \
;         dma16((const char*)(gbase), (voff)[_i], ldsb + (bufoff) + ldsw + _i * 8192); } while (0)
; #define PG8_LDA(dst, b, h) do { const int a1_ = opqv(aoff0) ^ 64; _Pragma("unroll") for (int m = 0; m < 4; ++m) { dst[m][0] = *(const LAS bf16x8*)(lds + PG8_SA(b, h) + aoff0 + m * 2048); dst[m][1] = *(const LAS bf16x8*)(lds + PG8_SA(b, h) + a1_ + m * 2048); } } while (0)
; #define PG8_WAIT_V(n) asm volatile("s_waitcnt vmcnt(" #n ")" ::: "memory")
; #define PG8_BAR __builtin_amdgcn_s_barrier()
; template <class Epi>
; __device__ __forceinline__ void gemm_phase(LAS unsigned char* lds, const Gemm g, const StaticOrder& S, const Epi& E, int wave_) {
;     ...
;         const bool has_next = S.next(ui + 1, nxt);
;         const char* nA = has_next ? (const char*)g.A + (size_t)nxt.pm * tstepA : cA; const char* nB = has_next ? (const char*)g.Bt + (size_t)nxt.pn * tstepB : cB;
; #pragma unroll 1
;         for (int t = 0; t < nt; t += 2) {
;             const bool last = (t == nt - 2);
;             const char* a1 = cA + (size_t)(t + 1) * kstep;
;             const char* a2 = last ? nA : cA + (size_t)(t + 2) * kstep; const char* b2 = last ? nB : cB + (size_t)(t + 2) * kstep;
;             const char* a3 = a2 + kstep; const char* b3 = b2 + kstep;
;             PG8_STAGE(PG8_SA(1, 1), a1 + hstepA, voffA); PG8_LDB(B0, 0, 0); PG8_LDB(B1, 0, 1); PG8_SCHED; PG8_LDA(At, 0, 0);
;             PG8_WAIT_V(8); PG8_WAIT_L(0); PG8_BAR; PG8_MMA(0, 0, At, B0); PG8_MMA(0, 1, At, B1); PG8_BAR; PG8_SCHED;
;             PG8_STAGE(PG8_SB(0, 0), b2, voffB); PG8_STAGE(PG8_SB(0, 1), b2 + hstepB, voffB); PG8_STAGE(PG8_SA(0, 0), a2, voffA); PG8_LDA(At, 0, 1);
;             PG8_WAIT_V(8); PG8_WAIT_L(0); PG8_BAR; PG8_MMA(1, 0, At, B0); PG8_MMA(1, 1, At, B1); PG8_BAR; PG8_SCHED;
;             PG8_STAGE(PG8_SA(0, 1), a2 + hstepA, voffA); PG8_LDB(B0, 1, 0); PG8_LDB(B1, 1, 1); PG8_SCHED; PG8_LDA(At, 1, 0);
;             PG8_WAIT_V(8); PG8_WAIT_L(0); PG8_BAR; PG8_MMA(0, 0, At, B0); PG8_MMA(0, 1, At, B1); PG8_BAR; PG8_SCHED;
;             PG8_STAGE(PG8_SB(1, 0), b3, voffB); PG8_STAGE(PG8_SB(1, 1), b3 + hstepB, voffB); PG8_STAGE(PG8_SA(1, 0), a3, voffA); PG8_LDA(At, 1, 1);
;             PG8_WAIT_V(8); PG8_WAIT_L(0); PG8_BAR; PG8_MMA(1, 0, At, B0); PG8_MMA(1, 1, At, B1); PG8_BAR; PG8_SCHED;
	s_setprio 0
	s_add_u32 s48, s48, 0x80080
	s_addc_u32 s49, s49, 0
	v_mov_b32_e32 v160, v237
	s_nop 0
	s_nop 0
	v_xad_u32 v190, v160, 64, 0
	ds_read_b128 v[160:163], v191 offset:49152
	ds_read_b128 v[164:167], v191 offset:51200
	ds_read_b128 v[168:171], v190 offset:49152
	ds_read_b128 v[172:175], v190 offset:51200
	ds_read_b128 v[176:179], v191 offset:53248
	ds_read_b128 v[180:183], v191 offset:55296
	ds_read_b128 v[192:195], v190 offset:53248
	ds_read_b128 v[196:199], v190 offset:55296
	s_mov_b32 m0, s35
	s_nop 0
	global_load_lds_dwordx4 v233, s[64:65]
	s_mov_b32 m0, s33
	s_nop 0
	global_load_lds_dwordx4 v235, s[64:65]
	s_mov_b32 m0, s77
	s_nop 0
	global_load_lds_dwordx4 v233, s[48:49]
	s_mov_b32 m0, s3
	s_nop 0
	global_load_lds_dwordx4 v235, s[48:49]
	s_mov_b32 m0, s22
	s_nop 0
	global_load_lds_dwordx4 v184, s[46:47]
	s_mov_b32 m0, s2
	s_nop 0
	global_load_lds_dwordx4 v234, s[46:47]
	s_waitcnt vmcnt(8)
	s_waitcnt lgkmcnt(0)
	s_setprio 1
	s_barrier
	v_mfma_f32_16x16x32_bf16 v[116:119], v[88:91], v[160:163], v[116:119]
	v_mfma_f32_16x16x32_bf16 v[104:107], v[92:95], v[160:163], v[104:107]
	v_mfma_f32_16x16x32_bf16 v[84:87], v[88:91], v[164:167], v[84:87]
	v_mfma_f32_16x16x32_bf16 v[80:83], v[92:95], v[164:167], v[80:83]
	v_mfma_f32_16x16x32_bf16 v[76:79], v[88:91], v[176:179], v[76:79]
	v_mfma_f32_16x16x32_bf16 v[72:75], v[92:95], v[176:179], v[72:75]
	v_mfma_f32_16x16x32_bf16 v[68:71], v[88:91], v[180:183], v[68:71]
	v_mfma_f32_16x16x32_bf16 v[64:67], v[92:95], v[180:183], v[64:67]
	v_mfma_f32_16x16x32_bf16 v[116:119], v[96:99], v[168:171], v[116:119]
	v_mfma_f32_16x16x32_bf16 v[104:107], v[100:103], v[168:171], v[104:107]
	v_mfma_f32_16x16x32_bf16 v[84:87], v[96:99], v[172:175], v[84:87]
	v_mfma_f32_16x16x32_bf16 v[80:83], v[100:103], v[172:175], v[80:83]
	v_mfma_f32_16x16x32_bf16 v[76:79], v[96:99], v[192:195], v[76:79]
	v_mfma_f32_16x16x32_bf16 v[72:75], v[100:103], v[192:195], v[72:75]
	v_mfma_f32_16x16x32_bf16 v[68:71], v[96:99], v[196:199], v[68:71]
	v_mfma_f32_16x16x32_bf16 v[64:67], v[100:103], v[196:199], v[64:67]
	v_mfma_f32_16x16x32_bf16 v[28:31], v[108:111], v[160:163], v[28:31]
	v_mfma_f32_16x16x32_bf16 v[24:27], v[112:115], v[160:163], v[24:27]
	v_mfma_f32_16x16x32_bf16 v[20:23], v[108:111], v[164:167], v[20:23]
	v_mfma_f32_16x16x32_bf16 v[16:19], v[112:115], v[164:167], v[16:19]
	v_mfma_f32_16x16x32_bf16 v[12:15], v[108:111], v[176:179], v[12:15]
	v_mfma_f32_16x16x32_bf16 v[8:11], v[112:115], v[176:179], v[8:11]
	v_mfma_f32_16x16x32_bf16 v[4:7], v[108:111], v[180:183], v[4:7]
	v_mfma_f32_16x16x32_bf16 v[0:3], v[112:115], v[180:183], v[0:3]
	v_mfma_f32_16x16x32_bf16 v[28:31], v[120:123], v[168:171], v[28:31]
	v_mfma_f32_16x16x32_bf16 v[24:27], v[124:127], v[168:171], v[24:27]
	v_mfma_f32_16x16x32_bf16 v[20:23], v[120:123], v[172:175], v[20:23]
	v_mfma_f32_16x16x32_bf16 v[16:19], v[124:127], v[172:175], v[16:19]
	v_mfma_f32_16x16x32_bf16 v[12:15], v[120:123], v[192:195], v[12:15]
	v_mfma_f32_16x16x32_bf16 v[8:11], v[124:127], v[192:195], v[8:11]
	v_mfma_f32_16x16x32_bf16 v[4:7], v[120:123], v[196:199], v[4:7]
	v_mfma_f32_16x16x32_bf16 v[0:3], v[124:127], v[196:199], v[0:3]
	s_barrier
	s_setprio 0
	s_add_i32 s79, s79, 2
	s_add_u32 s75, s75, 0x100
	s_addc_u32 s78, s78, 0
	s_add_u32 s12, s12, 0x100
	s_addc_u32 s13, s13, 0
	s_cmp_gt_u32 s79, 29
	s_cbranch_scc0 .LBB0_1776
	s_branch .Lpeel_exit_0
.LBB0_1776:
	s_add_u32 s46, s12, 0xfff80080
	s_addc_u32 s47, s13, -1
	s_cmp_eq_u32 s79, 28
	s_cselect_b32 s64, s17, s46
	s_cselect_b32 s65, s16, s47
	s_cselect_b32 s48, s59, s75
	s_cselect_b32 s49, s57, s78
	s_add_u32 s46, s64, 0x80
	v_mov_b32_e32 v88, v238
	s_addc_u32 s47, s65, 0
	v_add_u32_e32 v92, s23, v238
	v_xad_u32 v100, v88, 64, s23
	v_mov_b32_e32 v108, v238
	s_add_i32 s82, 0, 0x14000
	ds_read_b128 v[88:91], v92
	ds_read_b128 v[92:95], v92 offset:2048
	ds_read_b128 v[96:99], v100
	ds_read_b128 v[100:103], v100 offset:2048
	v_add_u32_e32 v112, s82, v238
	v_xad_u32 v124, v108, 64, s82
	ds_read_b128 v[108:111], v112
	ds_read_b128 v[112:115], v112 offset:2048
	ds_read_b128 v[120:123], v124
	ds_read_b128 v[124:127], v124 offset:2048
	v_mov_b32_e32 v160, v237
	v_add_u32_e32 v191, 0, v237
	v_xad_u32 v190, v160, 64, 0
	ds_read_b128 v[160:163], v191
	ds_read_b128 v[164:167], v191 offset:2048
	ds_read_b128 v[168:171], v190
	ds_read_b128 v[172:175], v190 offset:2048
	ds_read_b128 v[176:179], v191 offset:4096
	ds_read_b128 v[180:183], v191 offset:6144
	ds_read_b128 v[192:195], v190 offset:4096
	ds_read_b128 v[196:199], v190 offset:6144
	s_mov_b32 m0, s14
	s_nop 0
	global_load_lds_dwordx4 v184, s[12:13]
	s_mov_b32 m0, s15
	s_nop 0
	global_load_lds_dwordx4 v234, s[12:13]
	s_waitcnt vmcnt(8)
	s_waitcnt lgkmcnt(0)
	s_setprio 1
	s_barrier
; #define PG8_STAGE(bufoff, gbase, voff) do { _Pragma("unroll") for (int _i = 0; _i < 2; ++_i) \
;         dma16((const char*)(gbase), (voff)[_i], ldsb + (bufoff) + ldsw + _i * 8192); } while (0)
; #define PG8_LDA(dst, b, h) do { const int a1_ = opqv(aoff0) ^ 64; _Pragma("unroll") for (int m = 0; m < 4; ++m) { dst[m][0] = *(const LAS bf16x8*)(lds + PG8_SA(b, h) + aoff0 + m * 2048); dst[m][1] = *(const LAS bf16x8*)(lds + PG8_SA(b, h) + a1_ + m * 2048); } } while (0)
; #define PG8_MMA(ai, bj, At, Bt) do { __builtin_amdgcn_s_setprio(1); _Pragma("unroll") for (int m = 0; m < 4; ++m) _Pragma("unroll") for (int n = 0; n < 2; ++n) _Pragma("unroll") for (int k = 0; k < 2; ++k) \
;         acc[ai][bj][m][n] = __builtin_amdgcn_mfma_f32_16x16x32_bf16(Bt[n][k], At[m][k], acc[ai][bj][m][n], 0, 0, 0); __builtin_amdgcn_s_setprio(0); } while (0)
; #define PG8_WAIT_V(n) asm volatile("s_waitcnt vmcnt(" #n ")" ::: "memory")
; #define PG8_WAIT_L(n) asm volatile("s_waitcnt lgkmcnt(" #n ")" ::: "memory")
; #define PG8_BAR __builtin_amdgcn_s_barrier()
; #define PG8_SCHED __builtin_amdgcn_sched_barrier(0)
; template <class Epi>
; __device__ __forceinline__ void gemm_phase(LAS unsigned char* lds, const Gemm g, const StaticOrder& S, const Epi& E, int wave_) {
;     ...
;             PG8_WAIT_V(8); PG8_WAIT_L(0); PG8_BAR; PG8_MMA(0, 0, At, B0); PG8_MMA(0, 1, At, B1); PG8_BAR; PG8_SCHED;
;             PG8_STAGE(PG8_SB(0, 0), b2, voffB); PG8_STAGE(PG8_SB(0, 1), b2 + hstepB, voffB); PG8_STAGE(PG8_SA(0, 0), a2, voffA); PG8_LDA(At, 0, 1);
;             PG8_WAIT_V(8); PG8_WAIT_L(0); PG8_BAR; PG8_MMA(1, 0, At, B0); PG8_MMA(1, 1, At, B1); PG8_BAR; PG8_SCHED;
	v_mfma_f32_16x16x32_bf16 v[156:159], v[88:91], v[160:163], v[156:159]
	v_mfma_f32_16x16x32_bf16 v[152:155], v[92:95], v[160:163], v[152:155]
	v_mfma_f32_16x16x32_bf16 v[148:151], v[88:91], v[164:167], v[148:151]
	v_mfma_f32_16x16x32_bf16 v[144:147], v[92:95], v[164:167], v[144:147]
	v_mfma_f32_16x16x32_bf16 v[140:143], v[88:91], v[176:179], v[140:143]
	v_mfma_f32_16x16x32_bf16 v[136:139], v[92:95], v[176:179], v[136:139]
	v_mfma_f32_16x16x32_bf16 v[132:135], v[88:91], v[180:183], v[132:135]
	v_mfma_f32_16x16x32_bf16 v[128:131], v[92:95], v[180:183], v[128:131]
	v_mfma_f32_16x16x32_bf16 v[156:159], v[96:99], v[168:171], v[156:159]
	v_mfma_f32_16x16x32_bf16 v[152:155], v[100:103], v[168:171], v[152:155]
	v_mfma_f32_16x16x32_bf16 v[148:151], v[96:99], v[172:175], v[148:151]
	v_mfma_f32_16x16x32_bf16 v[144:147], v[100:103], v[172:175], v[144:147]
	v_mfma_f32_16x16x32_bf16 v[140:143], v[96:99], v[192:195], v[140:143]
	v_mfma_f32_16x16x32_bf16 v[136:139], v[100:103], v[192:195], v[136:139]
	v_mfma_f32_16x16x32_bf16 v[132:135], v[96:99], v[196:199], v[132:135]
	v_mfma_f32_16x16x32_bf16 v[128:131], v[100:103], v[196:199], v[128:131]
	v_mfma_f32_16x16x32_bf16 v[60:63], v[108:111], v[160:163], v[60:63]
	v_mfma_f32_16x16x32_bf16 v[56:59], v[112:115], v[160:163], v[56:59]
	v_mfma_f32_16x16x32_bf16 v[52:55], v[108:111], v[164:167], v[52:55]
	v_mfma_f32_16x16x32_bf16 v[48:51], v[112:115], v[164:167], v[48:51]
	v_mfma_f32_16x16x32_bf16 v[44:47], v[108:111], v[176:179], v[44:47]
	v_mfma_f32_16x16x32_bf16 v[40:43], v[112:115], v[176:179], v[40:43]
	v_mfma_f32_16x16x32_bf16 v[36:39], v[108:111], v[180:183], v[36:39]
	v_mfma_f32_16x16x32_bf16 v[32:35], v[112:115], v[180:183], v[32:35]
	v_mfma_f32_16x16x32_bf16 v[60:63], v[120:123], v[168:171], v[60:63]
	v_mfma_f32_16x16x32_bf16 v[56:59], v[124:127], v[168:171], v[56:59]
	v_mfma_f32_16x16x32_bf16 v[52:55], v[120:123], v[172:175], v[52:55]
	v_mfma_f32_16x16x32_bf16 v[48:51], v[124:127], v[172:175], v[48:51]
	v_mfma_f32_16x16x32_bf16 v[44:47], v[120:123], v[192:195], v[44:47]
	v_mfma_f32_16x16x32_bf16 v[40:43], v[124:127], v[192:195], v[40:43]
	v_mfma_f32_16x16x32_bf16 v[36:39], v[120:123], v[196:199], v[36:39]
	v_mfma_f32_16x16x32_bf16 v[32:35], v[124:127], v[196:199], v[32:35]
	s_barrier
	s_setprio 0
	v_mov_b32_e32 v160, v237
	s_add_u32 s82, s48, 0x80000
	s_addc_u32 s83, s49, 0
	s_nop 0
	s_nop 0
	s_nop 0
	v_xad_u32 v190, v160, 64, 0
	ds_read_b128 v[160:163], v191 offset:16384
	ds_read_b128 v[164:167], v191 offset:18432
	ds_read_b128 v[168:171], v190 offset:16384
	ds_read_b128 v[172:175], v190 offset:18432
	ds_read_b128 v[176:179], v191 offset:20480
	ds_read_b128 v[180:183], v191 offset:22528
	ds_read_b128 v[192:195], v190 offset:20480
	ds_read_b128 v[196:199], v190 offset:22528
	s_mov_b32 m0, s80
	s_nop 0
	global_load_lds_dwordx4 v233, s[48:49]
	s_mov_b32 m0, s81
	s_nop 0
	global_load_lds_dwordx4 v235, s[48:49]
	s_mov_b32 m0, s29
	s_nop 0
	global_load_lds_dwordx4 v233, s[82:83]
	s_mov_b32 m0, s88
	s_nop 0
	global_load_lds_dwordx4 v235, s[82:83]
	s_mov_b32 m0, s76
	s_nop 0
	global_load_lds_dwordx4 v184, s[64:65]
	s_mov_b32 m0, s89
	s_nop 0
	global_load_lds_dwordx4 v234, s[64:65]
	s_waitcnt vmcnt(8)
	s_waitcnt lgkmcnt(0)
	s_setprio 1
	s_barrier
	v_mfma_f32_16x16x32_bf16 v[116:119], v[88:91], v[160:163], v[116:119]
	v_mfma_f32_16x16x32_bf16 v[104:107], v[92:95], v[160:163], v[104:107]
	v_mfma_f32_16x16x32_bf16 v[84:87], v[88:91], v[164:167], v[84:87]
	v_mfma_f32_16x16x32_bf16 v[80:83], v[92:95], v[164:167], v[80:83]
	v_mfma_f32_16x16x32_bf16 v[76:79], v[88:91], v[176:179], v[76:79]
	v_mfma_f32_16x16x32_bf16 v[72:75], v[92:95], v[176:179], v[72:75]
	v_mfma_f32_16x16x32_bf16 v[68:71], v[88:91], v[180:183], v[68:71]
	v_mfma_f32_16x16x32_bf16 v[64:67], v[92:95], v[180:183], v[64:67]
	v_mfma_f32_16x16x32_bf16 v[116:119], v[96:99], v[168:171], v[116:119]
	v_mfma_f32_16x16x32_bf16 v[104:107], v[100:103], v[168:171], v[104:107]
	v_mfma_f32_16x16x32_bf16 v[84:87], v[96:99], v[172:175], v[84:87]
	v_mfma_f32_16x16x32_bf16 v[80:83], v[100:103], v[172:175], v[80:83]
	v_mfma_f32_16x16x32_bf16 v[76:79], v[96:99], v[192:195], v[76:79]
	v_mfma_f32_16x16x32_bf16 v[72:75], v[100:103], v[192:195], v[72:75]
	v_mfma_f32_16x16x32_bf16 v[68:71], v[96:99], v[196:199], v[68:71]
	v_mfma_f32_16x16x32_bf16 v[64:67], v[100:103], v[196:199], v[64:67]
	v_mfma_f32_16x16x32_bf16 v[28:31], v[108:111], v[160:163], v[28:31]
	v_mfma_f32_16x16x32_bf16 v[24:27], v[112:115], v[160:163], v[24:27]
	v_mfma_f32_16x16x32_bf16 v[20:23], v[108:111], v[164:167], v[20:23]
	v_mfma_f32_16x16x32_bf16 v[16:19], v[112:115], v[164:167], v[16:19]
	v_mfma_f32_16x16x32_bf16 v[12:15], v[108:111], v[176:179], v[12:15]
	v_mfma_f32_16x16x32_bf16 v[8:11], v[112:115], v[176:179], v[8:11]
	v_mfma_f32_16x16x32_bf16 v[4:7], v[108:111], v[180:183], v[4:7]
	v_mfma_f32_16x16x32_bf16 v[0:3], v[112:115], v[180:183], v[0:3]
	v_mfma_f32_16x16x32_bf16 v[28:31], v[120:123], v[168:171], v[28:31]
	v_mfma_f32_16x16x32_bf16 v[24:27], v[124:127], v[168:171], v[24:27]
	v_mfma_f32_16x16x32_bf16 v[20:23], v[120:123], v[172:175], v[20:23]
	v_mfma_f32_16x16x32_bf16 v[16:19], v[124:127], v[172:175], v[16:19]
	v_mfma_f32_16x16x32_bf16 v[12:15], v[120:123], v[192:195], v[12:15]
	v_mfma_f32_16x16x32_bf16 v[8:11], v[124:127], v[192:195], v[8:11]
	v_mfma_f32_16x16x32_bf16 v[4:7], v[120:123], v[196:199], v[4:7]
	v_mfma_f32_16x16x32_bf16 v[0:3], v[124:127], v[196:199], v[0:3]
	s_barrier
; #define PG8_STAGE(bufoff, gbase, voff) do { _Pragma("unroll") for (int _i = 0; _i < 2; ++_i) \
;         dma16((const char*)(gbase), (voff)[_i], ldsb + (bufoff) + ldsw + _i * 8192); } while (0)
; #define PG8_LDA(dst, b, h) do { const int a1_ = opqv(aoff0) ^ 64; _Pragma("unroll") for (int m = 0; m < 4; ++m) { dst[m][0] = *(const LAS bf16x8*)(lds + PG8_SA(b, h) + aoff0 + m * 2048); dst[m][1] = *(const LAS bf16x8*)(lds + PG8_SA(b, h) + a1_ + m * 2048); } } while (0)
; #define PG8_LDB(dst, b, h) do { const int b1_ = opqv(boff0) ^ 64; _Pragma("unroll") for (int n = 0; n < 2; ++n) { dst[n][0] = *(const LAS bf16x8*)(lds + PG8_SB(b, h) + boff0 + n * 2048); dst[n][1] = *(const LAS bf16x8*)(lds + PG8_SB(b, h) + b1_ + n * 2048); } } while (0)
; #define PG8_MMA(ai, bj, At, Bt) do { __builtin_amdgcn_s_setprio(1); _Pragma("unroll") for (int m = 0; m < 4; ++m) _Pragma("unroll") for (int n = 0; n < 2; ++n) _Pragma("unroll") for (int k = 0; k < 2; ++k) \
;         acc[ai][bj][m][n] = __builtin_amdgcn_mfma_f32_16x16x32_bf16(Bt[n][k], At[m][k], acc[ai][bj][m][n], 0, 0, 0); __builtin_amdgcn_s_setprio(0); } while (0)
; #define PG8_WAIT_V(n) asm volatile("s_waitcnt vmcnt(" #n ")" ::: "memory")
; #define PG8_WAIT_L(n) asm volatile("s_waitcnt lgkmcnt(" #n ")" ::: "memory")
; #define PG8_BAR __builtin_amdgcn_s_barrier()
; #define PG8_SCHED __builtin_amdgcn_sched_barrier(0)
; template <class Epi>
; __device__ __forceinline__ void gemm_phase(LAS unsigned char* lds, const Gemm g, const StaticOrder& S, const Epi& E, int wave_) {
;     ...
;             PG8_STAGE(PG8_SA(0, 1), a2 + hstepA, voffA); PG8_LDB(B0, 1, 0); PG8_LDB(B1, 1, 1); PG8_SCHED; PG8_LDA(At, 1, 0);
;             PG8_WAIT_V(8); PG8_WAIT_L(0); PG8_BAR; PG8_MMA(0, 0, At, B0); PG8_MMA(0, 1, At, B1); PG8_BAR; PG8_SCHED;
;             PG8_STAGE(PG8_SB(1, 0), b3, voffB); PG8_STAGE(PG8_SB(1, 1), b3 + hstepB, voffB); PG8_STAGE(PG8_SA(1, 0), a3, voffA); PG8_LDA(At, 1, 1);
;             PG8_WAIT_V(8); PG8_WAIT_L(0); PG8_BAR; PG8_MMA(1, 0, At, B0); PG8_MMA(1, 1, At, B1); PG8_BAR; PG8_SCHED;
	s_setprio 0
	s_add_u32 s64, s64, 0x80000
	s_addc_u32 s65, s65, 0
	s_mov_b32 m0, s1
	s_nop 0
	global_load_lds_dwordx4 v184, s[64:65]
	v_mov_b32_e32 v88, v238
	s_mov_b32 m0, s69
	s_nop 0
	global_load_lds_dwordx4 v234, s[64:65]
	v_add_u32_e32 v92, s34, v238
	v_xad_u32 v100, v88, 64, s34
	v_mov_b32_e32 v108, v238
	s_add_i32 s64, 0, 0x1c000
	ds_read_b128 v[88:91], v92
	ds_read_b128 v[92:95], v92 offset:2048
	ds_read_b128 v[96:99], v100
	ds_read_b128 v[100:103], v100 offset:2048
	v_add_u32_e32 v112, s64, v238
	v_xad_u32 v124, v108, 64, s64
	ds_read_b128 v[108:111], v112
	ds_read_b128 v[112:115], v112 offset:2048
	ds_read_b128 v[120:123], v124
	ds_read_b128 v[124:127], v124 offset:2048
	v_mov_b32_e32 v160, v237
	s_nop 0
	v_xad_u32 v190, v160, 64, 0
	ds_read_b128 v[160:163], v191 offset:32768
	ds_read_b128 v[164:167], v191 offset:34816
	ds_read_b128 v[168:171], v190 offset:32768
	ds_read_b128 v[172:175], v190 offset:34816
	ds_read_b128 v[176:179], v191 offset:36864
	ds_read_b128 v[180:183], v191 offset:38912
	ds_read_b128 v[192:195], v190 offset:36864
	ds_read_b128 v[196:199], v190 offset:38912
	s_waitcnt vmcnt(8)
	s_waitcnt lgkmcnt(0)
	s_setprio 1
	s_barrier
	v_mfma_f32_16x16x32_bf16 v[156:159], v[88:91], v[160:163], v[156:159]
	v_mfma_f32_16x16x32_bf16 v[152:155], v[92:95], v[160:163], v[152:155]
	v_mfma_f32_16x16x32_bf16 v[148:151], v[88:91], v[164:167], v[148:151]
	v_mfma_f32_16x16x32_bf16 v[144:147], v[92:95], v[164:167], v[144:147]
	v_mfma_f32_16x16x32_bf16 v[140:143], v[88:91], v[176:179], v[140:143]
	v_mfma_f32_16x16x32_bf16 v[136:139], v[92:95], v[176:179], v[136:139]
	v_mfma_f32_16x16x32_bf16 v[132:135], v[88:91], v[180:183], v[132:135]
	v_mfma_f32_16x16x32_bf16 v[128:131], v[92:95], v[180:183], v[128:131]
	v_mfma_f32_16x16x32_bf16 v[156:159], v[96:99], v[168:171], v[156:159]
	v_mfma_f32_16x16x32_bf16 v[152:155], v[100:103], v[168:171], v[152:155]
	v_mfma_f32_16x16x32_bf16 v[148:151], v[96:99], v[172:175], v[148:151]
	v_mfma_f32_16x16x32_bf16 v[144:147], v[100:103], v[172:175], v[144:147]
	v_mfma_f32_16x16x32_bf16 v[140:143], v[96:99], v[192:195], v[140:143]
	v_mfma_f32_16x16x32_bf16 v[136:139], v[100:103], v[192:195], v[136:139]
	v_mfma_f32_16x16x32_bf16 v[132:135], v[96:99], v[196:199], v[132:135]
	v_mfma_f32_16x16x32_bf16 v[128:131], v[100:103], v[196:199], v[128:131]
	v_mfma_f32_16x16x32_bf16 v[60:63], v[108:111], v[160:163], v[60:63]
	s_add_u32 s64, s48, 0x80
	s_addc_u32 s65, s49, 0
	v_mfma_f32_16x16x32_bf16 v[56:59], v[112:115], v[160:163], v[56:59]
	v_mfma_f32_16x16x32_bf16 v[52:55], v[108:111], v[164:167], v[52:55]
	v_mfma_f32_16x16x32_bf16 v[48:51], v[112:115], v[164:167], v[48:51]
	v_mfma_f32_16x16x32_bf16 v[44:47], v[108:111], v[176:179], v[44:47]
	v_mfma_f32_16x16x32_bf16 v[40:43], v[112:115], v[176:179], v[40:43]
	v_mfma_f32_16x16x32_bf16 v[36:39], v[108:111], v[180:183], v[36:39]
	v_mfma_f32_16x16x32_bf16 v[32:35], v[112:115], v[180:183], v[32:35]
	v_mfma_f32_16x16x32_bf16 v[60:63], v[120:123], v[168:171], v[60:63]
	v_mfma_f32_16x16x32_bf16 v[56:59], v[124:127], v[168:171], v[56:59]
	v_mfma_f32_16x16x32_bf16 v[52:55], v[120:123], v[172:175], v[52:55]
	v_mfma_f32_16x16x32_bf16 v[48:51], v[124:127], v[172:175], v[48:51]
	v_mfma_f32_16x16x32_bf16 v[44:47], v[120:123], v[192:195], v[44:47]
	v_mfma_f32_16x16x32_bf16 v[40:43], v[124:127], v[192:195], v[40:43]
	v_mfma_f32_16x16x32_bf16 v[36:39], v[120:123], v[196:199], v[36:39]
	v_mfma_f32_16x16x32_bf16 v[32:35], v[124:127], v[196:199], v[32:35]
	s_barrier
	s_setprio 0
	s_add_u32 s48, s48, 0x80080
	s_addc_u32 s49, s49, 0
	v_mov_b32_e32 v160, v237
	s_nop 0
	s_nop 0
	v_xad_u32 v190, v160, 64, 0
	ds_read_b128 v[160:163], v191 offset:49152
	ds_read_b128 v[164:167], v191 offset:51200
	ds_read_b128 v[168:171], v190 offset:49152
	ds_read_b128 v[172:175], v190 offset:51200
	ds_read_b128 v[176:179], v191 offset:53248
	ds_read_b128 v[180:183], v191 offset:55296
	ds_read_b128 v[192:195], v190 offset:53248
	ds_read_b128 v[196:199], v190 offset:55296
	s_mov_b32 m0, s35
	s_nop 0
	global_load_lds_dwordx4 v233, s[64:65]
	s_mov_b32 m0, s33
	s_nop 0
	global_load_lds_dwordx4 v235, s[64:65]
	s_mov_b32 m0, s77
	s_nop 0
	global_load_lds_dwordx4 v233, s[48:49]
	s_mov_b32 m0, s3
	s_nop 0
	global_load_lds_dwordx4 v235, s[48:49]
	s_mov_b32 m0, s22
	s_nop 0
	global_load_lds_dwordx4 v184, s[46:47]
	s_mov_b32 m0, s2
	s_nop 0
	global_load_lds_dwordx4 v234, s[46:47]
	s_waitcnt vmcnt(8)
	s_waitcnt lgkmcnt(0)
	s_setprio 1
	s_barrier
	v_mfma_f32_16x16x32_bf16 v[116:119], v[88:91], v[160:163], v[116:119]
	v_mfma_f32_16x16x32_bf16 v[104:107], v[92:95], v[160:163], v[104:107]
	v_mfma_f32_16x16x32_bf16 v[84:87], v[88:91], v[164:167], v[84:87]
	v_mfma_f32_16x16x32_bf16 v[80:83], v[92:95], v[164:167], v[80:83]
	v_mfma_f32_16x16x32_bf16 v[76:79], v[88:91], v[176:179], v[76:79]
	v_mfma_f32_16x16x32_bf16 v[72:75], v[92:95], v[176:179], v[72:75]
	v_mfma_f32_16x16x32_bf16 v[68:71], v[88:91], v[180:183], v[68:71]
	v_mfma_f32_16x16x32_bf16 v[64:67], v[92:95], v[180:183], v[64:67]
	v_mfma_f32_16x16x32_bf16 v[116:119], v[96:99], v[168:171], v[116:119]
	v_mfma_f32_16x16x32_bf16 v[104:107], v[100:103], v[168:171], v[104:107]
	v_mfma_f32_16x16x32_bf16 v[84:87], v[96:99], v[172:175], v[84:87]
	v_mfma_f32_16x16x32_bf16 v[80:83], v[100:103], v[172:175], v[80:83]
	v_mfma_f32_16x16x32_bf16 v[76:79], v[96:99], v[192:195], v[76:79]
	v_mfma_f32_16x16x32_bf16 v[72:75], v[100:103], v[192:195], v[72:75]
	v_mfma_f32_16x16x32_bf16 v[68:71], v[96:99], v[196:199], v[68:71]
	v_mfma_f32_16x16x32_bf16 v[64:67], v[100:103], v[196:199], v[64:67]
	v_mfma_f32_16x16x32_bf16 v[28:31], v[108:111], v[160:163], v[28:31]
	v_mfma_f32_16x16x32_bf16 v[24:27], v[112:115], v[160:163], v[24:27]
	v_mfma_f32_16x16x32_bf16 v[20:23], v[108:111], v[164:167], v[20:23]
	v_mfma_f32_16x16x32_bf16 v[16:19], v[112:115], v[164:167], v[16:19]
	v_mfma_f32_16x16x32_bf16 v[12:15], v[108:111], v[176:179], v[12:15]
	v_mfma_f32_16x16x32_bf16 v[8:11], v[112:115], v[176:179], v[8:11]
	v_mfma_f32_16x16x32_bf16 v[4:7], v[108:111], v[180:183], v[4:7]
	v_mfma_f32_16x16x32_bf16 v[0:3], v[112:115], v[180:183], v[0:3]
	v_mfma_f32_16x16x32_bf16 v[28:31], v[120:123], v[168:171], v[28:31]
	v_mfma_f32_16x16x32_bf16 v[24:27], v[124:127], v[168:171], v[24:27]
	v_mfma_f32_16x16x32_bf16 v[20:23], v[120:123], v[172:175], v[20:23]
	v_mfma_f32_16x16x32_bf16 v[16:19], v[124:127], v[172:175], v[16:19]
	v_mfma_f32_16x16x32_bf16 v[12:15], v[120:123], v[192:195], v[12:15]
	v_mfma_f32_16x16x32_bf16 v[8:11], v[124:127], v[192:195], v[8:11]
	v_mfma_f32_16x16x32_bf16 v[4:7], v[120:123], v[196:199], v[4:7]
	v_mfma_f32_16x16x32_bf16 v[0:3], v[124:127], v[196:199], v[0:3]
	s_barrier
	s_setprio 0
	s_add_i32 s79, s79, 2
	s_add_u32 s75, s75, 0x100
	s_addc_u32 s78, s78, 0
	s_add_u32 s12, s12, 0x100
	s_addc_u32 s13, s13, 0
	s_cmp_gt_u32 s79, 29
	s_cbranch_scc0 .LBB0_1776
